# residual epilogues (FFN2, LRUout, Wo) pipelined across the two wave rows: barrier behind each batch of loads
# baseline (speedup 1.0000x reference)
; #define PG8_STAGE(bufoff, gbase, voff) do { _Pragma("unroll") for (int _i = 0; _i < 2; ++_i) \
;         __builtin_amdgcn_global_load_lds((const unsigned*)((const char*)(gbase) + (voff)[_i]), (LAS unsigned*)(lds + (bufoff) + ldsw + _i * 8192), 16, 0, 0); } while (0)
; #define PG8_LDA(dst, b, h) do { _Pragma("unroll") for (int m = 0; m < 4; ++m) _Pragma("unroll") for (int k = 0; k < 2; ++k) dst[m][k] = *(const LAS bf16x8*)(lds + PG8_SA(b, h) + aoff + m * 2048 + k * 1024); } while (0)
; #define PG8_LDB(dst, b, h) do { _Pragma("unroll") for (int n = 0; n < 2; ++n) _Pragma("unroll") for (int k = 0; k < 2; ++k) dst[n][k] = *(const LAS bf16x8*)(lds + PG8_SB(b, h) + boff + n * 2048 + k * 1024); } while (0)
; #define PG8_MMA(ai, bj, At, Bt) do { __builtin_amdgcn_s_setprio(1); _Pragma("unroll") for (int m = 0; m < 4; ++m) _Pragma("unroll") for (int n = 0; n < 2; ++n) _Pragma("unroll") for (int k = 0; k < 2; ++k) \
;         acc[ai][bj][m][n] = __builtin_amdgcn_mfma_f32_16x16x32_bf16(Bt[n][k], At[m][k], acc[ai][bj][m][n], 0, 0, 0); __builtin_amdgcn_s_setprio(0); } while (0)
; #define PG8_WAIT_V(n) asm volatile("s_waitcnt vmcnt(" #n ")" ::: "memory")
; #define PG8_WAIT_L(n) asm volatile("s_waitcnt lgkmcnt(" #n ")" ::: "memory")
; template <class Epi>
; __device__ __forceinline__ void gemm_phase(LAS unsigned char* lds, const Gemm g, const StaticOrder& S, const Epi& E) {
;     ...
;         for (int t = 0; t < nt; t += 2) {
;             const bool last = (t == nt - 2);
;             const char* a1 = cA + (size_t)(t + 1) * kstep;
;             const char* a2 = last ? nA : cA + (size_t)(t + 2) * kstep; const char* b2 = last ? nB : cB + (size_t)(t + 2) * kstep;
;             const char* a3 = a2 + kstep; const char* b3 = b2 + kstep;
;             PG8_LDB(B0, 0, 0); PG8_SCHED; PG8_LDA(At, 0, 0); PG8_STAGE(PG8_SA(1, 1), a1 + hstepA, voffA);
;             PG8_WAIT_L(8); PG8_BAR; PG8_WAIT_L(0); PG8_MMA(0, 0, At, B0); PG8_BAR; PG8_SCHED;
;             PG8_LDB(B1, 0, 1); PG8_STAGE(PG8_SB(0, 0), b2, voffB);
;             PG8_BAR; PG8_WAIT_L(0); PG8_MMA(0, 1, At, B1); PG8_BAR;
;             PG8_LDA(At, 0, 1); PG8_STAGE(PG8_SA(0, 0), a2, voffA);
;             PG8_BAR; PG8_WAIT_L(0); PG8_MMA(1, 0, At, B0); PG8_BAR; PG8_SCHED;
;             PG8_STAGE(PG8_SB(0, 1), b2 + hstepB, voffB);
;             PG8_WAIT_V(6); PG8_BAR; PG8_MMA(1, 1, At, B1); PG8_BAR;
.LBB0_411:
	ds_read_b128 v[140:143], v149
	ds_read_b128 v[152:155], v149 offset:1024
	ds_read_b128 v[156:159], v149 offset:2048
	ds_read_b128 v[160:163], v149 offset:3072
	s_add_u32 s28, s26, 0x100
	s_addc_u32 s29, s27, 0
	s_cmp_eq_u32 s68, 40
	s_cselect_b32 s35, s11, s29
	s_cselect_b32 s34, s10, s28
	s_cselect_b32 s31, s13, s63
	s_cselect_b32 s30, s12, s49
	v_lshl_add_u64 v[144:145], s[26:27], 0, v[132:133]
	s_add_i32 m0, s36, 0xc000
	ds_read_b128 v[164:167], v150
	ds_read_b128 v[168:171], v150 offset:1024
	ds_read_b128 v[172:175], v150 offset:2048
	ds_read_b128 v[176:179], v150 offset:3072
	ds_read_b128 v[180:183], v150 offset:4096
	ds_read_b128 v[184:187], v150 offset:5120
	ds_read_b128 v[188:191], v150 offset:6144
	ds_read_b128 v[192:195], v150 offset:7168
	global_load_lds_dwordx4 v[144:145], off
	v_lshl_add_u64 v[144:145], s[26:27], 0, v[134:135]
	s_add_i32 m0, s36, 0xe000
	s_nop 0
	global_load_lds_dwordx4 v[144:145], off
	ds_read_b128 v[196:199], v151
	ds_read_b128 v[200:203], v151 offset:1024
	ds_read_b128 v[204:207], v151 offset:2048
	ds_read_b128 v[208:211], v151 offset:3072
	s_waitcnt lgkmcnt(0)
	s_barrier
	s_setprio 1
	v_mfma_f32_16x16x32_bf16 v[124:127], v[140:143], v[164:167], v[124:127]
	v_mfma_f32_16x16x32_bf16 v[120:123], v[156:159], v[164:167], v[120:123]
	v_mfma_f32_16x16x32_bf16 v[112:115], v[140:143], v[172:175], v[112:115]
	v_mfma_f32_16x16x32_bf16 v[104:107], v[156:159], v[172:175], v[104:107]
	v_mfma_f32_16x16x32_bf16 v[92:95], v[140:143], v[180:183], v[92:95]
	v_mfma_f32_16x16x32_bf16 v[88:91], v[156:159], v[180:183], v[88:91]
	v_mfma_f32_16x16x32_bf16 v[80:83], v[140:143], v[188:191], v[80:83]
	v_mfma_f32_16x16x32_bf16 v[72:75], v[156:159], v[188:191], v[72:75]
	v_mfma_f32_16x16x32_bf16 v[124:127], v[152:155], v[168:171], v[124:127]
	v_mfma_f32_16x16x32_bf16 v[120:123], v[160:163], v[168:171], v[120:123]
	v_mfma_f32_16x16x32_bf16 v[112:115], v[152:155], v[176:179], v[112:115]
	v_mfma_f32_16x16x32_bf16 v[104:107], v[160:163], v[176:179], v[104:107]
	v_mfma_f32_16x16x32_bf16 v[92:95], v[152:155], v[184:187], v[92:95]
	v_mfma_f32_16x16x32_bf16 v[88:91], v[160:163], v[184:187], v[88:91]
	v_mfma_f32_16x16x32_bf16 v[80:83], v[152:155], v[192:195], v[80:83]
	v_mfma_f32_16x16x32_bf16 v[72:75], v[160:163], v[192:195], v[72:75]
	v_mfma_f32_16x16x32_bf16 v[116:119], v[196:199], v[164:167], v[116:119]
	v_mfma_f32_16x16x32_bf16 v[108:111], v[204:207], v[164:167], v[108:111]
	v_mfma_f32_16x16x32_bf16 v[100:103], v[196:199], v[172:175], v[100:103]
	v_mfma_f32_16x16x32_bf16 v[96:99], v[204:207], v[172:175], v[96:99]
	v_mfma_f32_16x16x32_bf16 v[84:87], v[196:199], v[180:183], v[84:87]
	v_mfma_f32_16x16x32_bf16 v[76:79], v[204:207], v[180:183], v[76:79]
	v_mfma_f32_16x16x32_bf16 v[68:71], v[196:199], v[188:191], v[68:71]
	v_mfma_f32_16x16x32_bf16 v[64:67], v[204:207], v[188:191], v[64:67]
	v_mfma_f32_16x16x32_bf16 v[116:119], v[200:203], v[168:171], v[116:119]
	v_mfma_f32_16x16x32_bf16 v[108:111], v[208:211], v[168:171], v[108:111]
	v_mfma_f32_16x16x32_bf16 v[100:103], v[200:203], v[176:179], v[100:103]
	v_mfma_f32_16x16x32_bf16 v[96:99], v[208:211], v[176:179], v[96:99]
	v_mfma_f32_16x16x32_bf16 v[84:87], v[200:203], v[184:187], v[84:87]
	v_mfma_f32_16x16x32_bf16 v[76:79], v[208:211], v[184:187], v[76:79]
	v_mfma_f32_16x16x32_bf16 v[68:71], v[200:203], v[192:195], v[68:71]
	v_mfma_f32_16x16x32_bf16 v[64:67], v[208:211], v[192:195], v[64:67]
	s_setprio 0
	s_barrier
	s_nop 1
	ds_read_b128 v[164:167], v150 offset:16384
	ds_read_b128 v[168:171], v150 offset:17408
	ds_read_b128 v[172:175], v150 offset:18432
	ds_read_b128 v[176:179], v150 offset:19456
	ds_read_b128 v[180:183], v150 offset:20480
	ds_read_b128 v[184:187], v150 offset:21504
	ds_read_b128 v[188:191], v150 offset:22528
	ds_read_b128 v[192:195], v150 offset:23552
	s_add_i32 s26, s43, s7
	v_lshl_add_u64 v[144:145], s[30:31], 0, v[128:129]
	s_mov_b32 m0, s26
	s_nop 0
	global_load_lds_dwordx4 v[144:145], off
	v_lshl_add_u64 v[212:213], s[30:31], 0, v[130:131]
	s_add_i32 m0, s26, 0x2000
	s_nop 0
	global_load_lds_dwordx4 v[212:213], off
	s_mov_b32 m0, s36
	v_lshl_add_u64 v[214:215], s[34:35], 0, v[128:129]
	global_load_lds_dwordx4 v[214:215], off
	v_lshl_add_u64 v[216:217], s[34:35], 0, v[130:131]
	s_mov_b32 m0, s37
	s_nop 0
	global_load_lds_dwordx4 v[216:217], off
	s_add_u32 s26, s30, 0xb0000
	s_addc_u32 s27, s31, 0
	s_add_i32 s69, s44, s7
	v_lshl_add_u64 v[254:255], s[26:27], 0, v[128:129]
	s_mov_b32 m0, s69
	s_nop 0
	global_load_lds_dwordx4 v[254:255], off
	v_lshl_add_u64 v[254:255], s[26:27], 0, v[130:131]
	s_add_i32 m0, s69, 0x2000
	s_nop 0
	global_load_lds_dwordx4 v[254:255], off
	s_waitcnt vmcnt(6)
	s_waitcnt lgkmcnt(0)
	s_barrier
; #define PG8_STAGE(bufoff, gbase, voff) do { _Pragma("unroll") for (int _i = 0; _i < 2; ++_i) \
;         __builtin_amdgcn_global_load_lds((const unsigned*)((const char*)(gbase) + (voff)[_i]), (LAS unsigned*)(lds + (bufoff) + ldsw + _i * 8192), 16, 0, 0); } while (0)
; #define PG8_LDA(dst, b, h) do { _Pragma("unroll") for (int m = 0; m < 4; ++m) _Pragma("unroll") for (int k = 0; k < 2; ++k) dst[m][k] = *(const LAS bf16x8*)(lds + PG8_SA(b, h) + aoff + m * 2048 + k * 1024); } while (0)
; #define PG8_LDB(dst, b, h) do { _Pragma("unroll") for (int n = 0; n < 2; ++n) _Pragma("unroll") for (int k = 0; k < 2; ++k) dst[n][k] = *(const LAS bf16x8*)(lds + PG8_SB(b, h) + boff + n * 2048 + k * 1024); } while (0)
; #define PG8_MMA(ai, bj, At, Bt) do { __builtin_amdgcn_s_setprio(1); _Pragma("unroll") for (int m = 0; m < 4; ++m) _Pragma("unroll") for (int n = 0; n < 2; ++n) _Pragma("unroll") for (int k = 0; k < 2; ++k) \
;         acc[ai][bj][m][n] = __builtin_amdgcn_mfma_f32_16x16x32_bf16(Bt[n][k], At[m][k], acc[ai][bj][m][n], 0, 0, 0); __builtin_amdgcn_s_setprio(0); } while (0)
; #define PG8_WAIT_V(n) asm volatile("s_waitcnt vmcnt(" #n ")" ::: "memory")
; #define PG8_WAIT_L(n) asm volatile("s_waitcnt lgkmcnt(" #n ")" ::: "memory")
; #define PG8_BAR __builtin_amdgcn_s_barrier()
; #define PG8_SCHED __builtin_amdgcn_sched_barrier(0)
; template <class Epi>
; __device__ __forceinline__ void gemm_phase(LAS unsigned char* lds, const Gemm g, const StaticOrder& S, const Epi& E) {
;     ...
;             PG8_BAR; PG8_WAIT_L(0); PG8_MMA(0, 1, At, B1); PG8_BAR;
;             PG8_LDA(At, 0, 1); PG8_STAGE(PG8_SA(0, 0), a2, voffA);
;             PG8_BAR; PG8_WAIT_L(0); PG8_MMA(1, 0, At, B0); PG8_BAR; PG8_SCHED;
;             PG8_STAGE(PG8_SB(0, 1), b2 + hstepB, voffB);
;             PG8_WAIT_V(6); PG8_BAR; PG8_MMA(1, 1, At, B1); PG8_BAR;
;             PG8_LDB(B0, 1, 0); PG8_SCHED; PG8_LDA(At, 1, 0); PG8_STAGE(PG8_SA(0, 1), a2 + hstepA, voffA);
;             PG8_WAIT_L(8); PG8_BAR; PG8_WAIT_L(0); PG8_MMA(0, 0, At, B0); PG8_BAR; PG8_SCHED;
;             PG8_LDB(B1, 1, 1); PG8_STAGE(PG8_SB(1, 0), b3, voffB);
;             PG8_BAR; PG8_WAIT_L(0); PG8_MMA(0, 1, At, B1); PG8_BAR;
;             PG8_LDA(At, 1, 1); PG8_STAGE(PG8_SA(1, 0), a3, voffA);
;             PG8_BAR; PG8_WAIT_L(0); PG8_MMA(1, 0, At, B0); PG8_BAR; PG8_SCHED;
	s_setprio 1
	v_mfma_f32_16x16x32_bf16 v[60:63], v[140:143], v[164:167], v[60:63]
	v_mfma_f32_16x16x32_bf16 v[56:59], v[156:159], v[164:167], v[56:59]
	v_mfma_f32_16x16x32_bf16 v[48:51], v[140:143], v[172:175], v[48:51]
	v_mfma_f32_16x16x32_bf16 v[40:43], v[156:159], v[172:175], v[40:43]
	v_mfma_f32_16x16x32_bf16 v[28:31], v[140:143], v[180:183], v[28:31]
	v_mfma_f32_16x16x32_bf16 v[24:27], v[156:159], v[180:183], v[24:27]
	v_mfma_f32_16x16x32_bf16 v[16:19], v[140:143], v[188:191], v[16:19]
	v_mfma_f32_16x16x32_bf16 v[8:11], v[156:159], v[188:191], v[8:11]
	v_mfma_f32_16x16x32_bf16 v[60:63], v[152:155], v[168:171], v[60:63]
	v_mfma_f32_16x16x32_bf16 v[56:59], v[160:163], v[168:171], v[56:59]
	v_mfma_f32_16x16x32_bf16 v[48:51], v[152:155], v[176:179], v[48:51]
	v_mfma_f32_16x16x32_bf16 v[40:43], v[160:163], v[176:179], v[40:43]
	v_mfma_f32_16x16x32_bf16 v[28:31], v[152:155], v[184:187], v[28:31]
	v_mfma_f32_16x16x32_bf16 v[24:27], v[160:163], v[184:187], v[24:27]
	v_mfma_f32_16x16x32_bf16 v[16:19], v[152:155], v[192:195], v[16:19]
	v_mfma_f32_16x16x32_bf16 v[8:11], v[160:163], v[192:195], v[8:11]
	v_mfma_f32_16x16x32_bf16 v[52:55], v[196:199], v[164:167], v[52:55]
	v_mfma_f32_16x16x32_bf16 v[44:47], v[204:207], v[164:167], v[44:47]
	v_mfma_f32_16x16x32_bf16 v[36:39], v[196:199], v[172:175], v[36:39]
	v_mfma_f32_16x16x32_bf16 v[32:35], v[204:207], v[172:175], v[32:35]
	v_mfma_f32_16x16x32_bf16 v[20:23], v[196:199], v[180:183], v[20:23]
	v_mfma_f32_16x16x32_bf16 v[12:15], v[204:207], v[180:183], v[12:15]
	v_mfma_f32_16x16x32_bf16 v[4:7], v[196:199], v[188:191], v[4:7]
	v_mfma_f32_16x16x32_bf16 v[0:3], v[204:207], v[188:191], v[0:3]
	v_mfma_f32_16x16x32_bf16 v[52:55], v[200:203], v[168:171], v[52:55]
	v_mfma_f32_16x16x32_bf16 v[44:47], v[208:211], v[168:171], v[44:47]
	v_mfma_f32_16x16x32_bf16 v[36:39], v[200:203], v[176:179], v[36:39]
	v_mfma_f32_16x16x32_bf16 v[32:35], v[208:211], v[176:179], v[32:35]
	v_mfma_f32_16x16x32_bf16 v[20:23], v[200:203], v[184:187], v[20:23]
	v_mfma_f32_16x16x32_bf16 v[12:15], v[208:211], v[184:187], v[12:15]
	v_mfma_f32_16x16x32_bf16 v[4:7], v[200:203], v[192:195], v[4:7]
	v_mfma_f32_16x16x32_bf16 v[0:3], v[208:211], v[192:195], v[0:3]
	s_setprio 0
	s_add_i32 s69, 0, 0x18000
	v_add_u32_e32 v160, s69, v147
	s_barrier
	ds_read_b128 v[140:143], v160
	ds_read_b128 v[152:155], v160 offset:1024
	ds_read_b128 v[156:159], v160 offset:2048
	ds_read_b128 v[160:163], v160 offset:3072
	s_add_u32 s26, s34, 0xb0000
	s_addc_u32 s27, s35, 0
	s_mov_b32 m0, s38
	v_lshl_add_u64 v[196:197], s[26:27], 0, v[128:129]
	ds_read_b128 v[164:167], v150 offset:32768
	ds_read_b128 v[168:171], v150 offset:33792
	ds_read_b128 v[172:175], v150 offset:34816
	ds_read_b128 v[176:179], v150 offset:35840
	ds_read_b128 v[180:183], v150 offset:36864
	ds_read_b128 v[184:187], v150 offset:37888
	ds_read_b128 v[188:191], v150 offset:38912
	ds_read_b128 v[192:195], v150 offset:39936
	global_load_lds_dwordx4 v[196:197], off
	v_lshl_add_u64 v[196:197], s[26:27], 0, v[130:131]
	s_mov_b32 m0, s39
	s_nop 0
	global_load_lds_dwordx4 v[196:197], off
	s_add_i32 s34, 0, 0x1c000
	v_add_u32_e32 v208, s34, v147
	ds_read_b128 v[196:199], v208
	ds_read_b128 v[200:203], v208 offset:1024
	ds_read_b128 v[204:207], v208 offset:2048
	ds_read_b128 v[208:211], v208 offset:3072
	s_waitcnt lgkmcnt(0)
	s_barrier
	s_setprio 1
	v_mfma_f32_16x16x32_bf16 v[124:127], v[140:143], v[164:167], v[124:127]
	v_mfma_f32_16x16x32_bf16 v[120:123], v[156:159], v[164:167], v[120:123]
	v_mfma_f32_16x16x32_bf16 v[112:115], v[140:143], v[172:175], v[112:115]
	v_mfma_f32_16x16x32_bf16 v[104:107], v[156:159], v[172:175], v[104:107]
	v_mfma_f32_16x16x32_bf16 v[92:95], v[140:143], v[180:183], v[92:95]
	v_mfma_f32_16x16x32_bf16 v[88:91], v[156:159], v[180:183], v[88:91]
	v_mfma_f32_16x16x32_bf16 v[80:83], v[140:143], v[188:191], v[80:83]
	v_mfma_f32_16x16x32_bf16 v[72:75], v[156:159], v[188:191], v[72:75]
	v_mfma_f32_16x16x32_bf16 v[124:127], v[152:155], v[168:171], v[124:127]
	v_mfma_f32_16x16x32_bf16 v[120:123], v[160:163], v[168:171], v[120:123]
	v_mfma_f32_16x16x32_bf16 v[112:115], v[152:155], v[176:179], v[112:115]
	v_mfma_f32_16x16x32_bf16 v[104:107], v[160:163], v[176:179], v[104:107]
	v_mfma_f32_16x16x32_bf16 v[92:95], v[152:155], v[184:187], v[92:95]
	v_mfma_f32_16x16x32_bf16 v[88:91], v[160:163], v[184:187], v[88:91]
	v_mfma_f32_16x16x32_bf16 v[80:83], v[152:155], v[192:195], v[80:83]
	v_mfma_f32_16x16x32_bf16 v[72:75], v[160:163], v[192:195], v[72:75]
	v_mfma_f32_16x16x32_bf16 v[116:119], v[196:199], v[164:167], v[116:119]
	v_mfma_f32_16x16x32_bf16 v[108:111], v[204:207], v[164:167], v[108:111]
	v_mfma_f32_16x16x32_bf16 v[100:103], v[196:199], v[172:175], v[100:103]
	v_mfma_f32_16x16x32_bf16 v[96:99], v[204:207], v[172:175], v[96:99]
	v_mfma_f32_16x16x32_bf16 v[84:87], v[196:199], v[180:183], v[84:87]
	v_mfma_f32_16x16x32_bf16 v[76:79], v[204:207], v[180:183], v[76:79]
	v_mfma_f32_16x16x32_bf16 v[68:71], v[196:199], v[188:191], v[68:71]
	v_mfma_f32_16x16x32_bf16 v[64:67], v[204:207], v[188:191], v[64:67]
	v_mfma_f32_16x16x32_bf16 v[116:119], v[200:203], v[168:171], v[116:119]
	v_mfma_f32_16x16x32_bf16 v[108:111], v[208:211], v[168:171], v[108:111]
	v_mfma_f32_16x16x32_bf16 v[100:103], v[200:203], v[176:179], v[100:103]
	v_mfma_f32_16x16x32_bf16 v[96:99], v[208:211], v[176:179], v[96:99]
	v_mfma_f32_16x16x32_bf16 v[84:87], v[200:203], v[184:187], v[84:87]
	v_mfma_f32_16x16x32_bf16 v[76:79], v[208:211], v[184:187], v[76:79]
	v_mfma_f32_16x16x32_bf16 v[68:71], v[200:203], v[192:195], v[68:71]
	v_mfma_f32_16x16x32_bf16 v[64:67], v[208:211], v[192:195], v[64:67]
	s_setprio 0
	s_barrier
; #define PG8_MMA(ai, bj, At, Bt) do { __builtin_amdgcn_s_setprio(1); _Pragma("unroll") for (int m = 0; m < 4; ++m) _Pragma("unroll") for (int n = 0; n < 2; ++n) _Pragma("unroll") for (int k = 0; k < 2; ++k) \
;         acc[ai][bj][m][n] = __builtin_amdgcn_mfma_f32_16x16x32_bf16(Bt[n][k], At[m][k], acc[ai][bj][m][n], 0, 0, 0); __builtin_amdgcn_s_setprio(0); } while (0)
; #define PG8_WAIT_V(n) asm volatile("s_waitcnt vmcnt(" #n ")" ::: "memory")
; #define PG8_BAR __builtin_amdgcn_s_barrier()
; template <class Epi>
; __device__ __forceinline__ void gemm_phase(LAS unsigned char* lds, const Gemm g, const StaticOrder& S, const Epi& E) {
;     ...
;             PG8_WAIT_V(6); PG8_BAR; PG8_MMA(1, 1, At, B1); PG8_BAR;
;         }
;     __device__ __forceinline__ void operator()(AccRef acc, const Unit& u, int wr, int wc, int fr, int fq) const {
;         const int row0 = u.pm * 256 + wr * 64 + fr, col0 = u.pn * 256 + wc * 32 + 4 * fq;
;         f32x4 sv[2][2], bv[2][2];
; #pragma unroll
;         for (int bj = 0; bj < 2; ++bj)
; #pragma unroll
;             for (int n = 0; n < 2; ++n) {
;                 sv[bj][n] = scale ? *(const f32x4*)(scale + col0 + bj * 128 + n * 16) : (f32x4){1.f, 1.f, 1.f, 1.f};
;                 bv[bj][n] = bias ? *(const f32x4*)(bias + col0 + bj * 128 + n * 16) : (f32x4){0.f, 0.f, 0.f, 0.f}; }
; #pragma unroll
;         for (int ai = 0; ai < 2; ++ai)
; #pragma unroll
;             for (int mh = 0; mh < 2; ++mh) {
;                 f32x4 bs[2][2][2];
; #pragma unroll
;                 for (int m = 0; m < 2; ++m)
; #pragma unroll
;                     for (int bj = 0; bj < 2; ++bj)
; #pragma unroll
;                         for (int n = 0; n < 2; ++n) bs[m][bj][n] = *(const f32x4*)(base + (size_t)(row0 + ai * 128 + (2 * mh + m) * 16) * D + col0 + bj * 128 + n * 16);
	s_nop 1
	ds_read_b128 v[164:167], v150 offset:49152
	ds_read_b128 v[168:171], v150 offset:50176
	ds_read_b128 v[172:175], v150 offset:51200
	ds_read_b128 v[176:179], v150 offset:52224
	ds_read_b128 v[180:183], v150 offset:53248
	ds_read_b128 v[184:187], v150 offset:54272
	ds_read_b128 v[188:191], v150 offset:55296
	ds_read_b128 v[192:195], v150 offset:56320
	s_add_i32 s26, s69, s7
	v_lshl_add_u64 v[254:255], v[144:145], 0, s[16:17]
	s_mov_b32 m0, s26
	s_nop 0
	global_load_lds_dwordx4 v[254:255], off
	v_lshl_add_u64 v[254:255], v[212:213], 0, s[16:17]
	s_add_i32 m0, s26, 0x2000
	s_nop 0
	global_load_lds_dwordx4 v[254:255], off
	s_mov_b32 m0, s41
	v_lshl_add_u64 v[254:255], v[214:215], 0, s[16:17]
	global_load_lds_dwordx4 v[254:255], off
	v_lshl_add_u64 v[144:145], v[216:217], 0, s[16:17]
	s_mov_b32 m0, s42
	s_nop 0
	global_load_lds_dwordx4 v[144:145], off
	s_add_u32 s26, s30, 0xb0080
	s_addc_u32 s27, s31, 0
	s_add_i32 s30, s34, s7
	v_lshl_add_u64 v[254:255], s[26:27], 0, v[128:129]
	s_mov_b32 m0, s30
	s_nop 0
	global_load_lds_dwordx4 v[254:255], off
	v_lshl_add_u64 v[254:255], s[26:27], 0, v[130:131]
	s_add_i32 m0, s30, 0x2000
	s_nop 0
	global_load_lds_dwordx4 v[254:255], off
	s_waitcnt vmcnt(6)
	s_waitcnt lgkmcnt(0)
	s_barrier
	s_setprio 1
	v_mfma_f32_16x16x32_bf16 v[60:63], v[140:143], v[164:167], v[60:63]
	v_mfma_f32_16x16x32_bf16 v[56:59], v[156:159], v[164:167], v[56:59]
	v_mfma_f32_16x16x32_bf16 v[48:51], v[140:143], v[172:175], v[48:51]
	v_mfma_f32_16x16x32_bf16 v[40:43], v[156:159], v[172:175], v[40:43]
	v_mfma_f32_16x16x32_bf16 v[28:31], v[140:143], v[180:183], v[28:31]
	v_mfma_f32_16x16x32_bf16 v[24:27], v[156:159], v[180:183], v[24:27]
	v_mfma_f32_16x16x32_bf16 v[16:19], v[140:143], v[188:191], v[16:19]
	v_mfma_f32_16x16x32_bf16 v[8:11], v[156:159], v[188:191], v[8:11]
	v_mfma_f32_16x16x32_bf16 v[60:63], v[152:155], v[168:171], v[60:63]
	v_mfma_f32_16x16x32_bf16 v[56:59], v[160:163], v[168:171], v[56:59]
	v_mfma_f32_16x16x32_bf16 v[48:51], v[152:155], v[176:179], v[48:51]
	v_mfma_f32_16x16x32_bf16 v[40:43], v[160:163], v[176:179], v[40:43]
	v_mfma_f32_16x16x32_bf16 v[28:31], v[152:155], v[184:187], v[28:31]
	v_mfma_f32_16x16x32_bf16 v[24:27], v[160:163], v[184:187], v[24:27]
	v_mfma_f32_16x16x32_bf16 v[16:19], v[152:155], v[192:195], v[16:19]
	v_mfma_f32_16x16x32_bf16 v[8:11], v[160:163], v[192:195], v[8:11]
	v_mfma_f32_16x16x32_bf16 v[52:55], v[196:199], v[164:167], v[52:55]
	v_mfma_f32_16x16x32_bf16 v[44:47], v[204:207], v[164:167], v[44:47]
	v_mfma_f32_16x16x32_bf16 v[36:39], v[196:199], v[172:175], v[36:39]
	v_mfma_f32_16x16x32_bf16 v[32:35], v[204:207], v[172:175], v[32:35]
	v_mfma_f32_16x16x32_bf16 v[20:23], v[196:199], v[180:183], v[20:23]
	v_mfma_f32_16x16x32_bf16 v[12:15], v[204:207], v[180:183], v[12:15]
	v_mfma_f32_16x16x32_bf16 v[4:7], v[196:199], v[188:191], v[4:7]
	v_mfma_f32_16x16x32_bf16 v[0:3], v[204:207], v[188:191], v[0:3]
	v_mfma_f32_16x16x32_bf16 v[52:55], v[200:203], v[168:171], v[52:55]
	v_mfma_f32_16x16x32_bf16 v[44:47], v[208:211], v[168:171], v[44:47]
	v_mfma_f32_16x16x32_bf16 v[36:39], v[200:203], v[176:179], v[36:39]
	v_mfma_f32_16x16x32_bf16 v[32:35], v[208:211], v[176:179], v[32:35]
	v_mfma_f32_16x16x32_bf16 v[20:23], v[200:203], v[184:187], v[20:23]
	v_mfma_f32_16x16x32_bf16 v[12:15], v[208:211], v[184:187], v[12:15]
	v_mfma_f32_16x16x32_bf16 v[4:7], v[200:203], v[192:195], v[4:7]
	v_mfma_f32_16x16x32_bf16 v[0:3], v[208:211], v[192:195], v[0:3]
	s_setprio 0
	s_add_i32 s68, s68, 2
	s_add_u32 s49, s49, 0x100
	s_addc_u32 s63, s63, 0
	s_cmp_gt_u32 s68, 41
	s_mov_b64 s[26:27], s[28:29]
	s_barrier
	s_cbranch_scc0 .LBB0_411
	v_lshl_or_b32 v144, s47, 8, v148
	v_lshl_add_u32 v145, s48, 8, v146
	v_lshlrev_b32_e32 v144, 2, v144
	v_lshl_add_u32 v145, v145, 12, v144
	v_add_u32_e32 v216, 0x10000, v145
	v_add_u32_e32 v217, 0x20000, v145
	v_add_u32_e32 v218, 0x30000, v145
	v_add_u32_e32 v220, 0x80000, v145
	v_add_u32_e32 v221, 0x90000, v145
	v_add_u32_e32 v222, 0xa0000, v145
	v_add_u32_e32 v223, 0xb0000, v145
	v_and_b32_e32 v235, 8, v146
	v_cmp_ne_u32_e32 vcc, 0, v235
	v_mov_b32_e32 v232, 0xffff8040
	s_nop 0
	v_cndmask_b32_e32 v232, 0, v232, vcc
	v_mov_b32_e32 v233, 64
	v_mov_b32_e32 v235, 0x8000
	v_cndmask_b32_e32 v233, v235, v233, vcc
	v_add_u32_e32 v224, v145, v232
	v_add_u32_e32 v225, v216, v232
	v_add_u32_e32 v226, v217, v232
	v_add_u32_e32 v227, v218, v232
	v_add_u32_e32 v228, v220, v232
	v_add_u32_e32 v229, v221, v232
	v_add_u32_e32 v230, v222, v232
	v_add_u32_e32 v231, v223, v232
	s_and_b64 vcc, exec, s[8:9]
	s_mov_b32 s47, s45
	s_mov_b32 s48, s46
	s_mov_b64 s[28:29], s[12:13]
	s_mov_b64 s[26:27], s[10:11]
	global_load_dwordx4 v[140:143], v224, s[52:53]
	v_add_u32_e32 v144, v145, v233
	global_load_dwordx4 v[152:155], v144, s[52:53]
	global_load_dwordx4 v[156:159], v224, s[52:53] offset:512
	v_add_u32_e32 v144, v145, v233
	global_load_dwordx4 v[160:163], v144, s[52:53] offset:512
	global_load_dwordx4 v[164:167], v225, s[52:53]
	v_add_u32_e32 v144, v216, v233
	global_load_dwordx4 v[168:171], v144, s[52:53]
	global_load_dwordx4 v[172:175], v225, s[52:53] offset:512
	v_add_u32_e32 v144, v216, v233
	global_load_dwordx4 v[176:179], v144, s[52:53] offset:512
	global_load_dwordx4 v[180:183], v226, s[52:53]
	v_add_u32_e32 v144, v217, v233
	global_load_dwordx4 v[184:187], v144, s[52:53]
	global_load_dwordx4 v[188:191], v226, s[52:53] offset:512
	v_add_u32_e32 v144, v217, v233
	global_load_dwordx4 v[192:195], v144, s[52:53] offset:512
	global_load_dwordx4 v[196:199], v227, s[52:53]
	v_add_u32_e32 v144, v218, v233
	global_load_dwordx4 v[200:203], v144, s[52:53]
	global_load_dwordx4 v[204:207], v227, s[52:53] offset:512
	v_add_u32_e32 v144, v218, v233
	global_load_dwordx4 v[208:211], v144, s[52:53] offset:512
	s_barrier
;     __device__ __forceinline__ void operator()(AccRef acc, const Unit& u, int wr, int wc, int fr, int fq) const {
;     ...
;                         for (int n = 0; n < 2; ++n) bs[m][bj][n] = *(const f32x4*)(base + (size_t)(row0 + ai * 128 + (2 * mh + m) * 16) * D + col0 + bj * 128 + n * 16);
; #pragma unroll
;                 for (int m = 0; m < 2; ++m)
; #pragma unroll
;                     for (int bj = 0; bj < 2; ++bj)
; #pragma unroll
;                         for (int n = 0; n < 2; ++n) *(f32x4*)(out + (size_t)(row0 + ai * 128 + (2 * mh + m) * 16) * D + col0 + bj * 128 + n * 16) = bs[m][bj][n] + sv[bj][n] * (acc[ai][bj][2 * mh + m][n] + bv[bj][n]);
	v_pk_add_f32 v[124:125], v[124:125], 0 op_sel_hi:[1,0]
	v_pk_add_f32 v[126:127], v[126:127], 0 op_sel_hi:[1,0]
	v_pk_add_f32 v[120:121], v[120:121], 0 op_sel_hi:[1,0]
	v_pk_add_f32 v[122:123], v[122:123], 0 op_sel_hi:[1,0]
	v_pk_add_f32 v[116:117], v[116:117], 0 op_sel_hi:[1,0]
	v_pk_add_f32 v[118:119], v[118:119], 0 op_sel_hi:[1,0]
	v_pk_add_f32 v[108:109], v[108:109], 0 op_sel_hi:[1,0]
	v_pk_add_f32 v[110:111], v[110:111], 0 op_sel_hi:[1,0]
	v_pk_add_f32 v[112:113], v[112:113], 0 op_sel_hi:[1,0]
	v_pk_add_f32 v[114:115], v[114:115], 0 op_sel_hi:[1,0]
	v_pk_add_f32 v[104:105], v[104:105], 0 op_sel_hi:[1,0]
	v_pk_add_f32 v[106:107], v[106:107], 0 op_sel_hi:[1,0]
	v_pk_add_f32 v[100:101], v[100:101], 0 op_sel_hi:[1,0]
	v_pk_add_f32 v[102:103], v[102:103], 0 op_sel_hi:[1,0]
	v_pk_add_f32 v[96:97], v[96:97], 0 op_sel_hi:[1,0]
	v_pk_add_f32 v[98:99], v[98:99], 0 op_sel_hi:[1,0]
	v_pk_add_f32 v[92:93], v[92:93], 0 op_sel_hi:[1,0]
	v_pk_add_f32 v[94:95], v[94:95], 0 op_sel_hi:[1,0]
	v_pk_add_f32 v[88:89], v[88:89], 0 op_sel_hi:[1,0]
	v_pk_add_f32 v[90:91], v[90:91], 0 op_sel_hi:[1,0]
	v_pk_add_f32 v[84:85], v[84:85], 0 op_sel_hi:[1,0]
	v_pk_add_f32 v[86:87], v[86:87], 0 op_sel_hi:[1,0]
	v_pk_add_f32 v[76:77], v[76:77], 0 op_sel_hi:[1,0]
	v_pk_add_f32 v[78:79], v[78:79], 0 op_sel_hi:[1,0]
	v_pk_add_f32 v[80:81], v[80:81], 0 op_sel_hi:[1,0]
	v_pk_add_f32 v[82:83], v[82:83], 0 op_sel_hi:[1,0]
	v_pk_add_f32 v[72:73], v[72:73], 0 op_sel_hi:[1,0]
	v_pk_add_f32 v[74:75], v[74:75], 0 op_sel_hi:[1,0]
	v_pk_add_f32 v[68:69], v[68:69], 0 op_sel_hi:[1,0]
	v_pk_add_f32 v[70:71], v[70:71], 0 op_sel_hi:[1,0]
	v_pk_add_f32 v[64:65], v[64:65], 0 op_sel_hi:[1,0]
	v_pk_add_f32 v[66:67], v[66:67], 0 op_sel_hi:[1,0]
	v_pk_add_f32 v[60:61], v[60:61], 0 op_sel_hi:[1,0]
	v_pk_add_f32 v[62:63], v[62:63], 0 op_sel_hi:[1,0]
	v_pk_add_f32 v[56:57], v[56:57], 0 op_sel_hi:[1,0]
	v_pk_add_f32 v[58:59], v[58:59], 0 op_sel_hi:[1,0]
	v_pk_add_f32 v[52:53], v[52:53], 0 op_sel_hi:[1,0]
	v_pk_add_f32 v[54:55], v[54:55], 0 op_sel_hi:[1,0]
	v_pk_add_f32 v[44:45], v[44:45], 0 op_sel_hi:[1,0]
	v_pk_add_f32 v[46:47], v[46:47], 0 op_sel_hi:[1,0]
	v_pk_add_f32 v[48:49], v[48:49], 0 op_sel_hi:[1,0]
	v_pk_add_f32 v[50:51], v[50:51], 0 op_sel_hi:[1,0]
	v_pk_add_f32 v[40:41], v[40:41], 0 op_sel_hi:[1,0]
	v_pk_add_f32 v[42:43], v[42:43], 0 op_sel_hi:[1,0]
	v_pk_add_f32 v[36:37], v[36:37], 0 op_sel_hi:[1,0]
	v_pk_add_f32 v[38:39], v[38:39], 0 op_sel_hi:[1,0]
	v_pk_add_f32 v[32:33], v[32:33], 0 op_sel_hi:[1,0]
	v_pk_add_f32 v[34:35], v[34:35], 0 op_sel_hi:[1,0]
	v_pk_add_f32 v[28:29], v[28:29], 0 op_sel_hi:[1,0]
	v_pk_add_f32 v[30:31], v[30:31], 0 op_sel_hi:[1,0]
	v_pk_add_f32 v[24:25], v[24:25], 0 op_sel_hi:[1,0]
	v_pk_add_f32 v[26:27], v[26:27], 0 op_sel_hi:[1,0]
	v_pk_add_f32 v[20:21], v[20:21], 0 op_sel_hi:[1,0]
	v_pk_add_f32 v[22:23], v[22:23], 0 op_sel_hi:[1,0]
	v_pk_add_f32 v[12:13], v[12:13], 0 op_sel_hi:[1,0]
	v_pk_add_f32 v[14:15], v[14:15], 0 op_sel_hi:[1,0]
	v_pk_add_f32 v[16:17], v[16:17], 0 op_sel_hi:[1,0]
	v_pk_add_f32 v[18:19], v[18:19], 0 op_sel_hi:[1,0]
	v_pk_add_f32 v[8:9], v[8:9], 0 op_sel_hi:[1,0]
	v_pk_add_f32 v[10:11], v[10:11], 0 op_sel_hi:[1,0]
	v_pk_add_f32 v[4:5], v[4:5], 0 op_sel_hi:[1,0]
	v_pk_add_f32 v[6:7], v[6:7], 0 op_sel_hi:[1,0]
	v_pk_add_f32 v[0:1], v[0:1], 0 op_sel_hi:[1,0]
	v_pk_add_f32 v[2:3], v[2:3], 0 op_sel_hi:[1,0]
	s_waitcnt vmcnt(8)
	v_mov_b32_e32 v212, v124
	v_mov_b32_e32 v213, v125
	v_mov_b32_e32 v214, v126
	v_mov_b32_e32 v215, v127
	s_nop 0
	v_mov_b32_dpp v124, v120 row_shr:8 row_mask:0xf bank_mask:0xc
	v_mov_b32_dpp v125, v121 row_shr:8 row_mask:0xf bank_mask:0xc
	v_mov_b32_dpp v126, v122 row_shr:8 row_mask:0xf bank_mask:0xc
	v_mov_b32_dpp v127, v123 row_shr:8 row_mask:0xf bank_mask:0xc
	v_mov_b32_dpp v120, v212 row_shl:8 row_mask:0xf bank_mask:0x3
	v_mov_b32_dpp v121, v213 row_shl:8 row_mask:0xf bank_mask:0x3
	v_mov_b32_dpp v122, v214 row_shl:8 row_mask:0xf bank_mask:0x3
	v_mov_b32_dpp v123, v215 row_shl:8 row_mask:0xf bank_mask:0x3
	v_mov_b32_e32 v212, v116
	v_mov_b32_e32 v213, v117
	v_mov_b32_e32 v214, v118
	v_mov_b32_e32 v215, v119
	s_nop 0
	v_mov_b32_dpp v116, v108 row_shr:8 row_mask:0xf bank_mask:0xc
	v_mov_b32_dpp v117, v109 row_shr:8 row_mask:0xf bank_mask:0xc
	v_mov_b32_dpp v118, v110 row_shr:8 row_mask:0xf bank_mask:0xc
	v_mov_b32_dpp v119, v111 row_shr:8 row_mask:0xf bank_mask:0xc
	v_mov_b32_dpp v108, v212 row_shl:8 row_mask:0xf bank_mask:0x3
	v_mov_b32_dpp v109, v213 row_shl:8 row_mask:0xf bank_mask:0x3
	v_mov_b32_dpp v110, v214 row_shl:8 row_mask:0xf bank_mask:0x3
	v_mov_b32_dpp v111, v215 row_shl:8 row_mask:0xf bank_mask:0x3
	v_mov_b32_e32 v212, v112
	v_mov_b32_e32 v213, v113
	v_mov_b32_e32 v214, v114
	v_mov_b32_e32 v215, v115
	s_nop 0
	v_mov_b32_dpp v112, v104 row_shr:8 row_mask:0xf bank_mask:0xc
	v_mov_b32_dpp v113, v105 row_shr:8 row_mask:0xf bank_mask:0xc
	v_mov_b32_dpp v114, v106 row_shr:8 row_mask:0xf bank_mask:0xc
	v_mov_b32_dpp v115, v107 row_shr:8 row_mask:0xf bank_mask:0xc
	v_mov_b32_dpp v104, v212 row_shl:8 row_mask:0xf bank_mask:0x3
	v_mov_b32_dpp v105, v213 row_shl:8 row_mask:0xf bank_mask:0x3
	v_mov_b32_dpp v106, v214 row_shl:8 row_mask:0xf bank_mask:0x3
	v_mov_b32_dpp v107, v215 row_shl:8 row_mask:0xf bank_mask:0x3
	v_mov_b32_e32 v212, v100
	v_mov_b32_e32 v213, v101
	v_mov_b32_e32 v214, v102
	v_mov_b32_e32 v215, v103
	s_nop 0
	v_mov_b32_dpp v100, v96 row_shr:8 row_mask:0xf bank_mask:0xc
	v_mov_b32_dpp v101, v97 row_shr:8 row_mask:0xf bank_mask:0xc
	v_mov_b32_dpp v102, v98 row_shr:8 row_mask:0xf bank_mask:0xc
	v_mov_b32_dpp v103, v99 row_shr:8 row_mask:0xf bank_mask:0xc
	v_mov_b32_dpp v96, v212 row_shl:8 row_mask:0xf bank_mask:0x3
;     __device__ __forceinline__ void operator()(AccRef acc, const Unit& u, int wr, int wc, int fr, int fq) const {
;     ...
;                         for (int n = 0; n < 2; ++n) bs[m][bj][n] = *(const f32x4*)(base + (size_t)(row0 + ai * 128 + (2 * mh + m) * 16) * D + col0 + bj * 128 + n * 16);
; #pragma unroll
;                 for (int m = 0; m < 2; ++m)
; #pragma unroll
;                     for (int bj = 0; bj < 2; ++bj)
; #pragma unroll
;                         for (int n = 0; n < 2; ++n) *(f32x4*)(out + (size_t)(row0 + ai * 128 + (2 * mh + m) * 16) * D + col0 + bj * 128 + n * 16) = bs[m][bj][n] + sv[bj][n] * (acc[ai][bj][2 * mh + m][n] + bv[bj][n]);
;                 asm volatile("" ::: "memory"); }
	v_mov_b32_dpp v97, v213 row_shl:8 row_mask:0xf bank_mask:0x3
	v_mov_b32_dpp v98, v214 row_shl:8 row_mask:0xf bank_mask:0x3
	v_mov_b32_dpp v99, v215 row_shl:8 row_mask:0xf bank_mask:0x3
	v_pk_add_f32 v[124:125], v[124:125], v[140:141]
	v_pk_add_f32 v[126:127], v[126:127], v[142:143]
	v_pk_add_f32 v[120:121], v[120:121], v[152:153]
	v_pk_add_f32 v[122:123], v[122:123], v[154:155]
	v_pk_add_f32 v[116:117], v[116:117], v[156:157]
	v_pk_add_f32 v[118:119], v[118:119], v[158:159]
	v_pk_add_f32 v[108:109], v[108:109], v[160:161]
	v_pk_add_f32 v[110:111], v[110:111], v[162:163]
	v_pk_add_f32 v[112:113], v[112:113], v[164:165]
	v_pk_add_f32 v[114:115], v[114:115], v[166:167]
	v_pk_add_f32 v[104:105], v[104:105], v[168:169]
	v_pk_add_f32 v[106:107], v[106:107], v[170:171]
	v_pk_add_f32 v[100:101], v[100:101], v[172:173]
	v_pk_add_f32 v[102:103], v[102:103], v[174:175]
	v_pk_add_f32 v[96:97], v[96:97], v[176:177]
	v_pk_add_f32 v[98:99], v[98:99], v[178:179]
	global_store_dwordx4 v224, v[124:127], s[52:53]
	v_add_u32_e32 v144, v145, v233
	global_store_dwordx4 v144, v[120:123], s[52:53]
	global_store_dwordx4 v224, v[116:119], s[52:53] offset:512
	v_add_u32_e32 v144, v145, v233
	global_store_dwordx4 v144, v[108:111], s[52:53] offset:512
	global_store_dwordx4 v225, v[112:115], s[52:53]
	v_add_u32_e32 v144, v216, v233
	global_store_dwordx4 v144, v[104:107], s[52:53]
	global_store_dwordx4 v225, v[100:103], s[52:53] offset:512
	v_add_u32_e32 v144, v216, v233
	global_store_dwordx4 v144, v[96:99], s[52:53] offset:512
	global_load_dwordx4 v[140:143], v228, s[52:53]
	v_add_u32_e32 v144, v220, v233
	global_load_dwordx4 v[152:155], v144, s[52:53]
	global_load_dwordx4 v[156:159], v228, s[52:53] offset:512
	v_add_u32_e32 v144, v220, v233
	global_load_dwordx4 v[160:163], v144, s[52:53] offset:512
	global_load_dwordx4 v[164:167], v229, s[52:53]
	v_add_u32_e32 v144, v221, v233
	global_load_dwordx4 v[168:171], v144, s[52:53]
	global_load_dwordx4 v[172:175], v229, s[52:53] offset:512
	v_add_u32_e32 v144, v221, v233
	global_load_dwordx4 v[176:179], v144, s[52:53] offset:512
	s_barrier
	s_waitcnt vmcnt(16)
	v_mov_b32_e32 v212, v92
	v_mov_b32_e32 v213, v93
	v_mov_b32_e32 v214, v94
	v_mov_b32_e32 v215, v95
	s_nop 0
	v_mov_b32_dpp v92, v88 row_shr:8 row_mask:0xf bank_mask:0xc
	v_mov_b32_dpp v93, v89 row_shr:8 row_mask:0xf bank_mask:0xc
	v_mov_b32_dpp v94, v90 row_shr:8 row_mask:0xf bank_mask:0xc
	v_mov_b32_dpp v95, v91 row_shr:8 row_mask:0xf bank_mask:0xc
	v_mov_b32_dpp v88, v212 row_shl:8 row_mask:0xf bank_mask:0x3
	v_mov_b32_dpp v89, v213 row_shl:8 row_mask:0xf bank_mask:0x3
	v_mov_b32_dpp v90, v214 row_shl:8 row_mask:0xf bank_mask:0x3
	v_mov_b32_dpp v91, v215 row_shl:8 row_mask:0xf bank_mask:0x3
	v_mov_b32_e32 v212, v84
	v_mov_b32_e32 v213, v85
	v_mov_b32_e32 v214, v86
	v_mov_b32_e32 v215, v87
	s_nop 0
	v_mov_b32_dpp v84, v76 row_shr:8 row_mask:0xf bank_mask:0xc
	v_mov_b32_dpp v85, v77 row_shr:8 row_mask:0xf bank_mask:0xc
	v_mov_b32_dpp v86, v78 row_shr:8 row_mask:0xf bank_mask:0xc
	v_mov_b32_dpp v87, v79 row_shr:8 row_mask:0xf bank_mask:0xc
	v_mov_b32_dpp v76, v212 row_shl:8 row_mask:0xf bank_mask:0x3
	v_mov_b32_dpp v77, v213 row_shl:8 row_mask:0xf bank_mask:0x3
	v_mov_b32_dpp v78, v214 row_shl:8 row_mask:0xf bank_mask:0x3
	v_mov_b32_dpp v79, v215 row_shl:8 row_mask:0xf bank_mask:0x3
	v_mov_b32_e32 v212, v80
	v_mov_b32_e32 v213, v81
	v_mov_b32_e32 v214, v82
	v_mov_b32_e32 v215, v83
	s_nop 0
	v_mov_b32_dpp v80, v72 row_shr:8 row_mask:0xf bank_mask:0xc
	v_mov_b32_dpp v81, v73 row_shr:8 row_mask:0xf bank_mask:0xc
	v_mov_b32_dpp v82, v74 row_shr:8 row_mask:0xf bank_mask:0xc
	v_mov_b32_dpp v83, v75 row_shr:8 row_mask:0xf bank_mask:0xc
	v_mov_b32_dpp v72, v212 row_shl:8 row_mask:0xf bank_mask:0x3
	v_mov_b32_dpp v73, v213 row_shl:8 row_mask:0xf bank_mask:0x3
	v_mov_b32_dpp v74, v214 row_shl:8 row_mask:0xf bank_mask:0x3
	v_mov_b32_dpp v75, v215 row_shl:8 row_mask:0xf bank_mask:0x3
	v_mov_b32_e32 v212, v68
	v_mov_b32_e32 v213, v69
	v_mov_b32_e32 v214, v70
	v_mov_b32_e32 v215, v71
	s_nop 0
	v_mov_b32_dpp v68, v64 row_shr:8 row_mask:0xf bank_mask:0xc
	v_mov_b32_dpp v69, v65 row_shr:8 row_mask:0xf bank_mask:0xc
	v_mov_b32_dpp v70, v66 row_shr:8 row_mask:0xf bank_mask:0xc
	v_mov_b32_dpp v71, v67 row_shr:8 row_mask:0xf bank_mask:0xc
	v_mov_b32_dpp v64, v212 row_shl:8 row_mask:0xf bank_mask:0x3
	v_mov_b32_dpp v65, v213 row_shl:8 row_mask:0xf bank_mask:0x3
	v_mov_b32_dpp v66, v214 row_shl:8 row_mask:0xf bank_mask:0x3
	v_mov_b32_dpp v67, v215 row_shl:8 row_mask:0xf bank_mask:0x3
	v_pk_add_f32 v[92:93], v[92:93], v[180:181]
	v_pk_add_f32 v[94:95], v[94:95], v[182:183]
	v_pk_add_f32 v[88:89], v[88:89], v[184:185]
	v_pk_add_f32 v[90:91], v[90:91], v[186:187]
	v_pk_add_f32 v[84:85], v[84:85], v[188:189]
	v_pk_add_f32 v[86:87], v[86:87], v[190:191]
	v_pk_add_f32 v[76:77], v[76:77], v[192:193]
	v_pk_add_f32 v[78:79], v[78:79], v[194:195]
	v_pk_add_f32 v[80:81], v[80:81], v[196:197]
	v_pk_add_f32 v[82:83], v[82:83], v[198:199]
	v_pk_add_f32 v[72:73], v[72:73], v[200:201]
	v_pk_add_f32 v[74:75], v[74:75], v[202:203]
	v_pk_add_f32 v[68:69], v[68:69], v[204:205]
	v_pk_add_f32 v[70:71], v[70:71], v[206:207]
	v_pk_add_f32 v[64:65], v[64:65], v[208:209]
	v_pk_add_f32 v[66:67], v[66:67], v[210:211]
	global_store_dwordx4 v226, v[92:95], s[52:53]
	v_add_u32_e32 v144, v217, v233
	global_store_dwordx4 v144, v[88:91], s[52:53]
	global_store_dwordx4 v226, v[84:87], s[52:53] offset:512
	v_add_u32_e32 v144, v217, v233
	global_store_dwordx4 v144, v[76:79], s[52:53] offset:512
	global_store_dwordx4 v227, v[80:83], s[52:53]
	v_add_u32_e32 v144, v218, v233
	global_store_dwordx4 v144, v[72:75], s[52:53]
	global_store_dwordx4 v227, v[68:71], s[52:53] offset:512
	v_add_u32_e32 v144, v218, v233
	global_store_dwordx4 v144, v[64:67], s[52:53] offset:512
	global_load_dwordx4 v[180:183], v230, s[52:53]
	v_add_u32_e32 v144, v222, v233
	global_load_dwordx4 v[184:187], v144, s[52:53]
	global_load_dwordx4 v[188:191], v230, s[52:53] offset:512
	v_add_u32_e32 v144, v222, v233
	global_load_dwordx4 v[192:195], v144, s[52:53] offset:512
	global_load_dwordx4 v[196:199], v231, s[52:53]
	v_add_u32_e32 v144, v223, v233
	global_load_dwordx4 v[200:203], v144, s[52:53]
	global_load_dwordx4 v[204:207], v231, s[52:53] offset:512
	v_add_u32_e32 v144, v223, v233
	global_load_dwordx4 v[208:211], v144, s[52:53] offset:512
	s_barrier
;     __device__ __forceinline__ void operator()(AccRef acc, const Unit& u, int wr, int wc, int fr, int fq) const {
;     ...
;                         for (int n = 0; n < 2; ++n) bs[m][bj][n] = *(const f32x4*)(base + (size_t)(row0 + ai * 128 + (2 * mh + m) * 16) * D + col0 + bj * 128 + n * 16);
; #pragma unroll
;                 for (int m = 0; m < 2; ++m)
; #pragma unroll
;                     for (int bj = 0; bj < 2; ++bj)
; #pragma unroll
;                         for (int n = 0; n < 2; ++n) *(f32x4*)(out + (size_t)(row0 + ai * 128 + (2 * mh + m) * 16) * D + col0 + bj * 128 + n * 16) = bs[m][bj][n] + sv[bj][n] * (acc[ai][bj][2 * mh + m][n] + bv[bj][n]);
;                 asm volatile("" ::: "memory"); }
	s_waitcnt vmcnt(16)
	v_mov_b32_e32 v212, v60
	v_mov_b32_e32 v213, v61
	v_mov_b32_e32 v214, v62
	v_mov_b32_e32 v215, v63
	s_nop 0
	v_mov_b32_dpp v60, v56 row_shr:8 row_mask:0xf bank_mask:0xc
	v_mov_b32_dpp v61, v57 row_shr:8 row_mask:0xf bank_mask:0xc
	v_mov_b32_dpp v62, v58 row_shr:8 row_mask:0xf bank_mask:0xc
	v_mov_b32_dpp v63, v59 row_shr:8 row_mask:0xf bank_mask:0xc
	v_mov_b32_dpp v56, v212 row_shl:8 row_mask:0xf bank_mask:0x3
	v_mov_b32_dpp v57, v213 row_shl:8 row_mask:0xf bank_mask:0x3
	v_mov_b32_dpp v58, v214 row_shl:8 row_mask:0xf bank_mask:0x3
	v_mov_b32_dpp v59, v215 row_shl:8 row_mask:0xf bank_mask:0x3
	v_mov_b32_e32 v212, v52
	v_mov_b32_e32 v213, v53
	v_mov_b32_e32 v214, v54
	v_mov_b32_e32 v215, v55
	s_nop 0
	v_mov_b32_dpp v52, v44 row_shr:8 row_mask:0xf bank_mask:0xc
	v_mov_b32_dpp v53, v45 row_shr:8 row_mask:0xf bank_mask:0xc
	v_mov_b32_dpp v54, v46 row_shr:8 row_mask:0xf bank_mask:0xc
	v_mov_b32_dpp v55, v47 row_shr:8 row_mask:0xf bank_mask:0xc
	v_mov_b32_dpp v44, v212 row_shl:8 row_mask:0xf bank_mask:0x3
	v_mov_b32_dpp v45, v213 row_shl:8 row_mask:0xf bank_mask:0x3
	v_mov_b32_dpp v46, v214 row_shl:8 row_mask:0xf bank_mask:0x3
	v_mov_b32_dpp v47, v215 row_shl:8 row_mask:0xf bank_mask:0x3
	v_mov_b32_e32 v212, v48
	v_mov_b32_e32 v213, v49
	v_mov_b32_e32 v214, v50
	v_mov_b32_e32 v215, v51
	s_nop 0
	v_mov_b32_dpp v48, v40 row_shr:8 row_mask:0xf bank_mask:0xc
	v_mov_b32_dpp v49, v41 row_shr:8 row_mask:0xf bank_mask:0xc
	v_mov_b32_dpp v50, v42 row_shr:8 row_mask:0xf bank_mask:0xc
	v_mov_b32_dpp v51, v43 row_shr:8 row_mask:0xf bank_mask:0xc
	v_mov_b32_dpp v40, v212 row_shl:8 row_mask:0xf bank_mask:0x3
	v_mov_b32_dpp v41, v213 row_shl:8 row_mask:0xf bank_mask:0x3
	v_mov_b32_dpp v42, v214 row_shl:8 row_mask:0xf bank_mask:0x3
	v_mov_b32_dpp v43, v215 row_shl:8 row_mask:0xf bank_mask:0x3
	v_mov_b32_e32 v212, v36
	v_mov_b32_e32 v213, v37
	v_mov_b32_e32 v214, v38
	v_mov_b32_e32 v215, v39
	s_nop 0
	v_mov_b32_dpp v36, v32 row_shr:8 row_mask:0xf bank_mask:0xc
	v_mov_b32_dpp v37, v33 row_shr:8 row_mask:0xf bank_mask:0xc
	v_mov_b32_dpp v38, v34 row_shr:8 row_mask:0xf bank_mask:0xc
	v_mov_b32_dpp v39, v35 row_shr:8 row_mask:0xf bank_mask:0xc
	v_mov_b32_dpp v32, v212 row_shl:8 row_mask:0xf bank_mask:0x3
	v_mov_b32_dpp v33, v213 row_shl:8 row_mask:0xf bank_mask:0x3
	v_mov_b32_dpp v34, v214 row_shl:8 row_mask:0xf bank_mask:0x3
	v_mov_b32_dpp v35, v215 row_shl:8 row_mask:0xf bank_mask:0x3
	v_pk_add_f32 v[60:61], v[60:61], v[140:141]
	v_pk_add_f32 v[62:63], v[62:63], v[142:143]
	v_pk_add_f32 v[56:57], v[56:57], v[152:153]
	v_pk_add_f32 v[58:59], v[58:59], v[154:155]
	v_pk_add_f32 v[52:53], v[52:53], v[156:157]
	v_pk_add_f32 v[54:55], v[54:55], v[158:159]
	v_pk_add_f32 v[44:45], v[44:45], v[160:161]
	v_pk_add_f32 v[46:47], v[46:47], v[162:163]
	v_pk_add_f32 v[48:49], v[48:49], v[164:165]
	v_pk_add_f32 v[50:51], v[50:51], v[166:167]
	v_pk_add_f32 v[40:41], v[40:41], v[168:169]
	v_pk_add_f32 v[42:43], v[42:43], v[170:171]
	v_pk_add_f32 v[36:37], v[36:37], v[172:173]
	v_pk_add_f32 v[38:39], v[38:39], v[174:175]
	v_pk_add_f32 v[32:33], v[32:33], v[176:177]
	v_pk_add_f32 v[34:35], v[34:35], v[178:179]
	global_store_dwordx4 v228, v[60:63], s[52:53]
	v_add_u32_e32 v144, v220, v233
	global_store_dwordx4 v144, v[56:59], s[52:53]
	global_store_dwordx4 v228, v[52:55], s[52:53] offset:512
	v_add_u32_e32 v144, v220, v233
	global_store_dwordx4 v144, v[44:47], s[52:53] offset:512
	global_store_dwordx4 v229, v[48:51], s[52:53]
	v_add_u32_e32 v144, v221, v233
	global_store_dwordx4 v144, v[40:43], s[52:53]
	global_store_dwordx4 v229, v[36:39], s[52:53] offset:512
	v_add_u32_e32 v144, v221, v233
	global_store_dwordx4 v144, v[32:35], s[52:53] offset:512
	s_barrier
;     __device__ __forceinline__ void operator()(AccRef acc, const Unit& u, int wr, int wc, int fr, int fq) const {
;     ...
;                         for (int n = 0; n < 2; ++n) bs[m][bj][n] = *(const f32x4*)(base + (size_t)(row0 + ai * 128 + (2 * mh + m) * 16) * D + col0 + bj * 128 + n * 16);
; #pragma unroll
;                 for (int m = 0; m < 2; ++m)
; #pragma unroll
;                     for (int bj = 0; bj < 2; ++bj)
; #pragma unroll
;                         for (int n = 0; n < 2; ++n) *(f32x4*)(out + (size_t)(row0 + ai * 128 + (2 * mh + m) * 16) * D + col0 + bj * 128 + n * 16) = bs[m][bj][n] + sv[bj][n] * (acc[ai][bj][2 * mh + m][n] + bv[bj][n]);
;                 asm volatile("" ::: "memory"); }
	s_waitcnt vmcnt(8)
	v_mov_b32_e32 v212, v28
	v_mov_b32_e32 v213, v29
	v_mov_b32_e32 v214, v30
	v_mov_b32_e32 v215, v31
	s_nop 0
	v_mov_b32_dpp v28, v24 row_shr:8 row_mask:0xf bank_mask:0xc
	v_mov_b32_dpp v29, v25 row_shr:8 row_mask:0xf bank_mask:0xc
	v_mov_b32_dpp v30, v26 row_shr:8 row_mask:0xf bank_mask:0xc
	v_mov_b32_dpp v31, v27 row_shr:8 row_mask:0xf bank_mask:0xc
	v_mov_b32_dpp v24, v212 row_shl:8 row_mask:0xf bank_mask:0x3
	v_mov_b32_dpp v25, v213 row_shl:8 row_mask:0xf bank_mask:0x3
	v_mov_b32_dpp v26, v214 row_shl:8 row_mask:0xf bank_mask:0x3
	v_mov_b32_dpp v27, v215 row_shl:8 row_mask:0xf bank_mask:0x3
	v_mov_b32_e32 v212, v20
	v_mov_b32_e32 v213, v21
	v_mov_b32_e32 v214, v22
	v_mov_b32_e32 v215, v23
	s_nop 0
	v_mov_b32_dpp v20, v12 row_shr:8 row_mask:0xf bank_mask:0xc
	v_mov_b32_dpp v21, v13 row_shr:8 row_mask:0xf bank_mask:0xc
	v_mov_b32_dpp v22, v14 row_shr:8 row_mask:0xf bank_mask:0xc
	v_mov_b32_dpp v23, v15 row_shr:8 row_mask:0xf bank_mask:0xc
	v_mov_b32_dpp v12, v212 row_shl:8 row_mask:0xf bank_mask:0x3
	v_mov_b32_dpp v13, v213 row_shl:8 row_mask:0xf bank_mask:0x3
	v_mov_b32_dpp v14, v214 row_shl:8 row_mask:0xf bank_mask:0x3
	v_mov_b32_dpp v15, v215 row_shl:8 row_mask:0xf bank_mask:0x3
	v_mov_b32_e32 v212, v16
	v_mov_b32_e32 v213, v17
	v_mov_b32_e32 v214, v18
	v_mov_b32_e32 v215, v19
	s_nop 0
	v_mov_b32_dpp v16, v8 row_shr:8 row_mask:0xf bank_mask:0xc
	v_mov_b32_dpp v17, v9 row_shr:8 row_mask:0xf bank_mask:0xc
	v_mov_b32_dpp v18, v10 row_shr:8 row_mask:0xf bank_mask:0xc
	v_mov_b32_dpp v19, v11 row_shr:8 row_mask:0xf bank_mask:0xc
	v_mov_b32_dpp v8, v212 row_shl:8 row_mask:0xf bank_mask:0x3
	v_mov_b32_dpp v9, v213 row_shl:8 row_mask:0xf bank_mask:0x3
	v_mov_b32_dpp v10, v214 row_shl:8 row_mask:0xf bank_mask:0x3
	v_mov_b32_dpp v11, v215 row_shl:8 row_mask:0xf bank_mask:0x3
	v_mov_b32_e32 v212, v4
	v_mov_b32_e32 v213, v5
	v_mov_b32_e32 v214, v6
	v_mov_b32_e32 v215, v7
	s_nop 0
	v_mov_b32_dpp v4, v0 row_shr:8 row_mask:0xf bank_mask:0xc
	v_mov_b32_dpp v5, v1 row_shr:8 row_mask:0xf bank_mask:0xc
	v_mov_b32_dpp v6, v2 row_shr:8 row_mask:0xf bank_mask:0xc
	v_mov_b32_dpp v7, v3 row_shr:8 row_mask:0xf bank_mask:0xc
	v_mov_b32_dpp v0, v212 row_shl:8 row_mask:0xf bank_mask:0x3
	v_mov_b32_dpp v1, v213 row_shl:8 row_mask:0xf bank_mask:0x3
	v_mov_b32_dpp v2, v214 row_shl:8 row_mask:0xf bank_mask:0x3
	v_mov_b32_dpp v3, v215 row_shl:8 row_mask:0xf bank_mask:0x3
	v_pk_add_f32 v[28:29], v[28:29], v[180:181]
	v_pk_add_f32 v[30:31], v[30:31], v[182:183]
	v_pk_add_f32 v[24:25], v[24:25], v[184:185]
	v_pk_add_f32 v[26:27], v[26:27], v[186:187]
	v_pk_add_f32 v[20:21], v[20:21], v[188:189]
	v_pk_add_f32 v[22:23], v[22:23], v[190:191]
	v_pk_add_f32 v[12:13], v[12:13], v[192:193]
	v_pk_add_f32 v[14:15], v[14:15], v[194:195]
	v_pk_add_f32 v[16:17], v[16:17], v[196:197]
	v_pk_add_f32 v[18:19], v[18:19], v[198:199]
	v_pk_add_f32 v[8:9], v[8:9], v[200:201]
	v_pk_add_f32 v[10:11], v[10:11], v[202:203]
	v_pk_add_f32 v[4:5], v[4:5], v[204:205]
	v_pk_add_f32 v[6:7], v[6:7], v[206:207]
	v_pk_add_f32 v[0:1], v[0:1], v[208:209]
	v_pk_add_f32 v[2:3], v[2:3], v[210:211]
	global_store_dwordx4 v230, v[28:31], s[52:53]
	v_add_u32_e32 v144, v222, v233
	global_store_dwordx4 v144, v[24:27], s[52:53]
	global_store_dwordx4 v230, v[20:23], s[52:53] offset:512
	v_add_u32_e32 v144, v222, v233
	global_store_dwordx4 v144, v[12:15], s[52:53] offset:512
	global_store_dwordx4 v231, v[16:19], s[52:53]
	v_add_u32_e32 v144, v223, v233
	global_store_dwordx4 v144, v[8:11], s[52:53]
	global_store_dwordx4 v231, v[4:7], s[52:53] offset:512
	v_add_u32_e32 v144, v223, v233
	global_store_dwordx4 v144, v[0:3], s[52:53] offset:512
	s_cbranch_vccz .LBB0_400
	s_waitcnt vmcnt(0)
	s_cmpk_gt_u32 s4, 0xff
	s_cbranch_scc1 .LBB0_415
	s_barrier

; #define PG8_STAGE(bufoff, gbase, voff) do { _Pragma("unroll") for (int _i = 0; _i < 2; ++_i) \
;         __builtin_amdgcn_global_load_lds((const unsigned*)((const char*)(gbase) + (voff)[_i]), (LAS unsigned*)(lds + (bufoff) + ldsw + _i * 8192), 16, 0, 0); } while (0)
; #define PG8_LDA(dst, b, h) do { _Pragma("unroll") for (int m = 0; m < 4; ++m) _Pragma("unroll") for (int k = 0; k < 2; ++k) dst[m][k] = *(const LAS bf16x8*)(lds + PG8_SA(b, h) + aoff + m * 2048 + k * 1024); } while (0)
; #define PG8_LDB(dst, b, h) do { _Pragma("unroll") for (int n = 0; n < 2; ++n) _Pragma("unroll") for (int k = 0; k < 2; ++k) dst[n][k] = *(const LAS bf16x8*)(lds + PG8_SB(b, h) + boff + n * 2048 + k * 1024); } while (0)
; #define PG8_MMA(ai, bj, At, Bt) do { __builtin_amdgcn_s_setprio(1); _Pragma("unroll") for (int m = 0; m < 4; ++m) _Pragma("unroll") for (int n = 0; n < 2; ++n) _Pragma("unroll") for (int k = 0; k < 2; ++k) \
;         acc[ai][bj][m][n] = __builtin_amdgcn_mfma_f32_16x16x32_bf16(Bt[n][k], At[m][k], acc[ai][bj][m][n], 0, 0, 0); __builtin_amdgcn_s_setprio(0); } while (0)
; #define PG8_WAIT_V(n) asm volatile("s_waitcnt vmcnt(" #n ")" ::: "memory")
; #define PG8_WAIT_L(n) asm volatile("s_waitcnt lgkmcnt(" #n ")" ::: "memory")
; template <class Epi>
; __device__ __forceinline__ void gemm_phase(LAS unsigned char* lds, const Gemm g, const StaticOrder& S, const Epi& E) {
;     ...
;         for (int t = 0; t < nt; t += 2) {
;             const bool last = (t == nt - 2);
;             const char* a1 = cA + (size_t)(t + 1) * kstep;
;             const char* a2 = last ? nA : cA + (size_t)(t + 2) * kstep; const char* b2 = last ? nB : cB + (size_t)(t + 2) * kstep;
;             const char* a3 = a2 + kstep; const char* b3 = b2 + kstep;
;             PG8_LDB(B0, 0, 0); PG8_SCHED; PG8_LDA(At, 0, 0); PG8_STAGE(PG8_SA(1, 1), a1 + hstepA, voffA);
;             PG8_WAIT_L(8); PG8_BAR; PG8_WAIT_L(0); PG8_MMA(0, 0, At, B0); PG8_BAR; PG8_SCHED;
;             PG8_LDB(B1, 0, 1); PG8_STAGE(PG8_SB(0, 0), b2, voffB);
;             PG8_BAR; PG8_WAIT_L(0); PG8_MMA(0, 1, At, B1); PG8_BAR;
;             PG8_LDA(At, 0, 1); PG8_STAGE(PG8_SA(0, 0), a2, voffA);
;             PG8_BAR; PG8_WAIT_L(0); PG8_MMA(1, 0, At, B0); PG8_BAR; PG8_SCHED;
;             PG8_STAGE(PG8_SB(0, 1), b2 + hstepB, voffB);
;             PG8_WAIT_V(6); PG8_BAR; PG8_MMA(1, 1, At, B1); PG8_BAR;
.LBB0_860:
	ds_read_b128 v[140:143], v149
	ds_read_b128 v[152:155], v149 offset:1024
	ds_read_b128 v[156:159], v149 offset:2048
	ds_read_b128 v[160:163], v149 offset:3072
	s_add_u32 s30, s28, 0x100
	s_addc_u32 s31, s29, 0
	s_cmp_eq_u32 s68, 40
	s_cselect_b32 s37, s13, s31
	s_cselect_b32 s36, s12, s30
	s_cselect_b32 s35, s15, s63
	s_cselect_b32 s34, s14, s49
	v_lshl_add_u64 v[144:145], s[28:29], 0, v[132:133]
	s_add_i32 m0, s8, 0xc000
	ds_read_b128 v[164:167], v150
	ds_read_b128 v[168:171], v150 offset:1024
	ds_read_b128 v[172:175], v150 offset:2048
	ds_read_b128 v[176:179], v150 offset:3072
	ds_read_b128 v[180:183], v150 offset:4096
	ds_read_b128 v[184:187], v150 offset:5120
	ds_read_b128 v[188:191], v150 offset:6144
	ds_read_b128 v[192:195], v150 offset:7168
	global_load_lds_dwordx4 v[144:145], off
	v_lshl_add_u64 v[144:145], s[28:29], 0, v[134:135]
	s_add_i32 m0, s8, 0xe000
	s_nop 0
	global_load_lds_dwordx4 v[144:145], off
	ds_read_b128 v[196:199], v151
	ds_read_b128 v[200:203], v151 offset:1024
	ds_read_b128 v[204:207], v151 offset:2048
	ds_read_b128 v[208:211], v151 offset:3072
	s_waitcnt lgkmcnt(0)
	s_barrier
	s_setprio 1
	v_mfma_f32_16x16x32_bf16 v[124:127], v[140:143], v[164:167], v[124:127]
	v_mfma_f32_16x16x32_bf16 v[120:123], v[156:159], v[164:167], v[120:123]
	v_mfma_f32_16x16x32_bf16 v[112:115], v[140:143], v[172:175], v[112:115]
	v_mfma_f32_16x16x32_bf16 v[104:107], v[156:159], v[172:175], v[104:107]
	v_mfma_f32_16x16x32_bf16 v[92:95], v[140:143], v[180:183], v[92:95]
	v_mfma_f32_16x16x32_bf16 v[88:91], v[156:159], v[180:183], v[88:91]
	v_mfma_f32_16x16x32_bf16 v[80:83], v[140:143], v[188:191], v[80:83]
	v_mfma_f32_16x16x32_bf16 v[72:75], v[156:159], v[188:191], v[72:75]
	v_mfma_f32_16x16x32_bf16 v[124:127], v[152:155], v[168:171], v[124:127]
	v_mfma_f32_16x16x32_bf16 v[120:123], v[160:163], v[168:171], v[120:123]
	v_mfma_f32_16x16x32_bf16 v[112:115], v[152:155], v[176:179], v[112:115]
	v_mfma_f32_16x16x32_bf16 v[104:107], v[160:163], v[176:179], v[104:107]
	v_mfma_f32_16x16x32_bf16 v[92:95], v[152:155], v[184:187], v[92:95]
	v_mfma_f32_16x16x32_bf16 v[88:91], v[160:163], v[184:187], v[88:91]
	v_mfma_f32_16x16x32_bf16 v[80:83], v[152:155], v[192:195], v[80:83]
	v_mfma_f32_16x16x32_bf16 v[72:75], v[160:163], v[192:195], v[72:75]
	v_mfma_f32_16x16x32_bf16 v[116:119], v[196:199], v[164:167], v[116:119]
	v_mfma_f32_16x16x32_bf16 v[108:111], v[204:207], v[164:167], v[108:111]
	v_mfma_f32_16x16x32_bf16 v[100:103], v[196:199], v[172:175], v[100:103]
	v_mfma_f32_16x16x32_bf16 v[96:99], v[204:207], v[172:175], v[96:99]
	v_mfma_f32_16x16x32_bf16 v[84:87], v[196:199], v[180:183], v[84:87]
	v_mfma_f32_16x16x32_bf16 v[76:79], v[204:207], v[180:183], v[76:79]
	v_mfma_f32_16x16x32_bf16 v[68:71], v[196:199], v[188:191], v[68:71]
	v_mfma_f32_16x16x32_bf16 v[64:67], v[204:207], v[188:191], v[64:67]
	v_mfma_f32_16x16x32_bf16 v[116:119], v[200:203], v[168:171], v[116:119]
	v_mfma_f32_16x16x32_bf16 v[108:111], v[208:211], v[168:171], v[108:111]
	v_mfma_f32_16x16x32_bf16 v[100:103], v[200:203], v[176:179], v[100:103]
	v_mfma_f32_16x16x32_bf16 v[96:99], v[208:211], v[176:179], v[96:99]
	v_mfma_f32_16x16x32_bf16 v[84:87], v[200:203], v[184:187], v[84:87]
	v_mfma_f32_16x16x32_bf16 v[76:79], v[208:211], v[184:187], v[76:79]
	v_mfma_f32_16x16x32_bf16 v[68:71], v[200:203], v[192:195], v[68:71]
	v_mfma_f32_16x16x32_bf16 v[64:67], v[208:211], v[192:195], v[64:67]
	s_setprio 0
	s_barrier
	s_nop 1
	ds_read_b128 v[164:167], v150 offset:16384
	ds_read_b128 v[168:171], v150 offset:17408
	ds_read_b128 v[172:175], v150 offset:18432
	ds_read_b128 v[176:179], v150 offset:19456
	ds_read_b128 v[180:183], v150 offset:20480
	ds_read_b128 v[184:187], v150 offset:21504
	ds_read_b128 v[188:191], v150 offset:22528
	ds_read_b128 v[192:195], v150 offset:23552
	s_add_i32 s28, s43, s7
	v_lshl_add_u64 v[144:145], s[34:35], 0, v[128:129]
	s_mov_b32 m0, s28
	s_nop 0
	global_load_lds_dwordx4 v[144:145], off
	v_lshl_add_u64 v[212:213], s[34:35], 0, v[130:131]
	s_add_i32 m0, s28, 0x2000
	s_nop 0
	global_load_lds_dwordx4 v[212:213], off
	s_mov_b32 m0, s8
	v_lshl_add_u64 v[214:215], s[36:37], 0, v[128:129]
	global_load_lds_dwordx4 v[214:215], off
	v_lshl_add_u64 v[216:217], s[36:37], 0, v[130:131]
	s_mov_b32 m0, s9
	s_nop 0
	global_load_lds_dwordx4 v[216:217], off
	s_add_u32 s28, s34, 0xb0000
	s_addc_u32 s29, s35, 0
	s_add_i32 s69, s44, s7
	v_lshl_add_u64 v[254:255], s[28:29], 0, v[128:129]
	s_mov_b32 m0, s69
	s_nop 0
	global_load_lds_dwordx4 v[254:255], off
	v_lshl_add_u64 v[254:255], s[28:29], 0, v[130:131]
	s_add_i32 m0, s69, 0x2000
	s_nop 0
	global_load_lds_dwordx4 v[254:255], off
	s_waitcnt vmcnt(6)
	s_waitcnt lgkmcnt(0)
	s_barrier
; #define PG8_STAGE(bufoff, gbase, voff) do { _Pragma("unroll") for (int _i = 0; _i < 2; ++_i) \
;         __builtin_amdgcn_global_load_lds((const unsigned*)((const char*)(gbase) + (voff)[_i]), (LAS unsigned*)(lds + (bufoff) + ldsw + _i * 8192), 16, 0, 0); } while (0)
; #define PG8_LDA(dst, b, h) do { _Pragma("unroll") for (int m = 0; m < 4; ++m) _Pragma("unroll") for (int k = 0; k < 2; ++k) dst[m][k] = *(const LAS bf16x8*)(lds + PG8_SA(b, h) + aoff + m * 2048 + k * 1024); } while (0)
; #define PG8_LDB(dst, b, h) do { _Pragma("unroll") for (int n = 0; n < 2; ++n) _Pragma("unroll") for (int k = 0; k < 2; ++k) dst[n][k] = *(const LAS bf16x8*)(lds + PG8_SB(b, h) + boff + n * 2048 + k * 1024); } while (0)
; #define PG8_MMA(ai, bj, At, Bt) do { __builtin_amdgcn_s_setprio(1); _Pragma("unroll") for (int m = 0; m < 4; ++m) _Pragma("unroll") for (int n = 0; n < 2; ++n) _Pragma("unroll") for (int k = 0; k < 2; ++k) \
;         acc[ai][bj][m][n] = __builtin_amdgcn_mfma_f32_16x16x32_bf16(Bt[n][k], At[m][k], acc[ai][bj][m][n], 0, 0, 0); __builtin_amdgcn_s_setprio(0); } while (0)
; #define PG8_WAIT_V(n) asm volatile("s_waitcnt vmcnt(" #n ")" ::: "memory")
; #define PG8_WAIT_L(n) asm volatile("s_waitcnt lgkmcnt(" #n ")" ::: "memory")
; #define PG8_BAR __builtin_amdgcn_s_barrier()
; #define PG8_SCHED __builtin_amdgcn_sched_barrier(0)
; template <class Epi>
; __device__ __forceinline__ void gemm_phase(LAS unsigned char* lds, const Gemm g, const StaticOrder& S, const Epi& E) {
;     ...
;             PG8_BAR; PG8_WAIT_L(0); PG8_MMA(0, 1, At, B1); PG8_BAR;
;             PG8_LDA(At, 0, 1); PG8_STAGE(PG8_SA(0, 0), a2, voffA);
;             PG8_BAR; PG8_WAIT_L(0); PG8_MMA(1, 0, At, B0); PG8_BAR; PG8_SCHED;
;             PG8_STAGE(PG8_SB(0, 1), b2 + hstepB, voffB);
;             PG8_WAIT_V(6); PG8_BAR; PG8_MMA(1, 1, At, B1); PG8_BAR;
;             PG8_LDB(B0, 1, 0); PG8_SCHED; PG8_LDA(At, 1, 0); PG8_STAGE(PG8_SA(0, 1), a2 + hstepA, voffA);
;             PG8_WAIT_L(8); PG8_BAR; PG8_WAIT_L(0); PG8_MMA(0, 0, At, B0); PG8_BAR; PG8_SCHED;
;             PG8_LDB(B1, 1, 1); PG8_STAGE(PG8_SB(1, 0), b3, voffB);
;             PG8_BAR; PG8_WAIT_L(0); PG8_MMA(0, 1, At, B1); PG8_BAR;
;             PG8_LDA(At, 1, 1); PG8_STAGE(PG8_SA(1, 0), a3, voffA);
;             PG8_BAR; PG8_WAIT_L(0); PG8_MMA(1, 0, At, B0); PG8_BAR; PG8_SCHED;
	s_setprio 1
	v_mfma_f32_16x16x32_bf16 v[60:63], v[140:143], v[164:167], v[60:63]
	v_mfma_f32_16x16x32_bf16 v[56:59], v[156:159], v[164:167], v[56:59]
	v_mfma_f32_16x16x32_bf16 v[48:51], v[140:143], v[172:175], v[48:51]
	v_mfma_f32_16x16x32_bf16 v[40:43], v[156:159], v[172:175], v[40:43]
	v_mfma_f32_16x16x32_bf16 v[28:31], v[140:143], v[180:183], v[28:31]
	v_mfma_f32_16x16x32_bf16 v[24:27], v[156:159], v[180:183], v[24:27]
	v_mfma_f32_16x16x32_bf16 v[16:19], v[140:143], v[188:191], v[16:19]
	v_mfma_f32_16x16x32_bf16 v[8:11], v[156:159], v[188:191], v[8:11]
	v_mfma_f32_16x16x32_bf16 v[60:63], v[152:155], v[168:171], v[60:63]
	v_mfma_f32_16x16x32_bf16 v[56:59], v[160:163], v[168:171], v[56:59]
	v_mfma_f32_16x16x32_bf16 v[48:51], v[152:155], v[176:179], v[48:51]
	v_mfma_f32_16x16x32_bf16 v[40:43], v[160:163], v[176:179], v[40:43]
	v_mfma_f32_16x16x32_bf16 v[28:31], v[152:155], v[184:187], v[28:31]
	v_mfma_f32_16x16x32_bf16 v[24:27], v[160:163], v[184:187], v[24:27]
	v_mfma_f32_16x16x32_bf16 v[16:19], v[152:155], v[192:195], v[16:19]
	v_mfma_f32_16x16x32_bf16 v[8:11], v[160:163], v[192:195], v[8:11]
	v_mfma_f32_16x16x32_bf16 v[52:55], v[196:199], v[164:167], v[52:55]
	v_mfma_f32_16x16x32_bf16 v[44:47], v[204:207], v[164:167], v[44:47]
	v_mfma_f32_16x16x32_bf16 v[36:39], v[196:199], v[172:175], v[36:39]
	v_mfma_f32_16x16x32_bf16 v[32:35], v[204:207], v[172:175], v[32:35]
	v_mfma_f32_16x16x32_bf16 v[20:23], v[196:199], v[180:183], v[20:23]
	v_mfma_f32_16x16x32_bf16 v[12:15], v[204:207], v[180:183], v[12:15]
	v_mfma_f32_16x16x32_bf16 v[4:7], v[196:199], v[188:191], v[4:7]
	v_mfma_f32_16x16x32_bf16 v[0:3], v[204:207], v[188:191], v[0:3]
	v_mfma_f32_16x16x32_bf16 v[52:55], v[200:203], v[168:171], v[52:55]
	v_mfma_f32_16x16x32_bf16 v[44:47], v[208:211], v[168:171], v[44:47]
	v_mfma_f32_16x16x32_bf16 v[36:39], v[200:203], v[176:179], v[36:39]
	v_mfma_f32_16x16x32_bf16 v[32:35], v[208:211], v[176:179], v[32:35]
	v_mfma_f32_16x16x32_bf16 v[20:23], v[200:203], v[184:187], v[20:23]
	v_mfma_f32_16x16x32_bf16 v[12:15], v[208:211], v[184:187], v[12:15]
	v_mfma_f32_16x16x32_bf16 v[4:7], v[200:203], v[192:195], v[4:7]
	v_mfma_f32_16x16x32_bf16 v[0:3], v[208:211], v[192:195], v[0:3]
	s_setprio 0
	s_add_i32 s69, 0, 0x18000
	v_add_u32_e32 v160, s69, v147
	s_barrier
	ds_read_b128 v[140:143], v160
	ds_read_b128 v[152:155], v160 offset:1024
	ds_read_b128 v[156:159], v160 offset:2048
	ds_read_b128 v[160:163], v160 offset:3072
	s_add_u32 s28, s36, 0xb0000
	s_addc_u32 s29, s37, 0
	s_mov_b32 m0, s38
	v_lshl_add_u64 v[196:197], s[28:29], 0, v[128:129]
	ds_read_b128 v[164:167], v150 offset:32768
	ds_read_b128 v[168:171], v150 offset:33792
	ds_read_b128 v[172:175], v150 offset:34816
	ds_read_b128 v[176:179], v150 offset:35840
	ds_read_b128 v[180:183], v150 offset:36864
	ds_read_b128 v[184:187], v150 offset:37888
	ds_read_b128 v[188:191], v150 offset:38912
	ds_read_b128 v[192:195], v150 offset:39936
	global_load_lds_dwordx4 v[196:197], off
	v_lshl_add_u64 v[196:197], s[28:29], 0, v[130:131]
	s_mov_b32 m0, s39
	s_nop 0
	global_load_lds_dwordx4 v[196:197], off
	s_add_i32 s36, 0, 0x1c000
	v_add_u32_e32 v208, s36, v147
	ds_read_b128 v[196:199], v208
	ds_read_b128 v[200:203], v208 offset:1024
	ds_read_b128 v[204:207], v208 offset:2048
	ds_read_b128 v[208:211], v208 offset:3072
	s_waitcnt lgkmcnt(0)
	s_barrier
	s_setprio 1
	v_mfma_f32_16x16x32_bf16 v[124:127], v[140:143], v[164:167], v[124:127]
	v_mfma_f32_16x16x32_bf16 v[120:123], v[156:159], v[164:167], v[120:123]
	v_mfma_f32_16x16x32_bf16 v[112:115], v[140:143], v[172:175], v[112:115]
	v_mfma_f32_16x16x32_bf16 v[104:107], v[156:159], v[172:175], v[104:107]
	v_mfma_f32_16x16x32_bf16 v[92:95], v[140:143], v[180:183], v[92:95]
	v_mfma_f32_16x16x32_bf16 v[88:91], v[156:159], v[180:183], v[88:91]
	v_mfma_f32_16x16x32_bf16 v[80:83], v[140:143], v[188:191], v[80:83]
	v_mfma_f32_16x16x32_bf16 v[72:75], v[156:159], v[188:191], v[72:75]
	v_mfma_f32_16x16x32_bf16 v[124:127], v[152:155], v[168:171], v[124:127]
	v_mfma_f32_16x16x32_bf16 v[120:123], v[160:163], v[168:171], v[120:123]
	v_mfma_f32_16x16x32_bf16 v[112:115], v[152:155], v[176:179], v[112:115]
	v_mfma_f32_16x16x32_bf16 v[104:107], v[160:163], v[176:179], v[104:107]
	v_mfma_f32_16x16x32_bf16 v[92:95], v[152:155], v[184:187], v[92:95]
	v_mfma_f32_16x16x32_bf16 v[88:91], v[160:163], v[184:187], v[88:91]
	v_mfma_f32_16x16x32_bf16 v[80:83], v[152:155], v[192:195], v[80:83]
	v_mfma_f32_16x16x32_bf16 v[72:75], v[160:163], v[192:195], v[72:75]
	v_mfma_f32_16x16x32_bf16 v[116:119], v[196:199], v[164:167], v[116:119]
	v_mfma_f32_16x16x32_bf16 v[108:111], v[204:207], v[164:167], v[108:111]
	v_mfma_f32_16x16x32_bf16 v[100:103], v[196:199], v[172:175], v[100:103]
	v_mfma_f32_16x16x32_bf16 v[96:99], v[204:207], v[172:175], v[96:99]
	v_mfma_f32_16x16x32_bf16 v[84:87], v[196:199], v[180:183], v[84:87]
	v_mfma_f32_16x16x32_bf16 v[76:79], v[204:207], v[180:183], v[76:79]
	v_mfma_f32_16x16x32_bf16 v[68:71], v[196:199], v[188:191], v[68:71]
	v_mfma_f32_16x16x32_bf16 v[64:67], v[204:207], v[188:191], v[64:67]
	v_mfma_f32_16x16x32_bf16 v[116:119], v[200:203], v[168:171], v[116:119]
	v_mfma_f32_16x16x32_bf16 v[108:111], v[208:211], v[168:171], v[108:111]
	v_mfma_f32_16x16x32_bf16 v[100:103], v[200:203], v[176:179], v[100:103]
	v_mfma_f32_16x16x32_bf16 v[96:99], v[208:211], v[176:179], v[96:99]
	v_mfma_f32_16x16x32_bf16 v[84:87], v[200:203], v[184:187], v[84:87]
	v_mfma_f32_16x16x32_bf16 v[76:79], v[208:211], v[184:187], v[76:79]
	v_mfma_f32_16x16x32_bf16 v[68:71], v[200:203], v[192:195], v[68:71]
	v_mfma_f32_16x16x32_bf16 v[64:67], v[208:211], v[192:195], v[64:67]
	s_setprio 0
	s_barrier
; #define PG8_MMA(ai, bj, At, Bt) do { __builtin_amdgcn_s_setprio(1); _Pragma("unroll") for (int m = 0; m < 4; ++m) _Pragma("unroll") for (int n = 0; n < 2; ++n) _Pragma("unroll") for (int k = 0; k < 2; ++k) \
;         acc[ai][bj][m][n] = __builtin_amdgcn_mfma_f32_16x16x32_bf16(Bt[n][k], At[m][k], acc[ai][bj][m][n], 0, 0, 0); __builtin_amdgcn_s_setprio(0); } while (0)
; #define PG8_WAIT_V(n) asm volatile("s_waitcnt vmcnt(" #n ")" ::: "memory")
; #define PG8_BAR __builtin_amdgcn_s_barrier()
; template <class Epi>
; __device__ __forceinline__ void gemm_phase(LAS unsigned char* lds, const Gemm g, const StaticOrder& S, const Epi& E) {
;     ...
;             PG8_WAIT_V(6); PG8_BAR; PG8_MMA(1, 1, At, B1); PG8_BAR;
;         }
;     __device__ __forceinline__ void operator()(AccRef acc, const Unit& u, int wr, int wc, int fr, int fq) const {
;         const int row0 = u.pm * 256 + wr * 64 + fr, col0 = u.pn * 256 + wc * 32 + 4 * fq;
;         f32x4 sv[2][2], bv[2][2];
; #pragma unroll
;         for (int bj = 0; bj < 2; ++bj)
; #pragma unroll
;             for (int n = 0; n < 2; ++n) {
;                 sv[bj][n] = scale ? *(const f32x4*)(scale + col0 + bj * 128 + n * 16) : (f32x4){1.f, 1.f, 1.f, 1.f};
;                 bv[bj][n] = bias ? *(const f32x4*)(bias + col0 + bj * 128 + n * 16) : (f32x4){0.f, 0.f, 0.f, 0.f}; }
; #pragma unroll
;         for (int ai = 0; ai < 2; ++ai)
; #pragma unroll
;             for (int mh = 0; mh < 2; ++mh) {
;                 f32x4 bs[2][2][2];
; #pragma unroll
;                 for (int m = 0; m < 2; ++m)
; #pragma unroll
;                     for (int bj = 0; bj < 2; ++bj)
; #pragma unroll
;                         for (int n = 0; n < 2; ++n) bs[m][bj][n] = *(const f32x4*)(base + (size_t)(row0 + ai * 128 + (2 * mh + m) * 16) * D + col0 + bj * 128 + n * 16);
	s_nop 1
	ds_read_b128 v[164:167], v150 offset:49152
	ds_read_b128 v[168:171], v150 offset:50176
	ds_read_b128 v[172:175], v150 offset:51200
	ds_read_b128 v[176:179], v150 offset:52224
	ds_read_b128 v[180:183], v150 offset:53248
	ds_read_b128 v[184:187], v150 offset:54272
	ds_read_b128 v[188:191], v150 offset:55296
	ds_read_b128 v[192:195], v150 offset:56320
	s_add_i32 s28, s69, s7
	v_lshl_add_u64 v[254:255], v[144:145], 0, s[20:21]
	s_mov_b32 m0, s28
	s_nop 0
	global_load_lds_dwordx4 v[254:255], off
	v_lshl_add_u64 v[254:255], v[212:213], 0, s[20:21]
	s_add_i32 m0, s28, 0x2000
	s_nop 0
	global_load_lds_dwordx4 v[254:255], off
	s_mov_b32 m0, s41
	v_lshl_add_u64 v[254:255], v[214:215], 0, s[20:21]
	global_load_lds_dwordx4 v[254:255], off
	v_lshl_add_u64 v[144:145], v[216:217], 0, s[20:21]
	s_mov_b32 m0, s42
	s_nop 0
	global_load_lds_dwordx4 v[144:145], off
	s_add_u32 s28, s34, 0xb0080
	s_addc_u32 s29, s35, 0
	s_add_i32 s34, s36, s7
	v_lshl_add_u64 v[254:255], s[28:29], 0, v[128:129]
	s_mov_b32 m0, s34
	s_nop 0
	global_load_lds_dwordx4 v[254:255], off
	v_lshl_add_u64 v[254:255], s[28:29], 0, v[130:131]
	s_add_i32 m0, s34, 0x2000
	s_nop 0
	global_load_lds_dwordx4 v[254:255], off
	s_waitcnt vmcnt(6)
	s_waitcnt lgkmcnt(0)
	s_barrier
	s_setprio 1
	v_mfma_f32_16x16x32_bf16 v[60:63], v[140:143], v[164:167], v[60:63]
	v_mfma_f32_16x16x32_bf16 v[56:59], v[156:159], v[164:167], v[56:59]
	v_mfma_f32_16x16x32_bf16 v[48:51], v[140:143], v[172:175], v[48:51]
	v_mfma_f32_16x16x32_bf16 v[40:43], v[156:159], v[172:175], v[40:43]
	v_mfma_f32_16x16x32_bf16 v[28:31], v[140:143], v[180:183], v[28:31]
	v_mfma_f32_16x16x32_bf16 v[24:27], v[156:159], v[180:183], v[24:27]
	v_mfma_f32_16x16x32_bf16 v[16:19], v[140:143], v[188:191], v[16:19]
	v_mfma_f32_16x16x32_bf16 v[8:11], v[156:159], v[188:191], v[8:11]
	v_mfma_f32_16x16x32_bf16 v[60:63], v[152:155], v[168:171], v[60:63]
	v_mfma_f32_16x16x32_bf16 v[56:59], v[160:163], v[168:171], v[56:59]
	v_mfma_f32_16x16x32_bf16 v[48:51], v[152:155], v[176:179], v[48:51]
	v_mfma_f32_16x16x32_bf16 v[40:43], v[160:163], v[176:179], v[40:43]
	v_mfma_f32_16x16x32_bf16 v[28:31], v[152:155], v[184:187], v[28:31]
	v_mfma_f32_16x16x32_bf16 v[24:27], v[160:163], v[184:187], v[24:27]
	v_mfma_f32_16x16x32_bf16 v[16:19], v[152:155], v[192:195], v[16:19]
	v_mfma_f32_16x16x32_bf16 v[8:11], v[160:163], v[192:195], v[8:11]
	v_mfma_f32_16x16x32_bf16 v[52:55], v[196:199], v[164:167], v[52:55]
	v_mfma_f32_16x16x32_bf16 v[44:47], v[204:207], v[164:167], v[44:47]
	v_mfma_f32_16x16x32_bf16 v[36:39], v[196:199], v[172:175], v[36:39]
	v_mfma_f32_16x16x32_bf16 v[32:35], v[204:207], v[172:175], v[32:35]
	v_mfma_f32_16x16x32_bf16 v[20:23], v[196:199], v[180:183], v[20:23]
	v_mfma_f32_16x16x32_bf16 v[12:15], v[204:207], v[180:183], v[12:15]
	v_mfma_f32_16x16x32_bf16 v[4:7], v[196:199], v[188:191], v[4:7]
	v_mfma_f32_16x16x32_bf16 v[0:3], v[204:207], v[188:191], v[0:3]
	v_mfma_f32_16x16x32_bf16 v[52:55], v[200:203], v[168:171], v[52:55]
	v_mfma_f32_16x16x32_bf16 v[44:47], v[208:211], v[168:171], v[44:47]
	v_mfma_f32_16x16x32_bf16 v[36:39], v[200:203], v[176:179], v[36:39]
	v_mfma_f32_16x16x32_bf16 v[32:35], v[208:211], v[176:179], v[32:35]
	v_mfma_f32_16x16x32_bf16 v[20:23], v[200:203], v[184:187], v[20:23]
	v_mfma_f32_16x16x32_bf16 v[12:15], v[208:211], v[184:187], v[12:15]
	v_mfma_f32_16x16x32_bf16 v[4:7], v[200:203], v[192:195], v[4:7]
	v_mfma_f32_16x16x32_bf16 v[0:3], v[208:211], v[192:195], v[0:3]
	s_setprio 0
	s_add_i32 s68, s68, 2
	s_add_u32 s49, s49, 0x100
	s_addc_u32 s63, s63, 0
	s_cmp_gt_u32 s68, 41
	s_mov_b64 s[28:29], s[30:31]
	s_barrier
	s_cbranch_scc0 .LBB0_860
	v_lshl_or_b32 v144, s47, 8, v148
	v_lshl_add_u32 v145, s48, 8, v146
	v_lshlrev_b32_e32 v144, 2, v144
	v_lshl_add_u32 v145, v145, 12, v144
	v_add_u32_e32 v216, 0x10000, v145
	v_add_u32_e32 v217, 0x20000, v145
	v_add_u32_e32 v218, 0x30000, v145
	v_add_u32_e32 v220, 0x80000, v145
	v_add_u32_e32 v221, 0x90000, v145
	v_add_u32_e32 v222, 0xa0000, v145
	v_add_u32_e32 v223, 0xb0000, v145
	v_and_b32_e32 v235, 8, v146
	v_cmp_ne_u32_e32 vcc, 0, v235
	v_mov_b32_e32 v232, 0xffff8040
	s_nop 0
	v_cndmask_b32_e32 v232, 0, v232, vcc
	v_mov_b32_e32 v233, 64
	v_mov_b32_e32 v235, 0x8000
	v_cndmask_b32_e32 v233, v235, v233, vcc
	v_add_u32_e32 v224, v145, v232
	v_add_u32_e32 v225, v216, v232
	v_add_u32_e32 v226, v217, v232
	v_add_u32_e32 v227, v218, v232
	v_add_u32_e32 v228, v220, v232
	v_add_u32_e32 v229, v221, v232
	v_add_u32_e32 v230, v222, v232
	v_add_u32_e32 v231, v223, v232
	s_and_b64 vcc, exec, s[10:11]
	s_mov_b32 s47, s45
	s_mov_b32 s48, s46
	s_mov_b64 s[30:31], s[14:15]
	s_mov_b64 s[28:29], s[12:13]
	global_load_dwordx4 v[140:143], v224, s[52:53]
	v_add_u32_e32 v144, v145, v233
	global_load_dwordx4 v[152:155], v144, s[52:53]
	global_load_dwordx4 v[156:159], v224, s[52:53] offset:512
	v_add_u32_e32 v144, v145, v233
	global_load_dwordx4 v[160:163], v144, s[52:53] offset:512
	global_load_dwordx4 v[164:167], v225, s[52:53]
	v_add_u32_e32 v144, v216, v233
	global_load_dwordx4 v[168:171], v144, s[52:53]
	global_load_dwordx4 v[172:175], v225, s[52:53] offset:512
	v_add_u32_e32 v144, v216, v233
	global_load_dwordx4 v[176:179], v144, s[52:53] offset:512
	global_load_dwordx4 v[180:183], v226, s[52:53]
	v_add_u32_e32 v144, v217, v233
	global_load_dwordx4 v[184:187], v144, s[52:53]
	global_load_dwordx4 v[188:191], v226, s[52:53] offset:512
	v_add_u32_e32 v144, v217, v233
	global_load_dwordx4 v[192:195], v144, s[52:53] offset:512
	global_load_dwordx4 v[196:199], v227, s[52:53]
	v_add_u32_e32 v144, v218, v233
	global_load_dwordx4 v[200:203], v144, s[52:53]
	global_load_dwordx4 v[204:207], v227, s[52:53] offset:512
	v_add_u32_e32 v144, v218, v233
	global_load_dwordx4 v[208:211], v144, s[52:53] offset:512
	s_barrier
;     __device__ __forceinline__ void operator()(AccRef acc, const Unit& u, int wr, int wc, int fr, int fq) const {
;     ...
;                         for (int n = 0; n < 2; ++n) bs[m][bj][n] = *(const f32x4*)(base + (size_t)(row0 + ai * 128 + (2 * mh + m) * 16) * D + col0 + bj * 128 + n * 16);
; #pragma unroll
;                 for (int m = 0; m < 2; ++m)
; #pragma unroll
;                     for (int bj = 0; bj < 2; ++bj)
; #pragma unroll
;                         for (int n = 0; n < 2; ++n) *(f32x4*)(out + (size_t)(row0 + ai * 128 + (2 * mh + m) * 16) * D + col0 + bj * 128 + n * 16) = bs[m][bj][n] + sv[bj][n] * (acc[ai][bj][2 * mh + m][n] + bv[bj][n]);
	v_pk_add_f32 v[124:125], v[124:125], 0 op_sel_hi:[1,0]
	v_pk_add_f32 v[126:127], v[126:127], 0 op_sel_hi:[1,0]
	v_pk_add_f32 v[120:121], v[120:121], 0 op_sel_hi:[1,0]
	v_pk_add_f32 v[122:123], v[122:123], 0 op_sel_hi:[1,0]
	v_pk_add_f32 v[116:117], v[116:117], 0 op_sel_hi:[1,0]
	v_pk_add_f32 v[118:119], v[118:119], 0 op_sel_hi:[1,0]
	v_pk_add_f32 v[108:109], v[108:109], 0 op_sel_hi:[1,0]
	v_pk_add_f32 v[110:111], v[110:111], 0 op_sel_hi:[1,0]
	v_pk_add_f32 v[112:113], v[112:113], 0 op_sel_hi:[1,0]
	v_pk_add_f32 v[114:115], v[114:115], 0 op_sel_hi:[1,0]
	v_pk_add_f32 v[104:105], v[104:105], 0 op_sel_hi:[1,0]
	v_pk_add_f32 v[106:107], v[106:107], 0 op_sel_hi:[1,0]
	v_pk_add_f32 v[100:101], v[100:101], 0 op_sel_hi:[1,0]
	v_pk_add_f32 v[102:103], v[102:103], 0 op_sel_hi:[1,0]
	v_pk_add_f32 v[96:97], v[96:97], 0 op_sel_hi:[1,0]
	v_pk_add_f32 v[98:99], v[98:99], 0 op_sel_hi:[1,0]
	v_pk_add_f32 v[92:93], v[92:93], 0 op_sel_hi:[1,0]
	v_pk_add_f32 v[94:95], v[94:95], 0 op_sel_hi:[1,0]
	v_pk_add_f32 v[88:89], v[88:89], 0 op_sel_hi:[1,0]
	v_pk_add_f32 v[90:91], v[90:91], 0 op_sel_hi:[1,0]
	v_pk_add_f32 v[84:85], v[84:85], 0 op_sel_hi:[1,0]
	v_pk_add_f32 v[86:87], v[86:87], 0 op_sel_hi:[1,0]
	v_pk_add_f32 v[76:77], v[76:77], 0 op_sel_hi:[1,0]
	v_pk_add_f32 v[78:79], v[78:79], 0 op_sel_hi:[1,0]
	v_pk_add_f32 v[80:81], v[80:81], 0 op_sel_hi:[1,0]
	v_pk_add_f32 v[82:83], v[82:83], 0 op_sel_hi:[1,0]
	v_pk_add_f32 v[72:73], v[72:73], 0 op_sel_hi:[1,0]
	v_pk_add_f32 v[74:75], v[74:75], 0 op_sel_hi:[1,0]
	v_pk_add_f32 v[68:69], v[68:69], 0 op_sel_hi:[1,0]
	v_pk_add_f32 v[70:71], v[70:71], 0 op_sel_hi:[1,0]
	v_pk_add_f32 v[64:65], v[64:65], 0 op_sel_hi:[1,0]
	v_pk_add_f32 v[66:67], v[66:67], 0 op_sel_hi:[1,0]
	v_pk_add_f32 v[60:61], v[60:61], 0 op_sel_hi:[1,0]
	v_pk_add_f32 v[62:63], v[62:63], 0 op_sel_hi:[1,0]
	v_pk_add_f32 v[56:57], v[56:57], 0 op_sel_hi:[1,0]
	v_pk_add_f32 v[58:59], v[58:59], 0 op_sel_hi:[1,0]
	v_pk_add_f32 v[52:53], v[52:53], 0 op_sel_hi:[1,0]
	v_pk_add_f32 v[54:55], v[54:55], 0 op_sel_hi:[1,0]
	v_pk_add_f32 v[44:45], v[44:45], 0 op_sel_hi:[1,0]
	v_pk_add_f32 v[46:47], v[46:47], 0 op_sel_hi:[1,0]
	v_pk_add_f32 v[48:49], v[48:49], 0 op_sel_hi:[1,0]
	v_pk_add_f32 v[50:51], v[50:51], 0 op_sel_hi:[1,0]
	v_pk_add_f32 v[40:41], v[40:41], 0 op_sel_hi:[1,0]
	v_pk_add_f32 v[42:43], v[42:43], 0 op_sel_hi:[1,0]
	v_pk_add_f32 v[36:37], v[36:37], 0 op_sel_hi:[1,0]
	v_pk_add_f32 v[38:39], v[38:39], 0 op_sel_hi:[1,0]
	v_pk_add_f32 v[32:33], v[32:33], 0 op_sel_hi:[1,0]
	v_pk_add_f32 v[34:35], v[34:35], 0 op_sel_hi:[1,0]
	v_pk_add_f32 v[28:29], v[28:29], 0 op_sel_hi:[1,0]
	v_pk_add_f32 v[30:31], v[30:31], 0 op_sel_hi:[1,0]
	v_pk_add_f32 v[24:25], v[24:25], 0 op_sel_hi:[1,0]
	v_pk_add_f32 v[26:27], v[26:27], 0 op_sel_hi:[1,0]
	v_pk_add_f32 v[20:21], v[20:21], 0 op_sel_hi:[1,0]
	v_pk_add_f32 v[22:23], v[22:23], 0 op_sel_hi:[1,0]
	v_pk_add_f32 v[12:13], v[12:13], 0 op_sel_hi:[1,0]
	v_pk_add_f32 v[14:15], v[14:15], 0 op_sel_hi:[1,0]
	v_pk_add_f32 v[16:17], v[16:17], 0 op_sel_hi:[1,0]
	v_pk_add_f32 v[18:19], v[18:19], 0 op_sel_hi:[1,0]
	v_pk_add_f32 v[8:9], v[8:9], 0 op_sel_hi:[1,0]
	v_pk_add_f32 v[10:11], v[10:11], 0 op_sel_hi:[1,0]
	v_pk_add_f32 v[4:5], v[4:5], 0 op_sel_hi:[1,0]
	v_pk_add_f32 v[6:7], v[6:7], 0 op_sel_hi:[1,0]
	v_pk_add_f32 v[0:1], v[0:1], 0 op_sel_hi:[1,0]
	v_pk_add_f32 v[2:3], v[2:3], 0 op_sel_hi:[1,0]
	s_waitcnt vmcnt(8)
	v_mov_b32_e32 v212, v124
	v_mov_b32_e32 v213, v125
	v_mov_b32_e32 v214, v126
	v_mov_b32_e32 v215, v127
	s_nop 0
	v_mov_b32_dpp v124, v120 row_shr:8 row_mask:0xf bank_mask:0xc
	v_mov_b32_dpp v125, v121 row_shr:8 row_mask:0xf bank_mask:0xc
	v_mov_b32_dpp v126, v122 row_shr:8 row_mask:0xf bank_mask:0xc
	v_mov_b32_dpp v127, v123 row_shr:8 row_mask:0xf bank_mask:0xc
	v_mov_b32_dpp v120, v212 row_shl:8 row_mask:0xf bank_mask:0x3
	v_mov_b32_dpp v121, v213 row_shl:8 row_mask:0xf bank_mask:0x3
	v_mov_b32_dpp v122, v214 row_shl:8 row_mask:0xf bank_mask:0x3
	v_mov_b32_dpp v123, v215 row_shl:8 row_mask:0xf bank_mask:0x3
	v_mov_b32_e32 v212, v116
	v_mov_b32_e32 v213, v117
	v_mov_b32_e32 v214, v118
	v_mov_b32_e32 v215, v119
	s_nop 0
	v_mov_b32_dpp v116, v108 row_shr:8 row_mask:0xf bank_mask:0xc
	v_mov_b32_dpp v117, v109 row_shr:8 row_mask:0xf bank_mask:0xc
	v_mov_b32_dpp v118, v110 row_shr:8 row_mask:0xf bank_mask:0xc
	v_mov_b32_dpp v119, v111 row_shr:8 row_mask:0xf bank_mask:0xc
	v_mov_b32_dpp v108, v212 row_shl:8 row_mask:0xf bank_mask:0x3
	v_mov_b32_dpp v109, v213 row_shl:8 row_mask:0xf bank_mask:0x3
	v_mov_b32_dpp v110, v214 row_shl:8 row_mask:0xf bank_mask:0x3
	v_mov_b32_dpp v111, v215 row_shl:8 row_mask:0xf bank_mask:0x3
	v_mov_b32_e32 v212, v112
	v_mov_b32_e32 v213, v113
	v_mov_b32_e32 v214, v114
	v_mov_b32_e32 v215, v115
	s_nop 0
	v_mov_b32_dpp v112, v104 row_shr:8 row_mask:0xf bank_mask:0xc
	v_mov_b32_dpp v113, v105 row_shr:8 row_mask:0xf bank_mask:0xc
	v_mov_b32_dpp v114, v106 row_shr:8 row_mask:0xf bank_mask:0xc
	v_mov_b32_dpp v115, v107 row_shr:8 row_mask:0xf bank_mask:0xc
	v_mov_b32_dpp v104, v212 row_shl:8 row_mask:0xf bank_mask:0x3
	v_mov_b32_dpp v105, v213 row_shl:8 row_mask:0xf bank_mask:0x3
	v_mov_b32_dpp v106, v214 row_shl:8 row_mask:0xf bank_mask:0x3
	v_mov_b32_dpp v107, v215 row_shl:8 row_mask:0xf bank_mask:0x3
	v_mov_b32_e32 v212, v100
	v_mov_b32_e32 v213, v101
	v_mov_b32_e32 v214, v102
	v_mov_b32_e32 v215, v103
	s_nop 0
	v_mov_b32_dpp v100, v96 row_shr:8 row_mask:0xf bank_mask:0xc
	v_mov_b32_dpp v101, v97 row_shr:8 row_mask:0xf bank_mask:0xc
	v_mov_b32_dpp v102, v98 row_shr:8 row_mask:0xf bank_mask:0xc
	v_mov_b32_dpp v103, v99 row_shr:8 row_mask:0xf bank_mask:0xc
	v_mov_b32_dpp v96, v212 row_shl:8 row_mask:0xf bank_mask:0x3
;     __device__ __forceinline__ void operator()(AccRef acc, const Unit& u, int wr, int wc, int fr, int fq) const {
;     ...
;                         for (int n = 0; n < 2; ++n) bs[m][bj][n] = *(const f32x4*)(base + (size_t)(row0 + ai * 128 + (2 * mh + m) * 16) * D + col0 + bj * 128 + n * 16);
; #pragma unroll
;                 for (int m = 0; m < 2; ++m)
; #pragma unroll
;                     for (int bj = 0; bj < 2; ++bj)
; #pragma unroll
;                         for (int n = 0; n < 2; ++n) *(f32x4*)(out + (size_t)(row0 + ai * 128 + (2 * mh + m) * 16) * D + col0 + bj * 128 + n * 16) = bs[m][bj][n] + sv[bj][n] * (acc[ai][bj][2 * mh + m][n] + bv[bj][n]);
;                 asm volatile("" ::: "memory"); }
	v_mov_b32_dpp v97, v213 row_shl:8 row_mask:0xf bank_mask:0x3
	v_mov_b32_dpp v98, v214 row_shl:8 row_mask:0xf bank_mask:0x3
	v_mov_b32_dpp v99, v215 row_shl:8 row_mask:0xf bank_mask:0x3
	v_pk_add_f32 v[124:125], v[124:125], v[140:141]
	v_pk_add_f32 v[126:127], v[126:127], v[142:143]
	v_pk_add_f32 v[120:121], v[120:121], v[152:153]
	v_pk_add_f32 v[122:123], v[122:123], v[154:155]
	v_pk_add_f32 v[116:117], v[116:117], v[156:157]
	v_pk_add_f32 v[118:119], v[118:119], v[158:159]
	v_pk_add_f32 v[108:109], v[108:109], v[160:161]
	v_pk_add_f32 v[110:111], v[110:111], v[162:163]
	v_pk_add_f32 v[112:113], v[112:113], v[164:165]
	v_pk_add_f32 v[114:115], v[114:115], v[166:167]
	v_pk_add_f32 v[104:105], v[104:105], v[168:169]
	v_pk_add_f32 v[106:107], v[106:107], v[170:171]
	v_pk_add_f32 v[100:101], v[100:101], v[172:173]
	v_pk_add_f32 v[102:103], v[102:103], v[174:175]
	v_pk_add_f32 v[96:97], v[96:97], v[176:177]
	v_pk_add_f32 v[98:99], v[98:99], v[178:179]
	global_store_dwordx4 v224, v[124:127], s[52:53]
	v_add_u32_e32 v144, v145, v233
	global_store_dwordx4 v144, v[120:123], s[52:53]
	global_store_dwordx4 v224, v[116:119], s[52:53] offset:512
	v_add_u32_e32 v144, v145, v233
	global_store_dwordx4 v144, v[108:111], s[52:53] offset:512
	global_store_dwordx4 v225, v[112:115], s[52:53]
	v_add_u32_e32 v144, v216, v233
	global_store_dwordx4 v144, v[104:107], s[52:53]
	global_store_dwordx4 v225, v[100:103], s[52:53] offset:512
	v_add_u32_e32 v144, v216, v233
	global_store_dwordx4 v144, v[96:99], s[52:53] offset:512
	global_load_dwordx4 v[140:143], v228, s[52:53]
	v_add_u32_e32 v144, v220, v233
	global_load_dwordx4 v[152:155], v144, s[52:53]
	global_load_dwordx4 v[156:159], v228, s[52:53] offset:512
	v_add_u32_e32 v144, v220, v233
	global_load_dwordx4 v[160:163], v144, s[52:53] offset:512
	global_load_dwordx4 v[164:167], v229, s[52:53]
	v_add_u32_e32 v144, v221, v233
	global_load_dwordx4 v[168:171], v144, s[52:53]
	global_load_dwordx4 v[172:175], v229, s[52:53] offset:512
	v_add_u32_e32 v144, v221, v233
	global_load_dwordx4 v[176:179], v144, s[52:53] offset:512
	s_barrier
	s_waitcnt vmcnt(16)
	v_mov_b32_e32 v212, v92
	v_mov_b32_e32 v213, v93
	v_mov_b32_e32 v214, v94
	v_mov_b32_e32 v215, v95
	s_nop 0
	v_mov_b32_dpp v92, v88 row_shr:8 row_mask:0xf bank_mask:0xc
	v_mov_b32_dpp v93, v89 row_shr:8 row_mask:0xf bank_mask:0xc
	v_mov_b32_dpp v94, v90 row_shr:8 row_mask:0xf bank_mask:0xc
	v_mov_b32_dpp v95, v91 row_shr:8 row_mask:0xf bank_mask:0xc
	v_mov_b32_dpp v88, v212 row_shl:8 row_mask:0xf bank_mask:0x3
	v_mov_b32_dpp v89, v213 row_shl:8 row_mask:0xf bank_mask:0x3
	v_mov_b32_dpp v90, v214 row_shl:8 row_mask:0xf bank_mask:0x3
	v_mov_b32_dpp v91, v215 row_shl:8 row_mask:0xf bank_mask:0x3
	v_mov_b32_e32 v212, v84
	v_mov_b32_e32 v213, v85
	v_mov_b32_e32 v214, v86
	v_mov_b32_e32 v215, v87
	s_nop 0
	v_mov_b32_dpp v84, v76 row_shr:8 row_mask:0xf bank_mask:0xc
	v_mov_b32_dpp v85, v77 row_shr:8 row_mask:0xf bank_mask:0xc
	v_mov_b32_dpp v86, v78 row_shr:8 row_mask:0xf bank_mask:0xc
	v_mov_b32_dpp v87, v79 row_shr:8 row_mask:0xf bank_mask:0xc
	v_mov_b32_dpp v76, v212 row_shl:8 row_mask:0xf bank_mask:0x3
	v_mov_b32_dpp v77, v213 row_shl:8 row_mask:0xf bank_mask:0x3
	v_mov_b32_dpp v78, v214 row_shl:8 row_mask:0xf bank_mask:0x3
	v_mov_b32_dpp v79, v215 row_shl:8 row_mask:0xf bank_mask:0x3
	v_mov_b32_e32 v212, v80
	v_mov_b32_e32 v213, v81
	v_mov_b32_e32 v214, v82
	v_mov_b32_e32 v215, v83
	s_nop 0
	v_mov_b32_dpp v80, v72 row_shr:8 row_mask:0xf bank_mask:0xc
	v_mov_b32_dpp v81, v73 row_shr:8 row_mask:0xf bank_mask:0xc
	v_mov_b32_dpp v82, v74 row_shr:8 row_mask:0xf bank_mask:0xc
	v_mov_b32_dpp v83, v75 row_shr:8 row_mask:0xf bank_mask:0xc
	v_mov_b32_dpp v72, v212 row_shl:8 row_mask:0xf bank_mask:0x3
	v_mov_b32_dpp v73, v213 row_shl:8 row_mask:0xf bank_mask:0x3
	v_mov_b32_dpp v74, v214 row_shl:8 row_mask:0xf bank_mask:0x3
	v_mov_b32_dpp v75, v215 row_shl:8 row_mask:0xf bank_mask:0x3
	v_mov_b32_e32 v212, v68
	v_mov_b32_e32 v213, v69
	v_mov_b32_e32 v214, v70
	v_mov_b32_e32 v215, v71
	s_nop 0
	v_mov_b32_dpp v68, v64 row_shr:8 row_mask:0xf bank_mask:0xc
	v_mov_b32_dpp v69, v65 row_shr:8 row_mask:0xf bank_mask:0xc
	v_mov_b32_dpp v70, v66 row_shr:8 row_mask:0xf bank_mask:0xc
	v_mov_b32_dpp v71, v67 row_shr:8 row_mask:0xf bank_mask:0xc
	v_mov_b32_dpp v64, v212 row_shl:8 row_mask:0xf bank_mask:0x3
	v_mov_b32_dpp v65, v213 row_shl:8 row_mask:0xf bank_mask:0x3
	v_mov_b32_dpp v66, v214 row_shl:8 row_mask:0xf bank_mask:0x3
	v_mov_b32_dpp v67, v215 row_shl:8 row_mask:0xf bank_mask:0x3
	v_pk_add_f32 v[92:93], v[92:93], v[180:181]
	v_pk_add_f32 v[94:95], v[94:95], v[182:183]
	v_pk_add_f32 v[88:89], v[88:89], v[184:185]
	v_pk_add_f32 v[90:91], v[90:91], v[186:187]
	v_pk_add_f32 v[84:85], v[84:85], v[188:189]
	v_pk_add_f32 v[86:87], v[86:87], v[190:191]
	v_pk_add_f32 v[76:77], v[76:77], v[192:193]
	v_pk_add_f32 v[78:79], v[78:79], v[194:195]
	v_pk_add_f32 v[80:81], v[80:81], v[196:197]
	v_pk_add_f32 v[82:83], v[82:83], v[198:199]
	v_pk_add_f32 v[72:73], v[72:73], v[200:201]
	v_pk_add_f32 v[74:75], v[74:75], v[202:203]
	v_pk_add_f32 v[68:69], v[68:69], v[204:205]
	v_pk_add_f32 v[70:71], v[70:71], v[206:207]
	v_pk_add_f32 v[64:65], v[64:65], v[208:209]
	v_pk_add_f32 v[66:67], v[66:67], v[210:211]
	global_store_dwordx4 v226, v[92:95], s[52:53]
	v_add_u32_e32 v144, v217, v233
	global_store_dwordx4 v144, v[88:91], s[52:53]
	global_store_dwordx4 v226, v[84:87], s[52:53] offset:512
	v_add_u32_e32 v144, v217, v233
	global_store_dwordx4 v144, v[76:79], s[52:53] offset:512
	global_store_dwordx4 v227, v[80:83], s[52:53]
	v_add_u32_e32 v144, v218, v233
	global_store_dwordx4 v144, v[72:75], s[52:53]
	global_store_dwordx4 v227, v[68:71], s[52:53] offset:512
	v_add_u32_e32 v144, v218, v233
	global_store_dwordx4 v144, v[64:67], s[52:53] offset:512
	global_load_dwordx4 v[180:183], v230, s[52:53]
	v_add_u32_e32 v144, v222, v233
	global_load_dwordx4 v[184:187], v144, s[52:53]
	global_load_dwordx4 v[188:191], v230, s[52:53] offset:512
	v_add_u32_e32 v144, v222, v233
	global_load_dwordx4 v[192:195], v144, s[52:53] offset:512
	global_load_dwordx4 v[196:199], v231, s[52:53]
	v_add_u32_e32 v144, v223, v233
	global_load_dwordx4 v[200:203], v144, s[52:53]
	global_load_dwordx4 v[204:207], v231, s[52:53] offset:512
	v_add_u32_e32 v144, v223, v233
	global_load_dwordx4 v[208:211], v144, s[52:53] offset:512
	s_barrier
;     __device__ __forceinline__ void operator()(AccRef acc, const Unit& u, int wr, int wc, int fr, int fq) const {
;     ...
;                         for (int n = 0; n < 2; ++n) bs[m][bj][n] = *(const f32x4*)(base + (size_t)(row0 + ai * 128 + (2 * mh + m) * 16) * D + col0 + bj * 128 + n * 16);
; #pragma unroll
;                 for (int m = 0; m < 2; ++m)
; #pragma unroll
;                     for (int bj = 0; bj < 2; ++bj)
; #pragma unroll
;                         for (int n = 0; n < 2; ++n) *(f32x4*)(out + (size_t)(row0 + ai * 128 + (2 * mh + m) * 16) * D + col0 + bj * 128 + n * 16) = bs[m][bj][n] + sv[bj][n] * (acc[ai][bj][2 * mh + m][n] + bv[bj][n]);
;                 asm volatile("" ::: "memory"); }
	s_waitcnt vmcnt(16)
	v_mov_b32_e32 v212, v60
	v_mov_b32_e32 v213, v61
	v_mov_b32_e32 v214, v62
	v_mov_b32_e32 v215, v63
	s_nop 0
	v_mov_b32_dpp v60, v56 row_shr:8 row_mask:0xf bank_mask:0xc
	v_mov_b32_dpp v61, v57 row_shr:8 row_mask:0xf bank_mask:0xc
	v_mov_b32_dpp v62, v58 row_shr:8 row_mask:0xf bank_mask:0xc
	v_mov_b32_dpp v63, v59 row_shr:8 row_mask:0xf bank_mask:0xc
	v_mov_b32_dpp v56, v212 row_shl:8 row_mask:0xf bank_mask:0x3
	v_mov_b32_dpp v57, v213 row_shl:8 row_mask:0xf bank_mask:0x3
	v_mov_b32_dpp v58, v214 row_shl:8 row_mask:0xf bank_mask:0x3
	v_mov_b32_dpp v59, v215 row_shl:8 row_mask:0xf bank_mask:0x3
	v_mov_b32_e32 v212, v52
	v_mov_b32_e32 v213, v53
	v_mov_b32_e32 v214, v54
	v_mov_b32_e32 v215, v55
	s_nop 0
	v_mov_b32_dpp v52, v44 row_shr:8 row_mask:0xf bank_mask:0xc
	v_mov_b32_dpp v53, v45 row_shr:8 row_mask:0xf bank_mask:0xc
	v_mov_b32_dpp v54, v46 row_shr:8 row_mask:0xf bank_mask:0xc
	v_mov_b32_dpp v55, v47 row_shr:8 row_mask:0xf bank_mask:0xc
	v_mov_b32_dpp v44, v212 row_shl:8 row_mask:0xf bank_mask:0x3
	v_mov_b32_dpp v45, v213 row_shl:8 row_mask:0xf bank_mask:0x3
	v_mov_b32_dpp v46, v214 row_shl:8 row_mask:0xf bank_mask:0x3
	v_mov_b32_dpp v47, v215 row_shl:8 row_mask:0xf bank_mask:0x3
	v_mov_b32_e32 v212, v48
	v_mov_b32_e32 v213, v49
	v_mov_b32_e32 v214, v50
	v_mov_b32_e32 v215, v51
	s_nop 0
	v_mov_b32_dpp v48, v40 row_shr:8 row_mask:0xf bank_mask:0xc
	v_mov_b32_dpp v49, v41 row_shr:8 row_mask:0xf bank_mask:0xc
	v_mov_b32_dpp v50, v42 row_shr:8 row_mask:0xf bank_mask:0xc
	v_mov_b32_dpp v51, v43 row_shr:8 row_mask:0xf bank_mask:0xc
	v_mov_b32_dpp v40, v212 row_shl:8 row_mask:0xf bank_mask:0x3
	v_mov_b32_dpp v41, v213 row_shl:8 row_mask:0xf bank_mask:0x3
	v_mov_b32_dpp v42, v214 row_shl:8 row_mask:0xf bank_mask:0x3
	v_mov_b32_dpp v43, v215 row_shl:8 row_mask:0xf bank_mask:0x3
	v_mov_b32_e32 v212, v36
	v_mov_b32_e32 v213, v37
	v_mov_b32_e32 v214, v38
	v_mov_b32_e32 v215, v39
	s_nop 0
	v_mov_b32_dpp v36, v32 row_shr:8 row_mask:0xf bank_mask:0xc
	v_mov_b32_dpp v37, v33 row_shr:8 row_mask:0xf bank_mask:0xc
	v_mov_b32_dpp v38, v34 row_shr:8 row_mask:0xf bank_mask:0xc
	v_mov_b32_dpp v39, v35 row_shr:8 row_mask:0xf bank_mask:0xc
	v_mov_b32_dpp v32, v212 row_shl:8 row_mask:0xf bank_mask:0x3
	v_mov_b32_dpp v33, v213 row_shl:8 row_mask:0xf bank_mask:0x3
	v_mov_b32_dpp v34, v214 row_shl:8 row_mask:0xf bank_mask:0x3
	v_mov_b32_dpp v35, v215 row_shl:8 row_mask:0xf bank_mask:0x3
	v_pk_add_f32 v[60:61], v[60:61], v[140:141]
	v_pk_add_f32 v[62:63], v[62:63], v[142:143]
	v_pk_add_f32 v[56:57], v[56:57], v[152:153]
	v_pk_add_f32 v[58:59], v[58:59], v[154:155]
	v_pk_add_f32 v[52:53], v[52:53], v[156:157]
	v_pk_add_f32 v[54:55], v[54:55], v[158:159]
	v_pk_add_f32 v[44:45], v[44:45], v[160:161]
	v_pk_add_f32 v[46:47], v[46:47], v[162:163]
	v_pk_add_f32 v[48:49], v[48:49], v[164:165]
	v_pk_add_f32 v[50:51], v[50:51], v[166:167]
	v_pk_add_f32 v[40:41], v[40:41], v[168:169]
	v_pk_add_f32 v[42:43], v[42:43], v[170:171]
	v_pk_add_f32 v[36:37], v[36:37], v[172:173]
	v_pk_add_f32 v[38:39], v[38:39], v[174:175]
	v_pk_add_f32 v[32:33], v[32:33], v[176:177]
	v_pk_add_f32 v[34:35], v[34:35], v[178:179]
	global_store_dwordx4 v228, v[60:63], s[52:53]
	v_add_u32_e32 v144, v220, v233
	global_store_dwordx4 v144, v[56:59], s[52:53]
	global_store_dwordx4 v228, v[52:55], s[52:53] offset:512
	v_add_u32_e32 v144, v220, v233
	global_store_dwordx4 v144, v[44:47], s[52:53] offset:512
	global_store_dwordx4 v229, v[48:51], s[52:53]
	v_add_u32_e32 v144, v221, v233
	global_store_dwordx4 v144, v[40:43], s[52:53]
	global_store_dwordx4 v229, v[36:39], s[52:53] offset:512
	v_add_u32_e32 v144, v221, v233
	global_store_dwordx4 v144, v[32:35], s[52:53] offset:512
	s_barrier
; #define PG8_WAIT_V(n) asm volatile("s_waitcnt vmcnt(" #n ")" ::: "memory")
; #define PG8_BAR __builtin_amdgcn_s_barrier()
; template <class Epi>
; __device__ __forceinline__ void gemm_phase(LAS unsigned char* lds, const Gemm g, const StaticOrder& S, const Epi& E) {
;     ...
;     PG8_WAIT_V(0);
;     if (wr == 0) PG8_BAR;
;     PG8_BAR;
;     __device__ __forceinline__ void operator()(AccRef acc, const Unit& u, int wr, int wc, int fr, int fq) const {
;     ...
;                 for (int m = 0; m < 2; ++m)
; #pragma unroll
;                     for (int bj = 0; bj < 2; ++bj)
; #pragma unroll
;                         for (int n = 0; n < 2; ++n) *(f32x4*)(out + (size_t)(row0 + ai * 128 + (2 * mh + m) * 16) * D + col0 + bj * 128 + n * 16) = bs[m][bj][n] + sv[bj][n] * (acc[ai][bj][2 * mh + m][n] + bv[bj][n]);
;                 asm volatile("" ::: "memory"); }
	s_waitcnt vmcnt(8)
	v_mov_b32_e32 v212, v28
	v_mov_b32_e32 v213, v29
	v_mov_b32_e32 v214, v30
	v_mov_b32_e32 v215, v31
	s_nop 0
	v_mov_b32_dpp v28, v24 row_shr:8 row_mask:0xf bank_mask:0xc
	v_mov_b32_dpp v29, v25 row_shr:8 row_mask:0xf bank_mask:0xc
	v_mov_b32_dpp v30, v26 row_shr:8 row_mask:0xf bank_mask:0xc
	v_mov_b32_dpp v31, v27 row_shr:8 row_mask:0xf bank_mask:0xc
	v_mov_b32_dpp v24, v212 row_shl:8 row_mask:0xf bank_mask:0x3
	v_mov_b32_dpp v25, v213 row_shl:8 row_mask:0xf bank_mask:0x3
	v_mov_b32_dpp v26, v214 row_shl:8 row_mask:0xf bank_mask:0x3
	v_mov_b32_dpp v27, v215 row_shl:8 row_mask:0xf bank_mask:0x3
	v_mov_b32_e32 v212, v20
	v_mov_b32_e32 v213, v21
	v_mov_b32_e32 v214, v22
	v_mov_b32_e32 v215, v23
	s_nop 0
	v_mov_b32_dpp v20, v12 row_shr:8 row_mask:0xf bank_mask:0xc
	v_mov_b32_dpp v21, v13 row_shr:8 row_mask:0xf bank_mask:0xc
	v_mov_b32_dpp v22, v14 row_shr:8 row_mask:0xf bank_mask:0xc
	v_mov_b32_dpp v23, v15 row_shr:8 row_mask:0xf bank_mask:0xc
	v_mov_b32_dpp v12, v212 row_shl:8 row_mask:0xf bank_mask:0x3
	v_mov_b32_dpp v13, v213 row_shl:8 row_mask:0xf bank_mask:0x3
	v_mov_b32_dpp v14, v214 row_shl:8 row_mask:0xf bank_mask:0x3
	v_mov_b32_dpp v15, v215 row_shl:8 row_mask:0xf bank_mask:0x3
	v_mov_b32_e32 v212, v16
	v_mov_b32_e32 v213, v17
	v_mov_b32_e32 v214, v18
	v_mov_b32_e32 v215, v19
	s_nop 0
	v_mov_b32_dpp v16, v8 row_shr:8 row_mask:0xf bank_mask:0xc
	v_mov_b32_dpp v17, v9 row_shr:8 row_mask:0xf bank_mask:0xc
	v_mov_b32_dpp v18, v10 row_shr:8 row_mask:0xf bank_mask:0xc
	v_mov_b32_dpp v19, v11 row_shr:8 row_mask:0xf bank_mask:0xc
	v_mov_b32_dpp v8, v212 row_shl:8 row_mask:0xf bank_mask:0x3
	v_mov_b32_dpp v9, v213 row_shl:8 row_mask:0xf bank_mask:0x3
	v_mov_b32_dpp v10, v214 row_shl:8 row_mask:0xf bank_mask:0x3
	v_mov_b32_dpp v11, v215 row_shl:8 row_mask:0xf bank_mask:0x3
	v_mov_b32_e32 v212, v4
	v_mov_b32_e32 v213, v5
	v_mov_b32_e32 v214, v6
	v_mov_b32_e32 v215, v7
	s_nop 0
	v_mov_b32_dpp v4, v0 row_shr:8 row_mask:0xf bank_mask:0xc
	v_mov_b32_dpp v5, v1 row_shr:8 row_mask:0xf bank_mask:0xc
	v_mov_b32_dpp v6, v2 row_shr:8 row_mask:0xf bank_mask:0xc
	v_mov_b32_dpp v7, v3 row_shr:8 row_mask:0xf bank_mask:0xc
	v_mov_b32_dpp v0, v212 row_shl:8 row_mask:0xf bank_mask:0x3
	v_mov_b32_dpp v1, v213 row_shl:8 row_mask:0xf bank_mask:0x3
	v_mov_b32_dpp v2, v214 row_shl:8 row_mask:0xf bank_mask:0x3
	v_mov_b32_dpp v3, v215 row_shl:8 row_mask:0xf bank_mask:0x3
	v_pk_add_f32 v[28:29], v[28:29], v[180:181]
	v_pk_add_f32 v[30:31], v[30:31], v[182:183]
	v_pk_add_f32 v[24:25], v[24:25], v[184:185]
	v_pk_add_f32 v[26:27], v[26:27], v[186:187]
	v_pk_add_f32 v[20:21], v[20:21], v[188:189]
	v_pk_add_f32 v[22:23], v[22:23], v[190:191]
	v_pk_add_f32 v[12:13], v[12:13], v[192:193]
	v_pk_add_f32 v[14:15], v[14:15], v[194:195]
	v_pk_add_f32 v[16:17], v[16:17], v[196:197]
	v_pk_add_f32 v[18:19], v[18:19], v[198:199]
	v_pk_add_f32 v[8:9], v[8:9], v[200:201]
	v_pk_add_f32 v[10:11], v[10:11], v[202:203]
	v_pk_add_f32 v[4:5], v[4:5], v[204:205]
	v_pk_add_f32 v[6:7], v[6:7], v[206:207]
	v_pk_add_f32 v[0:1], v[0:1], v[208:209]
	v_pk_add_f32 v[2:3], v[2:3], v[210:211]
	global_store_dwordx4 v230, v[28:31], s[52:53]
	v_add_u32_e32 v144, v222, v233
	global_store_dwordx4 v144, v[24:27], s[52:53]
	global_store_dwordx4 v230, v[20:23], s[52:53] offset:512
	v_add_u32_e32 v144, v222, v233
	global_store_dwordx4 v144, v[12:15], s[52:53] offset:512
	global_store_dwordx4 v231, v[16:19], s[52:53]
	v_add_u32_e32 v144, v223, v233
	global_store_dwordx4 v144, v[8:11], s[52:53]
	global_store_dwordx4 v231, v[4:7], s[52:53] offset:512
	v_add_u32_e32 v144, v223, v233
	global_store_dwordx4 v144, v[0:3], s[52:53] offset:512
	s_cbranch_vccz .LBB0_849
	s_waitcnt vmcnt(0)
	s_cmpk_gt_u32 s4, 0xff
	s_cbranch_scc1 .LBB0_864
	s_barrier

; #define PG8_STAGE(bufoff, gbase, voff) do { _Pragma("unroll") for (int _i = 0; _i < 2; ++_i) \
;         __builtin_amdgcn_global_load_lds((const unsigned*)((const char*)(gbase) + (voff)[_i]), (LAS unsigned*)(lds + (bufoff) + ldsw + _i * 8192), 16, 0, 0); } while (0)
; #define PG8_LDA(dst, b, h) do { _Pragma("unroll") for (int m = 0; m < 4; ++m) _Pragma("unroll") for (int k = 0; k < 2; ++k) dst[m][k] = *(const LAS bf16x8*)(lds + PG8_SA(b, h) + aoff + m * 2048 + k * 1024); } while (0)
; #define PG8_LDB(dst, b, h) do { _Pragma("unroll") for (int n = 0; n < 2; ++n) _Pragma("unroll") for (int k = 0; k < 2; ++k) dst[n][k] = *(const LAS bf16x8*)(lds + PG8_SB(b, h) + boff + n * 2048 + k * 1024); } while (0)
; #define PG8_MMA(ai, bj, At, Bt) do { __builtin_amdgcn_s_setprio(1); _Pragma("unroll") for (int m = 0; m < 4; ++m) _Pragma("unroll") for (int n = 0; n < 2; ++n) _Pragma("unroll") for (int k = 0; k < 2; ++k) \
;         acc[ai][bj][m][n] = __builtin_amdgcn_mfma_f32_16x16x32_bf16(Bt[n][k], At[m][k], acc[ai][bj][m][n], 0, 0, 0); __builtin_amdgcn_s_setprio(0); } while (0)
; #define PG8_WAIT_V(n) asm volatile("s_waitcnt vmcnt(" #n ")" ::: "memory")
; #define PG8_WAIT_L(n) asm volatile("s_waitcnt lgkmcnt(" #n ")" ::: "memory")
; #define PG8_BAR __builtin_amdgcn_s_barrier()
; #define PG8_SCHED __builtin_amdgcn_sched_barrier(0)
; template <class Epi>
; __device__ __forceinline__ void gemm_phase(LAS unsigned char* lds, const Gemm g, const StaticOrder& S, const Epi& E) {
;     ...
;             PG8_LDB(B0, 0, 0); PG8_SCHED; PG8_LDA(At, 0, 0); PG8_STAGE(PG8_SA(1, 1), a1 + hstepA, voffA);
;             PG8_WAIT_L(8); PG8_BAR; PG8_WAIT_L(0); PG8_MMA(0, 0, At, B0); PG8_BAR; PG8_SCHED;
;             PG8_LDB(B1, 0, 1); PG8_STAGE(PG8_SB(0, 0), b2, voffB);
;             PG8_BAR; PG8_WAIT_L(0); PG8_MMA(0, 1, At, B1); PG8_BAR;
;             PG8_LDA(At, 0, 1); PG8_STAGE(PG8_SA(0, 0), a2, voffA);
;             PG8_BAR; PG8_WAIT_L(0); PG8_MMA(1, 0, At, B0); PG8_BAR; PG8_SCHED;
;             PG8_STAGE(PG8_SB(0, 1), b2 + hstepB, voffB);
;             PG8_WAIT_V(6); PG8_BAR; PG8_MMA(1, 1, At, B1); PG8_BAR;
.LBB0_1239:
	ds_read_b128 v[140:143], v149
	ds_read_b128 v[152:155], v149 offset:1024
	ds_read_b128 v[156:159], v149 offset:2048
	ds_read_b128 v[160:163], v149 offset:3072
	s_add_u32 s40, s38, 0xfffc0080
	s_addc_u32 s41, s39, -1
	s_cmp_eq_u32 s76, 12
	s_cselect_b32 s43, s29, s41
	s_cselect_b32 s42, s72, s40
	s_cselect_b32 s41, s27, s75
	s_cselect_b32 s40, s73, s74
	v_lshl_add_u64 v[144:145], s[38:39], 0, v[132:133]
	s_add_i32 m0, s8, 0xc000
	ds_read_b128 v[164:167], v150
	ds_read_b128 v[168:171], v150 offset:1024
	ds_read_b128 v[172:175], v150 offset:2048
	ds_read_b128 v[176:179], v150 offset:3072
	ds_read_b128 v[180:183], v150 offset:4096
	ds_read_b128 v[184:187], v150 offset:5120
	ds_read_b128 v[188:191], v150 offset:6144
	ds_read_b128 v[192:195], v150 offset:7168
	global_load_lds_dwordx4 v[144:145], off
	v_lshl_add_u64 v[144:145], s[38:39], 0, v[134:135]
	s_add_i32 m0, s8, 0xe000
	s_nop 0
	global_load_lds_dwordx4 v[144:145], off
	ds_read_b128 v[196:199], v151
	ds_read_b128 v[200:203], v151 offset:1024
	ds_read_b128 v[204:207], v151 offset:2048
	ds_read_b128 v[208:211], v151 offset:3072
	s_waitcnt lgkmcnt(0)
	s_barrier
	s_setprio 1
	v_mfma_f32_16x16x32_bf16 v[124:127], v[140:143], v[164:167], v[124:127]
	v_mfma_f32_16x16x32_bf16 v[120:123], v[156:159], v[164:167], v[120:123]
	v_mfma_f32_16x16x32_bf16 v[112:115], v[140:143], v[172:175], v[112:115]
	v_mfma_f32_16x16x32_bf16 v[104:107], v[156:159], v[172:175], v[104:107]
	v_mfma_f32_16x16x32_bf16 v[92:95], v[140:143], v[180:183], v[92:95]
	v_mfma_f32_16x16x32_bf16 v[88:91], v[156:159], v[180:183], v[88:91]
	v_mfma_f32_16x16x32_bf16 v[80:83], v[140:143], v[188:191], v[80:83]
	v_mfma_f32_16x16x32_bf16 v[72:75], v[156:159], v[188:191], v[72:75]
	v_mfma_f32_16x16x32_bf16 v[124:127], v[152:155], v[168:171], v[124:127]
	v_mfma_f32_16x16x32_bf16 v[120:123], v[160:163], v[168:171], v[120:123]
	v_mfma_f32_16x16x32_bf16 v[112:115], v[152:155], v[176:179], v[112:115]
	v_mfma_f32_16x16x32_bf16 v[104:107], v[160:163], v[176:179], v[104:107]
	v_mfma_f32_16x16x32_bf16 v[92:95], v[152:155], v[184:187], v[92:95]
	v_mfma_f32_16x16x32_bf16 v[88:91], v[160:163], v[184:187], v[88:91]
	v_mfma_f32_16x16x32_bf16 v[80:83], v[152:155], v[192:195], v[80:83]
	v_mfma_f32_16x16x32_bf16 v[72:75], v[160:163], v[192:195], v[72:75]
	v_mfma_f32_16x16x32_bf16 v[116:119], v[196:199], v[164:167], v[116:119]
	v_mfma_f32_16x16x32_bf16 v[108:111], v[204:207], v[164:167], v[108:111]
	v_mfma_f32_16x16x32_bf16 v[100:103], v[196:199], v[172:175], v[100:103]
	v_mfma_f32_16x16x32_bf16 v[96:99], v[204:207], v[172:175], v[96:99]
	v_mfma_f32_16x16x32_bf16 v[84:87], v[196:199], v[180:183], v[84:87]
	v_mfma_f32_16x16x32_bf16 v[76:79], v[204:207], v[180:183], v[76:79]
	v_mfma_f32_16x16x32_bf16 v[68:71], v[196:199], v[188:191], v[68:71]
	v_mfma_f32_16x16x32_bf16 v[64:67], v[204:207], v[188:191], v[64:67]
	v_mfma_f32_16x16x32_bf16 v[116:119], v[200:203], v[168:171], v[116:119]
	v_mfma_f32_16x16x32_bf16 v[108:111], v[208:211], v[168:171], v[108:111]
	v_mfma_f32_16x16x32_bf16 v[100:103], v[200:203], v[176:179], v[100:103]
	v_mfma_f32_16x16x32_bf16 v[96:99], v[208:211], v[176:179], v[96:99]
	v_mfma_f32_16x16x32_bf16 v[84:87], v[200:203], v[184:187], v[84:87]
	v_mfma_f32_16x16x32_bf16 v[76:79], v[208:211], v[184:187], v[76:79]
	v_mfma_f32_16x16x32_bf16 v[68:71], v[200:203], v[192:195], v[68:71]
	v_mfma_f32_16x16x32_bf16 v[64:67], v[208:211], v[192:195], v[64:67]
	s_setprio 0
	s_barrier
	s_nop 1
	ds_read_b128 v[164:167], v150 offset:16384
	ds_read_b128 v[168:171], v150 offset:17408
	ds_read_b128 v[172:175], v150 offset:18432
	ds_read_b128 v[176:179], v150 offset:19456
	ds_read_b128 v[180:183], v150 offset:20480
	ds_read_b128 v[184:187], v150 offset:21504
	ds_read_b128 v[188:191], v150 offset:22528
	ds_read_b128 v[192:195], v150 offset:23552
	s_add_i32 s77, s48, s7
	v_lshl_add_u64 v[144:145], s[40:41], 0, v[128:129]
	s_mov_b32 m0, s77
	s_nop 0
	global_load_lds_dwordx4 v[144:145], off
	v_lshl_add_u64 v[212:213], s[40:41], 0, v[130:131]
	s_add_i32 m0, s77, 0x2000
	s_nop 0
	global_load_lds_dwordx4 v[212:213], off
	s_mov_b32 m0, s8
	v_lshl_add_u64 v[214:215], s[42:43], 0, v[128:129]
	global_load_lds_dwordx4 v[214:215], off
	v_lshl_add_u64 v[216:217], s[42:43], 0, v[130:131]
	s_mov_b32 m0, s9
	s_nop 0
	global_load_lds_dwordx4 v[216:217], off
	s_add_u32 s78, s40, 0x40000
	s_addc_u32 s79, s41, 0
	s_add_i32 s77, s49, s7
	v_lshl_add_u64 v[254:255], s[78:79], 0, v[128:129]
	s_mov_b32 m0, s77
	s_nop 0
	global_load_lds_dwordx4 v[254:255], off
	v_lshl_add_u64 v[254:255], s[78:79], 0, v[130:131]
	s_add_i32 m0, s77, 0x2000
	s_nop 0
	global_load_lds_dwordx4 v[254:255], off
	s_waitcnt vmcnt(6)
	s_waitcnt lgkmcnt(0)
	s_barrier
; #define PG8_STAGE(bufoff, gbase, voff) do { _Pragma("unroll") for (int _i = 0; _i < 2; ++_i) \
;         __builtin_amdgcn_global_load_lds((const unsigned*)((const char*)(gbase) + (voff)[_i]), (LAS unsigned*)(lds + (bufoff) + ldsw + _i * 8192), 16, 0, 0); } while (0)
; #define PG8_LDA(dst, b, h) do { _Pragma("unroll") for (int m = 0; m < 4; ++m) _Pragma("unroll") for (int k = 0; k < 2; ++k) dst[m][k] = *(const LAS bf16x8*)(lds + PG8_SA(b, h) + aoff + m * 2048 + k * 1024); } while (0)
; #define PG8_LDB(dst, b, h) do { _Pragma("unroll") for (int n = 0; n < 2; ++n) _Pragma("unroll") for (int k = 0; k < 2; ++k) dst[n][k] = *(const LAS bf16x8*)(lds + PG8_SB(b, h) + boff + n * 2048 + k * 1024); } while (0)
; #define PG8_MMA(ai, bj, At, Bt) do { __builtin_amdgcn_s_setprio(1); _Pragma("unroll") for (int m = 0; m < 4; ++m) _Pragma("unroll") for (int n = 0; n < 2; ++n) _Pragma("unroll") for (int k = 0; k < 2; ++k) \
;         acc[ai][bj][m][n] = __builtin_amdgcn_mfma_f32_16x16x32_bf16(Bt[n][k], At[m][k], acc[ai][bj][m][n], 0, 0, 0); __builtin_amdgcn_s_setprio(0); } while (0)
; #define PG8_WAIT_V(n) asm volatile("s_waitcnt vmcnt(" #n ")" ::: "memory")
; #define PG8_WAIT_L(n) asm volatile("s_waitcnt lgkmcnt(" #n ")" ::: "memory")
; #define PG8_BAR __builtin_amdgcn_s_barrier()
; #define PG8_SCHED __builtin_amdgcn_sched_barrier(0)
; template <class Epi>
; __device__ __forceinline__ void gemm_phase(LAS unsigned char* lds, const Gemm g, const StaticOrder& S, const Epi& E) {
;     ...
;             PG8_BAR; PG8_WAIT_L(0); PG8_MMA(1, 0, At, B0); PG8_BAR; PG8_SCHED;
;             PG8_STAGE(PG8_SB(0, 1), b2 + hstepB, voffB);
;             PG8_WAIT_V(6); PG8_BAR; PG8_MMA(1, 1, At, B1); PG8_BAR;
;             PG8_LDB(B0, 1, 0); PG8_SCHED; PG8_LDA(At, 1, 0); PG8_STAGE(PG8_SA(0, 1), a2 + hstepA, voffA);
;             PG8_WAIT_L(8); PG8_BAR; PG8_WAIT_L(0); PG8_MMA(0, 0, At, B0); PG8_BAR; PG8_SCHED;
;             PG8_LDB(B1, 1, 1); PG8_STAGE(PG8_SB(1, 0), b3, voffB);
;             PG8_BAR; PG8_WAIT_L(0); PG8_MMA(0, 1, At, B1); PG8_BAR;
	s_setprio 1
	v_mfma_f32_16x16x32_bf16 v[60:63], v[140:143], v[164:167], v[60:63]
	v_mfma_f32_16x16x32_bf16 v[56:59], v[156:159], v[164:167], v[56:59]
	v_mfma_f32_16x16x32_bf16 v[48:51], v[140:143], v[172:175], v[48:51]
	v_mfma_f32_16x16x32_bf16 v[40:43], v[156:159], v[172:175], v[40:43]
	v_mfma_f32_16x16x32_bf16 v[28:31], v[140:143], v[180:183], v[28:31]
	v_mfma_f32_16x16x32_bf16 v[24:27], v[156:159], v[180:183], v[24:27]
	v_mfma_f32_16x16x32_bf16 v[16:19], v[140:143], v[188:191], v[16:19]
	v_mfma_f32_16x16x32_bf16 v[8:11], v[156:159], v[188:191], v[8:11]
	v_mfma_f32_16x16x32_bf16 v[60:63], v[152:155], v[168:171], v[60:63]
	v_mfma_f32_16x16x32_bf16 v[56:59], v[160:163], v[168:171], v[56:59]
	v_mfma_f32_16x16x32_bf16 v[48:51], v[152:155], v[176:179], v[48:51]
	v_mfma_f32_16x16x32_bf16 v[40:43], v[160:163], v[176:179], v[40:43]
	v_mfma_f32_16x16x32_bf16 v[28:31], v[152:155], v[184:187], v[28:31]
	v_mfma_f32_16x16x32_bf16 v[24:27], v[160:163], v[184:187], v[24:27]
	v_mfma_f32_16x16x32_bf16 v[16:19], v[152:155], v[192:195], v[16:19]
	v_mfma_f32_16x16x32_bf16 v[8:11], v[160:163], v[192:195], v[8:11]
	v_mfma_f32_16x16x32_bf16 v[52:55], v[196:199], v[164:167], v[52:55]
	v_mfma_f32_16x16x32_bf16 v[44:47], v[204:207], v[164:167], v[44:47]
	v_mfma_f32_16x16x32_bf16 v[36:39], v[196:199], v[172:175], v[36:39]
	v_mfma_f32_16x16x32_bf16 v[32:35], v[204:207], v[172:175], v[32:35]
	v_mfma_f32_16x16x32_bf16 v[20:23], v[196:199], v[180:183], v[20:23]
	v_mfma_f32_16x16x32_bf16 v[12:15], v[204:207], v[180:183], v[12:15]
	v_mfma_f32_16x16x32_bf16 v[4:7], v[196:199], v[188:191], v[4:7]
	v_mfma_f32_16x16x32_bf16 v[0:3], v[204:207], v[188:191], v[0:3]
	v_mfma_f32_16x16x32_bf16 v[52:55], v[200:203], v[168:171], v[52:55]
	v_mfma_f32_16x16x32_bf16 v[44:47], v[208:211], v[168:171], v[44:47]
	v_mfma_f32_16x16x32_bf16 v[36:39], v[200:203], v[176:179], v[36:39]
	v_mfma_f32_16x16x32_bf16 v[32:35], v[208:211], v[176:179], v[32:35]
	v_mfma_f32_16x16x32_bf16 v[20:23], v[200:203], v[184:187], v[20:23]
	v_mfma_f32_16x16x32_bf16 v[12:15], v[208:211], v[184:187], v[12:15]
	v_mfma_f32_16x16x32_bf16 v[4:7], v[200:203], v[192:195], v[4:7]
	v_mfma_f32_16x16x32_bf16 v[0:3], v[208:211], v[192:195], v[0:3]
	s_setprio 0
	s_add_i32 s77, 0, 0x18000
	v_add_u32_e32 v160, s77, v147
	s_barrier
	ds_read_b128 v[140:143], v160
	ds_read_b128 v[152:155], v160 offset:1024
	ds_read_b128 v[156:159], v160 offset:2048
	ds_read_b128 v[160:163], v160 offset:3072
	s_add_u32 s42, s42, 0x40000
	s_addc_u32 s43, s43, 0
	s_mov_b32 m0, s37
	v_lshl_add_u64 v[196:197], s[42:43], 0, v[128:129]
	ds_read_b128 v[164:167], v150 offset:32768
	ds_read_b128 v[168:171], v150 offset:33792
	ds_read_b128 v[172:175], v150 offset:34816
	ds_read_b128 v[176:179], v150 offset:35840
	ds_read_b128 v[180:183], v150 offset:36864
	ds_read_b128 v[184:187], v150 offset:37888
	ds_read_b128 v[188:191], v150 offset:38912
	ds_read_b128 v[192:195], v150 offset:39936
	global_load_lds_dwordx4 v[196:197], off
	v_lshl_add_u64 v[196:197], s[42:43], 0, v[130:131]
	s_mov_b32 m0, s44
	s_nop 0
	global_load_lds_dwordx4 v[196:197], off
	s_add_i32 s42, 0, 0x1c000
	v_add_u32_e32 v208, s42, v147
	ds_read_b128 v[196:199], v208
	ds_read_b128 v[200:203], v208 offset:1024
	ds_read_b128 v[204:207], v208 offset:2048
	ds_read_b128 v[208:211], v208 offset:3072
	s_waitcnt lgkmcnt(0)
	s_barrier
	s_setprio 1
	v_mfma_f32_16x16x32_bf16 v[124:127], v[140:143], v[164:167], v[124:127]
	v_mfma_f32_16x16x32_bf16 v[120:123], v[156:159], v[164:167], v[120:123]
	v_mfma_f32_16x16x32_bf16 v[112:115], v[140:143], v[172:175], v[112:115]
	v_mfma_f32_16x16x32_bf16 v[104:107], v[156:159], v[172:175], v[104:107]
	v_mfma_f32_16x16x32_bf16 v[92:95], v[140:143], v[180:183], v[92:95]
	v_mfma_f32_16x16x32_bf16 v[88:91], v[156:159], v[180:183], v[88:91]
	v_mfma_f32_16x16x32_bf16 v[80:83], v[140:143], v[188:191], v[80:83]
	v_mfma_f32_16x16x32_bf16 v[72:75], v[156:159], v[188:191], v[72:75]
	v_mfma_f32_16x16x32_bf16 v[124:127], v[152:155], v[168:171], v[124:127]
	v_mfma_f32_16x16x32_bf16 v[120:123], v[160:163], v[168:171], v[120:123]
	v_mfma_f32_16x16x32_bf16 v[112:115], v[152:155], v[176:179], v[112:115]
	v_mfma_f32_16x16x32_bf16 v[104:107], v[160:163], v[176:179], v[104:107]
	v_mfma_f32_16x16x32_bf16 v[92:95], v[152:155], v[184:187], v[92:95]
	v_mfma_f32_16x16x32_bf16 v[88:91], v[160:163], v[184:187], v[88:91]
	v_mfma_f32_16x16x32_bf16 v[80:83], v[152:155], v[192:195], v[80:83]
	v_mfma_f32_16x16x32_bf16 v[72:75], v[160:163], v[192:195], v[72:75]
	v_mfma_f32_16x16x32_bf16 v[116:119], v[196:199], v[164:167], v[116:119]
	v_mfma_f32_16x16x32_bf16 v[108:111], v[204:207], v[164:167], v[108:111]
	v_mfma_f32_16x16x32_bf16 v[100:103], v[196:199], v[172:175], v[100:103]
	v_mfma_f32_16x16x32_bf16 v[96:99], v[204:207], v[172:175], v[96:99]
	v_mfma_f32_16x16x32_bf16 v[84:87], v[196:199], v[180:183], v[84:87]
	v_mfma_f32_16x16x32_bf16 v[76:79], v[204:207], v[180:183], v[76:79]
	v_mfma_f32_16x16x32_bf16 v[68:71], v[196:199], v[188:191], v[68:71]
	v_mfma_f32_16x16x32_bf16 v[64:67], v[204:207], v[188:191], v[64:67]
	v_mfma_f32_16x16x32_bf16 v[116:119], v[200:203], v[168:171], v[116:119]
	v_mfma_f32_16x16x32_bf16 v[108:111], v[208:211], v[168:171], v[108:111]
	v_mfma_f32_16x16x32_bf16 v[100:103], v[200:203], v[176:179], v[100:103]
	v_mfma_f32_16x16x32_bf16 v[96:99], v[208:211], v[176:179], v[96:99]
	v_mfma_f32_16x16x32_bf16 v[84:87], v[200:203], v[184:187], v[84:87]
	v_mfma_f32_16x16x32_bf16 v[76:79], v[208:211], v[184:187], v[76:79]
	v_mfma_f32_16x16x32_bf16 v[68:71], v[200:203], v[192:195], v[68:71]
	v_mfma_f32_16x16x32_bf16 v[64:67], v[208:211], v[192:195], v[64:67]
	s_setprio 0
	s_barrier
; #define PG8_STAGE(bufoff, gbase, voff) do { _Pragma("unroll") for (int _i = 0; _i < 2; ++_i) \
;         __builtin_amdgcn_global_load_lds((const unsigned*)((const char*)(gbase) + (voff)[_i]), (LAS unsigned*)(lds + (bufoff) + ldsw + _i * 8192), 16, 0, 0); } while (0)
; #define PG8_LDA(dst, b, h) do { _Pragma("unroll") for (int m = 0; m < 4; ++m) _Pragma("unroll") for (int k = 0; k < 2; ++k) dst[m][k] = *(const LAS bf16x8*)(lds + PG8_SA(b, h) + aoff + m * 2048 + k * 1024); } while (0)
; #define PG8_WAIT_V(n) asm volatile("s_waitcnt vmcnt(" #n ")" ::: "memory")
; #define PG8_WAIT_L(n) asm volatile("s_waitcnt lgkmcnt(" #n ")" ::: "memory")
; #define PG8_BAR __builtin_amdgcn_s_barrier()
; #define PG8_SCHED __builtin_amdgcn_sched_barrier(0)
; template <class Epi>
; __device__ __forceinline__ void gemm_phase(LAS unsigned char* lds, const Gemm g, const StaticOrder& S, const Epi& E) {
;     ...
;             PG8_BAR; PG8_WAIT_L(0); PG8_MMA(0, 1, At, B1); PG8_BAR;
;             PG8_LDA(At, 1, 1); PG8_STAGE(PG8_SA(1, 0), a3, voffA);
;             PG8_BAR; PG8_WAIT_L(0); PG8_MMA(1, 0, At, B0); PG8_BAR; PG8_SCHED;
;             PG8_STAGE(PG8_SB(1, 1), b3 + hstepB, voffB);
;             PG8_WAIT_V(6); PG8_BAR; PG8_MMA(1, 1, At, B1); PG8_BAR;
;         }
;     __device__ __forceinline__ void operator()(AccRef acc, const Unit& u, int wr, int wc, int fr, int fq) const {
;         const int row0 = u.pm * 256 + wr * 64 + fr, col0 = u.pn * 256 + wc * 32 + 4 * fq;
;         f32x4 sv[2][2], bv[2][2];
; #pragma unroll
;         for (int bj = 0; bj < 2; ++bj)
; #pragma unroll
;             for (int n = 0; n < 2; ++n) {
;                 sv[bj][n] = scale ? *(const f32x4*)(scale + col0 + bj * 128 + n * 16) : (f32x4){1.f, 1.f, 1.f, 1.f};
;                 bv[bj][n] = bias ? *(const f32x4*)(bias + col0 + bj * 128 + n * 16) : (f32x4){0.f, 0.f, 0.f, 0.f}; }
; #pragma unroll
;         for (int ai = 0; ai < 2; ++ai)
; #pragma unroll
;             for (int mh = 0; mh < 2; ++mh) {
;                 f32x4 bs[2][2][2];
; #pragma unroll
;                 for (int m = 0; m < 2; ++m)
; #pragma unroll
;                     for (int bj = 0; bj < 2; ++bj)
; #pragma unroll
;                         for (int n = 0; n < 2; ++n) bs[m][bj][n] = *(const f32x4*)(base + (size_t)(row0 + ai * 128 + (2 * mh + m) * 16) * D + col0 + bj * 128 + n * 16);
	s_nop 1
	ds_read_b128 v[164:167], v150 offset:49152
	ds_read_b128 v[168:171], v150 offset:50176
	ds_read_b128 v[172:175], v150 offset:51200
	ds_read_b128 v[176:179], v150 offset:52224
	ds_read_b128 v[180:183], v150 offset:53248
	ds_read_b128 v[184:187], v150 offset:54272
	ds_read_b128 v[188:191], v150 offset:55296
	ds_read_b128 v[192:195], v150 offset:56320
	s_add_i32 s43, s77, s7
	v_lshl_add_u64 v[254:255], v[144:145], 0, s[12:13]
	s_mov_b32 m0, s43
	s_nop 0
	global_load_lds_dwordx4 v[254:255], off
	v_lshl_add_u64 v[254:255], v[212:213], 0, s[12:13]
	s_add_i32 m0, s43, 0x2000
	s_nop 0
	global_load_lds_dwordx4 v[254:255], off
	s_mov_b32 m0, s46
	v_lshl_add_u64 v[254:255], v[214:215], 0, s[12:13]
	global_load_lds_dwordx4 v[254:255], off
	v_lshl_add_u64 v[144:145], v[216:217], 0, s[12:13]
	s_mov_b32 m0, s47
	s_nop 0
	global_load_lds_dwordx4 v[144:145], off
	s_add_u32 s40, s40, 0x40080
	s_addc_u32 s41, s41, 0
	s_add_i32 s42, s42, s7
	v_lshl_add_u64 v[254:255], s[40:41], 0, v[128:129]
	s_mov_b32 m0, s42
	s_nop 0
	global_load_lds_dwordx4 v[254:255], off
	v_lshl_add_u64 v[254:255], s[40:41], 0, v[130:131]
	s_add_i32 m0, s42, 0x2000
	s_nop 0
	global_load_lds_dwordx4 v[254:255], off
	s_waitcnt vmcnt(6)
	s_waitcnt lgkmcnt(0)
	s_barrier
	s_setprio 1
	v_mfma_f32_16x16x32_bf16 v[60:63], v[140:143], v[164:167], v[60:63]
	v_mfma_f32_16x16x32_bf16 v[56:59], v[156:159], v[164:167], v[56:59]
	v_mfma_f32_16x16x32_bf16 v[48:51], v[140:143], v[172:175], v[48:51]
	v_mfma_f32_16x16x32_bf16 v[40:43], v[156:159], v[172:175], v[40:43]
	v_mfma_f32_16x16x32_bf16 v[28:31], v[140:143], v[180:183], v[28:31]
	v_mfma_f32_16x16x32_bf16 v[24:27], v[156:159], v[180:183], v[24:27]
	v_mfma_f32_16x16x32_bf16 v[16:19], v[140:143], v[188:191], v[16:19]
	v_mfma_f32_16x16x32_bf16 v[8:11], v[156:159], v[188:191], v[8:11]
	v_mfma_f32_16x16x32_bf16 v[60:63], v[152:155], v[168:171], v[60:63]
	v_mfma_f32_16x16x32_bf16 v[56:59], v[160:163], v[168:171], v[56:59]
	v_mfma_f32_16x16x32_bf16 v[48:51], v[152:155], v[176:179], v[48:51]
	v_mfma_f32_16x16x32_bf16 v[40:43], v[160:163], v[176:179], v[40:43]
	v_mfma_f32_16x16x32_bf16 v[28:31], v[152:155], v[184:187], v[28:31]
	v_mfma_f32_16x16x32_bf16 v[24:27], v[160:163], v[184:187], v[24:27]
	v_mfma_f32_16x16x32_bf16 v[16:19], v[152:155], v[192:195], v[16:19]
	v_mfma_f32_16x16x32_bf16 v[8:11], v[160:163], v[192:195], v[8:11]
	v_mfma_f32_16x16x32_bf16 v[52:55], v[196:199], v[164:167], v[52:55]
	v_mfma_f32_16x16x32_bf16 v[44:47], v[204:207], v[164:167], v[44:47]
	v_mfma_f32_16x16x32_bf16 v[36:39], v[196:199], v[172:175], v[36:39]
	v_mfma_f32_16x16x32_bf16 v[32:35], v[204:207], v[172:175], v[32:35]
	v_mfma_f32_16x16x32_bf16 v[20:23], v[196:199], v[180:183], v[20:23]
	v_mfma_f32_16x16x32_bf16 v[12:15], v[204:207], v[180:183], v[12:15]
	v_mfma_f32_16x16x32_bf16 v[4:7], v[196:199], v[188:191], v[4:7]
	v_mfma_f32_16x16x32_bf16 v[0:3], v[204:207], v[188:191], v[0:3]
	v_mfma_f32_16x16x32_bf16 v[52:55], v[200:203], v[168:171], v[52:55]
	v_mfma_f32_16x16x32_bf16 v[44:47], v[208:211], v[168:171], v[44:47]
	v_mfma_f32_16x16x32_bf16 v[36:39], v[200:203], v[176:179], v[36:39]
	v_mfma_f32_16x16x32_bf16 v[32:35], v[208:211], v[176:179], v[32:35]
	v_mfma_f32_16x16x32_bf16 v[20:23], v[200:203], v[184:187], v[20:23]
	v_mfma_f32_16x16x32_bf16 v[12:15], v[208:211], v[184:187], v[12:15]
	v_mfma_f32_16x16x32_bf16 v[4:7], v[200:203], v[192:195], v[4:7]
	v_mfma_f32_16x16x32_bf16 v[0:3], v[208:211], v[192:195], v[0:3]
	s_setprio 0
	s_add_i32 s76, s76, 2
	s_add_u32 s38, s38, 0x100
	s_addc_u32 s39, s39, 0
	s_add_u32 s74, s74, 0x100
	s_addc_u32 s75, s75, 0
	s_cmp_gt_u32 s76, 13
	s_barrier
	s_cbranch_scc0 .LBB0_1239
	v_lshl_or_b32 v144, s63, 8, v148
	v_lshl_add_u32 v145, s36, 8, v146
	v_lshlrev_b32_e32 v144, 2, v144
	v_lshl_add_u32 v145, v145, 12, v144
	v_add_u32_e32 v216, 0x10000, v145
	v_add_u32_e32 v217, 0x20000, v145
	v_add_u32_e32 v218, 0x30000, v145
	v_add_u32_e32 v220, 0x80000, v145
	v_add_u32_e32 v221, 0x90000, v145
	v_add_u32_e32 v222, 0xa0000, v145
	v_add_u32_e32 v223, 0xb0000, v145
	v_and_b32_e32 v235, 8, v146
	v_cmp_ne_u32_e32 vcc, 0, v235
	v_mov_b32_e32 v232, 0xffff8040
	s_nop 0
	v_cndmask_b32_e32 v232, 0, v232, vcc
	v_mov_b32_e32 v233, 64
	v_mov_b32_e32 v235, 0x8000
	v_cndmask_b32_e32 v233, v235, v233, vcc
	v_add_u32_e32 v224, v145, v232
	v_add_u32_e32 v225, v216, v232
	v_add_u32_e32 v226, v217, v232
	v_add_u32_e32 v227, v218, v232
	v_add_u32_e32 v228, v220, v232
	v_add_u32_e32 v229, v221, v232
	v_add_u32_e32 v230, v222, v232
	v_add_u32_e32 v231, v223, v232
	s_and_b64 vcc, exec, s[10:11]
	s_mov_b32 s63, s26
	s_mov_b32 s36, s28
	s_mov_b64 s[40:41], s[34:35]
	s_mov_b64 s[38:39], s[30:31]
	global_load_dwordx4 v[140:143], v224, s[52:53]
	v_add_u32_e32 v144, v145, v233
	global_load_dwordx4 v[152:155], v144, s[52:53]
	global_load_dwordx4 v[156:159], v224, s[52:53] offset:512
	v_add_u32_e32 v144, v145, v233
	global_load_dwordx4 v[160:163], v144, s[52:53] offset:512
	global_load_dwordx4 v[164:167], v225, s[52:53]
	v_add_u32_e32 v144, v216, v233
	global_load_dwordx4 v[168:171], v144, s[52:53]
	global_load_dwordx4 v[172:175], v225, s[52:53] offset:512
	v_add_u32_e32 v144, v216, v233
	global_load_dwordx4 v[176:179], v144, s[52:53] offset:512
	global_load_dwordx4 v[180:183], v226, s[52:53]
	v_add_u32_e32 v144, v217, v233
	global_load_dwordx4 v[184:187], v144, s[52:53]
	global_load_dwordx4 v[188:191], v226, s[52:53] offset:512
	v_add_u32_e32 v144, v217, v233
	global_load_dwordx4 v[192:195], v144, s[52:53] offset:512
	global_load_dwordx4 v[196:199], v227, s[52:53]
	v_add_u32_e32 v144, v218, v233
	global_load_dwordx4 v[200:203], v144, s[52:53]
	global_load_dwordx4 v[204:207], v227, s[52:53] offset:512
	v_add_u32_e32 v144, v218, v233
	global_load_dwordx4 v[208:211], v144, s[52:53] offset:512
	s_barrier
;     __device__ __forceinline__ void operator()(AccRef acc, const Unit& u, int wr, int wc, int fr, int fq) const {
;     ...
;                         for (int n = 0; n < 2; ++n) bs[m][bj][n] = *(const f32x4*)(base + (size_t)(row0 + ai * 128 + (2 * mh + m) * 16) * D + col0 + bj * 128 + n * 16);
; #pragma unroll
;                 for (int m = 0; m < 2; ++m)
; #pragma unroll
;                     for (int bj = 0; bj < 2; ++bj)
; #pragma unroll
;                         for (int n = 0; n < 2; ++n) *(f32x4*)(out + (size_t)(row0 + ai * 128 + (2 * mh + m) * 16) * D + col0 + bj * 128 + n * 16) = bs[m][bj][n] + sv[bj][n] * (acc[ai][bj][2 * mh + m][n] + bv[bj][n]);
	v_pk_add_f32 v[124:125], v[124:125], 0 op_sel_hi:[1,0]
	v_pk_add_f32 v[126:127], v[126:127], 0 op_sel_hi:[1,0]
	v_pk_add_f32 v[120:121], v[120:121], 0 op_sel_hi:[1,0]
	v_pk_add_f32 v[122:123], v[122:123], 0 op_sel_hi:[1,0]
	v_pk_add_f32 v[116:117], v[116:117], 0 op_sel_hi:[1,0]
	v_pk_add_f32 v[118:119], v[118:119], 0 op_sel_hi:[1,0]
	v_pk_add_f32 v[108:109], v[108:109], 0 op_sel_hi:[1,0]
	v_pk_add_f32 v[110:111], v[110:111], 0 op_sel_hi:[1,0]
	v_pk_add_f32 v[112:113], v[112:113], 0 op_sel_hi:[1,0]
	v_pk_add_f32 v[114:115], v[114:115], 0 op_sel_hi:[1,0]
	v_pk_add_f32 v[104:105], v[104:105], 0 op_sel_hi:[1,0]
	v_pk_add_f32 v[106:107], v[106:107], 0 op_sel_hi:[1,0]
	v_pk_add_f32 v[100:101], v[100:101], 0 op_sel_hi:[1,0]
	v_pk_add_f32 v[102:103], v[102:103], 0 op_sel_hi:[1,0]
	v_pk_add_f32 v[96:97], v[96:97], 0 op_sel_hi:[1,0]
	v_pk_add_f32 v[98:99], v[98:99], 0 op_sel_hi:[1,0]
	v_pk_add_f32 v[92:93], v[92:93], 0 op_sel_hi:[1,0]
	v_pk_add_f32 v[94:95], v[94:95], 0 op_sel_hi:[1,0]
	v_pk_add_f32 v[88:89], v[88:89], 0 op_sel_hi:[1,0]
	v_pk_add_f32 v[90:91], v[90:91], 0 op_sel_hi:[1,0]
	v_pk_add_f32 v[84:85], v[84:85], 0 op_sel_hi:[1,0]
	v_pk_add_f32 v[86:87], v[86:87], 0 op_sel_hi:[1,0]
	v_pk_add_f32 v[76:77], v[76:77], 0 op_sel_hi:[1,0]
	v_pk_add_f32 v[78:79], v[78:79], 0 op_sel_hi:[1,0]
	v_pk_add_f32 v[80:81], v[80:81], 0 op_sel_hi:[1,0]
	v_pk_add_f32 v[82:83], v[82:83], 0 op_sel_hi:[1,0]
	v_pk_add_f32 v[72:73], v[72:73], 0 op_sel_hi:[1,0]
	v_pk_add_f32 v[74:75], v[74:75], 0 op_sel_hi:[1,0]
	v_pk_add_f32 v[68:69], v[68:69], 0 op_sel_hi:[1,0]
	v_pk_add_f32 v[70:71], v[70:71], 0 op_sel_hi:[1,0]
	v_pk_add_f32 v[64:65], v[64:65], 0 op_sel_hi:[1,0]
	v_pk_add_f32 v[66:67], v[66:67], 0 op_sel_hi:[1,0]
	v_pk_add_f32 v[60:61], v[60:61], 0 op_sel_hi:[1,0]
	v_pk_add_f32 v[62:63], v[62:63], 0 op_sel_hi:[1,0]
	v_pk_add_f32 v[56:57], v[56:57], 0 op_sel_hi:[1,0]
	v_pk_add_f32 v[58:59], v[58:59], 0 op_sel_hi:[1,0]
	v_pk_add_f32 v[52:53], v[52:53], 0 op_sel_hi:[1,0]
	v_pk_add_f32 v[54:55], v[54:55], 0 op_sel_hi:[1,0]
	v_pk_add_f32 v[44:45], v[44:45], 0 op_sel_hi:[1,0]
	v_pk_add_f32 v[46:47], v[46:47], 0 op_sel_hi:[1,0]
	v_pk_add_f32 v[48:49], v[48:49], 0 op_sel_hi:[1,0]
	v_pk_add_f32 v[50:51], v[50:51], 0 op_sel_hi:[1,0]
	v_pk_add_f32 v[40:41], v[40:41], 0 op_sel_hi:[1,0]
	v_pk_add_f32 v[42:43], v[42:43], 0 op_sel_hi:[1,0]
	v_pk_add_f32 v[36:37], v[36:37], 0 op_sel_hi:[1,0]
	v_pk_add_f32 v[38:39], v[38:39], 0 op_sel_hi:[1,0]
	v_pk_add_f32 v[32:33], v[32:33], 0 op_sel_hi:[1,0]
	v_pk_add_f32 v[34:35], v[34:35], 0 op_sel_hi:[1,0]
	v_pk_add_f32 v[28:29], v[28:29], 0 op_sel_hi:[1,0]
	v_pk_add_f32 v[30:31], v[30:31], 0 op_sel_hi:[1,0]
	v_pk_add_f32 v[24:25], v[24:25], 0 op_sel_hi:[1,0]
	v_pk_add_f32 v[26:27], v[26:27], 0 op_sel_hi:[1,0]
	v_pk_add_f32 v[20:21], v[20:21], 0 op_sel_hi:[1,0]
	v_pk_add_f32 v[22:23], v[22:23], 0 op_sel_hi:[1,0]
	v_pk_add_f32 v[12:13], v[12:13], 0 op_sel_hi:[1,0]
	v_pk_add_f32 v[14:15], v[14:15], 0 op_sel_hi:[1,0]
	v_pk_add_f32 v[16:17], v[16:17], 0 op_sel_hi:[1,0]
	v_pk_add_f32 v[18:19], v[18:19], 0 op_sel_hi:[1,0]
	v_pk_add_f32 v[8:9], v[8:9], 0 op_sel_hi:[1,0]
	v_pk_add_f32 v[10:11], v[10:11], 0 op_sel_hi:[1,0]
	v_pk_add_f32 v[4:5], v[4:5], 0 op_sel_hi:[1,0]
	v_pk_add_f32 v[6:7], v[6:7], 0 op_sel_hi:[1,0]
	v_pk_add_f32 v[0:1], v[0:1], 0 op_sel_hi:[1,0]
	v_pk_add_f32 v[2:3], v[2:3], 0 op_sel_hi:[1,0]
	s_waitcnt vmcnt(8)
	v_mov_b32_e32 v212, v124
	v_mov_b32_e32 v213, v125
	v_mov_b32_e32 v214, v126
	v_mov_b32_e32 v215, v127
	s_nop 0
	v_mov_b32_dpp v124, v120 row_shr:8 row_mask:0xf bank_mask:0xc
	v_mov_b32_dpp v125, v121 row_shr:8 row_mask:0xf bank_mask:0xc
	v_mov_b32_dpp v126, v122 row_shr:8 row_mask:0xf bank_mask:0xc
	v_mov_b32_dpp v127, v123 row_shr:8 row_mask:0xf bank_mask:0xc
	v_mov_b32_dpp v120, v212 row_shl:8 row_mask:0xf bank_mask:0x3
	v_mov_b32_dpp v121, v213 row_shl:8 row_mask:0xf bank_mask:0x3
	v_mov_b32_dpp v122, v214 row_shl:8 row_mask:0xf bank_mask:0x3
	v_mov_b32_dpp v123, v215 row_shl:8 row_mask:0xf bank_mask:0x3
	v_mov_b32_e32 v212, v116
	v_mov_b32_e32 v213, v117
	v_mov_b32_e32 v214, v118
	v_mov_b32_e32 v215, v119
	s_nop 0
	v_mov_b32_dpp v116, v108 row_shr:8 row_mask:0xf bank_mask:0xc
	v_mov_b32_dpp v117, v109 row_shr:8 row_mask:0xf bank_mask:0xc
	v_mov_b32_dpp v118, v110 row_shr:8 row_mask:0xf bank_mask:0xc
	v_mov_b32_dpp v119, v111 row_shr:8 row_mask:0xf bank_mask:0xc
	v_mov_b32_dpp v108, v212 row_shl:8 row_mask:0xf bank_mask:0x3
	v_mov_b32_dpp v109, v213 row_shl:8 row_mask:0xf bank_mask:0x3
	v_mov_b32_dpp v110, v214 row_shl:8 row_mask:0xf bank_mask:0x3
	v_mov_b32_dpp v111, v215 row_shl:8 row_mask:0xf bank_mask:0x3
	v_mov_b32_e32 v212, v112
	v_mov_b32_e32 v213, v113
	v_mov_b32_e32 v214, v114
	v_mov_b32_e32 v215, v115
	s_nop 0
	v_mov_b32_dpp v112, v104 row_shr:8 row_mask:0xf bank_mask:0xc
	v_mov_b32_dpp v113, v105 row_shr:8 row_mask:0xf bank_mask:0xc
	v_mov_b32_dpp v114, v106 row_shr:8 row_mask:0xf bank_mask:0xc
	v_mov_b32_dpp v115, v107 row_shr:8 row_mask:0xf bank_mask:0xc
	v_mov_b32_dpp v104, v212 row_shl:8 row_mask:0xf bank_mask:0x3
	v_mov_b32_dpp v105, v213 row_shl:8 row_mask:0xf bank_mask:0x3
	v_mov_b32_dpp v106, v214 row_shl:8 row_mask:0xf bank_mask:0x3
	v_mov_b32_dpp v107, v215 row_shl:8 row_mask:0xf bank_mask:0x3
	v_mov_b32_e32 v212, v100
	v_mov_b32_e32 v213, v101
	v_mov_b32_e32 v214, v102
	v_mov_b32_e32 v215, v103
	s_nop 0
	v_mov_b32_dpp v100, v96 row_shr:8 row_mask:0xf bank_mask:0xc
	v_mov_b32_dpp v101, v97 row_shr:8 row_mask:0xf bank_mask:0xc
	v_mov_b32_dpp v102, v98 row_shr:8 row_mask:0xf bank_mask:0xc
	v_mov_b32_dpp v103, v99 row_shr:8 row_mask:0xf bank_mask:0xc
	v_mov_b32_dpp v96, v212 row_shl:8 row_mask:0xf bank_mask:0x3
;     __device__ __forceinline__ void operator()(AccRef acc, const Unit& u, int wr, int wc, int fr, int fq) const {
;     ...
;                         for (int n = 0; n < 2; ++n) bs[m][bj][n] = *(const f32x4*)(base + (size_t)(row0 + ai * 128 + (2 * mh + m) * 16) * D + col0 + bj * 128 + n * 16);
; #pragma unroll
;                 for (int m = 0; m < 2; ++m)
; #pragma unroll
;                     for (int bj = 0; bj < 2; ++bj)
; #pragma unroll
;                         for (int n = 0; n < 2; ++n) *(f32x4*)(out + (size_t)(row0 + ai * 128 + (2 * mh + m) * 16) * D + col0 + bj * 128 + n * 16) = bs[m][bj][n] + sv[bj][n] * (acc[ai][bj][2 * mh + m][n] + bv[bj][n]);
;                 asm volatile("" ::: "memory"); }
	v_mov_b32_dpp v97, v213 row_shl:8 row_mask:0xf bank_mask:0x3
	v_mov_b32_dpp v98, v214 row_shl:8 row_mask:0xf bank_mask:0x3
	v_mov_b32_dpp v99, v215 row_shl:8 row_mask:0xf bank_mask:0x3
	v_pk_add_f32 v[124:125], v[124:125], v[140:141]
	v_pk_add_f32 v[126:127], v[126:127], v[142:143]
	v_pk_add_f32 v[120:121], v[120:121], v[152:153]
	v_pk_add_f32 v[122:123], v[122:123], v[154:155]
	v_pk_add_f32 v[116:117], v[116:117], v[156:157]
	v_pk_add_f32 v[118:119], v[118:119], v[158:159]
	v_pk_add_f32 v[108:109], v[108:109], v[160:161]
	v_pk_add_f32 v[110:111], v[110:111], v[162:163]
	v_pk_add_f32 v[112:113], v[112:113], v[164:165]
	v_pk_add_f32 v[114:115], v[114:115], v[166:167]
	v_pk_add_f32 v[104:105], v[104:105], v[168:169]
	v_pk_add_f32 v[106:107], v[106:107], v[170:171]
	v_pk_add_f32 v[100:101], v[100:101], v[172:173]
	v_pk_add_f32 v[102:103], v[102:103], v[174:175]
	v_pk_add_f32 v[96:97], v[96:97], v[176:177]
	v_pk_add_f32 v[98:99], v[98:99], v[178:179]
	global_store_dwordx4 v224, v[124:127], s[52:53]
	v_add_u32_e32 v144, v145, v233
	global_store_dwordx4 v144, v[120:123], s[52:53]
	global_store_dwordx4 v224, v[116:119], s[52:53] offset:512
	v_add_u32_e32 v144, v145, v233
	global_store_dwordx4 v144, v[108:111], s[52:53] offset:512
	global_store_dwordx4 v225, v[112:115], s[52:53]
	v_add_u32_e32 v144, v216, v233
	global_store_dwordx4 v144, v[104:107], s[52:53]
	global_store_dwordx4 v225, v[100:103], s[52:53] offset:512
	v_add_u32_e32 v144, v216, v233
	global_store_dwordx4 v144, v[96:99], s[52:53] offset:512
	global_load_dwordx4 v[140:143], v228, s[52:53]
	v_add_u32_e32 v144, v220, v233
	global_load_dwordx4 v[152:155], v144, s[52:53]
	global_load_dwordx4 v[156:159], v228, s[52:53] offset:512
	v_add_u32_e32 v144, v220, v233
	global_load_dwordx4 v[160:163], v144, s[52:53] offset:512
	global_load_dwordx4 v[164:167], v229, s[52:53]
	v_add_u32_e32 v144, v221, v233
	global_load_dwordx4 v[168:171], v144, s[52:53]
	global_load_dwordx4 v[172:175], v229, s[52:53] offset:512
	v_add_u32_e32 v144, v221, v233
	global_load_dwordx4 v[176:179], v144, s[52:53] offset:512
	s_barrier
	s_waitcnt vmcnt(16)
	v_mov_b32_e32 v212, v92
	v_mov_b32_e32 v213, v93
	v_mov_b32_e32 v214, v94
	v_mov_b32_e32 v215, v95
	s_nop 0
	v_mov_b32_dpp v92, v88 row_shr:8 row_mask:0xf bank_mask:0xc
	v_mov_b32_dpp v93, v89 row_shr:8 row_mask:0xf bank_mask:0xc
	v_mov_b32_dpp v94, v90 row_shr:8 row_mask:0xf bank_mask:0xc
	v_mov_b32_dpp v95, v91 row_shr:8 row_mask:0xf bank_mask:0xc
	v_mov_b32_dpp v88, v212 row_shl:8 row_mask:0xf bank_mask:0x3
	v_mov_b32_dpp v89, v213 row_shl:8 row_mask:0xf bank_mask:0x3
	v_mov_b32_dpp v90, v214 row_shl:8 row_mask:0xf bank_mask:0x3
	v_mov_b32_dpp v91, v215 row_shl:8 row_mask:0xf bank_mask:0x3
	v_mov_b32_e32 v212, v84
	v_mov_b32_e32 v213, v85
	v_mov_b32_e32 v214, v86
	v_mov_b32_e32 v215, v87
	s_nop 0
	v_mov_b32_dpp v84, v76 row_shr:8 row_mask:0xf bank_mask:0xc
	v_mov_b32_dpp v85, v77 row_shr:8 row_mask:0xf bank_mask:0xc
	v_mov_b32_dpp v86, v78 row_shr:8 row_mask:0xf bank_mask:0xc
	v_mov_b32_dpp v87, v79 row_shr:8 row_mask:0xf bank_mask:0xc
	v_mov_b32_dpp v76, v212 row_shl:8 row_mask:0xf bank_mask:0x3
	v_mov_b32_dpp v77, v213 row_shl:8 row_mask:0xf bank_mask:0x3
	v_mov_b32_dpp v78, v214 row_shl:8 row_mask:0xf bank_mask:0x3
	v_mov_b32_dpp v79, v215 row_shl:8 row_mask:0xf bank_mask:0x3
	v_mov_b32_e32 v212, v80
	v_mov_b32_e32 v213, v81
	v_mov_b32_e32 v214, v82
	v_mov_b32_e32 v215, v83
	s_nop 0
	v_mov_b32_dpp v80, v72 row_shr:8 row_mask:0xf bank_mask:0xc
	v_mov_b32_dpp v81, v73 row_shr:8 row_mask:0xf bank_mask:0xc
	v_mov_b32_dpp v82, v74 row_shr:8 row_mask:0xf bank_mask:0xc
	v_mov_b32_dpp v83, v75 row_shr:8 row_mask:0xf bank_mask:0xc
	v_mov_b32_dpp v72, v212 row_shl:8 row_mask:0xf bank_mask:0x3
	v_mov_b32_dpp v73, v213 row_shl:8 row_mask:0xf bank_mask:0x3
	v_mov_b32_dpp v74, v214 row_shl:8 row_mask:0xf bank_mask:0x3
	v_mov_b32_dpp v75, v215 row_shl:8 row_mask:0xf bank_mask:0x3
	v_mov_b32_e32 v212, v68
	v_mov_b32_e32 v213, v69
	v_mov_b32_e32 v214, v70
	v_mov_b32_e32 v215, v71
	s_nop 0
	v_mov_b32_dpp v68, v64 row_shr:8 row_mask:0xf bank_mask:0xc
	v_mov_b32_dpp v69, v65 row_shr:8 row_mask:0xf bank_mask:0xc
	v_mov_b32_dpp v70, v66 row_shr:8 row_mask:0xf bank_mask:0xc
	v_mov_b32_dpp v71, v67 row_shr:8 row_mask:0xf bank_mask:0xc
	v_mov_b32_dpp v64, v212 row_shl:8 row_mask:0xf bank_mask:0x3
	v_mov_b32_dpp v65, v213 row_shl:8 row_mask:0xf bank_mask:0x3
	v_mov_b32_dpp v66, v214 row_shl:8 row_mask:0xf bank_mask:0x3
	v_mov_b32_dpp v67, v215 row_shl:8 row_mask:0xf bank_mask:0x3
	v_pk_add_f32 v[92:93], v[92:93], v[180:181]
	v_pk_add_f32 v[94:95], v[94:95], v[182:183]
	v_pk_add_f32 v[88:89], v[88:89], v[184:185]
	v_pk_add_f32 v[90:91], v[90:91], v[186:187]
	v_pk_add_f32 v[84:85], v[84:85], v[188:189]
	v_pk_add_f32 v[86:87], v[86:87], v[190:191]
	v_pk_add_f32 v[76:77], v[76:77], v[192:193]
	v_pk_add_f32 v[78:79], v[78:79], v[194:195]
	v_pk_add_f32 v[80:81], v[80:81], v[196:197]
	v_pk_add_f32 v[82:83], v[82:83], v[198:199]
	v_pk_add_f32 v[72:73], v[72:73], v[200:201]
	v_pk_add_f32 v[74:75], v[74:75], v[202:203]
	v_pk_add_f32 v[68:69], v[68:69], v[204:205]
	v_pk_add_f32 v[70:71], v[70:71], v[206:207]
	v_pk_add_f32 v[64:65], v[64:65], v[208:209]
	v_pk_add_f32 v[66:67], v[66:67], v[210:211]
	global_store_dwordx4 v226, v[92:95], s[52:53]
	v_add_u32_e32 v144, v217, v233
	global_store_dwordx4 v144, v[88:91], s[52:53]
	global_store_dwordx4 v226, v[84:87], s[52:53] offset:512
	v_add_u32_e32 v144, v217, v233
	global_store_dwordx4 v144, v[76:79], s[52:53] offset:512
	global_store_dwordx4 v227, v[80:83], s[52:53]
	v_add_u32_e32 v144, v218, v233
	global_store_dwordx4 v144, v[72:75], s[52:53]
	global_store_dwordx4 v227, v[68:71], s[52:53] offset:512
	v_add_u32_e32 v144, v218, v233
	global_store_dwordx4 v144, v[64:67], s[52:53] offset:512
	global_load_dwordx4 v[180:183], v230, s[52:53]
	v_add_u32_e32 v144, v222, v233
	global_load_dwordx4 v[184:187], v144, s[52:53]
	global_load_dwordx4 v[188:191], v230, s[52:53] offset:512
	v_add_u32_e32 v144, v222, v233
	global_load_dwordx4 v[192:195], v144, s[52:53] offset:512
	global_load_dwordx4 v[196:199], v231, s[52:53]
	v_add_u32_e32 v144, v223, v233
	global_load_dwordx4 v[200:203], v144, s[52:53]
	global_load_dwordx4 v[204:207], v231, s[52:53] offset:512
	v_add_u32_e32 v144, v223, v233
	global_load_dwordx4 v[208:211], v144, s[52:53] offset:512
	s_barrier
;     __device__ __forceinline__ void operator()(AccRef acc, const Unit& u, int wr, int wc, int fr, int fq) const {
;     ...
;                 for (int m = 0; m < 2; ++m)
; #pragma unroll
;                     for (int bj = 0; bj < 2; ++bj)
; #pragma unroll
;                         for (int n = 0; n < 2; ++n) *(f32x4*)(out + (size_t)(row0 + ai * 128 + (2 * mh + m) * 16) * D + col0 + bj * 128 + n * 16) = bs[m][bj][n] + sv[bj][n] * (acc[ai][bj][2 * mh + m][n] + bv[bj][n]);
;                 asm volatile("" ::: "memory"); }
	s_waitcnt vmcnt(16)
	v_mov_b32_e32 v212, v60
	v_mov_b32_e32 v213, v61
	v_mov_b32_e32 v214, v62
	v_mov_b32_e32 v215, v63
	s_nop 0
	v_mov_b32_dpp v60, v56 row_shr:8 row_mask:0xf bank_mask:0xc
	v_mov_b32_dpp v61, v57 row_shr:8 row_mask:0xf bank_mask:0xc
	v_mov_b32_dpp v62, v58 row_shr:8 row_mask:0xf bank_mask:0xc
	v_mov_b32_dpp v63, v59 row_shr:8 row_mask:0xf bank_mask:0xc
	v_mov_b32_dpp v56, v212 row_shl:8 row_mask:0xf bank_mask:0x3
	v_mov_b32_dpp v57, v213 row_shl:8 row_mask:0xf bank_mask:0x3
	v_mov_b32_dpp v58, v214 row_shl:8 row_mask:0xf bank_mask:0x3
	v_mov_b32_dpp v59, v215 row_shl:8 row_mask:0xf bank_mask:0x3
	v_mov_b32_e32 v212, v52
	v_mov_b32_e32 v213, v53
	v_mov_b32_e32 v214, v54
	v_mov_b32_e32 v215, v55
	s_nop 0
	v_mov_b32_dpp v52, v44 row_shr:8 row_mask:0xf bank_mask:0xc
	v_mov_b32_dpp v53, v45 row_shr:8 row_mask:0xf bank_mask:0xc
	v_mov_b32_dpp v54, v46 row_shr:8 row_mask:0xf bank_mask:0xc
	v_mov_b32_dpp v55, v47 row_shr:8 row_mask:0xf bank_mask:0xc
	v_mov_b32_dpp v44, v212 row_shl:8 row_mask:0xf bank_mask:0x3
	v_mov_b32_dpp v45, v213 row_shl:8 row_mask:0xf bank_mask:0x3
	v_mov_b32_dpp v46, v214 row_shl:8 row_mask:0xf bank_mask:0x3
	v_mov_b32_dpp v47, v215 row_shl:8 row_mask:0xf bank_mask:0x3
	v_mov_b32_e32 v212, v48
	v_mov_b32_e32 v213, v49
	v_mov_b32_e32 v214, v50
	v_mov_b32_e32 v215, v51
	s_nop 0
	v_mov_b32_dpp v48, v40 row_shr:8 row_mask:0xf bank_mask:0xc
	v_mov_b32_dpp v49, v41 row_shr:8 row_mask:0xf bank_mask:0xc
	v_mov_b32_dpp v50, v42 row_shr:8 row_mask:0xf bank_mask:0xc
	v_mov_b32_dpp v51, v43 row_shr:8 row_mask:0xf bank_mask:0xc
	v_mov_b32_dpp v40, v212 row_shl:8 row_mask:0xf bank_mask:0x3
	v_mov_b32_dpp v41, v213 row_shl:8 row_mask:0xf bank_mask:0x3
	v_mov_b32_dpp v42, v214 row_shl:8 row_mask:0xf bank_mask:0x3
	v_mov_b32_dpp v43, v215 row_shl:8 row_mask:0xf bank_mask:0x3
	v_mov_b32_e32 v212, v36
	v_mov_b32_e32 v213, v37
	v_mov_b32_e32 v214, v38
	v_mov_b32_e32 v215, v39
	s_nop 0
	v_mov_b32_dpp v36, v32 row_shr:8 row_mask:0xf bank_mask:0xc
	v_mov_b32_dpp v37, v33 row_shr:8 row_mask:0xf bank_mask:0xc
	v_mov_b32_dpp v38, v34 row_shr:8 row_mask:0xf bank_mask:0xc
	v_mov_b32_dpp v39, v35 row_shr:8 row_mask:0xf bank_mask:0xc
	v_mov_b32_dpp v32, v212 row_shl:8 row_mask:0xf bank_mask:0x3
	v_mov_b32_dpp v33, v213 row_shl:8 row_mask:0xf bank_mask:0x3
	v_mov_b32_dpp v34, v214 row_shl:8 row_mask:0xf bank_mask:0x3
	v_mov_b32_dpp v35, v215 row_shl:8 row_mask:0xf bank_mask:0x3
	v_pk_add_f32 v[60:61], v[60:61], v[140:141]
	v_pk_add_f32 v[62:63], v[62:63], v[142:143]
	v_pk_add_f32 v[56:57], v[56:57], v[152:153]
	v_pk_add_f32 v[58:59], v[58:59], v[154:155]
	v_pk_add_f32 v[52:53], v[52:53], v[156:157]
	v_pk_add_f32 v[54:55], v[54:55], v[158:159]
	v_pk_add_f32 v[44:45], v[44:45], v[160:161]
	v_pk_add_f32 v[46:47], v[46:47], v[162:163]
	v_pk_add_f32 v[48:49], v[48:49], v[164:165]
	v_pk_add_f32 v[50:51], v[50:51], v[166:167]
	v_pk_add_f32 v[40:41], v[40:41], v[168:169]
	v_pk_add_f32 v[42:43], v[42:43], v[170:171]
	v_pk_add_f32 v[36:37], v[36:37], v[172:173]
	v_pk_add_f32 v[38:39], v[38:39], v[174:175]
	v_pk_add_f32 v[32:33], v[32:33], v[176:177]
	v_pk_add_f32 v[34:35], v[34:35], v[178:179]
	global_store_dwordx4 v228, v[60:63], s[52:53]
	v_add_u32_e32 v144, v220, v233
	global_store_dwordx4 v144, v[56:59], s[52:53]
	global_store_dwordx4 v228, v[52:55], s[52:53] offset:512
	v_add_u32_e32 v144, v220, v233
	global_store_dwordx4 v144, v[44:47], s[52:53] offset:512
	global_store_dwordx4 v229, v[48:51], s[52:53]
	v_add_u32_e32 v144, v221, v233
	global_store_dwordx4 v144, v[40:43], s[52:53]
	global_store_dwordx4 v229, v[36:39], s[52:53] offset:512
	v_add_u32_e32 v144, v221, v233
	global_store_dwordx4 v144, v[32:35], s[52:53] offset:512
	s_barrier
; #define PG8_WAIT_V(n) asm volatile("s_waitcnt vmcnt(" #n ")" ::: "memory")
; #define PG8_BAR __builtin_amdgcn_s_barrier()
; template <class Epi>
; __device__ __forceinline__ void gemm_phase(LAS unsigned char* lds, const Gemm g, const StaticOrder& S, const Epi& E) {
;     ...
;     PG8_WAIT_V(0);
;     if (wr == 0) PG8_BAR;
;     PG8_BAR;
;     __device__ __forceinline__ void operator()(AccRef acc, const Unit& u, int wr, int wc, int fr, int fq) const {
;     ...
;                 for (int m = 0; m < 2; ++m)
; #pragma unroll
;                     for (int bj = 0; bj < 2; ++bj)
; #pragma unroll
;                         for (int n = 0; n < 2; ++n) *(f32x4*)(out + (size_t)(row0 + ai * 128 + (2 * mh + m) * 16) * D + col0 + bj * 128 + n * 16) = bs[m][bj][n] + sv[bj][n] * (acc[ai][bj][2 * mh + m][n] + bv[bj][n]);
;                 asm volatile("" ::: "memory"); }
	s_waitcnt vmcnt(8)
	v_mov_b32_e32 v212, v28
	v_mov_b32_e32 v213, v29
	v_mov_b32_e32 v214, v30
	v_mov_b32_e32 v215, v31
	s_nop 0
	v_mov_b32_dpp v28, v24 row_shr:8 row_mask:0xf bank_mask:0xc
	v_mov_b32_dpp v29, v25 row_shr:8 row_mask:0xf bank_mask:0xc
	v_mov_b32_dpp v30, v26 row_shr:8 row_mask:0xf bank_mask:0xc
	v_mov_b32_dpp v31, v27 row_shr:8 row_mask:0xf bank_mask:0xc
	v_mov_b32_dpp v24, v212 row_shl:8 row_mask:0xf bank_mask:0x3
	v_mov_b32_dpp v25, v213 row_shl:8 row_mask:0xf bank_mask:0x3
	v_mov_b32_dpp v26, v214 row_shl:8 row_mask:0xf bank_mask:0x3
	v_mov_b32_dpp v27, v215 row_shl:8 row_mask:0xf bank_mask:0x3
	v_mov_b32_e32 v212, v20
	v_mov_b32_e32 v213, v21
	v_mov_b32_e32 v214, v22
	v_mov_b32_e32 v215, v23
	s_nop 0
	v_mov_b32_dpp v20, v12 row_shr:8 row_mask:0xf bank_mask:0xc
	v_mov_b32_dpp v21, v13 row_shr:8 row_mask:0xf bank_mask:0xc
	v_mov_b32_dpp v22, v14 row_shr:8 row_mask:0xf bank_mask:0xc
	v_mov_b32_dpp v23, v15 row_shr:8 row_mask:0xf bank_mask:0xc
	v_mov_b32_dpp v12, v212 row_shl:8 row_mask:0xf bank_mask:0x3
	v_mov_b32_dpp v13, v213 row_shl:8 row_mask:0xf bank_mask:0x3
	v_mov_b32_dpp v14, v214 row_shl:8 row_mask:0xf bank_mask:0x3
	v_mov_b32_dpp v15, v215 row_shl:8 row_mask:0xf bank_mask:0x3
	v_mov_b32_e32 v212, v16
	v_mov_b32_e32 v213, v17
	v_mov_b32_e32 v214, v18
	v_mov_b32_e32 v215, v19
	s_nop 0
	v_mov_b32_dpp v16, v8 row_shr:8 row_mask:0xf bank_mask:0xc
	v_mov_b32_dpp v17, v9 row_shr:8 row_mask:0xf bank_mask:0xc
	v_mov_b32_dpp v18, v10 row_shr:8 row_mask:0xf bank_mask:0xc
	v_mov_b32_dpp v19, v11 row_shr:8 row_mask:0xf bank_mask:0xc
	v_mov_b32_dpp v8, v212 row_shl:8 row_mask:0xf bank_mask:0x3
	v_mov_b32_dpp v9, v213 row_shl:8 row_mask:0xf bank_mask:0x3
	v_mov_b32_dpp v10, v214 row_shl:8 row_mask:0xf bank_mask:0x3
	v_mov_b32_dpp v11, v215 row_shl:8 row_mask:0xf bank_mask:0x3
	v_mov_b32_e32 v212, v4
	v_mov_b32_e32 v213, v5
	v_mov_b32_e32 v214, v6
	v_mov_b32_e32 v215, v7
	s_nop 0
	v_mov_b32_dpp v4, v0 row_shr:8 row_mask:0xf bank_mask:0xc
	v_mov_b32_dpp v5, v1 row_shr:8 row_mask:0xf bank_mask:0xc
	v_mov_b32_dpp v6, v2 row_shr:8 row_mask:0xf bank_mask:0xc
	v_mov_b32_dpp v7, v3 row_shr:8 row_mask:0xf bank_mask:0xc
	v_mov_b32_dpp v0, v212 row_shl:8 row_mask:0xf bank_mask:0x3
	v_mov_b32_dpp v1, v213 row_shl:8 row_mask:0xf bank_mask:0x3
	v_mov_b32_dpp v2, v214 row_shl:8 row_mask:0xf bank_mask:0x3
	v_mov_b32_dpp v3, v215 row_shl:8 row_mask:0xf bank_mask:0x3
	v_pk_add_f32 v[28:29], v[28:29], v[180:181]
	v_pk_add_f32 v[30:31], v[30:31], v[182:183]
	v_pk_add_f32 v[24:25], v[24:25], v[184:185]
	v_pk_add_f32 v[26:27], v[26:27], v[186:187]
	v_pk_add_f32 v[20:21], v[20:21], v[188:189]
	v_pk_add_f32 v[22:23], v[22:23], v[190:191]
	v_pk_add_f32 v[12:13], v[12:13], v[192:193]
	v_pk_add_f32 v[14:15], v[14:15], v[194:195]
	v_pk_add_f32 v[16:17], v[16:17], v[196:197]
	v_pk_add_f32 v[18:19], v[18:19], v[198:199]
	v_pk_add_f32 v[8:9], v[8:9], v[200:201]
	v_pk_add_f32 v[10:11], v[10:11], v[202:203]
	v_pk_add_f32 v[4:5], v[4:5], v[204:205]
	v_pk_add_f32 v[6:7], v[6:7], v[206:207]
	v_pk_add_f32 v[0:1], v[0:1], v[208:209]
	v_pk_add_f32 v[2:3], v[2:3], v[210:211]
	global_store_dwordx4 v230, v[28:31], s[52:53]
	v_add_u32_e32 v144, v222, v233
	global_store_dwordx4 v144, v[24:27], s[52:53]
	global_store_dwordx4 v230, v[20:23], s[52:53] offset:512
	v_add_u32_e32 v144, v222, v233
	global_store_dwordx4 v144, v[12:15], s[52:53] offset:512
	global_store_dwordx4 v231, v[16:19], s[52:53]
	v_add_u32_e32 v144, v223, v233
	global_store_dwordx4 v144, v[8:11], s[52:53]
	global_store_dwordx4 v231, v[4:7], s[52:53] offset:512
	v_add_u32_e32 v144, v223, v233
	global_store_dwordx4 v144, v[0:3], s[52:53] offset:512
	s_cbranch_vccz .LBB0_1232
	s_waitcnt vmcnt(0)
	s_cmpk_gt_u32 s4, 0xff
	s_cbranch_scc1 .LBB0_1243
	s_barrier

; #define PG8_STAGE(bufoff, gbase, voff) do { _Pragma("unroll") for (int _i = 0; _i < 2; ++_i) \
;         __builtin_amdgcn_global_load_lds((const unsigned*)((const char*)(gbase) + (voff)[_i]), (LAS unsigned*)(lds + (bufoff) + ldsw + _i * 8192), 16, 0, 0); } while (0)
; #define PG8_LDA(dst, b, h) do { _Pragma("unroll") for (int m = 0; m < 4; ++m) _Pragma("unroll") for (int k = 0; k < 2; ++k) dst[m][k] = *(const LAS bf16x8*)(lds + PG8_SA(b, h) + aoff + m * 2048 + k * 1024); } while (0)
; #define PG8_LDB(dst, b, h) do { _Pragma("unroll") for (int n = 0; n < 2; ++n) _Pragma("unroll") for (int k = 0; k < 2; ++k) dst[n][k] = *(const LAS bf16x8*)(lds + PG8_SB(b, h) + boff + n * 2048 + k * 1024); } while (0)
; #define PG8_MMA(ai, bj, At, Bt) do { __builtin_amdgcn_s_setprio(1); _Pragma("unroll") for (int m = 0; m < 4; ++m) _Pragma("unroll") for (int n = 0; n < 2; ++n) _Pragma("unroll") for (int k = 0; k < 2; ++k) \
;         acc[ai][bj][m][n] = __builtin_amdgcn_mfma_f32_16x16x32_bf16(Bt[n][k], At[m][k], acc[ai][bj][m][n], 0, 0, 0); __builtin_amdgcn_s_setprio(0); } while (0)
; #define PG8_WAIT_V(n) asm volatile("s_waitcnt vmcnt(" #n ")" ::: "memory")
; #define PG8_WAIT_L(n) asm volatile("s_waitcnt lgkmcnt(" #n ")" ::: "memory")
; #define PG8_BAR __builtin_amdgcn_s_barrier()
; #define PG8_SCHED __builtin_amdgcn_sched_barrier(0)
; template <class Epi>
; __device__ __forceinline__ void gemm_phase(LAS unsigned char* lds, const Gemm g, const StaticOrder& S, const Epi& E) {
;     ...
;             PG8_LDB(B0, 0, 0); PG8_SCHED; PG8_LDA(At, 0, 0); PG8_STAGE(PG8_SA(1, 1), a1 + hstepA, voffA);
;             PG8_WAIT_L(8); PG8_BAR; PG8_WAIT_L(0); PG8_MMA(0, 0, At, B0); PG8_BAR; PG8_SCHED;
;             PG8_LDB(B1, 0, 1); PG8_STAGE(PG8_SB(0, 0), b2, voffB);
;             PG8_BAR; PG8_WAIT_L(0); PG8_MMA(0, 1, At, B1); PG8_BAR;
;             PG8_LDA(At, 0, 1); PG8_STAGE(PG8_SA(0, 0), a2, voffA);
;             PG8_BAR; PG8_WAIT_L(0); PG8_MMA(1, 0, At, B0); PG8_BAR; PG8_SCHED;
;             PG8_STAGE(PG8_SB(0, 1), b2 + hstepB, voffB);
;             PG8_WAIT_V(6); PG8_BAR; PG8_MMA(1, 1, At, B1); PG8_BAR;
.LBB0_1461:
	ds_read_b128 v[140:143], v149
	ds_read_b128 v[152:155], v149 offset:1024
	ds_read_b128 v[156:159], v149 offset:2048
	ds_read_b128 v[160:163], v149 offset:3072
	s_add_u32 s34, s30, 0x100
	s_addc_u32 s35, s31, 0
	s_cmp_eq_u32 s74, 40
	s_cselect_b32 s39, s13, s35
	s_cselect_b32 s38, s12, s34
	s_cselect_b32 s37, s15, s73
	s_cselect_b32 s36, s14, s72
	v_lshl_add_u64 v[144:145], s[30:31], 0, v[132:133]
	s_add_i32 m0, s8, 0xc000
	ds_read_b128 v[164:167], v150
	ds_read_b128 v[168:171], v150 offset:1024
	ds_read_b128 v[172:175], v150 offset:2048
	ds_read_b128 v[176:179], v150 offset:3072
	ds_read_b128 v[180:183], v150 offset:4096
	ds_read_b128 v[184:187], v150 offset:5120
	ds_read_b128 v[188:191], v150 offset:6144
	ds_read_b128 v[192:195], v150 offset:7168
	global_load_lds_dwordx4 v[144:145], off
	v_lshl_add_u64 v[144:145], s[30:31], 0, v[134:135]
	s_add_i32 m0, s8, 0xe000
	s_nop 0
	global_load_lds_dwordx4 v[144:145], off
	ds_read_b128 v[196:199], v151
	ds_read_b128 v[200:203], v151 offset:1024
	ds_read_b128 v[204:207], v151 offset:2048
	ds_read_b128 v[208:211], v151 offset:3072
	s_waitcnt lgkmcnt(0)
	s_barrier
	s_setprio 1
	v_mfma_f32_16x16x32_bf16 v[124:127], v[140:143], v[164:167], v[124:127]
	v_mfma_f32_16x16x32_bf16 v[120:123], v[156:159], v[164:167], v[120:123]
	v_mfma_f32_16x16x32_bf16 v[112:115], v[140:143], v[172:175], v[112:115]
	v_mfma_f32_16x16x32_bf16 v[104:107], v[156:159], v[172:175], v[104:107]
	v_mfma_f32_16x16x32_bf16 v[92:95], v[140:143], v[180:183], v[92:95]
	v_mfma_f32_16x16x32_bf16 v[88:91], v[156:159], v[180:183], v[88:91]
	v_mfma_f32_16x16x32_bf16 v[80:83], v[140:143], v[188:191], v[80:83]
	v_mfma_f32_16x16x32_bf16 v[72:75], v[156:159], v[188:191], v[72:75]
	v_mfma_f32_16x16x32_bf16 v[124:127], v[152:155], v[168:171], v[124:127]
	v_mfma_f32_16x16x32_bf16 v[120:123], v[160:163], v[168:171], v[120:123]
	v_mfma_f32_16x16x32_bf16 v[112:115], v[152:155], v[176:179], v[112:115]
	v_mfma_f32_16x16x32_bf16 v[104:107], v[160:163], v[176:179], v[104:107]
	v_mfma_f32_16x16x32_bf16 v[92:95], v[152:155], v[184:187], v[92:95]
	v_mfma_f32_16x16x32_bf16 v[88:91], v[160:163], v[184:187], v[88:91]
	v_mfma_f32_16x16x32_bf16 v[80:83], v[152:155], v[192:195], v[80:83]
	v_mfma_f32_16x16x32_bf16 v[72:75], v[160:163], v[192:195], v[72:75]
	v_mfma_f32_16x16x32_bf16 v[116:119], v[196:199], v[164:167], v[116:119]
	v_mfma_f32_16x16x32_bf16 v[108:111], v[204:207], v[164:167], v[108:111]
	v_mfma_f32_16x16x32_bf16 v[100:103], v[196:199], v[172:175], v[100:103]
	v_mfma_f32_16x16x32_bf16 v[96:99], v[204:207], v[172:175], v[96:99]
	v_mfma_f32_16x16x32_bf16 v[84:87], v[196:199], v[180:183], v[84:87]
	v_mfma_f32_16x16x32_bf16 v[76:79], v[204:207], v[180:183], v[76:79]
	v_mfma_f32_16x16x32_bf16 v[68:71], v[196:199], v[188:191], v[68:71]
	v_mfma_f32_16x16x32_bf16 v[64:67], v[204:207], v[188:191], v[64:67]
	v_mfma_f32_16x16x32_bf16 v[116:119], v[200:203], v[168:171], v[116:119]
	v_mfma_f32_16x16x32_bf16 v[108:111], v[208:211], v[168:171], v[108:111]
	v_mfma_f32_16x16x32_bf16 v[100:103], v[200:203], v[176:179], v[100:103]
	v_mfma_f32_16x16x32_bf16 v[96:99], v[208:211], v[176:179], v[96:99]
	v_mfma_f32_16x16x32_bf16 v[84:87], v[200:203], v[184:187], v[84:87]
	v_mfma_f32_16x16x32_bf16 v[76:79], v[208:211], v[184:187], v[76:79]
	v_mfma_f32_16x16x32_bf16 v[68:71], v[200:203], v[192:195], v[68:71]
	v_mfma_f32_16x16x32_bf16 v[64:67], v[208:211], v[192:195], v[64:67]
	s_setprio 0
	s_barrier
	s_nop 1
	ds_read_b128 v[164:167], v150 offset:16384
	ds_read_b128 v[168:171], v150 offset:17408
	ds_read_b128 v[172:175], v150 offset:18432
	ds_read_b128 v[176:179], v150 offset:19456
	ds_read_b128 v[180:183], v150 offset:20480
	ds_read_b128 v[184:187], v150 offset:21504
	ds_read_b128 v[188:191], v150 offset:22528
	ds_read_b128 v[192:195], v150 offset:23552
	s_add_i32 s30, s45, s7
	v_lshl_add_u64 v[144:145], s[36:37], 0, v[128:129]
	s_mov_b32 m0, s30
	s_nop 0
	global_load_lds_dwordx4 v[144:145], off
	v_lshl_add_u64 v[212:213], s[36:37], 0, v[130:131]
	s_add_i32 m0, s30, 0x2000
	s_nop 0
	global_load_lds_dwordx4 v[212:213], off
	s_mov_b32 m0, s8
	v_lshl_add_u64 v[214:215], s[38:39], 0, v[128:129]
	global_load_lds_dwordx4 v[214:215], off
	v_lshl_add_u64 v[216:217], s[38:39], 0, v[130:131]
	s_mov_b32 m0, s9
	s_nop 0
	global_load_lds_dwordx4 v[216:217], off
	s_add_u32 s30, s36, 0xb0000
	s_addc_u32 s31, s37, 0
	s_add_i32 s75, s46, s7
	v_lshl_add_u64 v[254:255], s[30:31], 0, v[128:129]
	s_mov_b32 m0, s75
	s_nop 0
	global_load_lds_dwordx4 v[254:255], off
	v_lshl_add_u64 v[254:255], s[30:31], 0, v[130:131]
	s_add_i32 m0, s75, 0x2000
	s_nop 0
	global_load_lds_dwordx4 v[254:255], off
	s_waitcnt vmcnt(6)
	s_waitcnt lgkmcnt(0)
	s_barrier
; #define PG8_STAGE(bufoff, gbase, voff) do { _Pragma("unroll") for (int _i = 0; _i < 2; ++_i) \
;         __builtin_amdgcn_global_load_lds((const unsigned*)((const char*)(gbase) + (voff)[_i]), (LAS unsigned*)(lds + (bufoff) + ldsw + _i * 8192), 16, 0, 0); } while (0)
; #define PG8_LDA(dst, b, h) do { _Pragma("unroll") for (int m = 0; m < 4; ++m) _Pragma("unroll") for (int k = 0; k < 2; ++k) dst[m][k] = *(const LAS bf16x8*)(lds + PG8_SA(b, h) + aoff + m * 2048 + k * 1024); } while (0)
; #define PG8_LDB(dst, b, h) do { _Pragma("unroll") for (int n = 0; n < 2; ++n) _Pragma("unroll") for (int k = 0; k < 2; ++k) dst[n][k] = *(const LAS bf16x8*)(lds + PG8_SB(b, h) + boff + n * 2048 + k * 1024); } while (0)
; #define PG8_MMA(ai, bj, At, Bt) do { __builtin_amdgcn_s_setprio(1); _Pragma("unroll") for (int m = 0; m < 4; ++m) _Pragma("unroll") for (int n = 0; n < 2; ++n) _Pragma("unroll") for (int k = 0; k < 2; ++k) \
;         acc[ai][bj][m][n] = __builtin_amdgcn_mfma_f32_16x16x32_bf16(Bt[n][k], At[m][k], acc[ai][bj][m][n], 0, 0, 0); __builtin_amdgcn_s_setprio(0); } while (0)
; #define PG8_WAIT_V(n) asm volatile("s_waitcnt vmcnt(" #n ")" ::: "memory")
; #define PG8_WAIT_L(n) asm volatile("s_waitcnt lgkmcnt(" #n ")" ::: "memory")
; #define PG8_BAR __builtin_amdgcn_s_barrier()
; #define PG8_SCHED __builtin_amdgcn_sched_barrier(0)
; template <class Epi>
; __device__ __forceinline__ void gemm_phase(LAS unsigned char* lds, const Gemm g, const StaticOrder& S, const Epi& E) {
;     ...
;             PG8_BAR; PG8_WAIT_L(0); PG8_MMA(1, 0, At, B0); PG8_BAR; PG8_SCHED;
;             PG8_STAGE(PG8_SB(0, 1), b2 + hstepB, voffB);
;             PG8_WAIT_V(6); PG8_BAR; PG8_MMA(1, 1, At, B1); PG8_BAR;
;             PG8_LDB(B0, 1, 0); PG8_SCHED; PG8_LDA(At, 1, 0); PG8_STAGE(PG8_SA(0, 1), a2 + hstepA, voffA);
;             PG8_WAIT_L(8); PG8_BAR; PG8_WAIT_L(0); PG8_MMA(0, 0, At, B0); PG8_BAR; PG8_SCHED;
;             PG8_LDB(B1, 1, 1); PG8_STAGE(PG8_SB(1, 0), b3, voffB);
;             PG8_BAR; PG8_WAIT_L(0); PG8_MMA(0, 1, At, B1); PG8_BAR;
	s_setprio 1
	v_mfma_f32_16x16x32_bf16 v[60:63], v[140:143], v[164:167], v[60:63]
	v_mfma_f32_16x16x32_bf16 v[56:59], v[156:159], v[164:167], v[56:59]
	v_mfma_f32_16x16x32_bf16 v[48:51], v[140:143], v[172:175], v[48:51]
	v_mfma_f32_16x16x32_bf16 v[40:43], v[156:159], v[172:175], v[40:43]
	v_mfma_f32_16x16x32_bf16 v[28:31], v[140:143], v[180:183], v[28:31]
	v_mfma_f32_16x16x32_bf16 v[24:27], v[156:159], v[180:183], v[24:27]
	v_mfma_f32_16x16x32_bf16 v[16:19], v[140:143], v[188:191], v[16:19]
	v_mfma_f32_16x16x32_bf16 v[8:11], v[156:159], v[188:191], v[8:11]
	v_mfma_f32_16x16x32_bf16 v[60:63], v[152:155], v[168:171], v[60:63]
	v_mfma_f32_16x16x32_bf16 v[56:59], v[160:163], v[168:171], v[56:59]
	v_mfma_f32_16x16x32_bf16 v[48:51], v[152:155], v[176:179], v[48:51]
	v_mfma_f32_16x16x32_bf16 v[40:43], v[160:163], v[176:179], v[40:43]
	v_mfma_f32_16x16x32_bf16 v[28:31], v[152:155], v[184:187], v[28:31]
	v_mfma_f32_16x16x32_bf16 v[24:27], v[160:163], v[184:187], v[24:27]
	v_mfma_f32_16x16x32_bf16 v[16:19], v[152:155], v[192:195], v[16:19]
	v_mfma_f32_16x16x32_bf16 v[8:11], v[160:163], v[192:195], v[8:11]
	v_mfma_f32_16x16x32_bf16 v[52:55], v[196:199], v[164:167], v[52:55]
	v_mfma_f32_16x16x32_bf16 v[44:47], v[204:207], v[164:167], v[44:47]
	v_mfma_f32_16x16x32_bf16 v[36:39], v[196:199], v[172:175], v[36:39]
	v_mfma_f32_16x16x32_bf16 v[32:35], v[204:207], v[172:175], v[32:35]
	v_mfma_f32_16x16x32_bf16 v[20:23], v[196:199], v[180:183], v[20:23]
	v_mfma_f32_16x16x32_bf16 v[12:15], v[204:207], v[180:183], v[12:15]
	v_mfma_f32_16x16x32_bf16 v[4:7], v[196:199], v[188:191], v[4:7]
	v_mfma_f32_16x16x32_bf16 v[0:3], v[204:207], v[188:191], v[0:3]
	v_mfma_f32_16x16x32_bf16 v[52:55], v[200:203], v[168:171], v[52:55]
	v_mfma_f32_16x16x32_bf16 v[44:47], v[208:211], v[168:171], v[44:47]
	v_mfma_f32_16x16x32_bf16 v[36:39], v[200:203], v[176:179], v[36:39]
	v_mfma_f32_16x16x32_bf16 v[32:35], v[208:211], v[176:179], v[32:35]
	v_mfma_f32_16x16x32_bf16 v[20:23], v[200:203], v[184:187], v[20:23]
	v_mfma_f32_16x16x32_bf16 v[12:15], v[208:211], v[184:187], v[12:15]
	v_mfma_f32_16x16x32_bf16 v[4:7], v[200:203], v[192:195], v[4:7]
	v_mfma_f32_16x16x32_bf16 v[0:3], v[208:211], v[192:195], v[0:3]
	s_setprio 0
	s_add_i32 s75, 0, 0x18000
	v_add_u32_e32 v160, s75, v147
	s_barrier
	ds_read_b128 v[140:143], v160
	ds_read_b128 v[152:155], v160 offset:1024
	ds_read_b128 v[156:159], v160 offset:2048
	ds_read_b128 v[160:163], v160 offset:3072
	s_add_u32 s30, s38, 0xb0000
	s_addc_u32 s31, s39, 0
	s_mov_b32 m0, s40
	v_lshl_add_u64 v[196:197], s[30:31], 0, v[128:129]
	ds_read_b128 v[164:167], v150 offset:32768
	ds_read_b128 v[168:171], v150 offset:33792
	ds_read_b128 v[172:175], v150 offset:34816
	ds_read_b128 v[176:179], v150 offset:35840
	ds_read_b128 v[180:183], v150 offset:36864
	ds_read_b128 v[184:187], v150 offset:37888
	ds_read_b128 v[188:191], v150 offset:38912
	ds_read_b128 v[192:195], v150 offset:39936
	global_load_lds_dwordx4 v[196:197], off
	v_lshl_add_u64 v[196:197], s[30:31], 0, v[130:131]
	s_mov_b32 m0, s41
	s_nop 0
	global_load_lds_dwordx4 v[196:197], off
	s_add_i32 s38, 0, 0x1c000
	v_add_u32_e32 v208, s38, v147
	ds_read_b128 v[196:199], v208
	ds_read_b128 v[200:203], v208 offset:1024
	ds_read_b128 v[204:207], v208 offset:2048
	ds_read_b128 v[208:211], v208 offset:3072
	s_waitcnt lgkmcnt(0)
	s_barrier
	s_setprio 1
	v_mfma_f32_16x16x32_bf16 v[124:127], v[140:143], v[164:167], v[124:127]
	v_mfma_f32_16x16x32_bf16 v[120:123], v[156:159], v[164:167], v[120:123]
	v_mfma_f32_16x16x32_bf16 v[112:115], v[140:143], v[172:175], v[112:115]
	v_mfma_f32_16x16x32_bf16 v[104:107], v[156:159], v[172:175], v[104:107]
	v_mfma_f32_16x16x32_bf16 v[92:95], v[140:143], v[180:183], v[92:95]
	v_mfma_f32_16x16x32_bf16 v[88:91], v[156:159], v[180:183], v[88:91]
	v_mfma_f32_16x16x32_bf16 v[80:83], v[140:143], v[188:191], v[80:83]
	v_mfma_f32_16x16x32_bf16 v[72:75], v[156:159], v[188:191], v[72:75]
	v_mfma_f32_16x16x32_bf16 v[124:127], v[152:155], v[168:171], v[124:127]
	v_mfma_f32_16x16x32_bf16 v[120:123], v[160:163], v[168:171], v[120:123]
	v_mfma_f32_16x16x32_bf16 v[112:115], v[152:155], v[176:179], v[112:115]
	v_mfma_f32_16x16x32_bf16 v[104:107], v[160:163], v[176:179], v[104:107]
	v_mfma_f32_16x16x32_bf16 v[92:95], v[152:155], v[184:187], v[92:95]
	v_mfma_f32_16x16x32_bf16 v[88:91], v[160:163], v[184:187], v[88:91]
	v_mfma_f32_16x16x32_bf16 v[80:83], v[152:155], v[192:195], v[80:83]
	v_mfma_f32_16x16x32_bf16 v[72:75], v[160:163], v[192:195], v[72:75]
	v_mfma_f32_16x16x32_bf16 v[116:119], v[196:199], v[164:167], v[116:119]
	v_mfma_f32_16x16x32_bf16 v[108:111], v[204:207], v[164:167], v[108:111]
	v_mfma_f32_16x16x32_bf16 v[100:103], v[196:199], v[172:175], v[100:103]
	v_mfma_f32_16x16x32_bf16 v[96:99], v[204:207], v[172:175], v[96:99]
	v_mfma_f32_16x16x32_bf16 v[84:87], v[196:199], v[180:183], v[84:87]
	v_mfma_f32_16x16x32_bf16 v[76:79], v[204:207], v[180:183], v[76:79]
	v_mfma_f32_16x16x32_bf16 v[68:71], v[196:199], v[188:191], v[68:71]
	v_mfma_f32_16x16x32_bf16 v[64:67], v[204:207], v[188:191], v[64:67]
	v_mfma_f32_16x16x32_bf16 v[116:119], v[200:203], v[168:171], v[116:119]
	v_mfma_f32_16x16x32_bf16 v[108:111], v[208:211], v[168:171], v[108:111]
	v_mfma_f32_16x16x32_bf16 v[100:103], v[200:203], v[176:179], v[100:103]
	v_mfma_f32_16x16x32_bf16 v[96:99], v[208:211], v[176:179], v[96:99]
	v_mfma_f32_16x16x32_bf16 v[84:87], v[200:203], v[184:187], v[84:87]
	v_mfma_f32_16x16x32_bf16 v[76:79], v[208:211], v[184:187], v[76:79]
	v_mfma_f32_16x16x32_bf16 v[68:71], v[200:203], v[192:195], v[68:71]
	v_mfma_f32_16x16x32_bf16 v[64:67], v[208:211], v[192:195], v[64:67]
	s_setprio 0
	s_barrier
; #define PG8_STAGE(bufoff, gbase, voff) do { _Pragma("unroll") for (int _i = 0; _i < 2; ++_i) \
;         __builtin_amdgcn_global_load_lds((const unsigned*)((const char*)(gbase) + (voff)[_i]), (LAS unsigned*)(lds + (bufoff) + ldsw + _i * 8192), 16, 0, 0); } while (0)
; #define PG8_LDA(dst, b, h) do { _Pragma("unroll") for (int m = 0; m < 4; ++m) _Pragma("unroll") for (int k = 0; k < 2; ++k) dst[m][k] = *(const LAS bf16x8*)(lds + PG8_SA(b, h) + aoff + m * 2048 + k * 1024); } while (0)
; #define PG8_WAIT_V(n) asm volatile("s_waitcnt vmcnt(" #n ")" ::: "memory")
; #define PG8_WAIT_L(n) asm volatile("s_waitcnt lgkmcnt(" #n ")" ::: "memory")
; #define PG8_BAR __builtin_amdgcn_s_barrier()
; #define PG8_SCHED __builtin_amdgcn_sched_barrier(0)
; template <class Epi>
; __device__ __forceinline__ void gemm_phase(LAS unsigned char* lds, const Gemm g, const StaticOrder& S, const Epi& E) {
;     ...
;             PG8_BAR; PG8_WAIT_L(0); PG8_MMA(0, 1, At, B1); PG8_BAR;
;             PG8_LDA(At, 1, 1); PG8_STAGE(PG8_SA(1, 0), a3, voffA);
;             PG8_BAR; PG8_WAIT_L(0); PG8_MMA(1, 0, At, B0); PG8_BAR; PG8_SCHED;
;             PG8_STAGE(PG8_SB(1, 1), b3 + hstepB, voffB);
;             PG8_WAIT_V(6); PG8_BAR; PG8_MMA(1, 1, At, B1); PG8_BAR;
;         }
;     __device__ __forceinline__ void operator()(AccRef acc, const Unit& u, int wr, int wc, int fr, int fq) const {
;         const int row0 = u.pm * 256 + wr * 64 + fr, col0 = u.pn * 256 + wc * 32 + 4 * fq;
;         f32x4 sv[2][2], bv[2][2];
; #pragma unroll
;         for (int bj = 0; bj < 2; ++bj)
; #pragma unroll
;             for (int n = 0; n < 2; ++n) {
;                 sv[bj][n] = scale ? *(const f32x4*)(scale + col0 + bj * 128 + n * 16) : (f32x4){1.f, 1.f, 1.f, 1.f};
;                 bv[bj][n] = bias ? *(const f32x4*)(bias + col0 + bj * 128 + n * 16) : (f32x4){0.f, 0.f, 0.f, 0.f}; }
; #pragma unroll
;         for (int ai = 0; ai < 2; ++ai)
; #pragma unroll
;             for (int mh = 0; mh < 2; ++mh) {
;                 f32x4 bs[2][2][2];
; #pragma unroll
;                 for (int m = 0; m < 2; ++m)
; #pragma unroll
;                     for (int bj = 0; bj < 2; ++bj)
; #pragma unroll
;                         for (int n = 0; n < 2; ++n) bs[m][bj][n] = *(const f32x4*)(base + (size_t)(row0 + ai * 128 + (2 * mh + m) * 16) * D + col0 + bj * 128 + n * 16);
	s_nop 1
	ds_read_b128 v[164:167], v150 offset:49152
	ds_read_b128 v[168:171], v150 offset:50176
	ds_read_b128 v[172:175], v150 offset:51200
	ds_read_b128 v[176:179], v150 offset:52224
	ds_read_b128 v[180:183], v150 offset:53248
	ds_read_b128 v[184:187], v150 offset:54272
	ds_read_b128 v[188:191], v150 offset:55296
	ds_read_b128 v[192:195], v150 offset:56320
	s_add_i32 s30, s75, s7
	v_lshl_add_u64 v[254:255], v[144:145], 0, s[22:23]
	s_mov_b32 m0, s30
	s_nop 0
	global_load_lds_dwordx4 v[254:255], off
	v_lshl_add_u64 v[254:255], v[212:213], 0, s[22:23]
	s_add_i32 m0, s30, 0x2000
	s_nop 0
	global_load_lds_dwordx4 v[254:255], off
	s_mov_b32 m0, s43
	v_lshl_add_u64 v[254:255], v[214:215], 0, s[22:23]
	global_load_lds_dwordx4 v[254:255], off
	v_lshl_add_u64 v[144:145], v[216:217], 0, s[22:23]
	s_mov_b32 m0, s44
	s_nop 0
	global_load_lds_dwordx4 v[144:145], off
	s_add_u32 s30, s36, 0xb0080
	s_addc_u32 s31, s37, 0
	s_add_i32 s36, s38, s7
	v_lshl_add_u64 v[254:255], s[30:31], 0, v[128:129]
	s_mov_b32 m0, s36
	s_nop 0
	global_load_lds_dwordx4 v[254:255], off
	v_lshl_add_u64 v[254:255], s[30:31], 0, v[130:131]
	s_add_i32 m0, s36, 0x2000
	s_nop 0
	global_load_lds_dwordx4 v[254:255], off
	s_waitcnt vmcnt(6)
	s_waitcnt lgkmcnt(0)
	s_barrier
	s_setprio 1
	v_mfma_f32_16x16x32_bf16 v[60:63], v[140:143], v[164:167], v[60:63]
	v_mfma_f32_16x16x32_bf16 v[56:59], v[156:159], v[164:167], v[56:59]
	v_mfma_f32_16x16x32_bf16 v[48:51], v[140:143], v[172:175], v[48:51]
	v_mfma_f32_16x16x32_bf16 v[40:43], v[156:159], v[172:175], v[40:43]
	v_mfma_f32_16x16x32_bf16 v[28:31], v[140:143], v[180:183], v[28:31]
	v_mfma_f32_16x16x32_bf16 v[24:27], v[156:159], v[180:183], v[24:27]
	v_mfma_f32_16x16x32_bf16 v[16:19], v[140:143], v[188:191], v[16:19]
	v_mfma_f32_16x16x32_bf16 v[8:11], v[156:159], v[188:191], v[8:11]
	v_mfma_f32_16x16x32_bf16 v[60:63], v[152:155], v[168:171], v[60:63]
	v_mfma_f32_16x16x32_bf16 v[56:59], v[160:163], v[168:171], v[56:59]
	v_mfma_f32_16x16x32_bf16 v[48:51], v[152:155], v[176:179], v[48:51]
	v_mfma_f32_16x16x32_bf16 v[40:43], v[160:163], v[176:179], v[40:43]
	v_mfma_f32_16x16x32_bf16 v[28:31], v[152:155], v[184:187], v[28:31]
	v_mfma_f32_16x16x32_bf16 v[24:27], v[160:163], v[184:187], v[24:27]
	v_mfma_f32_16x16x32_bf16 v[16:19], v[152:155], v[192:195], v[16:19]
	v_mfma_f32_16x16x32_bf16 v[8:11], v[160:163], v[192:195], v[8:11]
	v_mfma_f32_16x16x32_bf16 v[52:55], v[196:199], v[164:167], v[52:55]
	v_mfma_f32_16x16x32_bf16 v[44:47], v[204:207], v[164:167], v[44:47]
	v_mfma_f32_16x16x32_bf16 v[36:39], v[196:199], v[172:175], v[36:39]
	v_mfma_f32_16x16x32_bf16 v[32:35], v[204:207], v[172:175], v[32:35]
	v_mfma_f32_16x16x32_bf16 v[20:23], v[196:199], v[180:183], v[20:23]
	v_mfma_f32_16x16x32_bf16 v[12:15], v[204:207], v[180:183], v[12:15]
	v_mfma_f32_16x16x32_bf16 v[4:7], v[196:199], v[188:191], v[4:7]
	v_mfma_f32_16x16x32_bf16 v[0:3], v[204:207], v[188:191], v[0:3]
	v_mfma_f32_16x16x32_bf16 v[52:55], v[200:203], v[168:171], v[52:55]
	v_mfma_f32_16x16x32_bf16 v[44:47], v[208:211], v[168:171], v[44:47]
	v_mfma_f32_16x16x32_bf16 v[36:39], v[200:203], v[176:179], v[36:39]
	v_mfma_f32_16x16x32_bf16 v[32:35], v[208:211], v[176:179], v[32:35]
	v_mfma_f32_16x16x32_bf16 v[20:23], v[200:203], v[184:187], v[20:23]
	v_mfma_f32_16x16x32_bf16 v[12:15], v[208:211], v[184:187], v[12:15]
	v_mfma_f32_16x16x32_bf16 v[4:7], v[200:203], v[192:195], v[4:7]
	v_mfma_f32_16x16x32_bf16 v[0:3], v[208:211], v[192:195], v[0:3]
	s_setprio 0
	s_add_i32 s74, s74, 2
	s_add_u32 s72, s72, 0x100
	s_addc_u32 s73, s73, 0
	s_cmp_gt_u32 s74, 41
	s_mov_b64 s[30:31], s[34:35]
	s_barrier
	s_cbranch_scc0 .LBB0_1461
	v_lshl_or_b32 v144, s49, 8, v148
	v_lshl_add_u32 v145, s63, 8, v146
	v_lshlrev_b32_e32 v144, 2, v144
	v_lshl_add_u32 v145, v145, 12, v144
	v_add_u32_e32 v216, 0x10000, v145
	v_add_u32_e32 v217, 0x20000, v145
	v_add_u32_e32 v218, 0x30000, v145
	v_add_u32_e32 v220, 0x80000, v145
	v_add_u32_e32 v221, 0x90000, v145
	v_add_u32_e32 v222, 0xa0000, v145
	v_add_u32_e32 v223, 0xb0000, v145
	v_and_b32_e32 v235, 8, v146
	v_cmp_ne_u32_e32 vcc, 0, v235
	v_mov_b32_e32 v232, 0xffff8040
	s_nop 0
	v_cndmask_b32_e32 v232, 0, v232, vcc
	v_mov_b32_e32 v233, 64
	v_mov_b32_e32 v235, 0x8000
	v_cndmask_b32_e32 v233, v235, v233, vcc
	v_add_u32_e32 v224, v145, v232
	v_add_u32_e32 v225, v216, v232
	v_add_u32_e32 v226, v217, v232
	v_add_u32_e32 v227, v218, v232
	v_add_u32_e32 v228, v220, v232
	v_add_u32_e32 v229, v221, v232
	v_add_u32_e32 v230, v222, v232
	v_add_u32_e32 v231, v223, v232
	s_and_b64 vcc, exec, s[10:11]
	s_mov_b32 s49, s47
	s_mov_b32 s63, s48
	s_mov_b64 s[34:35], s[14:15]
	s_mov_b64 s[30:31], s[12:13]
	global_load_dwordx4 v[140:143], v224, s[52:53]
	v_add_u32_e32 v144, v145, v233
	global_load_dwordx4 v[152:155], v144, s[52:53]
	global_load_dwordx4 v[156:159], v224, s[52:53] offset:512
	v_add_u32_e32 v144, v145, v233
	global_load_dwordx4 v[160:163], v144, s[52:53] offset:512
	global_load_dwordx4 v[164:167], v225, s[52:53]
	v_add_u32_e32 v144, v216, v233
	global_load_dwordx4 v[168:171], v144, s[52:53]
	global_load_dwordx4 v[172:175], v225, s[52:53] offset:512
	v_add_u32_e32 v144, v216, v233
	global_load_dwordx4 v[176:179], v144, s[52:53] offset:512
	global_load_dwordx4 v[180:183], v226, s[52:53]
	v_add_u32_e32 v144, v217, v233
	global_load_dwordx4 v[184:187], v144, s[52:53]
	global_load_dwordx4 v[188:191], v226, s[52:53] offset:512
	v_add_u32_e32 v144, v217, v233
	global_load_dwordx4 v[192:195], v144, s[52:53] offset:512
	global_load_dwordx4 v[196:199], v227, s[52:53]
	v_add_u32_e32 v144, v218, v233
	global_load_dwordx4 v[200:203], v144, s[52:53]
	global_load_dwordx4 v[204:207], v227, s[52:53] offset:512
	v_add_u32_e32 v144, v218, v233
	global_load_dwordx4 v[208:211], v144, s[52:53] offset:512
	s_barrier
;     __device__ __forceinline__ void operator()(AccRef acc, const Unit& u, int wr, int wc, int fr, int fq) const {
;     ...
;                         for (int n = 0; n < 2; ++n) bs[m][bj][n] = *(const f32x4*)(base + (size_t)(row0 + ai * 128 + (2 * mh + m) * 16) * D + col0 + bj * 128 + n * 16);
; #pragma unroll
;                 for (int m = 0; m < 2; ++m)
; #pragma unroll
;                     for (int bj = 0; bj < 2; ++bj)
; #pragma unroll
;                         for (int n = 0; n < 2; ++n) *(f32x4*)(out + (size_t)(row0 + ai * 128 + (2 * mh + m) * 16) * D + col0 + bj * 128 + n * 16) = bs[m][bj][n] + sv[bj][n] * (acc[ai][bj][2 * mh + m][n] + bv[bj][n]);
	v_pk_add_f32 v[124:125], v[124:125], 0 op_sel_hi:[1,0]
	v_pk_add_f32 v[126:127], v[126:127], 0 op_sel_hi:[1,0]
	v_pk_add_f32 v[120:121], v[120:121], 0 op_sel_hi:[1,0]
	v_pk_add_f32 v[122:123], v[122:123], 0 op_sel_hi:[1,0]
	v_pk_add_f32 v[116:117], v[116:117], 0 op_sel_hi:[1,0]
	v_pk_add_f32 v[118:119], v[118:119], 0 op_sel_hi:[1,0]
	v_pk_add_f32 v[108:109], v[108:109], 0 op_sel_hi:[1,0]
	v_pk_add_f32 v[110:111], v[110:111], 0 op_sel_hi:[1,0]
	v_pk_add_f32 v[112:113], v[112:113], 0 op_sel_hi:[1,0]
	v_pk_add_f32 v[114:115], v[114:115], 0 op_sel_hi:[1,0]
	v_pk_add_f32 v[104:105], v[104:105], 0 op_sel_hi:[1,0]
	v_pk_add_f32 v[106:107], v[106:107], 0 op_sel_hi:[1,0]
	v_pk_add_f32 v[100:101], v[100:101], 0 op_sel_hi:[1,0]
	v_pk_add_f32 v[102:103], v[102:103], 0 op_sel_hi:[1,0]
	v_pk_add_f32 v[96:97], v[96:97], 0 op_sel_hi:[1,0]
	v_pk_add_f32 v[98:99], v[98:99], 0 op_sel_hi:[1,0]
	v_pk_add_f32 v[92:93], v[92:93], 0 op_sel_hi:[1,0]
	v_pk_add_f32 v[94:95], v[94:95], 0 op_sel_hi:[1,0]
	v_pk_add_f32 v[88:89], v[88:89], 0 op_sel_hi:[1,0]
	v_pk_add_f32 v[90:91], v[90:91], 0 op_sel_hi:[1,0]
	v_pk_add_f32 v[84:85], v[84:85], 0 op_sel_hi:[1,0]
	v_pk_add_f32 v[86:87], v[86:87], 0 op_sel_hi:[1,0]
	v_pk_add_f32 v[76:77], v[76:77], 0 op_sel_hi:[1,0]
	v_pk_add_f32 v[78:79], v[78:79], 0 op_sel_hi:[1,0]
	v_pk_add_f32 v[80:81], v[80:81], 0 op_sel_hi:[1,0]
	v_pk_add_f32 v[82:83], v[82:83], 0 op_sel_hi:[1,0]
	v_pk_add_f32 v[72:73], v[72:73], 0 op_sel_hi:[1,0]
	v_pk_add_f32 v[74:75], v[74:75], 0 op_sel_hi:[1,0]
	v_pk_add_f32 v[68:69], v[68:69], 0 op_sel_hi:[1,0]
	v_pk_add_f32 v[70:71], v[70:71], 0 op_sel_hi:[1,0]
	v_pk_add_f32 v[64:65], v[64:65], 0 op_sel_hi:[1,0]
	v_pk_add_f32 v[66:67], v[66:67], 0 op_sel_hi:[1,0]
	v_pk_add_f32 v[60:61], v[60:61], 0 op_sel_hi:[1,0]
	v_pk_add_f32 v[62:63], v[62:63], 0 op_sel_hi:[1,0]
	v_pk_add_f32 v[56:57], v[56:57], 0 op_sel_hi:[1,0]
	v_pk_add_f32 v[58:59], v[58:59], 0 op_sel_hi:[1,0]
	v_pk_add_f32 v[52:53], v[52:53], 0 op_sel_hi:[1,0]
	v_pk_add_f32 v[54:55], v[54:55], 0 op_sel_hi:[1,0]
	v_pk_add_f32 v[44:45], v[44:45], 0 op_sel_hi:[1,0]
	v_pk_add_f32 v[46:47], v[46:47], 0 op_sel_hi:[1,0]
	v_pk_add_f32 v[48:49], v[48:49], 0 op_sel_hi:[1,0]
	v_pk_add_f32 v[50:51], v[50:51], 0 op_sel_hi:[1,0]
	v_pk_add_f32 v[40:41], v[40:41], 0 op_sel_hi:[1,0]
	v_pk_add_f32 v[42:43], v[42:43], 0 op_sel_hi:[1,0]
	v_pk_add_f32 v[36:37], v[36:37], 0 op_sel_hi:[1,0]
	v_pk_add_f32 v[38:39], v[38:39], 0 op_sel_hi:[1,0]
	v_pk_add_f32 v[32:33], v[32:33], 0 op_sel_hi:[1,0]
	v_pk_add_f32 v[34:35], v[34:35], 0 op_sel_hi:[1,0]
	v_pk_add_f32 v[28:29], v[28:29], 0 op_sel_hi:[1,0]
	v_pk_add_f32 v[30:31], v[30:31], 0 op_sel_hi:[1,0]
	v_pk_add_f32 v[24:25], v[24:25], 0 op_sel_hi:[1,0]
	v_pk_add_f32 v[26:27], v[26:27], 0 op_sel_hi:[1,0]
	v_pk_add_f32 v[20:21], v[20:21], 0 op_sel_hi:[1,0]
	v_pk_add_f32 v[22:23], v[22:23], 0 op_sel_hi:[1,0]
	v_pk_add_f32 v[12:13], v[12:13], 0 op_sel_hi:[1,0]
	v_pk_add_f32 v[14:15], v[14:15], 0 op_sel_hi:[1,0]
	v_pk_add_f32 v[16:17], v[16:17], 0 op_sel_hi:[1,0]
	v_pk_add_f32 v[18:19], v[18:19], 0 op_sel_hi:[1,0]
	v_pk_add_f32 v[8:9], v[8:9], 0 op_sel_hi:[1,0]
	v_pk_add_f32 v[10:11], v[10:11], 0 op_sel_hi:[1,0]
	v_pk_add_f32 v[4:5], v[4:5], 0 op_sel_hi:[1,0]
	v_pk_add_f32 v[6:7], v[6:7], 0 op_sel_hi:[1,0]
	v_pk_add_f32 v[0:1], v[0:1], 0 op_sel_hi:[1,0]
	v_pk_add_f32 v[2:3], v[2:3], 0 op_sel_hi:[1,0]
	s_waitcnt vmcnt(8)
	v_mov_b32_e32 v212, v124
	v_mov_b32_e32 v213, v125
	v_mov_b32_e32 v214, v126
	v_mov_b32_e32 v215, v127
	s_nop 0
	v_mov_b32_dpp v124, v120 row_shr:8 row_mask:0xf bank_mask:0xc
	v_mov_b32_dpp v125, v121 row_shr:8 row_mask:0xf bank_mask:0xc
	v_mov_b32_dpp v126, v122 row_shr:8 row_mask:0xf bank_mask:0xc
	v_mov_b32_dpp v127, v123 row_shr:8 row_mask:0xf bank_mask:0xc
	v_mov_b32_dpp v120, v212 row_shl:8 row_mask:0xf bank_mask:0x3
	v_mov_b32_dpp v121, v213 row_shl:8 row_mask:0xf bank_mask:0x3
	v_mov_b32_dpp v122, v214 row_shl:8 row_mask:0xf bank_mask:0x3
	v_mov_b32_dpp v123, v215 row_shl:8 row_mask:0xf bank_mask:0x3
	v_mov_b32_e32 v212, v116
	v_mov_b32_e32 v213, v117
	v_mov_b32_e32 v214, v118
	v_mov_b32_e32 v215, v119
	s_nop 0
	v_mov_b32_dpp v116, v108 row_shr:8 row_mask:0xf bank_mask:0xc
	v_mov_b32_dpp v117, v109 row_shr:8 row_mask:0xf bank_mask:0xc
	v_mov_b32_dpp v118, v110 row_shr:8 row_mask:0xf bank_mask:0xc
	v_mov_b32_dpp v119, v111 row_shr:8 row_mask:0xf bank_mask:0xc
	v_mov_b32_dpp v108, v212 row_shl:8 row_mask:0xf bank_mask:0x3
	v_mov_b32_dpp v109, v213 row_shl:8 row_mask:0xf bank_mask:0x3
	v_mov_b32_dpp v110, v214 row_shl:8 row_mask:0xf bank_mask:0x3
	v_mov_b32_dpp v111, v215 row_shl:8 row_mask:0xf bank_mask:0x3
	v_mov_b32_e32 v212, v112
	v_mov_b32_e32 v213, v113
	v_mov_b32_e32 v214, v114
	v_mov_b32_e32 v215, v115
	s_nop 0
	v_mov_b32_dpp v112, v104 row_shr:8 row_mask:0xf bank_mask:0xc
	v_mov_b32_dpp v113, v105 row_shr:8 row_mask:0xf bank_mask:0xc
	v_mov_b32_dpp v114, v106 row_shr:8 row_mask:0xf bank_mask:0xc
	v_mov_b32_dpp v115, v107 row_shr:8 row_mask:0xf bank_mask:0xc
	v_mov_b32_dpp v104, v212 row_shl:8 row_mask:0xf bank_mask:0x3
	v_mov_b32_dpp v105, v213 row_shl:8 row_mask:0xf bank_mask:0x3
	v_mov_b32_dpp v106, v214 row_shl:8 row_mask:0xf bank_mask:0x3
	v_mov_b32_dpp v107, v215 row_shl:8 row_mask:0xf bank_mask:0x3
	v_mov_b32_e32 v212, v100
	v_mov_b32_e32 v213, v101
	v_mov_b32_e32 v214, v102
	v_mov_b32_e32 v215, v103
	s_nop 0
	v_mov_b32_dpp v100, v96 row_shr:8 row_mask:0xf bank_mask:0xc
	v_mov_b32_dpp v101, v97 row_shr:8 row_mask:0xf bank_mask:0xc
	v_mov_b32_dpp v102, v98 row_shr:8 row_mask:0xf bank_mask:0xc
	v_mov_b32_dpp v103, v99 row_shr:8 row_mask:0xf bank_mask:0xc
	v_mov_b32_dpp v96, v212 row_shl:8 row_mask:0xf bank_mask:0x3
;     __device__ __forceinline__ void operator()(AccRef acc, const Unit& u, int wr, int wc, int fr, int fq) const {
;     ...
;                         for (int n = 0; n < 2; ++n) bs[m][bj][n] = *(const f32x4*)(base + (size_t)(row0 + ai * 128 + (2 * mh + m) * 16) * D + col0 + bj * 128 + n * 16);
; #pragma unroll
;                 for (int m = 0; m < 2; ++m)
; #pragma unroll
;                     for (int bj = 0; bj < 2; ++bj)
; #pragma unroll
;                         for (int n = 0; n < 2; ++n) *(f32x4*)(out + (size_t)(row0 + ai * 128 + (2 * mh + m) * 16) * D + col0 + bj * 128 + n * 16) = bs[m][bj][n] + sv[bj][n] * (acc[ai][bj][2 * mh + m][n] + bv[bj][n]);
;                 asm volatile("" ::: "memory"); }
	v_mov_b32_dpp v97, v213 row_shl:8 row_mask:0xf bank_mask:0x3
	v_mov_b32_dpp v98, v214 row_shl:8 row_mask:0xf bank_mask:0x3
	v_mov_b32_dpp v99, v215 row_shl:8 row_mask:0xf bank_mask:0x3
	v_pk_add_f32 v[124:125], v[124:125], v[140:141]
	v_pk_add_f32 v[126:127], v[126:127], v[142:143]
	v_pk_add_f32 v[120:121], v[120:121], v[152:153]
	v_pk_add_f32 v[122:123], v[122:123], v[154:155]
	v_pk_add_f32 v[116:117], v[116:117], v[156:157]
	v_pk_add_f32 v[118:119], v[118:119], v[158:159]
	v_pk_add_f32 v[108:109], v[108:109], v[160:161]
	v_pk_add_f32 v[110:111], v[110:111], v[162:163]
	v_pk_add_f32 v[112:113], v[112:113], v[164:165]
	v_pk_add_f32 v[114:115], v[114:115], v[166:167]
	v_pk_add_f32 v[104:105], v[104:105], v[168:169]
	v_pk_add_f32 v[106:107], v[106:107], v[170:171]
	v_pk_add_f32 v[100:101], v[100:101], v[172:173]
	v_pk_add_f32 v[102:103], v[102:103], v[174:175]
	v_pk_add_f32 v[96:97], v[96:97], v[176:177]
	v_pk_add_f32 v[98:99], v[98:99], v[178:179]
	global_store_dwordx4 v224, v[124:127], s[52:53]
	v_add_u32_e32 v144, v145, v233
	global_store_dwordx4 v144, v[120:123], s[52:53]
	global_store_dwordx4 v224, v[116:119], s[52:53] offset:512
	v_add_u32_e32 v144, v145, v233
	global_store_dwordx4 v144, v[108:111], s[52:53] offset:512
	global_store_dwordx4 v225, v[112:115], s[52:53]
	v_add_u32_e32 v144, v216, v233
	global_store_dwordx4 v144, v[104:107], s[52:53]
	global_store_dwordx4 v225, v[100:103], s[52:53] offset:512
	v_add_u32_e32 v144, v216, v233
	global_store_dwordx4 v144, v[96:99], s[52:53] offset:512
	global_load_dwordx4 v[140:143], v228, s[52:53]
	v_add_u32_e32 v144, v220, v233
	global_load_dwordx4 v[152:155], v144, s[52:53]
	global_load_dwordx4 v[156:159], v228, s[52:53] offset:512
	v_add_u32_e32 v144, v220, v233
	global_load_dwordx4 v[160:163], v144, s[52:53] offset:512
	global_load_dwordx4 v[164:167], v229, s[52:53]
	v_add_u32_e32 v144, v221, v233
	global_load_dwordx4 v[168:171], v144, s[52:53]
	global_load_dwordx4 v[172:175], v229, s[52:53] offset:512
	v_add_u32_e32 v144, v221, v233
	global_load_dwordx4 v[176:179], v144, s[52:53] offset:512
	s_barrier
	s_waitcnt vmcnt(16)
	v_mov_b32_e32 v212, v92
	v_mov_b32_e32 v213, v93
	v_mov_b32_e32 v214, v94
	v_mov_b32_e32 v215, v95
	s_nop 0
	v_mov_b32_dpp v92, v88 row_shr:8 row_mask:0xf bank_mask:0xc
	v_mov_b32_dpp v93, v89 row_shr:8 row_mask:0xf bank_mask:0xc
	v_mov_b32_dpp v94, v90 row_shr:8 row_mask:0xf bank_mask:0xc
	v_mov_b32_dpp v95, v91 row_shr:8 row_mask:0xf bank_mask:0xc
	v_mov_b32_dpp v88, v212 row_shl:8 row_mask:0xf bank_mask:0x3
	v_mov_b32_dpp v89, v213 row_shl:8 row_mask:0xf bank_mask:0x3
	v_mov_b32_dpp v90, v214 row_shl:8 row_mask:0xf bank_mask:0x3
	v_mov_b32_dpp v91, v215 row_shl:8 row_mask:0xf bank_mask:0x3
	v_mov_b32_e32 v212, v84
	v_mov_b32_e32 v213, v85
	v_mov_b32_e32 v214, v86
	v_mov_b32_e32 v215, v87
	s_nop 0
	v_mov_b32_dpp v84, v76 row_shr:8 row_mask:0xf bank_mask:0xc
	v_mov_b32_dpp v85, v77 row_shr:8 row_mask:0xf bank_mask:0xc
	v_mov_b32_dpp v86, v78 row_shr:8 row_mask:0xf bank_mask:0xc
	v_mov_b32_dpp v87, v79 row_shr:8 row_mask:0xf bank_mask:0xc
	v_mov_b32_dpp v76, v212 row_shl:8 row_mask:0xf bank_mask:0x3
	v_mov_b32_dpp v77, v213 row_shl:8 row_mask:0xf bank_mask:0x3
	v_mov_b32_dpp v78, v214 row_shl:8 row_mask:0xf bank_mask:0x3
	v_mov_b32_dpp v79, v215 row_shl:8 row_mask:0xf bank_mask:0x3
	v_mov_b32_e32 v212, v80
	v_mov_b32_e32 v213, v81
	v_mov_b32_e32 v214, v82
	v_mov_b32_e32 v215, v83
	s_nop 0
	v_mov_b32_dpp v80, v72 row_shr:8 row_mask:0xf bank_mask:0xc
	v_mov_b32_dpp v81, v73 row_shr:8 row_mask:0xf bank_mask:0xc
	v_mov_b32_dpp v82, v74 row_shr:8 row_mask:0xf bank_mask:0xc
	v_mov_b32_dpp v83, v75 row_shr:8 row_mask:0xf bank_mask:0xc
	v_mov_b32_dpp v72, v212 row_shl:8 row_mask:0xf bank_mask:0x3
	v_mov_b32_dpp v73, v213 row_shl:8 row_mask:0xf bank_mask:0x3
	v_mov_b32_dpp v74, v214 row_shl:8 row_mask:0xf bank_mask:0x3
	v_mov_b32_dpp v75, v215 row_shl:8 row_mask:0xf bank_mask:0x3
	v_mov_b32_e32 v212, v68
	v_mov_b32_e32 v213, v69
	v_mov_b32_e32 v214, v70
	v_mov_b32_e32 v215, v71
	s_nop 0
	v_mov_b32_dpp v68, v64 row_shr:8 row_mask:0xf bank_mask:0xc
	v_mov_b32_dpp v69, v65 row_shr:8 row_mask:0xf bank_mask:0xc
	v_mov_b32_dpp v70, v66 row_shr:8 row_mask:0xf bank_mask:0xc
	v_mov_b32_dpp v71, v67 row_shr:8 row_mask:0xf bank_mask:0xc
	v_mov_b32_dpp v64, v212 row_shl:8 row_mask:0xf bank_mask:0x3
	v_mov_b32_dpp v65, v213 row_shl:8 row_mask:0xf bank_mask:0x3
	v_mov_b32_dpp v66, v214 row_shl:8 row_mask:0xf bank_mask:0x3
	v_mov_b32_dpp v67, v215 row_shl:8 row_mask:0xf bank_mask:0x3
	v_pk_add_f32 v[92:93], v[92:93], v[180:181]
	v_pk_add_f32 v[94:95], v[94:95], v[182:183]
	v_pk_add_f32 v[88:89], v[88:89], v[184:185]
	v_pk_add_f32 v[90:91], v[90:91], v[186:187]
	v_pk_add_f32 v[84:85], v[84:85], v[188:189]
	v_pk_add_f32 v[86:87], v[86:87], v[190:191]
	v_pk_add_f32 v[76:77], v[76:77], v[192:193]
	v_pk_add_f32 v[78:79], v[78:79], v[194:195]
	v_pk_add_f32 v[80:81], v[80:81], v[196:197]
	v_pk_add_f32 v[82:83], v[82:83], v[198:199]
	v_pk_add_f32 v[72:73], v[72:73], v[200:201]
	v_pk_add_f32 v[74:75], v[74:75], v[202:203]
	v_pk_add_f32 v[68:69], v[68:69], v[204:205]
	v_pk_add_f32 v[70:71], v[70:71], v[206:207]
	v_pk_add_f32 v[64:65], v[64:65], v[208:209]
	v_pk_add_f32 v[66:67], v[66:67], v[210:211]
	global_store_dwordx4 v226, v[92:95], s[52:53]
	v_add_u32_e32 v144, v217, v233
	global_store_dwordx4 v144, v[88:91], s[52:53]
	global_store_dwordx4 v226, v[84:87], s[52:53] offset:512
	v_add_u32_e32 v144, v217, v233
	global_store_dwordx4 v144, v[76:79], s[52:53] offset:512
	global_store_dwordx4 v227, v[80:83], s[52:53]
	v_add_u32_e32 v144, v218, v233
	global_store_dwordx4 v144, v[72:75], s[52:53]
	global_store_dwordx4 v227, v[68:71], s[52:53] offset:512
	v_add_u32_e32 v144, v218, v233
	global_store_dwordx4 v144, v[64:67], s[52:53] offset:512
	global_load_dwordx4 v[180:183], v230, s[52:53]
	v_add_u32_e32 v144, v222, v233
	global_load_dwordx4 v[184:187], v144, s[52:53]
	global_load_dwordx4 v[188:191], v230, s[52:53] offset:512
	v_add_u32_e32 v144, v222, v233
	global_load_dwordx4 v[192:195], v144, s[52:53] offset:512
	global_load_dwordx4 v[196:199], v231, s[52:53]
	v_add_u32_e32 v144, v223, v233
	global_load_dwordx4 v[200:203], v144, s[52:53]
	global_load_dwordx4 v[204:207], v231, s[52:53] offset:512
	v_add_u32_e32 v144, v223, v233
	global_load_dwordx4 v[208:211], v144, s[52:53] offset:512
	s_barrier
;     __device__ __forceinline__ void operator()(AccRef acc, const Unit& u, int wr, int wc, int fr, int fq) const {
;     ...
;                 for (int m = 0; m < 2; ++m)
; #pragma unroll
;                     for (int bj = 0; bj < 2; ++bj)
; #pragma unroll
;                         for (int n = 0; n < 2; ++n) *(f32x4*)(out + (size_t)(row0 + ai * 128 + (2 * mh + m) * 16) * D + col0 + bj * 128 + n * 16) = bs[m][bj][n] + sv[bj][n] * (acc[ai][bj][2 * mh + m][n] + bv[bj][n]);
;                 asm volatile("" ::: "memory"); }
	s_waitcnt vmcnt(16)
	v_mov_b32_e32 v212, v60
	v_mov_b32_e32 v213, v61
	v_mov_b32_e32 v214, v62
	v_mov_b32_e32 v215, v63
	s_nop 0
	v_mov_b32_dpp v60, v56 row_shr:8 row_mask:0xf bank_mask:0xc
	v_mov_b32_dpp v61, v57 row_shr:8 row_mask:0xf bank_mask:0xc
	v_mov_b32_dpp v62, v58 row_shr:8 row_mask:0xf bank_mask:0xc
	v_mov_b32_dpp v63, v59 row_shr:8 row_mask:0xf bank_mask:0xc
	v_mov_b32_dpp v56, v212 row_shl:8 row_mask:0xf bank_mask:0x3
	v_mov_b32_dpp v57, v213 row_shl:8 row_mask:0xf bank_mask:0x3
	v_mov_b32_dpp v58, v214 row_shl:8 row_mask:0xf bank_mask:0x3
	v_mov_b32_dpp v59, v215 row_shl:8 row_mask:0xf bank_mask:0x3
	v_mov_b32_e32 v212, v52
	v_mov_b32_e32 v213, v53
	v_mov_b32_e32 v214, v54
	v_mov_b32_e32 v215, v55
	s_nop 0
	v_mov_b32_dpp v52, v44 row_shr:8 row_mask:0xf bank_mask:0xc
	v_mov_b32_dpp v53, v45 row_shr:8 row_mask:0xf bank_mask:0xc
	v_mov_b32_dpp v54, v46 row_shr:8 row_mask:0xf bank_mask:0xc
	v_mov_b32_dpp v55, v47 row_shr:8 row_mask:0xf bank_mask:0xc
	v_mov_b32_dpp v44, v212 row_shl:8 row_mask:0xf bank_mask:0x3
	v_mov_b32_dpp v45, v213 row_shl:8 row_mask:0xf bank_mask:0x3
	v_mov_b32_dpp v46, v214 row_shl:8 row_mask:0xf bank_mask:0x3
	v_mov_b32_dpp v47, v215 row_shl:8 row_mask:0xf bank_mask:0x3
	v_mov_b32_e32 v212, v48
	v_mov_b32_e32 v213, v49
	v_mov_b32_e32 v214, v50
	v_mov_b32_e32 v215, v51
	s_nop 0
	v_mov_b32_dpp v48, v40 row_shr:8 row_mask:0xf bank_mask:0xc
	v_mov_b32_dpp v49, v41 row_shr:8 row_mask:0xf bank_mask:0xc
	v_mov_b32_dpp v50, v42 row_shr:8 row_mask:0xf bank_mask:0xc
	v_mov_b32_dpp v51, v43 row_shr:8 row_mask:0xf bank_mask:0xc
	v_mov_b32_dpp v40, v212 row_shl:8 row_mask:0xf bank_mask:0x3
	v_mov_b32_dpp v41, v213 row_shl:8 row_mask:0xf bank_mask:0x3
	v_mov_b32_dpp v42, v214 row_shl:8 row_mask:0xf bank_mask:0x3
	v_mov_b32_dpp v43, v215 row_shl:8 row_mask:0xf bank_mask:0x3
	v_mov_b32_e32 v212, v36
	v_mov_b32_e32 v213, v37
	v_mov_b32_e32 v214, v38
	v_mov_b32_e32 v215, v39
	s_nop 0
	v_mov_b32_dpp v36, v32 row_shr:8 row_mask:0xf bank_mask:0xc
	v_mov_b32_dpp v37, v33 row_shr:8 row_mask:0xf bank_mask:0xc
	v_mov_b32_dpp v38, v34 row_shr:8 row_mask:0xf bank_mask:0xc
	v_mov_b32_dpp v39, v35 row_shr:8 row_mask:0xf bank_mask:0xc
	v_mov_b32_dpp v32, v212 row_shl:8 row_mask:0xf bank_mask:0x3
	v_mov_b32_dpp v33, v213 row_shl:8 row_mask:0xf bank_mask:0x3
	v_mov_b32_dpp v34, v214 row_shl:8 row_mask:0xf bank_mask:0x3
	v_mov_b32_dpp v35, v215 row_shl:8 row_mask:0xf bank_mask:0x3
	v_pk_add_f32 v[60:61], v[60:61], v[140:141]
	v_pk_add_f32 v[62:63], v[62:63], v[142:143]
	v_pk_add_f32 v[56:57], v[56:57], v[152:153]
	v_pk_add_f32 v[58:59], v[58:59], v[154:155]
	v_pk_add_f32 v[52:53], v[52:53], v[156:157]
	v_pk_add_f32 v[54:55], v[54:55], v[158:159]
	v_pk_add_f32 v[44:45], v[44:45], v[160:161]
	v_pk_add_f32 v[46:47], v[46:47], v[162:163]
	v_pk_add_f32 v[48:49], v[48:49], v[164:165]
	v_pk_add_f32 v[50:51], v[50:51], v[166:167]
	v_pk_add_f32 v[40:41], v[40:41], v[168:169]
	v_pk_add_f32 v[42:43], v[42:43], v[170:171]
	v_pk_add_f32 v[36:37], v[36:37], v[172:173]
	v_pk_add_f32 v[38:39], v[38:39], v[174:175]
	v_pk_add_f32 v[32:33], v[32:33], v[176:177]
	v_pk_add_f32 v[34:35], v[34:35], v[178:179]
	global_store_dwordx4 v228, v[60:63], s[52:53]
	v_add_u32_e32 v144, v220, v233
	global_store_dwordx4 v144, v[56:59], s[52:53]
	global_store_dwordx4 v228, v[52:55], s[52:53] offset:512
	v_add_u32_e32 v144, v220, v233
	global_store_dwordx4 v144, v[44:47], s[52:53] offset:512
	global_store_dwordx4 v229, v[48:51], s[52:53]
	v_add_u32_e32 v144, v221, v233
	global_store_dwordx4 v144, v[40:43], s[52:53]
	global_store_dwordx4 v229, v[36:39], s[52:53] offset:512
	v_add_u32_e32 v144, v221, v233
	global_store_dwordx4 v144, v[32:35], s[52:53] offset:512
	s_barrier
; #define PG8_WAIT_V(n) asm volatile("s_waitcnt vmcnt(" #n ")" ::: "memory")
; #define PG8_BAR __builtin_amdgcn_s_barrier()
; template <class Epi>
; __device__ __forceinline__ void gemm_phase(LAS unsigned char* lds, const Gemm g, const StaticOrder& S, const Epi& E) {
;     ...
;     PG8_WAIT_V(0);
;     if (wr == 0) PG8_BAR;
;     PG8_BAR;
;     __device__ __forceinline__ void operator()(AccRef acc, const Unit& u, int wr, int wc, int fr, int fq) const {
;     ...
;                 for (int m = 0; m < 2; ++m)
; #pragma unroll
;                     for (int bj = 0; bj < 2; ++bj)
; #pragma unroll
;                         for (int n = 0; n < 2; ++n) *(f32x4*)(out + (size_t)(row0 + ai * 128 + (2 * mh + m) * 16) * D + col0 + bj * 128 + n * 16) = bs[m][bj][n] + sv[bj][n] * (acc[ai][bj][2 * mh + m][n] + bv[bj][n]);
;                 asm volatile("" ::: "memory"); }
	s_waitcnt vmcnt(8)
	v_mov_b32_e32 v212, v28
	v_mov_b32_e32 v213, v29
	v_mov_b32_e32 v214, v30
	v_mov_b32_e32 v215, v31
	s_nop 0
	v_mov_b32_dpp v28, v24 row_shr:8 row_mask:0xf bank_mask:0xc
	v_mov_b32_dpp v29, v25 row_shr:8 row_mask:0xf bank_mask:0xc
	v_mov_b32_dpp v30, v26 row_shr:8 row_mask:0xf bank_mask:0xc
	v_mov_b32_dpp v31, v27 row_shr:8 row_mask:0xf bank_mask:0xc
	v_mov_b32_dpp v24, v212 row_shl:8 row_mask:0xf bank_mask:0x3
	v_mov_b32_dpp v25, v213 row_shl:8 row_mask:0xf bank_mask:0x3
	v_mov_b32_dpp v26, v214 row_shl:8 row_mask:0xf bank_mask:0x3
	v_mov_b32_dpp v27, v215 row_shl:8 row_mask:0xf bank_mask:0x3
	v_mov_b32_e32 v212, v20
	v_mov_b32_e32 v213, v21
	v_mov_b32_e32 v214, v22
	v_mov_b32_e32 v215, v23
	s_nop 0
	v_mov_b32_dpp v20, v12 row_shr:8 row_mask:0xf bank_mask:0xc
	v_mov_b32_dpp v21, v13 row_shr:8 row_mask:0xf bank_mask:0xc
	v_mov_b32_dpp v22, v14 row_shr:8 row_mask:0xf bank_mask:0xc
	v_mov_b32_dpp v23, v15 row_shr:8 row_mask:0xf bank_mask:0xc
	v_mov_b32_dpp v12, v212 row_shl:8 row_mask:0xf bank_mask:0x3
	v_mov_b32_dpp v13, v213 row_shl:8 row_mask:0xf bank_mask:0x3
	v_mov_b32_dpp v14, v214 row_shl:8 row_mask:0xf bank_mask:0x3
	v_mov_b32_dpp v15, v215 row_shl:8 row_mask:0xf bank_mask:0x3
	v_mov_b32_e32 v212, v16
	v_mov_b32_e32 v213, v17
	v_mov_b32_e32 v214, v18
	v_mov_b32_e32 v215, v19
	s_nop 0
	v_mov_b32_dpp v16, v8 row_shr:8 row_mask:0xf bank_mask:0xc
	v_mov_b32_dpp v17, v9 row_shr:8 row_mask:0xf bank_mask:0xc
	v_mov_b32_dpp v18, v10 row_shr:8 row_mask:0xf bank_mask:0xc
	v_mov_b32_dpp v19, v11 row_shr:8 row_mask:0xf bank_mask:0xc
	v_mov_b32_dpp v8, v212 row_shl:8 row_mask:0xf bank_mask:0x3
	v_mov_b32_dpp v9, v213 row_shl:8 row_mask:0xf bank_mask:0x3
	v_mov_b32_dpp v10, v214 row_shl:8 row_mask:0xf bank_mask:0x3
	v_mov_b32_dpp v11, v215 row_shl:8 row_mask:0xf bank_mask:0x3
	v_mov_b32_e32 v212, v4
	v_mov_b32_e32 v213, v5
	v_mov_b32_e32 v214, v6
	v_mov_b32_e32 v215, v7
	s_nop 0
	v_mov_b32_dpp v4, v0 row_shr:8 row_mask:0xf bank_mask:0xc
	v_mov_b32_dpp v5, v1 row_shr:8 row_mask:0xf bank_mask:0xc
	v_mov_b32_dpp v6, v2 row_shr:8 row_mask:0xf bank_mask:0xc
	v_mov_b32_dpp v7, v3 row_shr:8 row_mask:0xf bank_mask:0xc
	v_mov_b32_dpp v0, v212 row_shl:8 row_mask:0xf bank_mask:0x3
	v_mov_b32_dpp v1, v213 row_shl:8 row_mask:0xf bank_mask:0x3
	v_mov_b32_dpp v2, v214 row_shl:8 row_mask:0xf bank_mask:0x3
	v_mov_b32_dpp v3, v215 row_shl:8 row_mask:0xf bank_mask:0x3
	v_pk_add_f32 v[28:29], v[28:29], v[180:181]
	v_pk_add_f32 v[30:31], v[30:31], v[182:183]
	v_pk_add_f32 v[24:25], v[24:25], v[184:185]
	v_pk_add_f32 v[26:27], v[26:27], v[186:187]
	v_pk_add_f32 v[20:21], v[20:21], v[188:189]
	v_pk_add_f32 v[22:23], v[22:23], v[190:191]
	v_pk_add_f32 v[12:13], v[12:13], v[192:193]
	v_pk_add_f32 v[14:15], v[14:15], v[194:195]
	v_pk_add_f32 v[16:17], v[16:17], v[196:197]
	v_pk_add_f32 v[18:19], v[18:19], v[198:199]
	v_pk_add_f32 v[8:9], v[8:9], v[200:201]
	v_pk_add_f32 v[10:11], v[10:11], v[202:203]
	v_pk_add_f32 v[4:5], v[4:5], v[204:205]
	v_pk_add_f32 v[6:7], v[6:7], v[206:207]
	v_pk_add_f32 v[0:1], v[0:1], v[208:209]
	v_pk_add_f32 v[2:3], v[2:3], v[210:211]
	global_store_dwordx4 v230, v[28:31], s[52:53]
	v_add_u32_e32 v144, v222, v233
	global_store_dwordx4 v144, v[24:27], s[52:53]
	global_store_dwordx4 v230, v[20:23], s[52:53] offset:512
	v_add_u32_e32 v144, v222, v233
	global_store_dwordx4 v144, v[12:15], s[52:53] offset:512
	global_store_dwordx4 v231, v[16:19], s[52:53]
	v_add_u32_e32 v144, v223, v233
	global_store_dwordx4 v144, v[8:11], s[52:53]
	global_store_dwordx4 v231, v[4:7], s[52:53] offset:512
	v_add_u32_e32 v144, v223, v233
	global_store_dwordx4 v144, v[0:3], s[52:53] offset:512
	s_cbranch_vccz .LBB0_1450
	s_waitcnt vmcnt(0)
	s_cmpk_gt_u32 s4, 0xff
	s_cbranch_scc1 .LBB0_1465
	s_barrier

; #define PG8_STAGE(bufoff, gbase, voff) do { _Pragma("unroll") for (int _i = 0; _i < 2; ++_i) \
;         __builtin_amdgcn_global_load_lds((const unsigned*)((const char*)(gbase) + (voff)[_i]), (LAS unsigned*)(lds + (bufoff) + ldsw + _i * 8192), 16, 0, 0); } while (0)
; #define PG8_LDA(dst, b, h) do { _Pragma("unroll") for (int m = 0; m < 4; ++m) _Pragma("unroll") for (int k = 0; k < 2; ++k) dst[m][k] = *(const LAS bf16x8*)(lds + PG8_SA(b, h) + aoff + m * 2048 + k * 1024); } while (0)
; #define PG8_LDB(dst, b, h) do { _Pragma("unroll") for (int n = 0; n < 2; ++n) _Pragma("unroll") for (int k = 0; k < 2; ++k) dst[n][k] = *(const LAS bf16x8*)(lds + PG8_SB(b, h) + boff + n * 2048 + k * 1024); } while (0)
; #define PG8_MMA(ai, bj, At, Bt) do { __builtin_amdgcn_s_setprio(1); _Pragma("unroll") for (int m = 0; m < 4; ++m) _Pragma("unroll") for (int n = 0; n < 2; ++n) _Pragma("unroll") for (int k = 0; k < 2; ++k) \
;         acc[ai][bj][m][n] = __builtin_amdgcn_mfma_f32_16x16x32_bf16(Bt[n][k], At[m][k], acc[ai][bj][m][n], 0, 0, 0); __builtin_amdgcn_s_setprio(0); } while (0)
; #define PG8_WAIT_V(n) asm volatile("s_waitcnt vmcnt(" #n ")" ::: "memory")
; #define PG8_WAIT_L(n) asm volatile("s_waitcnt lgkmcnt(" #n ")" ::: "memory")
; #define PG8_BAR __builtin_amdgcn_s_barrier()
; #define PG8_SCHED __builtin_amdgcn_sched_barrier(0)
; template <class Epi>
; __device__ __forceinline__ void gemm_phase(LAS unsigned char* lds, const Gemm g, const StaticOrder& S, const Epi& E) {
;     ...
;             PG8_LDB(B0, 0, 0); PG8_SCHED; PG8_LDA(At, 0, 0); PG8_STAGE(PG8_SA(1, 1), a1 + hstepA, voffA);
;             PG8_WAIT_L(8); PG8_BAR; PG8_WAIT_L(0); PG8_MMA(0, 0, At, B0); PG8_BAR; PG8_SCHED;
;             PG8_LDB(B1, 0, 1); PG8_STAGE(PG8_SB(0, 0), b2, voffB);
;             PG8_BAR; PG8_WAIT_L(0); PG8_MMA(0, 1, At, B1); PG8_BAR;
;             PG8_LDA(At, 0, 1); PG8_STAGE(PG8_SA(0, 0), a2, voffA);
;             PG8_BAR; PG8_WAIT_L(0); PG8_MMA(1, 0, At, B0); PG8_BAR; PG8_SCHED;
;             PG8_STAGE(PG8_SB(0, 1), b2 + hstepB, voffB);
;             PG8_WAIT_V(6); PG8_BAR; PG8_MMA(1, 1, At, B1); PG8_BAR;
.LBB0_1820:
	ds_read_b128 v[140:143], v149
	ds_read_b128 v[152:155], v149 offset:1024
	ds_read_b128 v[156:159], v149 offset:2048
	ds_read_b128 v[160:163], v149 offset:3072
	s_add_u32 s36, s34, 0xfffc0080
	s_addc_u32 s37, s35, -1
	s_cmp_eq_u32 s70, 12
	s_cselect_b32 s39, s25, s37
	s_cselect_b32 s38, s47, s36
	s_cselect_b32 s37, s23, s63
	s_cselect_b32 s36, s48, s49
	v_lshl_add_u64 v[144:145], s[34:35], 0, v[132:133]
	s_add_i32 m0, s8, 0xc000
	ds_read_b128 v[164:167], v150
	ds_read_b128 v[168:171], v150 offset:1024
	ds_read_b128 v[172:175], v150 offset:2048
	ds_read_b128 v[176:179], v150 offset:3072
	ds_read_b128 v[180:183], v150 offset:4096
	ds_read_b128 v[184:187], v150 offset:5120
	ds_read_b128 v[188:191], v150 offset:6144
	ds_read_b128 v[192:195], v150 offset:7168
	global_load_lds_dwordx4 v[144:145], off
	v_lshl_add_u64 v[144:145], s[34:35], 0, v[134:135]
	s_add_i32 m0, s8, 0xe000
	s_nop 0
	global_load_lds_dwordx4 v[144:145], off
	ds_read_b128 v[196:199], v151
	ds_read_b128 v[200:203], v151 offset:1024
	ds_read_b128 v[204:207], v151 offset:2048
	ds_read_b128 v[208:211], v151 offset:3072
	s_waitcnt lgkmcnt(0)
	s_barrier
	s_setprio 1
	v_mfma_f32_16x16x32_bf16 v[124:127], v[140:143], v[164:167], v[124:127]
	v_mfma_f32_16x16x32_bf16 v[120:123], v[156:159], v[164:167], v[120:123]
	v_mfma_f32_16x16x32_bf16 v[112:115], v[140:143], v[172:175], v[112:115]
	v_mfma_f32_16x16x32_bf16 v[104:107], v[156:159], v[172:175], v[104:107]
	v_mfma_f32_16x16x32_bf16 v[92:95], v[140:143], v[180:183], v[92:95]
	v_mfma_f32_16x16x32_bf16 v[88:91], v[156:159], v[180:183], v[88:91]
	v_mfma_f32_16x16x32_bf16 v[80:83], v[140:143], v[188:191], v[80:83]
	v_mfma_f32_16x16x32_bf16 v[72:75], v[156:159], v[188:191], v[72:75]
	v_mfma_f32_16x16x32_bf16 v[124:127], v[152:155], v[168:171], v[124:127]
	v_mfma_f32_16x16x32_bf16 v[120:123], v[160:163], v[168:171], v[120:123]
	v_mfma_f32_16x16x32_bf16 v[112:115], v[152:155], v[176:179], v[112:115]
	v_mfma_f32_16x16x32_bf16 v[104:107], v[160:163], v[176:179], v[104:107]
	v_mfma_f32_16x16x32_bf16 v[92:95], v[152:155], v[184:187], v[92:95]
	v_mfma_f32_16x16x32_bf16 v[88:91], v[160:163], v[184:187], v[88:91]
	v_mfma_f32_16x16x32_bf16 v[80:83], v[152:155], v[192:195], v[80:83]
	v_mfma_f32_16x16x32_bf16 v[72:75], v[160:163], v[192:195], v[72:75]
	v_mfma_f32_16x16x32_bf16 v[116:119], v[196:199], v[164:167], v[116:119]
	v_mfma_f32_16x16x32_bf16 v[108:111], v[204:207], v[164:167], v[108:111]
	v_mfma_f32_16x16x32_bf16 v[100:103], v[196:199], v[172:175], v[100:103]
	v_mfma_f32_16x16x32_bf16 v[96:99], v[204:207], v[172:175], v[96:99]
	v_mfma_f32_16x16x32_bf16 v[84:87], v[196:199], v[180:183], v[84:87]
	v_mfma_f32_16x16x32_bf16 v[76:79], v[204:207], v[180:183], v[76:79]
	v_mfma_f32_16x16x32_bf16 v[68:71], v[196:199], v[188:191], v[68:71]
	v_mfma_f32_16x16x32_bf16 v[64:67], v[204:207], v[188:191], v[64:67]
	v_mfma_f32_16x16x32_bf16 v[116:119], v[200:203], v[168:171], v[116:119]
	v_mfma_f32_16x16x32_bf16 v[108:111], v[208:211], v[168:171], v[108:111]
	v_mfma_f32_16x16x32_bf16 v[100:103], v[200:203], v[176:179], v[100:103]
	v_mfma_f32_16x16x32_bf16 v[96:99], v[208:211], v[176:179], v[96:99]
	v_mfma_f32_16x16x32_bf16 v[84:87], v[200:203], v[184:187], v[84:87]
	v_mfma_f32_16x16x32_bf16 v[76:79], v[208:211], v[184:187], v[76:79]
	v_mfma_f32_16x16x32_bf16 v[68:71], v[200:203], v[192:195], v[68:71]
	v_mfma_f32_16x16x32_bf16 v[64:67], v[208:211], v[192:195], v[64:67]
	s_setprio 0
	s_barrier
	s_nop 1
	ds_read_b128 v[164:167], v150 offset:16384
	ds_read_b128 v[168:171], v150 offset:17408
	ds_read_b128 v[172:175], v150 offset:18432
	ds_read_b128 v[176:179], v150 offset:19456
	ds_read_b128 v[180:183], v150 offset:20480
	ds_read_b128 v[184:187], v150 offset:21504
	ds_read_b128 v[188:191], v150 offset:22528
	ds_read_b128 v[192:195], v150 offset:23552
	s_add_i32 s71, s44, s7
	v_lshl_add_u64 v[144:145], s[36:37], 0, v[128:129]
	s_mov_b32 m0, s71
	s_nop 0
	global_load_lds_dwordx4 v[144:145], off
	v_lshl_add_u64 v[212:213], s[36:37], 0, v[130:131]
	s_add_i32 m0, s71, 0x2000
	s_nop 0
	global_load_lds_dwordx4 v[212:213], off
	s_mov_b32 m0, s8
	v_lshl_add_u64 v[214:215], s[38:39], 0, v[128:129]
	global_load_lds_dwordx4 v[214:215], off
	v_lshl_add_u64 v[216:217], s[38:39], 0, v[130:131]
	s_mov_b32 m0, s9
	s_nop 0
	global_load_lds_dwordx4 v[216:217], off
	s_add_u32 s72, s36, 0x40000
	s_addc_u32 s73, s37, 0
	s_add_i32 s71, s45, s7
	v_lshl_add_u64 v[254:255], s[72:73], 0, v[128:129]
	s_mov_b32 m0, s71
	s_nop 0
	global_load_lds_dwordx4 v[254:255], off
	v_lshl_add_u64 v[254:255], s[72:73], 0, v[130:131]
	s_add_i32 m0, s71, 0x2000
	s_nop 0
	global_load_lds_dwordx4 v[254:255], off
	s_waitcnt vmcnt(6)
	s_waitcnt lgkmcnt(0)
	s_barrier
; #define PG8_STAGE(bufoff, gbase, voff) do { _Pragma("unroll") for (int _i = 0; _i < 2; ++_i) \
;         __builtin_amdgcn_global_load_lds((const unsigned*)((const char*)(gbase) + (voff)[_i]), (LAS unsigned*)(lds + (bufoff) + ldsw + _i * 8192), 16, 0, 0); } while (0)
; #define PG8_LDA(dst, b, h) do { _Pragma("unroll") for (int m = 0; m < 4; ++m) _Pragma("unroll") for (int k = 0; k < 2; ++k) dst[m][k] = *(const LAS bf16x8*)(lds + PG8_SA(b, h) + aoff + m * 2048 + k * 1024); } while (0)
; #define PG8_LDB(dst, b, h) do { _Pragma("unroll") for (int n = 0; n < 2; ++n) _Pragma("unroll") for (int k = 0; k < 2; ++k) dst[n][k] = *(const LAS bf16x8*)(lds + PG8_SB(b, h) + boff + n * 2048 + k * 1024); } while (0)
; #define PG8_MMA(ai, bj, At, Bt) do { __builtin_amdgcn_s_setprio(1); _Pragma("unroll") for (int m = 0; m < 4; ++m) _Pragma("unroll") for (int n = 0; n < 2; ++n) _Pragma("unroll") for (int k = 0; k < 2; ++k) \
;         acc[ai][bj][m][n] = __builtin_amdgcn_mfma_f32_16x16x32_bf16(Bt[n][k], At[m][k], acc[ai][bj][m][n], 0, 0, 0); __builtin_amdgcn_s_setprio(0); } while (0)
; #define PG8_WAIT_V(n) asm volatile("s_waitcnt vmcnt(" #n ")" ::: "memory")
; #define PG8_WAIT_L(n) asm volatile("s_waitcnt lgkmcnt(" #n ")" ::: "memory")
; #define PG8_BAR __builtin_amdgcn_s_barrier()
; #define PG8_SCHED __builtin_amdgcn_sched_barrier(0)
; template <class Epi>
; __device__ __forceinline__ void gemm_phase(LAS unsigned char* lds, const Gemm g, const StaticOrder& S, const Epi& E) {
;     ...
;             PG8_BAR; PG8_WAIT_L(0); PG8_MMA(1, 0, At, B0); PG8_BAR; PG8_SCHED;
;             PG8_STAGE(PG8_SB(0, 1), b2 + hstepB, voffB);
;             PG8_WAIT_V(6); PG8_BAR; PG8_MMA(1, 1, At, B1); PG8_BAR;
;             PG8_LDB(B0, 1, 0); PG8_SCHED; PG8_LDA(At, 1, 0); PG8_STAGE(PG8_SA(0, 1), a2 + hstepA, voffA);
;             PG8_WAIT_L(8); PG8_BAR; PG8_WAIT_L(0); PG8_MMA(0, 0, At, B0); PG8_BAR; PG8_SCHED;
;             PG8_LDB(B1, 1, 1); PG8_STAGE(PG8_SB(1, 0), b3, voffB);
;             PG8_BAR; PG8_WAIT_L(0); PG8_MMA(0, 1, At, B1); PG8_BAR;
	s_setprio 1
	v_mfma_f32_16x16x32_bf16 v[60:63], v[140:143], v[164:167], v[60:63]
	v_mfma_f32_16x16x32_bf16 v[56:59], v[156:159], v[164:167], v[56:59]
	v_mfma_f32_16x16x32_bf16 v[48:51], v[140:143], v[172:175], v[48:51]
	v_mfma_f32_16x16x32_bf16 v[40:43], v[156:159], v[172:175], v[40:43]
	v_mfma_f32_16x16x32_bf16 v[28:31], v[140:143], v[180:183], v[28:31]
	v_mfma_f32_16x16x32_bf16 v[24:27], v[156:159], v[180:183], v[24:27]
	v_mfma_f32_16x16x32_bf16 v[16:19], v[140:143], v[188:191], v[16:19]
	v_mfma_f32_16x16x32_bf16 v[8:11], v[156:159], v[188:191], v[8:11]
	v_mfma_f32_16x16x32_bf16 v[60:63], v[152:155], v[168:171], v[60:63]
	v_mfma_f32_16x16x32_bf16 v[56:59], v[160:163], v[168:171], v[56:59]
	v_mfma_f32_16x16x32_bf16 v[48:51], v[152:155], v[176:179], v[48:51]
	v_mfma_f32_16x16x32_bf16 v[40:43], v[160:163], v[176:179], v[40:43]
	v_mfma_f32_16x16x32_bf16 v[28:31], v[152:155], v[184:187], v[28:31]
	v_mfma_f32_16x16x32_bf16 v[24:27], v[160:163], v[184:187], v[24:27]
	v_mfma_f32_16x16x32_bf16 v[16:19], v[152:155], v[192:195], v[16:19]
	v_mfma_f32_16x16x32_bf16 v[8:11], v[160:163], v[192:195], v[8:11]
	v_mfma_f32_16x16x32_bf16 v[52:55], v[196:199], v[164:167], v[52:55]
	v_mfma_f32_16x16x32_bf16 v[44:47], v[204:207], v[164:167], v[44:47]
	v_mfma_f32_16x16x32_bf16 v[36:39], v[196:199], v[172:175], v[36:39]
	v_mfma_f32_16x16x32_bf16 v[32:35], v[204:207], v[172:175], v[32:35]
	v_mfma_f32_16x16x32_bf16 v[20:23], v[196:199], v[180:183], v[20:23]
	v_mfma_f32_16x16x32_bf16 v[12:15], v[204:207], v[180:183], v[12:15]
	v_mfma_f32_16x16x32_bf16 v[4:7], v[196:199], v[188:191], v[4:7]
	v_mfma_f32_16x16x32_bf16 v[0:3], v[204:207], v[188:191], v[0:3]
	v_mfma_f32_16x16x32_bf16 v[52:55], v[200:203], v[168:171], v[52:55]
	v_mfma_f32_16x16x32_bf16 v[44:47], v[208:211], v[168:171], v[44:47]
	v_mfma_f32_16x16x32_bf16 v[36:39], v[200:203], v[176:179], v[36:39]
	v_mfma_f32_16x16x32_bf16 v[32:35], v[208:211], v[176:179], v[32:35]
	v_mfma_f32_16x16x32_bf16 v[20:23], v[200:203], v[184:187], v[20:23]
	v_mfma_f32_16x16x32_bf16 v[12:15], v[208:211], v[184:187], v[12:15]
	v_mfma_f32_16x16x32_bf16 v[4:7], v[200:203], v[192:195], v[4:7]
	v_mfma_f32_16x16x32_bf16 v[0:3], v[208:211], v[192:195], v[0:3]
	s_setprio 0
	s_add_i32 s71, 0, 0x18000
	v_add_u32_e32 v160, s71, v147
	s_barrier
	ds_read_b128 v[140:143], v160
	ds_read_b128 v[152:155], v160 offset:1024
	ds_read_b128 v[156:159], v160 offset:2048
	ds_read_b128 v[160:163], v160 offset:3072
	s_add_u32 s38, s38, 0x40000
	s_addc_u32 s39, s39, 0
	s_mov_b32 m0, s31
	v_lshl_add_u64 v[196:197], s[38:39], 0, v[128:129]
	ds_read_b128 v[164:167], v150 offset:32768
	ds_read_b128 v[168:171], v150 offset:33792
	ds_read_b128 v[172:175], v150 offset:34816
	ds_read_b128 v[176:179], v150 offset:35840
	ds_read_b128 v[180:183], v150 offset:36864
	ds_read_b128 v[184:187], v150 offset:37888
	ds_read_b128 v[188:191], v150 offset:38912
	ds_read_b128 v[192:195], v150 offset:39936
	global_load_lds_dwordx4 v[196:197], off
	v_lshl_add_u64 v[196:197], s[38:39], 0, v[130:131]
	s_mov_b32 m0, s40
	s_nop 0
	global_load_lds_dwordx4 v[196:197], off
	s_add_i32 s38, 0, 0x1c000
	v_add_u32_e32 v208, s38, v147
	ds_read_b128 v[196:199], v208
	ds_read_b128 v[200:203], v208 offset:1024
	ds_read_b128 v[204:207], v208 offset:2048
	ds_read_b128 v[208:211], v208 offset:3072
	s_waitcnt lgkmcnt(0)
	s_barrier
	s_setprio 1
	v_mfma_f32_16x16x32_bf16 v[124:127], v[140:143], v[164:167], v[124:127]
	v_mfma_f32_16x16x32_bf16 v[120:123], v[156:159], v[164:167], v[120:123]
	v_mfma_f32_16x16x32_bf16 v[112:115], v[140:143], v[172:175], v[112:115]
	v_mfma_f32_16x16x32_bf16 v[104:107], v[156:159], v[172:175], v[104:107]
	v_mfma_f32_16x16x32_bf16 v[92:95], v[140:143], v[180:183], v[92:95]
	v_mfma_f32_16x16x32_bf16 v[88:91], v[156:159], v[180:183], v[88:91]
	v_mfma_f32_16x16x32_bf16 v[80:83], v[140:143], v[188:191], v[80:83]
	v_mfma_f32_16x16x32_bf16 v[72:75], v[156:159], v[188:191], v[72:75]
	v_mfma_f32_16x16x32_bf16 v[124:127], v[152:155], v[168:171], v[124:127]
	v_mfma_f32_16x16x32_bf16 v[120:123], v[160:163], v[168:171], v[120:123]
	v_mfma_f32_16x16x32_bf16 v[112:115], v[152:155], v[176:179], v[112:115]
	v_mfma_f32_16x16x32_bf16 v[104:107], v[160:163], v[176:179], v[104:107]
	v_mfma_f32_16x16x32_bf16 v[92:95], v[152:155], v[184:187], v[92:95]
	v_mfma_f32_16x16x32_bf16 v[88:91], v[160:163], v[184:187], v[88:91]
	v_mfma_f32_16x16x32_bf16 v[80:83], v[152:155], v[192:195], v[80:83]
	v_mfma_f32_16x16x32_bf16 v[72:75], v[160:163], v[192:195], v[72:75]
	v_mfma_f32_16x16x32_bf16 v[116:119], v[196:199], v[164:167], v[116:119]
	v_mfma_f32_16x16x32_bf16 v[108:111], v[204:207], v[164:167], v[108:111]
	v_mfma_f32_16x16x32_bf16 v[100:103], v[196:199], v[172:175], v[100:103]
	v_mfma_f32_16x16x32_bf16 v[96:99], v[204:207], v[172:175], v[96:99]
	v_mfma_f32_16x16x32_bf16 v[84:87], v[196:199], v[180:183], v[84:87]
	v_mfma_f32_16x16x32_bf16 v[76:79], v[204:207], v[180:183], v[76:79]
	v_mfma_f32_16x16x32_bf16 v[68:71], v[196:199], v[188:191], v[68:71]
	v_mfma_f32_16x16x32_bf16 v[64:67], v[204:207], v[188:191], v[64:67]
	v_mfma_f32_16x16x32_bf16 v[116:119], v[200:203], v[168:171], v[116:119]
	v_mfma_f32_16x16x32_bf16 v[108:111], v[208:211], v[168:171], v[108:111]
	v_mfma_f32_16x16x32_bf16 v[100:103], v[200:203], v[176:179], v[100:103]
	v_mfma_f32_16x16x32_bf16 v[96:99], v[208:211], v[176:179], v[96:99]
	v_mfma_f32_16x16x32_bf16 v[84:87], v[200:203], v[184:187], v[84:87]
	v_mfma_f32_16x16x32_bf16 v[76:79], v[208:211], v[184:187], v[76:79]
	v_mfma_f32_16x16x32_bf16 v[68:71], v[200:203], v[192:195], v[68:71]
	v_mfma_f32_16x16x32_bf16 v[64:67], v[208:211], v[192:195], v[64:67]
	s_setprio 0
	s_barrier
; #define PG8_STAGE(bufoff, gbase, voff) do { _Pragma("unroll") for (int _i = 0; _i < 2; ++_i) \
;         __builtin_amdgcn_global_load_lds((const unsigned*)((const char*)(gbase) + (voff)[_i]), (LAS unsigned*)(lds + (bufoff) + ldsw + _i * 8192), 16, 0, 0); } while (0)
; #define PG8_LDA(dst, b, h) do { _Pragma("unroll") for (int m = 0; m < 4; ++m) _Pragma("unroll") for (int k = 0; k < 2; ++k) dst[m][k] = *(const LAS bf16x8*)(lds + PG8_SA(b, h) + aoff + m * 2048 + k * 1024); } while (0)
; #define PG8_WAIT_V(n) asm volatile("s_waitcnt vmcnt(" #n ")" ::: "memory")
; #define PG8_WAIT_L(n) asm volatile("s_waitcnt lgkmcnt(" #n ")" ::: "memory")
; #define PG8_BAR __builtin_amdgcn_s_barrier()
; #define PG8_SCHED __builtin_amdgcn_sched_barrier(0)
; template <class Epi>
; __device__ __forceinline__ void gemm_phase(LAS unsigned char* lds, const Gemm g, const StaticOrder& S, const Epi& E) {
;     ...
;             PG8_BAR; PG8_WAIT_L(0); PG8_MMA(0, 1, At, B1); PG8_BAR;
;             PG8_LDA(At, 1, 1); PG8_STAGE(PG8_SA(1, 0), a3, voffA);
;             PG8_BAR; PG8_WAIT_L(0); PG8_MMA(1, 0, At, B0); PG8_BAR; PG8_SCHED;
;             PG8_STAGE(PG8_SB(1, 1), b3 + hstepB, voffB);
;             PG8_WAIT_V(6); PG8_BAR; PG8_MMA(1, 1, At, B1); PG8_BAR;
;         }
;     __device__ __forceinline__ void operator()(AccRef acc, const Unit& u, int wr, int wc, int fr, int fq) const {
;         const int row0 = u.pm * 256 + wr * 64 + fr, col0 = u.pn * 256 + wc * 32 + 4 * fq;
;         f32x4 sv[2][2], bv[2][2];
; #pragma unroll
;         for (int bj = 0; bj < 2; ++bj)
; #pragma unroll
;             for (int n = 0; n < 2; ++n) {
;                 sv[bj][n] = scale ? *(const f32x4*)(scale + col0 + bj * 128 + n * 16) : (f32x4){1.f, 1.f, 1.f, 1.f};
;                 bv[bj][n] = bias ? *(const f32x4*)(bias + col0 + bj * 128 + n * 16) : (f32x4){0.f, 0.f, 0.f, 0.f}; }
; #pragma unroll
;         for (int ai = 0; ai < 2; ++ai)
; #pragma unroll
;             for (int mh = 0; mh < 2; ++mh) {
;                 f32x4 bs[2][2][2];
; #pragma unroll
;                 for (int m = 0; m < 2; ++m)
; #pragma unroll
;                     for (int bj = 0; bj < 2; ++bj)
; #pragma unroll
;                         for (int n = 0; n < 2; ++n) bs[m][bj][n] = *(const f32x4*)(base + (size_t)(row0 + ai * 128 + (2 * mh + m) * 16) * D + col0 + bj * 128 + n * 16);
	s_nop 1
	ds_read_b128 v[164:167], v150 offset:49152
	ds_read_b128 v[168:171], v150 offset:50176
	ds_read_b128 v[172:175], v150 offset:51200
	ds_read_b128 v[176:179], v150 offset:52224
	ds_read_b128 v[180:183], v150 offset:53248
	ds_read_b128 v[184:187], v150 offset:54272
	ds_read_b128 v[188:191], v150 offset:55296
	ds_read_b128 v[192:195], v150 offset:56320
	s_add_i32 s39, s71, s7
	v_lshl_add_u64 v[254:255], v[144:145], 0, s[12:13]
	s_mov_b32 m0, s39
	s_nop 0
	global_load_lds_dwordx4 v[254:255], off
	v_lshl_add_u64 v[254:255], v[212:213], 0, s[12:13]
	s_add_i32 m0, s39, 0x2000
	s_nop 0
	global_load_lds_dwordx4 v[254:255], off
	s_mov_b32 m0, s42
	v_lshl_add_u64 v[254:255], v[214:215], 0, s[12:13]
	global_load_lds_dwordx4 v[254:255], off
	v_lshl_add_u64 v[144:145], v[216:217], 0, s[12:13]
	s_mov_b32 m0, s43
	s_nop 0
	global_load_lds_dwordx4 v[144:145], off
	s_add_u32 s36, s36, 0x40080
	s_addc_u32 s37, s37, 0
	s_add_i32 s38, s38, s7
	v_lshl_add_u64 v[254:255], s[36:37], 0, v[128:129]
	s_mov_b32 m0, s38
	s_nop 0
	global_load_lds_dwordx4 v[254:255], off
	v_lshl_add_u64 v[254:255], s[36:37], 0, v[130:131]
	s_add_i32 m0, s38, 0x2000
	s_nop 0
	global_load_lds_dwordx4 v[254:255], off
	s_waitcnt vmcnt(6)
	s_waitcnt lgkmcnt(0)
	s_barrier
	s_setprio 1
	v_mfma_f32_16x16x32_bf16 v[60:63], v[140:143], v[164:167], v[60:63]
	v_mfma_f32_16x16x32_bf16 v[56:59], v[156:159], v[164:167], v[56:59]
	v_mfma_f32_16x16x32_bf16 v[48:51], v[140:143], v[172:175], v[48:51]
	v_mfma_f32_16x16x32_bf16 v[40:43], v[156:159], v[172:175], v[40:43]
	v_mfma_f32_16x16x32_bf16 v[28:31], v[140:143], v[180:183], v[28:31]
	v_mfma_f32_16x16x32_bf16 v[24:27], v[156:159], v[180:183], v[24:27]
	v_mfma_f32_16x16x32_bf16 v[16:19], v[140:143], v[188:191], v[16:19]
	v_mfma_f32_16x16x32_bf16 v[8:11], v[156:159], v[188:191], v[8:11]
	v_mfma_f32_16x16x32_bf16 v[60:63], v[152:155], v[168:171], v[60:63]
	v_mfma_f32_16x16x32_bf16 v[56:59], v[160:163], v[168:171], v[56:59]
	v_mfma_f32_16x16x32_bf16 v[48:51], v[152:155], v[176:179], v[48:51]
	v_mfma_f32_16x16x32_bf16 v[40:43], v[160:163], v[176:179], v[40:43]
	v_mfma_f32_16x16x32_bf16 v[28:31], v[152:155], v[184:187], v[28:31]
	v_mfma_f32_16x16x32_bf16 v[24:27], v[160:163], v[184:187], v[24:27]
	v_mfma_f32_16x16x32_bf16 v[16:19], v[152:155], v[192:195], v[16:19]
	v_mfma_f32_16x16x32_bf16 v[8:11], v[160:163], v[192:195], v[8:11]
	v_mfma_f32_16x16x32_bf16 v[52:55], v[196:199], v[164:167], v[52:55]
	v_mfma_f32_16x16x32_bf16 v[44:47], v[204:207], v[164:167], v[44:47]
	v_mfma_f32_16x16x32_bf16 v[36:39], v[196:199], v[172:175], v[36:39]
	v_mfma_f32_16x16x32_bf16 v[32:35], v[204:207], v[172:175], v[32:35]
	v_mfma_f32_16x16x32_bf16 v[20:23], v[196:199], v[180:183], v[20:23]
	v_mfma_f32_16x16x32_bf16 v[12:15], v[204:207], v[180:183], v[12:15]
	v_mfma_f32_16x16x32_bf16 v[4:7], v[196:199], v[188:191], v[4:7]
	v_mfma_f32_16x16x32_bf16 v[0:3], v[204:207], v[188:191], v[0:3]
	v_mfma_f32_16x16x32_bf16 v[52:55], v[200:203], v[168:171], v[52:55]
	v_mfma_f32_16x16x32_bf16 v[44:47], v[208:211], v[168:171], v[44:47]
	v_mfma_f32_16x16x32_bf16 v[36:39], v[200:203], v[176:179], v[36:39]
	v_mfma_f32_16x16x32_bf16 v[32:35], v[208:211], v[176:179], v[32:35]
	v_mfma_f32_16x16x32_bf16 v[20:23], v[200:203], v[184:187], v[20:23]
	v_mfma_f32_16x16x32_bf16 v[12:15], v[208:211], v[184:187], v[12:15]
	v_mfma_f32_16x16x32_bf16 v[4:7], v[200:203], v[192:195], v[4:7]
	v_mfma_f32_16x16x32_bf16 v[0:3], v[208:211], v[192:195], v[0:3]
	s_setprio 0
	s_add_i32 s70, s70, 2
	s_add_u32 s34, s34, 0x100
	s_addc_u32 s35, s35, 0
	s_add_u32 s49, s49, 0x100
	s_addc_u32 s63, s63, 0
	s_cmp_gt_u32 s70, 13
	s_barrier
	s_cbranch_scc0 .LBB0_1820
	v_lshl_or_b32 v144, s46, 8, v148
	v_lshl_add_u32 v145, s30, 8, v146
	v_lshlrev_b32_e32 v144, 2, v144
	v_lshl_add_u32 v145, v145, 12, v144
	v_add_u32_e32 v216, 0x10000, v145
	v_add_u32_e32 v217, 0x20000, v145
	v_add_u32_e32 v218, 0x30000, v145
	v_add_u32_e32 v220, 0x80000, v145
	v_add_u32_e32 v221, 0x90000, v145
	v_add_u32_e32 v222, 0xa0000, v145
	v_add_u32_e32 v223, 0xb0000, v145
	v_and_b32_e32 v235, 8, v146
	v_cmp_ne_u32_e32 vcc, 0, v235
	v_mov_b32_e32 v232, 0xffff8040
	s_nop 0
	v_cndmask_b32_e32 v232, 0, v232, vcc
	v_mov_b32_e32 v233, 64
	v_mov_b32_e32 v235, 0x8000
	v_cndmask_b32_e32 v233, v235, v233, vcc
	v_add_u32_e32 v224, v145, v232
	v_add_u32_e32 v225, v216, v232
	v_add_u32_e32 v226, v217, v232
	v_add_u32_e32 v227, v218, v232
	v_add_u32_e32 v228, v220, v232
	v_add_u32_e32 v229, v221, v232
	v_add_u32_e32 v230, v222, v232
	v_add_u32_e32 v231, v223, v232
	s_and_b64 vcc, exec, s[10:11]
	s_mov_b32 s46, s22
	s_mov_b32 s30, s24
	s_mov_b64 s[36:37], s[28:29]
	s_mov_b64 s[34:35], s[26:27]
	global_load_dwordx4 v[140:143], v224, s[52:53]
	v_add_u32_e32 v144, v145, v233
	global_load_dwordx4 v[152:155], v144, s[52:53]
	global_load_dwordx4 v[156:159], v224, s[52:53] offset:512
	v_add_u32_e32 v144, v145, v233
	global_load_dwordx4 v[160:163], v144, s[52:53] offset:512
	global_load_dwordx4 v[164:167], v225, s[52:53]
	v_add_u32_e32 v144, v216, v233
	global_load_dwordx4 v[168:171], v144, s[52:53]
	global_load_dwordx4 v[172:175], v225, s[52:53] offset:512
	v_add_u32_e32 v144, v216, v233
	global_load_dwordx4 v[176:179], v144, s[52:53] offset:512
	global_load_dwordx4 v[180:183], v226, s[52:53]
	v_add_u32_e32 v144, v217, v233
	global_load_dwordx4 v[184:187], v144, s[52:53]
	global_load_dwordx4 v[188:191], v226, s[52:53] offset:512
	v_add_u32_e32 v144, v217, v233
	global_load_dwordx4 v[192:195], v144, s[52:53] offset:512
	global_load_dwordx4 v[196:199], v227, s[52:53]
	v_add_u32_e32 v144, v218, v233
	global_load_dwordx4 v[200:203], v144, s[52:53]
	global_load_dwordx4 v[204:207], v227, s[52:53] offset:512
	v_add_u32_e32 v144, v218, v233
	global_load_dwordx4 v[208:211], v144, s[52:53] offset:512
	s_barrier
;     __device__ __forceinline__ void operator()(AccRef acc, const Unit& u, int wr, int wc, int fr, int fq) const {
;     ...
;                         for (int n = 0; n < 2; ++n) bs[m][bj][n] = *(const f32x4*)(base + (size_t)(row0 + ai * 128 + (2 * mh + m) * 16) * D + col0 + bj * 128 + n * 16);
; #pragma unroll
;                 for (int m = 0; m < 2; ++m)
; #pragma unroll
;                     for (int bj = 0; bj < 2; ++bj)
; #pragma unroll
;                         for (int n = 0; n < 2; ++n) *(f32x4*)(out + (size_t)(row0 + ai * 128 + (2 * mh + m) * 16) * D + col0 + bj * 128 + n * 16) = bs[m][bj][n] + sv[bj][n] * (acc[ai][bj][2 * mh + m][n] + bv[bj][n]);
	v_pk_add_f32 v[124:125], v[124:125], 0 op_sel_hi:[1,0]
	v_pk_add_f32 v[126:127], v[126:127], 0 op_sel_hi:[1,0]
	v_pk_add_f32 v[120:121], v[120:121], 0 op_sel_hi:[1,0]
	v_pk_add_f32 v[122:123], v[122:123], 0 op_sel_hi:[1,0]
	v_pk_add_f32 v[116:117], v[116:117], 0 op_sel_hi:[1,0]
	v_pk_add_f32 v[118:119], v[118:119], 0 op_sel_hi:[1,0]
	v_pk_add_f32 v[108:109], v[108:109], 0 op_sel_hi:[1,0]
	v_pk_add_f32 v[110:111], v[110:111], 0 op_sel_hi:[1,0]
	v_pk_add_f32 v[112:113], v[112:113], 0 op_sel_hi:[1,0]
	v_pk_add_f32 v[114:115], v[114:115], 0 op_sel_hi:[1,0]
	v_pk_add_f32 v[104:105], v[104:105], 0 op_sel_hi:[1,0]
	v_pk_add_f32 v[106:107], v[106:107], 0 op_sel_hi:[1,0]
	v_pk_add_f32 v[100:101], v[100:101], 0 op_sel_hi:[1,0]
	v_pk_add_f32 v[102:103], v[102:103], 0 op_sel_hi:[1,0]
	v_pk_add_f32 v[96:97], v[96:97], 0 op_sel_hi:[1,0]
	v_pk_add_f32 v[98:99], v[98:99], 0 op_sel_hi:[1,0]
	v_pk_add_f32 v[92:93], v[92:93], 0 op_sel_hi:[1,0]
	v_pk_add_f32 v[94:95], v[94:95], 0 op_sel_hi:[1,0]
	v_pk_add_f32 v[88:89], v[88:89], 0 op_sel_hi:[1,0]
	v_pk_add_f32 v[90:91], v[90:91], 0 op_sel_hi:[1,0]
	v_pk_add_f32 v[84:85], v[84:85], 0 op_sel_hi:[1,0]
	v_pk_add_f32 v[86:87], v[86:87], 0 op_sel_hi:[1,0]
	v_pk_add_f32 v[76:77], v[76:77], 0 op_sel_hi:[1,0]
	v_pk_add_f32 v[78:79], v[78:79], 0 op_sel_hi:[1,0]
	v_pk_add_f32 v[80:81], v[80:81], 0 op_sel_hi:[1,0]
	v_pk_add_f32 v[82:83], v[82:83], 0 op_sel_hi:[1,0]
	v_pk_add_f32 v[72:73], v[72:73], 0 op_sel_hi:[1,0]
	v_pk_add_f32 v[74:75], v[74:75], 0 op_sel_hi:[1,0]
	v_pk_add_f32 v[68:69], v[68:69], 0 op_sel_hi:[1,0]
	v_pk_add_f32 v[70:71], v[70:71], 0 op_sel_hi:[1,0]
	v_pk_add_f32 v[64:65], v[64:65], 0 op_sel_hi:[1,0]
	v_pk_add_f32 v[66:67], v[66:67], 0 op_sel_hi:[1,0]
	v_pk_add_f32 v[60:61], v[60:61], 0 op_sel_hi:[1,0]
	v_pk_add_f32 v[62:63], v[62:63], 0 op_sel_hi:[1,0]
	v_pk_add_f32 v[56:57], v[56:57], 0 op_sel_hi:[1,0]
	v_pk_add_f32 v[58:59], v[58:59], 0 op_sel_hi:[1,0]
	v_pk_add_f32 v[52:53], v[52:53], 0 op_sel_hi:[1,0]
	v_pk_add_f32 v[54:55], v[54:55], 0 op_sel_hi:[1,0]
	v_pk_add_f32 v[44:45], v[44:45], 0 op_sel_hi:[1,0]
	v_pk_add_f32 v[46:47], v[46:47], 0 op_sel_hi:[1,0]
	v_pk_add_f32 v[48:49], v[48:49], 0 op_sel_hi:[1,0]
	v_pk_add_f32 v[50:51], v[50:51], 0 op_sel_hi:[1,0]
	v_pk_add_f32 v[40:41], v[40:41], 0 op_sel_hi:[1,0]
	v_pk_add_f32 v[42:43], v[42:43], 0 op_sel_hi:[1,0]
	v_pk_add_f32 v[36:37], v[36:37], 0 op_sel_hi:[1,0]
	v_pk_add_f32 v[38:39], v[38:39], 0 op_sel_hi:[1,0]
	v_pk_add_f32 v[32:33], v[32:33], 0 op_sel_hi:[1,0]
	v_pk_add_f32 v[34:35], v[34:35], 0 op_sel_hi:[1,0]
	v_pk_add_f32 v[28:29], v[28:29], 0 op_sel_hi:[1,0]
	v_pk_add_f32 v[30:31], v[30:31], 0 op_sel_hi:[1,0]
	v_pk_add_f32 v[24:25], v[24:25], 0 op_sel_hi:[1,0]
	v_pk_add_f32 v[26:27], v[26:27], 0 op_sel_hi:[1,0]
	v_pk_add_f32 v[20:21], v[20:21], 0 op_sel_hi:[1,0]
	v_pk_add_f32 v[22:23], v[22:23], 0 op_sel_hi:[1,0]
	v_pk_add_f32 v[12:13], v[12:13], 0 op_sel_hi:[1,0]
	v_pk_add_f32 v[14:15], v[14:15], 0 op_sel_hi:[1,0]
	v_pk_add_f32 v[16:17], v[16:17], 0 op_sel_hi:[1,0]
	v_pk_add_f32 v[18:19], v[18:19], 0 op_sel_hi:[1,0]
	v_pk_add_f32 v[8:9], v[8:9], 0 op_sel_hi:[1,0]
	v_pk_add_f32 v[10:11], v[10:11], 0 op_sel_hi:[1,0]
	v_pk_add_f32 v[4:5], v[4:5], 0 op_sel_hi:[1,0]
	v_pk_add_f32 v[6:7], v[6:7], 0 op_sel_hi:[1,0]
	v_pk_add_f32 v[0:1], v[0:1], 0 op_sel_hi:[1,0]
	v_pk_add_f32 v[2:3], v[2:3], 0 op_sel_hi:[1,0]
	s_waitcnt vmcnt(8)
	v_mov_b32_e32 v212, v124
	v_mov_b32_e32 v213, v125
	v_mov_b32_e32 v214, v126
	v_mov_b32_e32 v215, v127
	s_nop 0
	v_mov_b32_dpp v124, v120 row_shr:8 row_mask:0xf bank_mask:0xc
	v_mov_b32_dpp v125, v121 row_shr:8 row_mask:0xf bank_mask:0xc
	v_mov_b32_dpp v126, v122 row_shr:8 row_mask:0xf bank_mask:0xc
	v_mov_b32_dpp v127, v123 row_shr:8 row_mask:0xf bank_mask:0xc
	v_mov_b32_dpp v120, v212 row_shl:8 row_mask:0xf bank_mask:0x3
	v_mov_b32_dpp v121, v213 row_shl:8 row_mask:0xf bank_mask:0x3
	v_mov_b32_dpp v122, v214 row_shl:8 row_mask:0xf bank_mask:0x3
	v_mov_b32_dpp v123, v215 row_shl:8 row_mask:0xf bank_mask:0x3
	v_mov_b32_e32 v212, v116
	v_mov_b32_e32 v213, v117
	v_mov_b32_e32 v214, v118
	v_mov_b32_e32 v215, v119
	s_nop 0
	v_mov_b32_dpp v116, v108 row_shr:8 row_mask:0xf bank_mask:0xc
	v_mov_b32_dpp v117, v109 row_shr:8 row_mask:0xf bank_mask:0xc
	v_mov_b32_dpp v118, v110 row_shr:8 row_mask:0xf bank_mask:0xc
	v_mov_b32_dpp v119, v111 row_shr:8 row_mask:0xf bank_mask:0xc
	v_mov_b32_dpp v108, v212 row_shl:8 row_mask:0xf bank_mask:0x3
	v_mov_b32_dpp v109, v213 row_shl:8 row_mask:0xf bank_mask:0x3
	v_mov_b32_dpp v110, v214 row_shl:8 row_mask:0xf bank_mask:0x3
	v_mov_b32_dpp v111, v215 row_shl:8 row_mask:0xf bank_mask:0x3
	v_mov_b32_e32 v212, v112
	v_mov_b32_e32 v213, v113
	v_mov_b32_e32 v214, v114
	v_mov_b32_e32 v215, v115
	s_nop 0
	v_mov_b32_dpp v112, v104 row_shr:8 row_mask:0xf bank_mask:0xc
	v_mov_b32_dpp v113, v105 row_shr:8 row_mask:0xf bank_mask:0xc
	v_mov_b32_dpp v114, v106 row_shr:8 row_mask:0xf bank_mask:0xc
	v_mov_b32_dpp v115, v107 row_shr:8 row_mask:0xf bank_mask:0xc
	v_mov_b32_dpp v104, v212 row_shl:8 row_mask:0xf bank_mask:0x3
	v_mov_b32_dpp v105, v213 row_shl:8 row_mask:0xf bank_mask:0x3
	v_mov_b32_dpp v106, v214 row_shl:8 row_mask:0xf bank_mask:0x3
	v_mov_b32_dpp v107, v215 row_shl:8 row_mask:0xf bank_mask:0x3
	v_mov_b32_e32 v212, v100
	v_mov_b32_e32 v213, v101
	v_mov_b32_e32 v214, v102
	v_mov_b32_e32 v215, v103
	s_nop 0
	v_mov_b32_dpp v100, v96 row_shr:8 row_mask:0xf bank_mask:0xc
	v_mov_b32_dpp v101, v97 row_shr:8 row_mask:0xf bank_mask:0xc
	v_mov_b32_dpp v102, v98 row_shr:8 row_mask:0xf bank_mask:0xc
	v_mov_b32_dpp v103, v99 row_shr:8 row_mask:0xf bank_mask:0xc
	v_mov_b32_dpp v96, v212 row_shl:8 row_mask:0xf bank_mask:0x3
;     __device__ __forceinline__ void operator()(AccRef acc, const Unit& u, int wr, int wc, int fr, int fq) const {
;     ...
;                         for (int n = 0; n < 2; ++n) bs[m][bj][n] = *(const f32x4*)(base + (size_t)(row0 + ai * 128 + (2 * mh + m) * 16) * D + col0 + bj * 128 + n * 16);
; #pragma unroll
;                 for (int m = 0; m < 2; ++m)
; #pragma unroll
;                     for (int bj = 0; bj < 2; ++bj)
; #pragma unroll
;                         for (int n = 0; n < 2; ++n) *(f32x4*)(out + (size_t)(row0 + ai * 128 + (2 * mh + m) * 16) * D + col0 + bj * 128 + n * 16) = bs[m][bj][n] + sv[bj][n] * (acc[ai][bj][2 * mh + m][n] + bv[bj][n]);
;                 asm volatile("" ::: "memory"); }
	v_mov_b32_dpp v97, v213 row_shl:8 row_mask:0xf bank_mask:0x3
	v_mov_b32_dpp v98, v214 row_shl:8 row_mask:0xf bank_mask:0x3
	v_mov_b32_dpp v99, v215 row_shl:8 row_mask:0xf bank_mask:0x3
	v_pk_add_f32 v[124:125], v[124:125], v[140:141]
	v_pk_add_f32 v[126:127], v[126:127], v[142:143]
	v_pk_add_f32 v[120:121], v[120:121], v[152:153]
	v_pk_add_f32 v[122:123], v[122:123], v[154:155]
	v_pk_add_f32 v[116:117], v[116:117], v[156:157]
	v_pk_add_f32 v[118:119], v[118:119], v[158:159]
	v_pk_add_f32 v[108:109], v[108:109], v[160:161]
	v_pk_add_f32 v[110:111], v[110:111], v[162:163]
	v_pk_add_f32 v[112:113], v[112:113], v[164:165]
	v_pk_add_f32 v[114:115], v[114:115], v[166:167]
	v_pk_add_f32 v[104:105], v[104:105], v[168:169]
	v_pk_add_f32 v[106:107], v[106:107], v[170:171]
	v_pk_add_f32 v[100:101], v[100:101], v[172:173]
	v_pk_add_f32 v[102:103], v[102:103], v[174:175]
	v_pk_add_f32 v[96:97], v[96:97], v[176:177]
	v_pk_add_f32 v[98:99], v[98:99], v[178:179]
	global_store_dwordx4 v224, v[124:127], s[52:53]
	v_add_u32_e32 v144, v145, v233
	global_store_dwordx4 v144, v[120:123], s[52:53]
	global_store_dwordx4 v224, v[116:119], s[52:53] offset:512
	v_add_u32_e32 v144, v145, v233
	global_store_dwordx4 v144, v[108:111], s[52:53] offset:512
	global_store_dwordx4 v225, v[112:115], s[52:53]
	v_add_u32_e32 v144, v216, v233
	global_store_dwordx4 v144, v[104:107], s[52:53]
	global_store_dwordx4 v225, v[100:103], s[52:53] offset:512
	v_add_u32_e32 v144, v216, v233
	global_store_dwordx4 v144, v[96:99], s[52:53] offset:512
	global_load_dwordx4 v[140:143], v228, s[52:53]
	v_add_u32_e32 v144, v220, v233
	global_load_dwordx4 v[152:155], v144, s[52:53]
	global_load_dwordx4 v[156:159], v228, s[52:53] offset:512
	v_add_u32_e32 v144, v220, v233
	global_load_dwordx4 v[160:163], v144, s[52:53] offset:512
	global_load_dwordx4 v[164:167], v229, s[52:53]
	v_add_u32_e32 v144, v221, v233
	global_load_dwordx4 v[168:171], v144, s[52:53]
	global_load_dwordx4 v[172:175], v229, s[52:53] offset:512
	v_add_u32_e32 v144, v221, v233
	global_load_dwordx4 v[176:179], v144, s[52:53] offset:512
	s_barrier
	s_waitcnt vmcnt(16)
	v_mov_b32_e32 v212, v92
	v_mov_b32_e32 v213, v93
	v_mov_b32_e32 v214, v94
	v_mov_b32_e32 v215, v95
	s_nop 0
	v_mov_b32_dpp v92, v88 row_shr:8 row_mask:0xf bank_mask:0xc
	v_mov_b32_dpp v93, v89 row_shr:8 row_mask:0xf bank_mask:0xc
	v_mov_b32_dpp v94, v90 row_shr:8 row_mask:0xf bank_mask:0xc
	v_mov_b32_dpp v95, v91 row_shr:8 row_mask:0xf bank_mask:0xc
	v_mov_b32_dpp v88, v212 row_shl:8 row_mask:0xf bank_mask:0x3
	v_mov_b32_dpp v89, v213 row_shl:8 row_mask:0xf bank_mask:0x3
	v_mov_b32_dpp v90, v214 row_shl:8 row_mask:0xf bank_mask:0x3
	v_mov_b32_dpp v91, v215 row_shl:8 row_mask:0xf bank_mask:0x3
	v_mov_b32_e32 v212, v84
	v_mov_b32_e32 v213, v85
	v_mov_b32_e32 v214, v86
	v_mov_b32_e32 v215, v87
	s_nop 0
	v_mov_b32_dpp v84, v76 row_shr:8 row_mask:0xf bank_mask:0xc
	v_mov_b32_dpp v85, v77 row_shr:8 row_mask:0xf bank_mask:0xc
	v_mov_b32_dpp v86, v78 row_shr:8 row_mask:0xf bank_mask:0xc
	v_mov_b32_dpp v87, v79 row_shr:8 row_mask:0xf bank_mask:0xc
	v_mov_b32_dpp v76, v212 row_shl:8 row_mask:0xf bank_mask:0x3
	v_mov_b32_dpp v77, v213 row_shl:8 row_mask:0xf bank_mask:0x3
	v_mov_b32_dpp v78, v214 row_shl:8 row_mask:0xf bank_mask:0x3
	v_mov_b32_dpp v79, v215 row_shl:8 row_mask:0xf bank_mask:0x3
	v_mov_b32_e32 v212, v80
	v_mov_b32_e32 v213, v81
	v_mov_b32_e32 v214, v82
	v_mov_b32_e32 v215, v83
	s_nop 0
	v_mov_b32_dpp v80, v72 row_shr:8 row_mask:0xf bank_mask:0xc
	v_mov_b32_dpp v81, v73 row_shr:8 row_mask:0xf bank_mask:0xc
	v_mov_b32_dpp v82, v74 row_shr:8 row_mask:0xf bank_mask:0xc
	v_mov_b32_dpp v83, v75 row_shr:8 row_mask:0xf bank_mask:0xc
	v_mov_b32_dpp v72, v212 row_shl:8 row_mask:0xf bank_mask:0x3
	v_mov_b32_dpp v73, v213 row_shl:8 row_mask:0xf bank_mask:0x3
	v_mov_b32_dpp v74, v214 row_shl:8 row_mask:0xf bank_mask:0x3
	v_mov_b32_dpp v75, v215 row_shl:8 row_mask:0xf bank_mask:0x3
	v_mov_b32_e32 v212, v68
	v_mov_b32_e32 v213, v69
	v_mov_b32_e32 v214, v70
	v_mov_b32_e32 v215, v71
	s_nop 0
	v_mov_b32_dpp v68, v64 row_shr:8 row_mask:0xf bank_mask:0xc
	v_mov_b32_dpp v69, v65 row_shr:8 row_mask:0xf bank_mask:0xc
	v_mov_b32_dpp v70, v66 row_shr:8 row_mask:0xf bank_mask:0xc
	v_mov_b32_dpp v71, v67 row_shr:8 row_mask:0xf bank_mask:0xc
	v_mov_b32_dpp v64, v212 row_shl:8 row_mask:0xf bank_mask:0x3
	v_mov_b32_dpp v65, v213 row_shl:8 row_mask:0xf bank_mask:0x3
	v_mov_b32_dpp v66, v214 row_shl:8 row_mask:0xf bank_mask:0x3
	v_mov_b32_dpp v67, v215 row_shl:8 row_mask:0xf bank_mask:0x3
	v_pk_add_f32 v[92:93], v[92:93], v[180:181]
	v_pk_add_f32 v[94:95], v[94:95], v[182:183]
	v_pk_add_f32 v[88:89], v[88:89], v[184:185]
	v_pk_add_f32 v[90:91], v[90:91], v[186:187]
	v_pk_add_f32 v[84:85], v[84:85], v[188:189]
	v_pk_add_f32 v[86:87], v[86:87], v[190:191]
	v_pk_add_f32 v[76:77], v[76:77], v[192:193]
	v_pk_add_f32 v[78:79], v[78:79], v[194:195]
	v_pk_add_f32 v[80:81], v[80:81], v[196:197]
	v_pk_add_f32 v[82:83], v[82:83], v[198:199]
	v_pk_add_f32 v[72:73], v[72:73], v[200:201]
	v_pk_add_f32 v[74:75], v[74:75], v[202:203]
	v_pk_add_f32 v[68:69], v[68:69], v[204:205]
	v_pk_add_f32 v[70:71], v[70:71], v[206:207]
	v_pk_add_f32 v[64:65], v[64:65], v[208:209]
	v_pk_add_f32 v[66:67], v[66:67], v[210:211]
	global_store_dwordx4 v226, v[92:95], s[52:53]
	v_add_u32_e32 v144, v217, v233
	global_store_dwordx4 v144, v[88:91], s[52:53]
	global_store_dwordx4 v226, v[84:87], s[52:53] offset:512
	v_add_u32_e32 v144, v217, v233
	global_store_dwordx4 v144, v[76:79], s[52:53] offset:512
	global_store_dwordx4 v227, v[80:83], s[52:53]
	v_add_u32_e32 v144, v218, v233
	global_store_dwordx4 v144, v[72:75], s[52:53]
	global_store_dwordx4 v227, v[68:71], s[52:53] offset:512
	v_add_u32_e32 v144, v218, v233
	global_store_dwordx4 v144, v[64:67], s[52:53] offset:512
	global_load_dwordx4 v[180:183], v230, s[52:53]
	v_add_u32_e32 v144, v222, v233
	global_load_dwordx4 v[184:187], v144, s[52:53]
	global_load_dwordx4 v[188:191], v230, s[52:53] offset:512
	v_add_u32_e32 v144, v222, v233
	global_load_dwordx4 v[192:195], v144, s[52:53] offset:512
	global_load_dwordx4 v[196:199], v231, s[52:53]
	v_add_u32_e32 v144, v223, v233
	global_load_dwordx4 v[200:203], v144, s[52:53]
	global_load_dwordx4 v[204:207], v231, s[52:53] offset:512
	v_add_u32_e32 v144, v223, v233
	global_load_dwordx4 v[208:211], v144, s[52:53] offset:512
	s_barrier
;     __device__ __forceinline__ void operator()(AccRef acc, const Unit& u, int wr, int wc, int fr, int fq) const {
;     ...
;                 for (int m = 0; m < 2; ++m)
; #pragma unroll
;                     for (int bj = 0; bj < 2; ++bj)
; #pragma unroll
;                         for (int n = 0; n < 2; ++n) *(f32x4*)(out + (size_t)(row0 + ai * 128 + (2 * mh + m) * 16) * D + col0 + bj * 128 + n * 16) = bs[m][bj][n] + sv[bj][n] * (acc[ai][bj][2 * mh + m][n] + bv[bj][n]);
;                 asm volatile("" ::: "memory"); }
	s_waitcnt vmcnt(16)
	v_mov_b32_e32 v212, v60
	v_mov_b32_e32 v213, v61
	v_mov_b32_e32 v214, v62
	v_mov_b32_e32 v215, v63
	s_nop 0
	v_mov_b32_dpp v60, v56 row_shr:8 row_mask:0xf bank_mask:0xc
	v_mov_b32_dpp v61, v57 row_shr:8 row_mask:0xf bank_mask:0xc
	v_mov_b32_dpp v62, v58 row_shr:8 row_mask:0xf bank_mask:0xc
	v_mov_b32_dpp v63, v59 row_shr:8 row_mask:0xf bank_mask:0xc
	v_mov_b32_dpp v56, v212 row_shl:8 row_mask:0xf bank_mask:0x3
	v_mov_b32_dpp v57, v213 row_shl:8 row_mask:0xf bank_mask:0x3
	v_mov_b32_dpp v58, v214 row_shl:8 row_mask:0xf bank_mask:0x3
	v_mov_b32_dpp v59, v215 row_shl:8 row_mask:0xf bank_mask:0x3
	v_mov_b32_e32 v212, v52
	v_mov_b32_e32 v213, v53
	v_mov_b32_e32 v214, v54
	v_mov_b32_e32 v215, v55
	s_nop 0
	v_mov_b32_dpp v52, v44 row_shr:8 row_mask:0xf bank_mask:0xc
	v_mov_b32_dpp v53, v45 row_shr:8 row_mask:0xf bank_mask:0xc
	v_mov_b32_dpp v54, v46 row_shr:8 row_mask:0xf bank_mask:0xc
	v_mov_b32_dpp v55, v47 row_shr:8 row_mask:0xf bank_mask:0xc
	v_mov_b32_dpp v44, v212 row_shl:8 row_mask:0xf bank_mask:0x3
	v_mov_b32_dpp v45, v213 row_shl:8 row_mask:0xf bank_mask:0x3
	v_mov_b32_dpp v46, v214 row_shl:8 row_mask:0xf bank_mask:0x3
	v_mov_b32_dpp v47, v215 row_shl:8 row_mask:0xf bank_mask:0x3
	v_mov_b32_e32 v212, v48
	v_mov_b32_e32 v213, v49
	v_mov_b32_e32 v214, v50
	v_mov_b32_e32 v215, v51
	s_nop 0
	v_mov_b32_dpp v48, v40 row_shr:8 row_mask:0xf bank_mask:0xc
	v_mov_b32_dpp v49, v41 row_shr:8 row_mask:0xf bank_mask:0xc
	v_mov_b32_dpp v50, v42 row_shr:8 row_mask:0xf bank_mask:0xc
	v_mov_b32_dpp v51, v43 row_shr:8 row_mask:0xf bank_mask:0xc
	v_mov_b32_dpp v40, v212 row_shl:8 row_mask:0xf bank_mask:0x3
	v_mov_b32_dpp v41, v213 row_shl:8 row_mask:0xf bank_mask:0x3
	v_mov_b32_dpp v42, v214 row_shl:8 row_mask:0xf bank_mask:0x3
	v_mov_b32_dpp v43, v215 row_shl:8 row_mask:0xf bank_mask:0x3
	v_mov_b32_e32 v212, v36
	v_mov_b32_e32 v213, v37
	v_mov_b32_e32 v214, v38
	v_mov_b32_e32 v215, v39
	s_nop 0
	v_mov_b32_dpp v36, v32 row_shr:8 row_mask:0xf bank_mask:0xc
	v_mov_b32_dpp v37, v33 row_shr:8 row_mask:0xf bank_mask:0xc
	v_mov_b32_dpp v38, v34 row_shr:8 row_mask:0xf bank_mask:0xc
	v_mov_b32_dpp v39, v35 row_shr:8 row_mask:0xf bank_mask:0xc
	v_mov_b32_dpp v32, v212 row_shl:8 row_mask:0xf bank_mask:0x3
	v_mov_b32_dpp v33, v213 row_shl:8 row_mask:0xf bank_mask:0x3
	v_mov_b32_dpp v34, v214 row_shl:8 row_mask:0xf bank_mask:0x3
	v_mov_b32_dpp v35, v215 row_shl:8 row_mask:0xf bank_mask:0x3
	v_pk_add_f32 v[60:61], v[60:61], v[140:141]
	v_pk_add_f32 v[62:63], v[62:63], v[142:143]
	v_pk_add_f32 v[56:57], v[56:57], v[152:153]
	v_pk_add_f32 v[58:59], v[58:59], v[154:155]
	v_pk_add_f32 v[52:53], v[52:53], v[156:157]
	v_pk_add_f32 v[54:55], v[54:55], v[158:159]
	v_pk_add_f32 v[44:45], v[44:45], v[160:161]
	v_pk_add_f32 v[46:47], v[46:47], v[162:163]
	v_pk_add_f32 v[48:49], v[48:49], v[164:165]
	v_pk_add_f32 v[50:51], v[50:51], v[166:167]
	v_pk_add_f32 v[40:41], v[40:41], v[168:169]
	v_pk_add_f32 v[42:43], v[42:43], v[170:171]
	v_pk_add_f32 v[36:37], v[36:37], v[172:173]
	v_pk_add_f32 v[38:39], v[38:39], v[174:175]
	v_pk_add_f32 v[32:33], v[32:33], v[176:177]
	v_pk_add_f32 v[34:35], v[34:35], v[178:179]
	global_store_dwordx4 v228, v[60:63], s[52:53]
	v_add_u32_e32 v144, v220, v233
	global_store_dwordx4 v144, v[56:59], s[52:53]
	global_store_dwordx4 v228, v[52:55], s[52:53] offset:512
	v_add_u32_e32 v144, v220, v233
	global_store_dwordx4 v144, v[44:47], s[52:53] offset:512
	global_store_dwordx4 v229, v[48:51], s[52:53]
	v_add_u32_e32 v144, v221, v233
	global_store_dwordx4 v144, v[40:43], s[52:53]
	global_store_dwordx4 v229, v[36:39], s[52:53] offset:512
	v_add_u32_e32 v144, v221, v233
	global_store_dwordx4 v144, v[32:35], s[52:53] offset:512
	s_barrier
; #define PG8_WAIT_V(n) asm volatile("s_waitcnt vmcnt(" #n ")" ::: "memory")
; #define PG8_BAR __builtin_amdgcn_s_barrier()
; template <class Epi>
; __device__ __forceinline__ void gemm_phase(LAS unsigned char* lds, const Gemm g, const StaticOrder& S, const Epi& E) {
;     ...
;     PG8_WAIT_V(0);
;     if (wr == 0) PG8_BAR;
;     PG8_BAR;
;     __device__ __forceinline__ void operator()(AccRef acc, const Unit& u, int wr, int wc, int fr, int fq) const {
;     ...
;                 for (int m = 0; m < 2; ++m)
; #pragma unroll
;                     for (int bj = 0; bj < 2; ++bj)
; #pragma unroll
;                         for (int n = 0; n < 2; ++n) *(f32x4*)(out + (size_t)(row0 + ai * 128 + (2 * mh + m) * 16) * D + col0 + bj * 128 + n * 16) = bs[m][bj][n] + sv[bj][n] * (acc[ai][bj][2 * mh + m][n] + bv[bj][n]);
;                 asm volatile("" ::: "memory"); }
	s_waitcnt vmcnt(8)
	v_mov_b32_e32 v212, v28
	v_mov_b32_e32 v213, v29
	v_mov_b32_e32 v214, v30
	v_mov_b32_e32 v215, v31
	s_nop 0
	v_mov_b32_dpp v28, v24 row_shr:8 row_mask:0xf bank_mask:0xc
	v_mov_b32_dpp v29, v25 row_shr:8 row_mask:0xf bank_mask:0xc
	v_mov_b32_dpp v30, v26 row_shr:8 row_mask:0xf bank_mask:0xc
	v_mov_b32_dpp v31, v27 row_shr:8 row_mask:0xf bank_mask:0xc
	v_mov_b32_dpp v24, v212 row_shl:8 row_mask:0xf bank_mask:0x3
	v_mov_b32_dpp v25, v213 row_shl:8 row_mask:0xf bank_mask:0x3
	v_mov_b32_dpp v26, v214 row_shl:8 row_mask:0xf bank_mask:0x3
	v_mov_b32_dpp v27, v215 row_shl:8 row_mask:0xf bank_mask:0x3
	v_mov_b32_e32 v212, v20
	v_mov_b32_e32 v213, v21
	v_mov_b32_e32 v214, v22
	v_mov_b32_e32 v215, v23
	s_nop 0
	v_mov_b32_dpp v20, v12 row_shr:8 row_mask:0xf bank_mask:0xc
	v_mov_b32_dpp v21, v13 row_shr:8 row_mask:0xf bank_mask:0xc
	v_mov_b32_dpp v22, v14 row_shr:8 row_mask:0xf bank_mask:0xc
	v_mov_b32_dpp v23, v15 row_shr:8 row_mask:0xf bank_mask:0xc
	v_mov_b32_dpp v12, v212 row_shl:8 row_mask:0xf bank_mask:0x3
	v_mov_b32_dpp v13, v213 row_shl:8 row_mask:0xf bank_mask:0x3
	v_mov_b32_dpp v14, v214 row_shl:8 row_mask:0xf bank_mask:0x3
	v_mov_b32_dpp v15, v215 row_shl:8 row_mask:0xf bank_mask:0x3
	v_mov_b32_e32 v212, v16
	v_mov_b32_e32 v213, v17
	v_mov_b32_e32 v214, v18
	v_mov_b32_e32 v215, v19
	s_nop 0
	v_mov_b32_dpp v16, v8 row_shr:8 row_mask:0xf bank_mask:0xc
	v_mov_b32_dpp v17, v9 row_shr:8 row_mask:0xf bank_mask:0xc
	v_mov_b32_dpp v18, v10 row_shr:8 row_mask:0xf bank_mask:0xc
	v_mov_b32_dpp v19, v11 row_shr:8 row_mask:0xf bank_mask:0xc
	v_mov_b32_dpp v8, v212 row_shl:8 row_mask:0xf bank_mask:0x3
	v_mov_b32_dpp v9, v213 row_shl:8 row_mask:0xf bank_mask:0x3
	v_mov_b32_dpp v10, v214 row_shl:8 row_mask:0xf bank_mask:0x3
	v_mov_b32_dpp v11, v215 row_shl:8 row_mask:0xf bank_mask:0x3
	v_mov_b32_e32 v212, v4
	v_mov_b32_e32 v213, v5
	v_mov_b32_e32 v214, v6
	v_mov_b32_e32 v215, v7
	s_nop 0
	v_mov_b32_dpp v4, v0 row_shr:8 row_mask:0xf bank_mask:0xc
	v_mov_b32_dpp v5, v1 row_shr:8 row_mask:0xf bank_mask:0xc
	v_mov_b32_dpp v6, v2 row_shr:8 row_mask:0xf bank_mask:0xc
	v_mov_b32_dpp v7, v3 row_shr:8 row_mask:0xf bank_mask:0xc
	v_mov_b32_dpp v0, v212 row_shl:8 row_mask:0xf bank_mask:0x3
	v_mov_b32_dpp v1, v213 row_shl:8 row_mask:0xf bank_mask:0x3
	v_mov_b32_dpp v2, v214 row_shl:8 row_mask:0xf bank_mask:0x3
	v_mov_b32_dpp v3, v215 row_shl:8 row_mask:0xf bank_mask:0x3
	v_pk_add_f32 v[28:29], v[28:29], v[180:181]
	v_pk_add_f32 v[30:31], v[30:31], v[182:183]
	v_pk_add_f32 v[24:25], v[24:25], v[184:185]
	v_pk_add_f32 v[26:27], v[26:27], v[186:187]
	v_pk_add_f32 v[20:21], v[20:21], v[188:189]
	v_pk_add_f32 v[22:23], v[22:23], v[190:191]
	v_pk_add_f32 v[12:13], v[12:13], v[192:193]
	v_pk_add_f32 v[14:15], v[14:15], v[194:195]
	v_pk_add_f32 v[16:17], v[16:17], v[196:197]
	v_pk_add_f32 v[18:19], v[18:19], v[198:199]
	v_pk_add_f32 v[8:9], v[8:9], v[200:201]
	v_pk_add_f32 v[10:11], v[10:11], v[202:203]
	v_pk_add_f32 v[4:5], v[4:5], v[204:205]
	v_pk_add_f32 v[6:7], v[6:7], v[206:207]
	v_pk_add_f32 v[0:1], v[0:1], v[208:209]
	v_pk_add_f32 v[2:3], v[2:3], v[210:211]
	global_store_dwordx4 v230, v[28:31], s[52:53]
	v_add_u32_e32 v144, v222, v233
	global_store_dwordx4 v144, v[24:27], s[52:53]
	global_store_dwordx4 v230, v[20:23], s[52:53] offset:512
	v_add_u32_e32 v144, v222, v233
	global_store_dwordx4 v144, v[12:15], s[52:53] offset:512
	global_store_dwordx4 v231, v[16:19], s[52:53]
	v_add_u32_e32 v144, v223, v233
	global_store_dwordx4 v144, v[8:11], s[52:53]
	global_store_dwordx4 v231, v[4:7], s[52:53] offset:512
	v_add_u32_e32 v144, v223, v233
	global_store_dwordx4 v144, v[0:3], s[52:53] offset:512
	s_cbranch_vccz .LBB0_1813
	s_waitcnt vmcnt(0)
	s_cmpk_gt_u32 s4, 0xff
	s_cbranch_scc1 .LBB0_1824
	s_barrier

; #define PG8_STAGE(bufoff, gbase, voff) do { _Pragma("unroll") for (int _i = 0; _i < 2; ++_i) \
;         __builtin_amdgcn_global_load_lds((const unsigned*)((const char*)(gbase) + (voff)[_i]), (LAS unsigned*)(lds + (bufoff) + ldsw + _i * 8192), 16, 0, 0); } while (0)
; #define PG8_LDA(dst, b, h) do { _Pragma("unroll") for (int m = 0; m < 4; ++m) _Pragma("unroll") for (int k = 0; k < 2; ++k) dst[m][k] = *(const LAS bf16x8*)(lds + PG8_SA(b, h) + aoff + m * 2048 + k * 1024); } while (0)
; #define PG8_LDB(dst, b, h) do { _Pragma("unroll") for (int n = 0; n < 2; ++n) _Pragma("unroll") for (int k = 0; k < 2; ++k) dst[n][k] = *(const LAS bf16x8*)(lds + PG8_SB(b, h) + boff + n * 2048 + k * 1024); } while (0)
; #define PG8_MMA(ai, bj, At, Bt) do { __builtin_amdgcn_s_setprio(1); _Pragma("unroll") for (int m = 0; m < 4; ++m) _Pragma("unroll") for (int n = 0; n < 2; ++n) _Pragma("unroll") for (int k = 0; k < 2; ++k) \
;         acc[ai][bj][m][n] = __builtin_amdgcn_mfma_f32_16x16x32_bf16(Bt[n][k], At[m][k], acc[ai][bj][m][n], 0, 0, 0); __builtin_amdgcn_s_setprio(0); } while (0)
; #define PG8_WAIT_V(n) asm volatile("s_waitcnt vmcnt(" #n ")" ::: "memory")
; #define PG8_WAIT_L(n) asm volatile("s_waitcnt lgkmcnt(" #n ")" ::: "memory")
; #define PG8_BAR __builtin_amdgcn_s_barrier()
; #define PG8_SCHED __builtin_amdgcn_sched_barrier(0)
; template <class Epi>
; __device__ __forceinline__ void gemm_phase(LAS unsigned char* lds, const Gemm g, const StaticOrder& S, const Epi& E) {
;     ...
;             PG8_LDB(B0, 0, 0); PG8_SCHED; PG8_LDA(At, 0, 0); PG8_STAGE(PG8_SA(1, 1), a1 + hstepA, voffA);
;             PG8_WAIT_L(8); PG8_BAR; PG8_WAIT_L(0); PG8_MMA(0, 0, At, B0); PG8_BAR; PG8_SCHED;
;             PG8_LDB(B1, 0, 1); PG8_STAGE(PG8_SB(0, 0), b2, voffB);
;             PG8_BAR; PG8_WAIT_L(0); PG8_MMA(0, 1, At, B1); PG8_BAR;
;             PG8_LDA(At, 0, 1); PG8_STAGE(PG8_SA(0, 0), a2, voffA);
;             PG8_BAR; PG8_WAIT_L(0); PG8_MMA(1, 0, At, B0); PG8_BAR; PG8_SCHED;
;             PG8_STAGE(PG8_SB(0, 1), b2 + hstepB, voffB);
;             PG8_WAIT_V(6); PG8_BAR; PG8_MMA(1, 1, At, B1); PG8_BAR;
.LBB0_2042:
	ds_read_b128 v[140:143], v149
	ds_read_b128 v[152:155], v149 offset:1024
	ds_read_b128 v[156:159], v149 offset:2048
	ds_read_b128 v[160:163], v149 offset:3072
	s_add_u32 s20, s18, 0x100
	s_addc_u32 s21, s19, 0
	s_cmp_eq_u32 s46, 40
	s_cselect_b32 s25, s5, s21
	s_cselect_b32 s24, s4, s20
	s_cselect_b32 s23, s7, s45
	s_cselect_b32 s22, s6, s44
	v_lshl_add_u64 v[144:145], s[18:19], 0, v[132:133]
	s_add_i32 m0, s30, 0xc000
	ds_read_b128 v[164:167], v150
	ds_read_b128 v[168:171], v150 offset:1024
	ds_read_b128 v[172:175], v150 offset:2048
	ds_read_b128 v[176:179], v150 offset:3072
	ds_read_b128 v[180:183], v150 offset:4096
	ds_read_b128 v[184:187], v150 offset:5120
	ds_read_b128 v[188:191], v150 offset:6144
	ds_read_b128 v[192:195], v150 offset:7168
	global_load_lds_dwordx4 v[144:145], off
	v_lshl_add_u64 v[144:145], s[18:19], 0, v[134:135]
	s_add_i32 m0, s30, 0xe000
	s_nop 0
	global_load_lds_dwordx4 v[144:145], off
	ds_read_b128 v[196:199], v151
	ds_read_b128 v[200:203], v151 offset:1024
	ds_read_b128 v[204:207], v151 offset:2048
	ds_read_b128 v[208:211], v151 offset:3072
	s_waitcnt lgkmcnt(0)
	s_barrier
	s_setprio 1
	v_mfma_f32_16x16x32_bf16 v[124:127], v[140:143], v[164:167], v[124:127]
	v_mfma_f32_16x16x32_bf16 v[120:123], v[156:159], v[164:167], v[120:123]
	v_mfma_f32_16x16x32_bf16 v[112:115], v[140:143], v[172:175], v[112:115]
	v_mfma_f32_16x16x32_bf16 v[104:107], v[156:159], v[172:175], v[104:107]
	v_mfma_f32_16x16x32_bf16 v[92:95], v[140:143], v[180:183], v[92:95]
	v_mfma_f32_16x16x32_bf16 v[88:91], v[156:159], v[180:183], v[88:91]
	v_mfma_f32_16x16x32_bf16 v[80:83], v[140:143], v[188:191], v[80:83]
	v_mfma_f32_16x16x32_bf16 v[72:75], v[156:159], v[188:191], v[72:75]
	v_mfma_f32_16x16x32_bf16 v[124:127], v[152:155], v[168:171], v[124:127]
	v_mfma_f32_16x16x32_bf16 v[120:123], v[160:163], v[168:171], v[120:123]
	v_mfma_f32_16x16x32_bf16 v[112:115], v[152:155], v[176:179], v[112:115]
	v_mfma_f32_16x16x32_bf16 v[104:107], v[160:163], v[176:179], v[104:107]
	v_mfma_f32_16x16x32_bf16 v[92:95], v[152:155], v[184:187], v[92:95]
	v_mfma_f32_16x16x32_bf16 v[88:91], v[160:163], v[184:187], v[88:91]
	v_mfma_f32_16x16x32_bf16 v[80:83], v[152:155], v[192:195], v[80:83]
	v_mfma_f32_16x16x32_bf16 v[72:75], v[160:163], v[192:195], v[72:75]
	v_mfma_f32_16x16x32_bf16 v[116:119], v[196:199], v[164:167], v[116:119]
	v_mfma_f32_16x16x32_bf16 v[108:111], v[204:207], v[164:167], v[108:111]
	v_mfma_f32_16x16x32_bf16 v[100:103], v[196:199], v[172:175], v[100:103]
	v_mfma_f32_16x16x32_bf16 v[96:99], v[204:207], v[172:175], v[96:99]
	v_mfma_f32_16x16x32_bf16 v[84:87], v[196:199], v[180:183], v[84:87]
	v_mfma_f32_16x16x32_bf16 v[76:79], v[204:207], v[180:183], v[76:79]
	v_mfma_f32_16x16x32_bf16 v[68:71], v[196:199], v[188:191], v[68:71]
	v_mfma_f32_16x16x32_bf16 v[64:67], v[204:207], v[188:191], v[64:67]
	v_mfma_f32_16x16x32_bf16 v[116:119], v[200:203], v[168:171], v[116:119]
	v_mfma_f32_16x16x32_bf16 v[108:111], v[208:211], v[168:171], v[108:111]
	v_mfma_f32_16x16x32_bf16 v[100:103], v[200:203], v[176:179], v[100:103]
	v_mfma_f32_16x16x32_bf16 v[96:99], v[208:211], v[176:179], v[96:99]
	v_mfma_f32_16x16x32_bf16 v[84:87], v[200:203], v[184:187], v[84:87]
	v_mfma_f32_16x16x32_bf16 v[76:79], v[208:211], v[184:187], v[76:79]
	v_mfma_f32_16x16x32_bf16 v[68:71], v[200:203], v[192:195], v[68:71]
	v_mfma_f32_16x16x32_bf16 v[64:67], v[208:211], v[192:195], v[64:67]
	s_setprio 0
	s_barrier
	s_nop 1
	ds_read_b128 v[164:167], v150 offset:16384
	ds_read_b128 v[168:171], v150 offset:17408
	ds_read_b128 v[172:175], v150 offset:18432
	ds_read_b128 v[176:179], v150 offset:19456
	ds_read_b128 v[180:183], v150 offset:20480
	ds_read_b128 v[184:187], v150 offset:21504
	ds_read_b128 v[188:191], v150 offset:22528
	ds_read_b128 v[192:195], v150 offset:23552
	s_add_i32 s18, s38, s29
	v_lshl_add_u64 v[144:145], s[22:23], 0, v[128:129]
	s_mov_b32 m0, s18
	s_nop 0
	global_load_lds_dwordx4 v[144:145], off
	v_lshl_add_u64 v[212:213], s[22:23], 0, v[130:131]
	s_add_i32 m0, s18, 0x2000
	s_nop 0
	global_load_lds_dwordx4 v[212:213], off
	s_mov_b32 m0, s30
	v_lshl_add_u64 v[214:215], s[24:25], 0, v[128:129]
	global_load_lds_dwordx4 v[214:215], off
	v_lshl_add_u64 v[216:217], s[24:25], 0, v[130:131]
	s_mov_b32 m0, s31
	s_nop 0
	global_load_lds_dwordx4 v[216:217], off
	s_add_u32 s18, s22, 0xb0000
	s_addc_u32 s19, s23, 0
	s_add_i32 s47, s39, s29
	v_lshl_add_u64 v[254:255], s[18:19], 0, v[128:129]
	s_mov_b32 m0, s47
	s_nop 0
	global_load_lds_dwordx4 v[254:255], off
	v_lshl_add_u64 v[254:255], s[18:19], 0, v[130:131]
	s_add_i32 m0, s47, 0x2000
	s_nop 0
	global_load_lds_dwordx4 v[254:255], off
	s_waitcnt vmcnt(6)
	s_waitcnt lgkmcnt(0)
	s_barrier
; #define PG8_STAGE(bufoff, gbase, voff) do { _Pragma("unroll") for (int _i = 0; _i < 2; ++_i) \
;         __builtin_amdgcn_global_load_lds((const unsigned*)((const char*)(gbase) + (voff)[_i]), (LAS unsigned*)(lds + (bufoff) + ldsw + _i * 8192), 16, 0, 0); } while (0)
; #define PG8_LDA(dst, b, h) do { _Pragma("unroll") for (int m = 0; m < 4; ++m) _Pragma("unroll") for (int k = 0; k < 2; ++k) dst[m][k] = *(const LAS bf16x8*)(lds + PG8_SA(b, h) + aoff + m * 2048 + k * 1024); } while (0)
; #define PG8_LDB(dst, b, h) do { _Pragma("unroll") for (int n = 0; n < 2; ++n) _Pragma("unroll") for (int k = 0; k < 2; ++k) dst[n][k] = *(const LAS bf16x8*)(lds + PG8_SB(b, h) + boff + n * 2048 + k * 1024); } while (0)
; #define PG8_WAIT_V(n) asm volatile("s_waitcnt vmcnt(" #n ")" ::: "memory")
; #define PG8_WAIT_L(n) asm volatile("s_waitcnt lgkmcnt(" #n ")" ::: "memory")
; #define PG8_BAR __builtin_amdgcn_s_barrier()
; #define PG8_SCHED __builtin_amdgcn_sched_barrier(0)
; template <class Epi>
; __device__ __forceinline__ void gemm_phase(LAS unsigned char* lds, const Gemm g, const StaticOrder& S, const Epi& E) {
;     ...
;             PG8_LDB(B0, 0, 0); PG8_SCHED; PG8_LDA(At, 0, 0); PG8_STAGE(PG8_SA(1, 1), a1 + hstepA, voffA);
;             PG8_WAIT_L(8); PG8_BAR; PG8_WAIT_L(0); PG8_MMA(0, 0, At, B0); PG8_BAR; PG8_SCHED;
;             PG8_LDB(B1, 0, 1); PG8_STAGE(PG8_SB(0, 0), b2, voffB);
;             PG8_BAR; PG8_WAIT_L(0); PG8_MMA(0, 1, At, B1); PG8_BAR;
;             PG8_LDA(At, 0, 1); PG8_STAGE(PG8_SA(0, 0), a2, voffA);
;             PG8_BAR; PG8_WAIT_L(0); PG8_MMA(1, 0, At, B0); PG8_BAR; PG8_SCHED;
;             PG8_STAGE(PG8_SB(0, 1), b2 + hstepB, voffB);
;             PG8_WAIT_V(6); PG8_BAR; PG8_MMA(1, 1, At, B1); PG8_BAR;
;             PG8_LDB(B0, 1, 0); PG8_SCHED; PG8_LDA(At, 1, 0); PG8_STAGE(PG8_SA(0, 1), a2 + hstepA, voffA);
;             PG8_WAIT_L(8); PG8_BAR; PG8_WAIT_L(0); PG8_MMA(0, 0, At, B0); PG8_BAR; PG8_SCHED;
;             PG8_LDB(B1, 1, 1); PG8_STAGE(PG8_SB(1, 0), b3, voffB);
;             PG8_BAR; PG8_WAIT_L(0); PG8_MMA(0, 1, At, B1); PG8_BAR;
;             PG8_LDA(At, 1, 1); PG8_STAGE(PG8_SA(1, 0), a3, voffA);
;             PG8_BAR; PG8_WAIT_L(0); PG8_MMA(1, 0, At, B0); PG8_BAR; PG8_SCHED;
;             PG8_STAGE(PG8_SB(1, 1), b3 + hstepB, voffB);
;             PG8_WAIT_V(6); PG8_BAR; PG8_MMA(1, 1, At, B1); PG8_BAR;
	s_setprio 1
	v_mfma_f32_16x16x32_bf16 v[60:63], v[140:143], v[164:167], v[60:63]
	v_mfma_f32_16x16x32_bf16 v[56:59], v[156:159], v[164:167], v[56:59]
	v_mfma_f32_16x16x32_bf16 v[48:51], v[140:143], v[172:175], v[48:51]
	v_mfma_f32_16x16x32_bf16 v[40:43], v[156:159], v[172:175], v[40:43]
	v_mfma_f32_16x16x32_bf16 v[28:31], v[140:143], v[180:183], v[28:31]
	v_mfma_f32_16x16x32_bf16 v[24:27], v[156:159], v[180:183], v[24:27]
	v_mfma_f32_16x16x32_bf16 v[16:19], v[140:143], v[188:191], v[16:19]
	v_mfma_f32_16x16x32_bf16 v[8:11], v[156:159], v[188:191], v[8:11]
	v_mfma_f32_16x16x32_bf16 v[60:63], v[152:155], v[168:171], v[60:63]
	v_mfma_f32_16x16x32_bf16 v[56:59], v[160:163], v[168:171], v[56:59]
	v_mfma_f32_16x16x32_bf16 v[48:51], v[152:155], v[176:179], v[48:51]
	v_mfma_f32_16x16x32_bf16 v[40:43], v[160:163], v[176:179], v[40:43]
	v_mfma_f32_16x16x32_bf16 v[28:31], v[152:155], v[184:187], v[28:31]
	v_mfma_f32_16x16x32_bf16 v[24:27], v[160:163], v[184:187], v[24:27]
	v_mfma_f32_16x16x32_bf16 v[16:19], v[152:155], v[192:195], v[16:19]
	v_mfma_f32_16x16x32_bf16 v[8:11], v[160:163], v[192:195], v[8:11]
	v_mfma_f32_16x16x32_bf16 v[52:55], v[196:199], v[164:167], v[52:55]
	v_mfma_f32_16x16x32_bf16 v[44:47], v[204:207], v[164:167], v[44:47]
	v_mfma_f32_16x16x32_bf16 v[36:39], v[196:199], v[172:175], v[36:39]
	v_mfma_f32_16x16x32_bf16 v[32:35], v[204:207], v[172:175], v[32:35]
	v_mfma_f32_16x16x32_bf16 v[20:23], v[196:199], v[180:183], v[20:23]
	v_mfma_f32_16x16x32_bf16 v[12:15], v[204:207], v[180:183], v[12:15]
	v_mfma_f32_16x16x32_bf16 v[4:7], v[196:199], v[188:191], v[4:7]
	v_mfma_f32_16x16x32_bf16 v[0:3], v[204:207], v[188:191], v[0:3]
	v_mfma_f32_16x16x32_bf16 v[52:55], v[200:203], v[168:171], v[52:55]
	v_mfma_f32_16x16x32_bf16 v[44:47], v[208:211], v[168:171], v[44:47]
	v_mfma_f32_16x16x32_bf16 v[36:39], v[200:203], v[176:179], v[36:39]
	v_mfma_f32_16x16x32_bf16 v[32:35], v[208:211], v[176:179], v[32:35]
	v_mfma_f32_16x16x32_bf16 v[20:23], v[200:203], v[184:187], v[20:23]
	v_mfma_f32_16x16x32_bf16 v[12:15], v[208:211], v[184:187], v[12:15]
	v_mfma_f32_16x16x32_bf16 v[4:7], v[200:203], v[192:195], v[4:7]
	v_mfma_f32_16x16x32_bf16 v[0:3], v[208:211], v[192:195], v[0:3]
	s_setprio 0
	s_add_i32 s47, 0, 0x18000
	v_add_u32_e32 v160, s47, v147
	s_barrier
	ds_read_b128 v[140:143], v160
	ds_read_b128 v[152:155], v160 offset:1024
	ds_read_b128 v[156:159], v160 offset:2048
	ds_read_b128 v[160:163], v160 offset:3072
	s_add_u32 s18, s24, 0xb0000
	s_addc_u32 s19, s25, 0
	s_mov_b32 m0, s33
	v_lshl_add_u64 v[196:197], s[18:19], 0, v[128:129]
	ds_read_b128 v[164:167], v150 offset:32768
	ds_read_b128 v[168:171], v150 offset:33792
	ds_read_b128 v[172:175], v150 offset:34816
	ds_read_b128 v[176:179], v150 offset:35840
	ds_read_b128 v[180:183], v150 offset:36864
	ds_read_b128 v[184:187], v150 offset:37888
	ds_read_b128 v[188:191], v150 offset:38912
	ds_read_b128 v[192:195], v150 offset:39936
	global_load_lds_dwordx4 v[196:197], off
	v_lshl_add_u64 v[196:197], s[18:19], 0, v[130:131]
	s_mov_b32 m0, s34
	s_nop 0
	global_load_lds_dwordx4 v[196:197], off
	s_add_i32 s24, 0, 0x1c000
	v_add_u32_e32 v208, s24, v147
	ds_read_b128 v[196:199], v208
	ds_read_b128 v[200:203], v208 offset:1024
	ds_read_b128 v[204:207], v208 offset:2048
	ds_read_b128 v[208:211], v208 offset:3072
	s_waitcnt lgkmcnt(0)
	s_barrier
	s_setprio 1
	v_mfma_f32_16x16x32_bf16 v[124:127], v[140:143], v[164:167], v[124:127]
	v_mfma_f32_16x16x32_bf16 v[120:123], v[156:159], v[164:167], v[120:123]
	v_mfma_f32_16x16x32_bf16 v[112:115], v[140:143], v[172:175], v[112:115]
	v_mfma_f32_16x16x32_bf16 v[104:107], v[156:159], v[172:175], v[104:107]
	v_mfma_f32_16x16x32_bf16 v[92:95], v[140:143], v[180:183], v[92:95]
	v_mfma_f32_16x16x32_bf16 v[88:91], v[156:159], v[180:183], v[88:91]
	v_mfma_f32_16x16x32_bf16 v[80:83], v[140:143], v[188:191], v[80:83]
	v_mfma_f32_16x16x32_bf16 v[72:75], v[156:159], v[188:191], v[72:75]
	v_mfma_f32_16x16x32_bf16 v[124:127], v[152:155], v[168:171], v[124:127]
	v_mfma_f32_16x16x32_bf16 v[120:123], v[160:163], v[168:171], v[120:123]
	v_mfma_f32_16x16x32_bf16 v[112:115], v[152:155], v[176:179], v[112:115]
	v_mfma_f32_16x16x32_bf16 v[104:107], v[160:163], v[176:179], v[104:107]
	v_mfma_f32_16x16x32_bf16 v[92:95], v[152:155], v[184:187], v[92:95]
	v_mfma_f32_16x16x32_bf16 v[88:91], v[160:163], v[184:187], v[88:91]
	v_mfma_f32_16x16x32_bf16 v[80:83], v[152:155], v[192:195], v[80:83]
	v_mfma_f32_16x16x32_bf16 v[72:75], v[160:163], v[192:195], v[72:75]
	v_mfma_f32_16x16x32_bf16 v[116:119], v[196:199], v[164:167], v[116:119]
	v_mfma_f32_16x16x32_bf16 v[108:111], v[204:207], v[164:167], v[108:111]
	v_mfma_f32_16x16x32_bf16 v[100:103], v[196:199], v[172:175], v[100:103]
	v_mfma_f32_16x16x32_bf16 v[96:99], v[204:207], v[172:175], v[96:99]
	v_mfma_f32_16x16x32_bf16 v[84:87], v[196:199], v[180:183], v[84:87]
	v_mfma_f32_16x16x32_bf16 v[76:79], v[204:207], v[180:183], v[76:79]
	v_mfma_f32_16x16x32_bf16 v[68:71], v[196:199], v[188:191], v[68:71]
	v_mfma_f32_16x16x32_bf16 v[64:67], v[204:207], v[188:191], v[64:67]
	v_mfma_f32_16x16x32_bf16 v[116:119], v[200:203], v[168:171], v[116:119]
	v_mfma_f32_16x16x32_bf16 v[108:111], v[208:211], v[168:171], v[108:111]
	v_mfma_f32_16x16x32_bf16 v[100:103], v[200:203], v[176:179], v[100:103]
	v_mfma_f32_16x16x32_bf16 v[96:99], v[208:211], v[176:179], v[96:99]
	v_mfma_f32_16x16x32_bf16 v[84:87], v[200:203], v[184:187], v[84:87]
	v_mfma_f32_16x16x32_bf16 v[76:79], v[208:211], v[184:187], v[76:79]
	v_mfma_f32_16x16x32_bf16 v[68:71], v[200:203], v[192:195], v[68:71]
	v_mfma_f32_16x16x32_bf16 v[64:67], v[208:211], v[192:195], v[64:67]
	s_setprio 0
	s_barrier
; #define PG8_STAGE(bufoff, gbase, voff) do { _Pragma("unroll") for (int _i = 0; _i < 2; ++_i) \
;         __builtin_amdgcn_global_load_lds((const unsigned*)((const char*)(gbase) + (voff)[_i]), (LAS unsigned*)(lds + (bufoff) + ldsw + _i * 8192), 16, 0, 0); } while (0)
; #define PG8_WAIT_V(n) asm volatile("s_waitcnt vmcnt(" #n ")" ::: "memory")
; #define PG8_WAIT_L(n) asm volatile("s_waitcnt lgkmcnt(" #n ")" ::: "memory")
; #define PG8_BAR __builtin_amdgcn_s_barrier()
; template <class Epi>
; __device__ __forceinline__ void gemm_phase(LAS unsigned char* lds, const Gemm g, const StaticOrder& S, const Epi& E) {
;     ...
;             PG8_WAIT_V(6); PG8_BAR; PG8_MMA(1, 1, At, B1); PG8_BAR;
;             PG8_LDB(B0, 1, 0); PG8_SCHED; PG8_LDA(At, 1, 0); PG8_STAGE(PG8_SA(0, 1), a2 + hstepA, voffA);
;             PG8_WAIT_L(8); PG8_BAR; PG8_WAIT_L(0); PG8_MMA(0, 0, At, B0); PG8_BAR; PG8_SCHED;
;             PG8_LDB(B1, 1, 1); PG8_STAGE(PG8_SB(1, 0), b3, voffB);
;             PG8_BAR; PG8_WAIT_L(0); PG8_MMA(0, 1, At, B1); PG8_BAR;
;             PG8_LDA(At, 1, 1); PG8_STAGE(PG8_SA(1, 0), a3, voffA);
;             PG8_BAR; PG8_WAIT_L(0); PG8_MMA(1, 0, At, B0); PG8_BAR; PG8_SCHED;
;             PG8_STAGE(PG8_SB(1, 1), b3 + hstepB, voffB);
;             PG8_WAIT_V(6); PG8_BAR; PG8_MMA(1, 1, At, B1); PG8_BAR;
;     __device__ __forceinline__ void operator()(AccRef acc, const Unit& u, int wr, int wc, int fr, int fq) const {
;         const int row0 = u.pm * 256 + wr * 64 + fr, col0 = u.pn * 256 + wc * 32 + 4 * fq;
;         f32x4 sv[2][2], bv[2][2];
; #pragma unroll
;         for (int bj = 0; bj < 2; ++bj)
; #pragma unroll
;             for (int n = 0; n < 2; ++n) {
;                 sv[bj][n] = scale ? *(const f32x4*)(scale + col0 + bj * 128 + n * 16) : (f32x4){1.f, 1.f, 1.f, 1.f};
;                 bv[bj][n] = bias ? *(const f32x4*)(bias + col0 + bj * 128 + n * 16) : (f32x4){0.f, 0.f, 0.f, 0.f}; }
; #pragma unroll
;         for (int ai = 0; ai < 2; ++ai)
; #pragma unroll
;             for (int mh = 0; mh < 2; ++mh) {
;                 f32x4 bs[2][2][2];
; #pragma unroll
;                 for (int m = 0; m < 2; ++m)
; #pragma unroll
;                     for (int bj = 0; bj < 2; ++bj)
; #pragma unroll
;                         for (int n = 0; n < 2; ++n) bs[m][bj][n] = *(const f32x4*)(base + (size_t)(row0 + ai * 128 + (2 * mh + m) * 16) * D + col0 + bj * 128 + n * 16);
	s_nop 1
	ds_read_b128 v[164:167], v150 offset:49152
	ds_read_b128 v[168:171], v150 offset:50176
	ds_read_b128 v[172:175], v150 offset:51200
	ds_read_b128 v[176:179], v150 offset:52224
	ds_read_b128 v[180:183], v150 offset:53248
	ds_read_b128 v[184:187], v150 offset:54272
	ds_read_b128 v[188:191], v150 offset:55296
	ds_read_b128 v[192:195], v150 offset:56320
	s_add_i32 s18, s47, s29
	v_lshl_add_u64 v[254:255], v[144:145], 0, s[10:11]
	s_mov_b32 m0, s18
	s_nop 0
	global_load_lds_dwordx4 v[254:255], off
	v_lshl_add_u64 v[254:255], v[212:213], 0, s[10:11]
	s_add_i32 m0, s18, 0x2000
	s_nop 0
	global_load_lds_dwordx4 v[254:255], off
	s_mov_b32 m0, s36
	v_lshl_add_u64 v[254:255], v[214:215], 0, s[10:11]
	global_load_lds_dwordx4 v[254:255], off
	v_lshl_add_u64 v[144:145], v[216:217], 0, s[10:11]
	s_mov_b32 m0, s37
	s_nop 0
	global_load_lds_dwordx4 v[144:145], off
	s_add_u32 s18, s22, 0xb0080
	s_addc_u32 s19, s23, 0
	s_add_i32 s22, s24, s29
	v_lshl_add_u64 v[254:255], s[18:19], 0, v[128:129]
	s_mov_b32 m0, s22
	s_nop 0
	global_load_lds_dwordx4 v[254:255], off
	v_lshl_add_u64 v[254:255], s[18:19], 0, v[130:131]
	s_add_i32 m0, s22, 0x2000
	s_nop 0
	global_load_lds_dwordx4 v[254:255], off
	s_waitcnt vmcnt(6)
	s_waitcnt lgkmcnt(0)
	s_barrier
	s_setprio 1
	v_mfma_f32_16x16x32_bf16 v[60:63], v[140:143], v[164:167], v[60:63]
	v_mfma_f32_16x16x32_bf16 v[56:59], v[156:159], v[164:167], v[56:59]
	v_mfma_f32_16x16x32_bf16 v[48:51], v[140:143], v[172:175], v[48:51]
	v_mfma_f32_16x16x32_bf16 v[40:43], v[156:159], v[172:175], v[40:43]
	v_mfma_f32_16x16x32_bf16 v[28:31], v[140:143], v[180:183], v[28:31]
	v_mfma_f32_16x16x32_bf16 v[24:27], v[156:159], v[180:183], v[24:27]
	v_mfma_f32_16x16x32_bf16 v[16:19], v[140:143], v[188:191], v[16:19]
	v_mfma_f32_16x16x32_bf16 v[8:11], v[156:159], v[188:191], v[8:11]
	v_mfma_f32_16x16x32_bf16 v[60:63], v[152:155], v[168:171], v[60:63]
	v_mfma_f32_16x16x32_bf16 v[56:59], v[160:163], v[168:171], v[56:59]
	v_mfma_f32_16x16x32_bf16 v[48:51], v[152:155], v[176:179], v[48:51]
	v_mfma_f32_16x16x32_bf16 v[40:43], v[160:163], v[176:179], v[40:43]
	v_mfma_f32_16x16x32_bf16 v[28:31], v[152:155], v[184:187], v[28:31]
	v_mfma_f32_16x16x32_bf16 v[24:27], v[160:163], v[184:187], v[24:27]
	v_mfma_f32_16x16x32_bf16 v[16:19], v[152:155], v[192:195], v[16:19]
	v_mfma_f32_16x16x32_bf16 v[8:11], v[160:163], v[192:195], v[8:11]
	v_mfma_f32_16x16x32_bf16 v[52:55], v[196:199], v[164:167], v[52:55]
	v_mfma_f32_16x16x32_bf16 v[44:47], v[204:207], v[164:167], v[44:47]
	v_mfma_f32_16x16x32_bf16 v[36:39], v[196:199], v[172:175], v[36:39]
	v_mfma_f32_16x16x32_bf16 v[32:35], v[204:207], v[172:175], v[32:35]
	v_mfma_f32_16x16x32_bf16 v[20:23], v[196:199], v[180:183], v[20:23]
	v_mfma_f32_16x16x32_bf16 v[12:15], v[204:207], v[180:183], v[12:15]
	v_mfma_f32_16x16x32_bf16 v[4:7], v[196:199], v[188:191], v[4:7]
	v_mfma_f32_16x16x32_bf16 v[0:3], v[204:207], v[188:191], v[0:3]
	v_mfma_f32_16x16x32_bf16 v[52:55], v[200:203], v[168:171], v[52:55]
	v_mfma_f32_16x16x32_bf16 v[44:47], v[208:211], v[168:171], v[44:47]
	v_mfma_f32_16x16x32_bf16 v[36:39], v[200:203], v[176:179], v[36:39]
	v_mfma_f32_16x16x32_bf16 v[32:35], v[208:211], v[176:179], v[32:35]
	v_mfma_f32_16x16x32_bf16 v[20:23], v[200:203], v[184:187], v[20:23]
	v_mfma_f32_16x16x32_bf16 v[12:15], v[208:211], v[184:187], v[12:15]
	v_mfma_f32_16x16x32_bf16 v[4:7], v[200:203], v[192:195], v[4:7]
	v_mfma_f32_16x16x32_bf16 v[0:3], v[208:211], v[192:195], v[0:3]
	s_setprio 0
	s_add_i32 s46, s46, 2
	s_add_u32 s44, s44, 0x100
	s_addc_u32 s45, s45, 0
	s_cmp_gt_u32 s46, 41
	s_mov_b64 s[18:19], s[20:21]
	s_barrier
	s_cbranch_scc0 .LBB0_2042
	v_lshl_or_b32 v144, s42, 8, v148
	v_lshl_add_u32 v145, s43, 8, v146
	v_lshlrev_b32_e32 v144, 2, v144
	v_lshl_add_u32 v145, v145, 12, v144
	v_add_u32_e32 v216, 0x10000, v145
	v_add_u32_e32 v217, 0x20000, v145
	v_add_u32_e32 v218, 0x30000, v145
	v_add_u32_e32 v220, 0x80000, v145
	v_add_u32_e32 v221, 0x90000, v145
	v_add_u32_e32 v222, 0xa0000, v145
	v_add_u32_e32 v223, 0xb0000, v145
	v_and_b32_e32 v235, 8, v146
	v_cmp_ne_u32_e32 vcc, 0, v235
	v_mov_b32_e32 v232, 0xffff8040
	s_nop 0
	v_cndmask_b32_e32 v232, 0, v232, vcc
	v_mov_b32_e32 v233, 64
	v_mov_b32_e32 v235, 0x8000
	v_cndmask_b32_e32 v233, v235, v233, vcc
	v_add_u32_e32 v224, v145, v232
	v_add_u32_e32 v225, v216, v232
	v_add_u32_e32 v226, v217, v232
	v_add_u32_e32 v227, v218, v232
	v_add_u32_e32 v228, v220, v232
	v_add_u32_e32 v229, v221, v232
	v_add_u32_e32 v230, v222, v232
	v_add_u32_e32 v231, v223, v232
	s_and_b64 vcc, exec, s[0:1]
	s_mov_b32 s42, s40
	s_mov_b32 s43, s41
	s_mov_b64 s[20:21], s[6:7]
	s_mov_b64 s[18:19], s[4:5]
	global_load_dwordx4 v[140:143], v224, s[52:53]
	v_add_u32_e32 v144, v145, v233
	global_load_dwordx4 v[152:155], v144, s[52:53]
	global_load_dwordx4 v[156:159], v224, s[52:53] offset:512
	v_add_u32_e32 v144, v145, v233
	global_load_dwordx4 v[160:163], v144, s[52:53] offset:512
	global_load_dwordx4 v[164:167], v225, s[52:53]
	v_add_u32_e32 v144, v216, v233
	global_load_dwordx4 v[168:171], v144, s[52:53]
	global_load_dwordx4 v[172:175], v225, s[52:53] offset:512
	v_add_u32_e32 v144, v216, v233
	global_load_dwordx4 v[176:179], v144, s[52:53] offset:512
	global_load_dwordx4 v[180:183], v226, s[52:53]
	v_add_u32_e32 v144, v217, v233
	global_load_dwordx4 v[184:187], v144, s[52:53]
	global_load_dwordx4 v[188:191], v226, s[52:53] offset:512
	v_add_u32_e32 v144, v217, v233
	global_load_dwordx4 v[192:195], v144, s[52:53] offset:512
	global_load_dwordx4 v[196:199], v227, s[52:53]
	v_add_u32_e32 v144, v218, v233
	global_load_dwordx4 v[200:203], v144, s[52:53]
	global_load_dwordx4 v[204:207], v227, s[52:53] offset:512
	v_add_u32_e32 v144, v218, v233
	global_load_dwordx4 v[208:211], v144, s[52:53] offset:512
	s_barrier
;     __device__ __forceinline__ void operator()(AccRef acc, const Unit& u, int wr, int wc, int fr, int fq) const {
;     ...
;                         for (int n = 0; n < 2; ++n) bs[m][bj][n] = *(const f32x4*)(base + (size_t)(row0 + ai * 128 + (2 * mh + m) * 16) * D + col0 + bj * 128 + n * 16);
; #pragma unroll
;                 for (int m = 0; m < 2; ++m)
; #pragma unroll
;                     for (int bj = 0; bj < 2; ++bj)
; #pragma unroll
;                         for (int n = 0; n < 2; ++n) *(f32x4*)(out + (size_t)(row0 + ai * 128 + (2 * mh + m) * 16) * D + col0 + bj * 128 + n * 16) = bs[m][bj][n] + sv[bj][n] * (acc[ai][bj][2 * mh + m][n] + bv[bj][n]);
	v_pk_add_f32 v[124:125], v[124:125], 0 op_sel_hi:[1,0]
	v_pk_add_f32 v[126:127], v[126:127], 0 op_sel_hi:[1,0]
	v_pk_add_f32 v[120:121], v[120:121], 0 op_sel_hi:[1,0]
	v_pk_add_f32 v[122:123], v[122:123], 0 op_sel_hi:[1,0]
	v_pk_add_f32 v[116:117], v[116:117], 0 op_sel_hi:[1,0]
	v_pk_add_f32 v[118:119], v[118:119], 0 op_sel_hi:[1,0]
	v_pk_add_f32 v[108:109], v[108:109], 0 op_sel_hi:[1,0]
	v_pk_add_f32 v[110:111], v[110:111], 0 op_sel_hi:[1,0]
	v_pk_add_f32 v[112:113], v[112:113], 0 op_sel_hi:[1,0]
	v_pk_add_f32 v[114:115], v[114:115], 0 op_sel_hi:[1,0]
	v_pk_add_f32 v[104:105], v[104:105], 0 op_sel_hi:[1,0]
	v_pk_add_f32 v[106:107], v[106:107], 0 op_sel_hi:[1,0]
	v_pk_add_f32 v[100:101], v[100:101], 0 op_sel_hi:[1,0]
	v_pk_add_f32 v[102:103], v[102:103], 0 op_sel_hi:[1,0]
	v_pk_add_f32 v[96:97], v[96:97], 0 op_sel_hi:[1,0]
	v_pk_add_f32 v[98:99], v[98:99], 0 op_sel_hi:[1,0]
	v_pk_add_f32 v[92:93], v[92:93], 0 op_sel_hi:[1,0]
	v_pk_add_f32 v[94:95], v[94:95], 0 op_sel_hi:[1,0]
	v_pk_add_f32 v[88:89], v[88:89], 0 op_sel_hi:[1,0]
	v_pk_add_f32 v[90:91], v[90:91], 0 op_sel_hi:[1,0]
	v_pk_add_f32 v[84:85], v[84:85], 0 op_sel_hi:[1,0]
	v_pk_add_f32 v[86:87], v[86:87], 0 op_sel_hi:[1,0]
	v_pk_add_f32 v[76:77], v[76:77], 0 op_sel_hi:[1,0]
	v_pk_add_f32 v[78:79], v[78:79], 0 op_sel_hi:[1,0]
	v_pk_add_f32 v[80:81], v[80:81], 0 op_sel_hi:[1,0]
	v_pk_add_f32 v[82:83], v[82:83], 0 op_sel_hi:[1,0]
	v_pk_add_f32 v[72:73], v[72:73], 0 op_sel_hi:[1,0]
	v_pk_add_f32 v[74:75], v[74:75], 0 op_sel_hi:[1,0]
	v_pk_add_f32 v[68:69], v[68:69], 0 op_sel_hi:[1,0]
	v_pk_add_f32 v[70:71], v[70:71], 0 op_sel_hi:[1,0]
	v_pk_add_f32 v[64:65], v[64:65], 0 op_sel_hi:[1,0]
	v_pk_add_f32 v[66:67], v[66:67], 0 op_sel_hi:[1,0]
	v_pk_add_f32 v[60:61], v[60:61], 0 op_sel_hi:[1,0]
	v_pk_add_f32 v[62:63], v[62:63], 0 op_sel_hi:[1,0]
	v_pk_add_f32 v[56:57], v[56:57], 0 op_sel_hi:[1,0]
	v_pk_add_f32 v[58:59], v[58:59], 0 op_sel_hi:[1,0]
	v_pk_add_f32 v[52:53], v[52:53], 0 op_sel_hi:[1,0]
	v_pk_add_f32 v[54:55], v[54:55], 0 op_sel_hi:[1,0]
	v_pk_add_f32 v[44:45], v[44:45], 0 op_sel_hi:[1,0]
	v_pk_add_f32 v[46:47], v[46:47], 0 op_sel_hi:[1,0]
	v_pk_add_f32 v[48:49], v[48:49], 0 op_sel_hi:[1,0]
	v_pk_add_f32 v[50:51], v[50:51], 0 op_sel_hi:[1,0]
	v_pk_add_f32 v[40:41], v[40:41], 0 op_sel_hi:[1,0]
	v_pk_add_f32 v[42:43], v[42:43], 0 op_sel_hi:[1,0]
	v_pk_add_f32 v[36:37], v[36:37], 0 op_sel_hi:[1,0]
	v_pk_add_f32 v[38:39], v[38:39], 0 op_sel_hi:[1,0]
	v_pk_add_f32 v[32:33], v[32:33], 0 op_sel_hi:[1,0]
	v_pk_add_f32 v[34:35], v[34:35], 0 op_sel_hi:[1,0]
	v_pk_add_f32 v[28:29], v[28:29], 0 op_sel_hi:[1,0]
	v_pk_add_f32 v[30:31], v[30:31], 0 op_sel_hi:[1,0]
	v_pk_add_f32 v[24:25], v[24:25], 0 op_sel_hi:[1,0]
	v_pk_add_f32 v[26:27], v[26:27], 0 op_sel_hi:[1,0]
	v_pk_add_f32 v[20:21], v[20:21], 0 op_sel_hi:[1,0]
	v_pk_add_f32 v[22:23], v[22:23], 0 op_sel_hi:[1,0]
	v_pk_add_f32 v[12:13], v[12:13], 0 op_sel_hi:[1,0]
	v_pk_add_f32 v[14:15], v[14:15], 0 op_sel_hi:[1,0]
	v_pk_add_f32 v[16:17], v[16:17], 0 op_sel_hi:[1,0]
	v_pk_add_f32 v[18:19], v[18:19], 0 op_sel_hi:[1,0]
	v_pk_add_f32 v[8:9], v[8:9], 0 op_sel_hi:[1,0]
	v_pk_add_f32 v[10:11], v[10:11], 0 op_sel_hi:[1,0]
	v_pk_add_f32 v[4:5], v[4:5], 0 op_sel_hi:[1,0]
	v_pk_add_f32 v[6:7], v[6:7], 0 op_sel_hi:[1,0]
	v_pk_add_f32 v[0:1], v[0:1], 0 op_sel_hi:[1,0]
	v_pk_add_f32 v[2:3], v[2:3], 0 op_sel_hi:[1,0]
	s_waitcnt vmcnt(8)
	v_mov_b32_e32 v212, v124
	v_mov_b32_e32 v213, v125
	v_mov_b32_e32 v214, v126
	v_mov_b32_e32 v215, v127
	s_nop 0
	v_mov_b32_dpp v124, v120 row_shr:8 row_mask:0xf bank_mask:0xc
	v_mov_b32_dpp v125, v121 row_shr:8 row_mask:0xf bank_mask:0xc
	v_mov_b32_dpp v126, v122 row_shr:8 row_mask:0xf bank_mask:0xc
	v_mov_b32_dpp v127, v123 row_shr:8 row_mask:0xf bank_mask:0xc
	v_mov_b32_dpp v120, v212 row_shl:8 row_mask:0xf bank_mask:0x3
	v_mov_b32_dpp v121, v213 row_shl:8 row_mask:0xf bank_mask:0x3
	v_mov_b32_dpp v122, v214 row_shl:8 row_mask:0xf bank_mask:0x3
	v_mov_b32_dpp v123, v215 row_shl:8 row_mask:0xf bank_mask:0x3
	v_mov_b32_e32 v212, v116
	v_mov_b32_e32 v213, v117
	v_mov_b32_e32 v214, v118
	v_mov_b32_e32 v215, v119
	s_nop 0
	v_mov_b32_dpp v116, v108 row_shr:8 row_mask:0xf bank_mask:0xc
	v_mov_b32_dpp v117, v109 row_shr:8 row_mask:0xf bank_mask:0xc
	v_mov_b32_dpp v118, v110 row_shr:8 row_mask:0xf bank_mask:0xc
	v_mov_b32_dpp v119, v111 row_shr:8 row_mask:0xf bank_mask:0xc
	v_mov_b32_dpp v108, v212 row_shl:8 row_mask:0xf bank_mask:0x3
	v_mov_b32_dpp v109, v213 row_shl:8 row_mask:0xf bank_mask:0x3
	v_mov_b32_dpp v110, v214 row_shl:8 row_mask:0xf bank_mask:0x3
	v_mov_b32_dpp v111, v215 row_shl:8 row_mask:0xf bank_mask:0x3
	v_mov_b32_e32 v212, v112
	v_mov_b32_e32 v213, v113
	v_mov_b32_e32 v214, v114
	v_mov_b32_e32 v215, v115
	s_nop 0
	v_mov_b32_dpp v112, v104 row_shr:8 row_mask:0xf bank_mask:0xc
	v_mov_b32_dpp v113, v105 row_shr:8 row_mask:0xf bank_mask:0xc
	v_mov_b32_dpp v114, v106 row_shr:8 row_mask:0xf bank_mask:0xc
	v_mov_b32_dpp v115, v107 row_shr:8 row_mask:0xf bank_mask:0xc
	v_mov_b32_dpp v104, v212 row_shl:8 row_mask:0xf bank_mask:0x3
	v_mov_b32_dpp v105, v213 row_shl:8 row_mask:0xf bank_mask:0x3
	v_mov_b32_dpp v106, v214 row_shl:8 row_mask:0xf bank_mask:0x3
	v_mov_b32_dpp v107, v215 row_shl:8 row_mask:0xf bank_mask:0x3
	v_mov_b32_e32 v212, v100
	v_mov_b32_e32 v213, v101
	v_mov_b32_e32 v214, v102
	v_mov_b32_e32 v215, v103
	s_nop 0
	v_mov_b32_dpp v100, v96 row_shr:8 row_mask:0xf bank_mask:0xc
	v_mov_b32_dpp v101, v97 row_shr:8 row_mask:0xf bank_mask:0xc
	v_mov_b32_dpp v102, v98 row_shr:8 row_mask:0xf bank_mask:0xc
	v_mov_b32_dpp v103, v99 row_shr:8 row_mask:0xf bank_mask:0xc
	v_mov_b32_dpp v96, v212 row_shl:8 row_mask:0xf bank_mask:0x3
;     __device__ __forceinline__ void operator()(AccRef acc, const Unit& u, int wr, int wc, int fr, int fq) const {
;     ...
;         for (int ai = 0; ai < 2; ++ai)
; #pragma unroll
;             for (int mh = 0; mh < 2; ++mh) {
;                 f32x4 bs[2][2][2];
; #pragma unroll
;                 for (int m = 0; m < 2; ++m)
; #pragma unroll
;                     for (int bj = 0; bj < 2; ++bj)
; #pragma unroll
;                         for (int n = 0; n < 2; ++n) bs[m][bj][n] = *(const f32x4*)(base + (size_t)(row0 + ai * 128 + (2 * mh + m) * 16) * D + col0 + bj * 128 + n * 16);
; #pragma unroll
;                 for (int m = 0; m < 2; ++m)
; #pragma unroll
;                     for (int bj = 0; bj < 2; ++bj)
; #pragma unroll
;                         for (int n = 0; n < 2; ++n) *(f32x4*)(out + (size_t)(row0 + ai * 128 + (2 * mh + m) * 16) * D + col0 + bj * 128 + n * 16) = bs[m][bj][n] + sv[bj][n] * (acc[ai][bj][2 * mh + m][n] + bv[bj][n]);
;                 asm volatile("" ::: "memory"); }
	v_mov_b32_dpp v97, v213 row_shl:8 row_mask:0xf bank_mask:0x3
	v_mov_b32_dpp v98, v214 row_shl:8 row_mask:0xf bank_mask:0x3
	v_mov_b32_dpp v99, v215 row_shl:8 row_mask:0xf bank_mask:0x3
	v_pk_add_f32 v[124:125], v[124:125], v[140:141]
	v_pk_add_f32 v[126:127], v[126:127], v[142:143]
	v_pk_add_f32 v[120:121], v[120:121], v[152:153]
	v_pk_add_f32 v[122:123], v[122:123], v[154:155]
	v_pk_add_f32 v[116:117], v[116:117], v[156:157]
	v_pk_add_f32 v[118:119], v[118:119], v[158:159]
	v_pk_add_f32 v[108:109], v[108:109], v[160:161]
	v_pk_add_f32 v[110:111], v[110:111], v[162:163]
	v_pk_add_f32 v[112:113], v[112:113], v[164:165]
	v_pk_add_f32 v[114:115], v[114:115], v[166:167]
	v_pk_add_f32 v[104:105], v[104:105], v[168:169]
	v_pk_add_f32 v[106:107], v[106:107], v[170:171]
	v_pk_add_f32 v[100:101], v[100:101], v[172:173]
	v_pk_add_f32 v[102:103], v[102:103], v[174:175]
	v_pk_add_f32 v[96:97], v[96:97], v[176:177]
	v_pk_add_f32 v[98:99], v[98:99], v[178:179]
	global_store_dwordx4 v224, v[124:127], s[52:53]
	v_add_u32_e32 v144, v145, v233
	global_store_dwordx4 v144, v[120:123], s[52:53]
	global_store_dwordx4 v224, v[116:119], s[52:53] offset:512
	v_add_u32_e32 v144, v145, v233
	global_store_dwordx4 v144, v[108:111], s[52:53] offset:512
	global_store_dwordx4 v225, v[112:115], s[52:53]
	v_add_u32_e32 v144, v216, v233
	global_store_dwordx4 v144, v[104:107], s[52:53]
	global_store_dwordx4 v225, v[100:103], s[52:53] offset:512
	v_add_u32_e32 v144, v216, v233
	global_store_dwordx4 v144, v[96:99], s[52:53] offset:512
	global_load_dwordx4 v[140:143], v228, s[52:53]
	v_add_u32_e32 v144, v220, v233
	global_load_dwordx4 v[152:155], v144, s[52:53]
	global_load_dwordx4 v[156:159], v228, s[52:53] offset:512
	v_add_u32_e32 v144, v220, v233
	global_load_dwordx4 v[160:163], v144, s[52:53] offset:512
	global_load_dwordx4 v[164:167], v229, s[52:53]
	v_add_u32_e32 v144, v221, v233
	global_load_dwordx4 v[168:171], v144, s[52:53]
	global_load_dwordx4 v[172:175], v229, s[52:53] offset:512
	v_add_u32_e32 v144, v221, v233
	global_load_dwordx4 v[176:179], v144, s[52:53] offset:512
	s_barrier
	s_waitcnt vmcnt(16)
	v_mov_b32_e32 v212, v92
	v_mov_b32_e32 v213, v93
	v_mov_b32_e32 v214, v94
	v_mov_b32_e32 v215, v95
	s_nop 0
	v_mov_b32_dpp v92, v88 row_shr:8 row_mask:0xf bank_mask:0xc
	v_mov_b32_dpp v93, v89 row_shr:8 row_mask:0xf bank_mask:0xc
	v_mov_b32_dpp v94, v90 row_shr:8 row_mask:0xf bank_mask:0xc
	v_mov_b32_dpp v95, v91 row_shr:8 row_mask:0xf bank_mask:0xc
	v_mov_b32_dpp v88, v212 row_shl:8 row_mask:0xf bank_mask:0x3
	v_mov_b32_dpp v89, v213 row_shl:8 row_mask:0xf bank_mask:0x3
	v_mov_b32_dpp v90, v214 row_shl:8 row_mask:0xf bank_mask:0x3
	v_mov_b32_dpp v91, v215 row_shl:8 row_mask:0xf bank_mask:0x3
	v_mov_b32_e32 v212, v84
	v_mov_b32_e32 v213, v85
	v_mov_b32_e32 v214, v86
	v_mov_b32_e32 v215, v87
	s_nop 0
	v_mov_b32_dpp v84, v76 row_shr:8 row_mask:0xf bank_mask:0xc
	v_mov_b32_dpp v85, v77 row_shr:8 row_mask:0xf bank_mask:0xc
	v_mov_b32_dpp v86, v78 row_shr:8 row_mask:0xf bank_mask:0xc
	v_mov_b32_dpp v87, v79 row_shr:8 row_mask:0xf bank_mask:0xc
	v_mov_b32_dpp v76, v212 row_shl:8 row_mask:0xf bank_mask:0x3
	v_mov_b32_dpp v77, v213 row_shl:8 row_mask:0xf bank_mask:0x3
	v_mov_b32_dpp v78, v214 row_shl:8 row_mask:0xf bank_mask:0x3
	v_mov_b32_dpp v79, v215 row_shl:8 row_mask:0xf bank_mask:0x3
	v_mov_b32_e32 v212, v80
	v_mov_b32_e32 v213, v81
	v_mov_b32_e32 v214, v82
	v_mov_b32_e32 v215, v83
	s_nop 0
	v_mov_b32_dpp v80, v72 row_shr:8 row_mask:0xf bank_mask:0xc
	v_mov_b32_dpp v81, v73 row_shr:8 row_mask:0xf bank_mask:0xc
	v_mov_b32_dpp v82, v74 row_shr:8 row_mask:0xf bank_mask:0xc
	v_mov_b32_dpp v83, v75 row_shr:8 row_mask:0xf bank_mask:0xc
	v_mov_b32_dpp v72, v212 row_shl:8 row_mask:0xf bank_mask:0x3
	v_mov_b32_dpp v73, v213 row_shl:8 row_mask:0xf bank_mask:0x3
	v_mov_b32_dpp v74, v214 row_shl:8 row_mask:0xf bank_mask:0x3
	v_mov_b32_dpp v75, v215 row_shl:8 row_mask:0xf bank_mask:0x3
	v_mov_b32_e32 v212, v68
	v_mov_b32_e32 v213, v69
	v_mov_b32_e32 v214, v70
	v_mov_b32_e32 v215, v71
	s_nop 0
	v_mov_b32_dpp v68, v64 row_shr:8 row_mask:0xf bank_mask:0xc
	v_mov_b32_dpp v69, v65 row_shr:8 row_mask:0xf bank_mask:0xc
	v_mov_b32_dpp v70, v66 row_shr:8 row_mask:0xf bank_mask:0xc
	v_mov_b32_dpp v71, v67 row_shr:8 row_mask:0xf bank_mask:0xc
	v_mov_b32_dpp v64, v212 row_shl:8 row_mask:0xf bank_mask:0x3
	v_mov_b32_dpp v65, v213 row_shl:8 row_mask:0xf bank_mask:0x3
	v_mov_b32_dpp v66, v214 row_shl:8 row_mask:0xf bank_mask:0x3
	v_mov_b32_dpp v67, v215 row_shl:8 row_mask:0xf bank_mask:0x3
	v_pk_add_f32 v[92:93], v[92:93], v[180:181]
	v_pk_add_f32 v[94:95], v[94:95], v[182:183]
	v_pk_add_f32 v[88:89], v[88:89], v[184:185]
	v_pk_add_f32 v[90:91], v[90:91], v[186:187]
	v_pk_add_f32 v[84:85], v[84:85], v[188:189]
	v_pk_add_f32 v[86:87], v[86:87], v[190:191]
	v_pk_add_f32 v[76:77], v[76:77], v[192:193]
	v_pk_add_f32 v[78:79], v[78:79], v[194:195]
	v_pk_add_f32 v[80:81], v[80:81], v[196:197]
	v_pk_add_f32 v[82:83], v[82:83], v[198:199]
	v_pk_add_f32 v[72:73], v[72:73], v[200:201]
	v_pk_add_f32 v[74:75], v[74:75], v[202:203]
	v_pk_add_f32 v[68:69], v[68:69], v[204:205]
	v_pk_add_f32 v[70:71], v[70:71], v[206:207]
	v_pk_add_f32 v[64:65], v[64:65], v[208:209]
	v_pk_add_f32 v[66:67], v[66:67], v[210:211]
	global_store_dwordx4 v226, v[92:95], s[52:53]
	v_add_u32_e32 v144, v217, v233
	global_store_dwordx4 v144, v[88:91], s[52:53]
	global_store_dwordx4 v226, v[84:87], s[52:53] offset:512
	v_add_u32_e32 v144, v217, v233
	global_store_dwordx4 v144, v[76:79], s[52:53] offset:512
	global_store_dwordx4 v227, v[80:83], s[52:53]
	v_add_u32_e32 v144, v218, v233
	global_store_dwordx4 v144, v[72:75], s[52:53]
	global_store_dwordx4 v227, v[68:71], s[52:53] offset:512
	v_add_u32_e32 v144, v218, v233
	global_store_dwordx4 v144, v[64:67], s[52:53] offset:512
	global_load_dwordx4 v[180:183], v230, s[52:53]
	v_add_u32_e32 v144, v222, v233
	global_load_dwordx4 v[184:187], v144, s[52:53]
	global_load_dwordx4 v[188:191], v230, s[52:53] offset:512
	v_add_u32_e32 v144, v222, v233
	global_load_dwordx4 v[192:195], v144, s[52:53] offset:512
	global_load_dwordx4 v[196:199], v231, s[52:53]
	v_add_u32_e32 v144, v223, v233
	global_load_dwordx4 v[200:203], v144, s[52:53]
	global_load_dwordx4 v[204:207], v231, s[52:53] offset:512
	v_add_u32_e32 v144, v223, v233
	global_load_dwordx4 v[208:211], v144, s[52:53] offset:512
	s_barrier
;     __device__ __forceinline__ void operator()(AccRef acc, const Unit& u, int wr, int wc, int fr, int fq) const {
;     ...
;                         for (int n = 0; n < 2; ++n) bs[m][bj][n] = *(const f32x4*)(base + (size_t)(row0 + ai * 128 + (2 * mh + m) * 16) * D + col0 + bj * 128 + n * 16);
; #pragma unroll
;                 for (int m = 0; m < 2; ++m)
; #pragma unroll
;                     for (int bj = 0; bj < 2; ++bj)
; #pragma unroll
;                         for (int n = 0; n < 2; ++n) *(f32x4*)(out + (size_t)(row0 + ai * 128 + (2 * mh + m) * 16) * D + col0 + bj * 128 + n * 16) = bs[m][bj][n] + sv[bj][n] * (acc[ai][bj][2 * mh + m][n] + bv[bj][n]);
;                 asm volatile("" ::: "memory"); }
	s_waitcnt vmcnt(16)
	v_mov_b32_e32 v212, v60
	v_mov_b32_e32 v213, v61
	v_mov_b32_e32 v214, v62
	v_mov_b32_e32 v215, v63
	s_nop 0
	v_mov_b32_dpp v60, v56 row_shr:8 row_mask:0xf bank_mask:0xc
	v_mov_b32_dpp v61, v57 row_shr:8 row_mask:0xf bank_mask:0xc
	v_mov_b32_dpp v62, v58 row_shr:8 row_mask:0xf bank_mask:0xc
	v_mov_b32_dpp v63, v59 row_shr:8 row_mask:0xf bank_mask:0xc
	v_mov_b32_dpp v56, v212 row_shl:8 row_mask:0xf bank_mask:0x3
	v_mov_b32_dpp v57, v213 row_shl:8 row_mask:0xf bank_mask:0x3
	v_mov_b32_dpp v58, v214 row_shl:8 row_mask:0xf bank_mask:0x3
	v_mov_b32_dpp v59, v215 row_shl:8 row_mask:0xf bank_mask:0x3
	v_mov_b32_e32 v212, v52
	v_mov_b32_e32 v213, v53
	v_mov_b32_e32 v214, v54
	v_mov_b32_e32 v215, v55
	s_nop 0
	v_mov_b32_dpp v52, v44 row_shr:8 row_mask:0xf bank_mask:0xc
	v_mov_b32_dpp v53, v45 row_shr:8 row_mask:0xf bank_mask:0xc
	v_mov_b32_dpp v54, v46 row_shr:8 row_mask:0xf bank_mask:0xc
	v_mov_b32_dpp v55, v47 row_shr:8 row_mask:0xf bank_mask:0xc
	v_mov_b32_dpp v44, v212 row_shl:8 row_mask:0xf bank_mask:0x3
	v_mov_b32_dpp v45, v213 row_shl:8 row_mask:0xf bank_mask:0x3
	v_mov_b32_dpp v46, v214 row_shl:8 row_mask:0xf bank_mask:0x3
	v_mov_b32_dpp v47, v215 row_shl:8 row_mask:0xf bank_mask:0x3
	v_mov_b32_e32 v212, v48
	v_mov_b32_e32 v213, v49
	v_mov_b32_e32 v214, v50
	v_mov_b32_e32 v215, v51
	s_nop 0
	v_mov_b32_dpp v48, v40 row_shr:8 row_mask:0xf bank_mask:0xc
	v_mov_b32_dpp v49, v41 row_shr:8 row_mask:0xf bank_mask:0xc
	v_mov_b32_dpp v50, v42 row_shr:8 row_mask:0xf bank_mask:0xc
	v_mov_b32_dpp v51, v43 row_shr:8 row_mask:0xf bank_mask:0xc
	v_mov_b32_dpp v40, v212 row_shl:8 row_mask:0xf bank_mask:0x3
	v_mov_b32_dpp v41, v213 row_shl:8 row_mask:0xf bank_mask:0x3
	v_mov_b32_dpp v42, v214 row_shl:8 row_mask:0xf bank_mask:0x3
	v_mov_b32_dpp v43, v215 row_shl:8 row_mask:0xf bank_mask:0x3
	v_mov_b32_e32 v212, v36
	v_mov_b32_e32 v213, v37
	v_mov_b32_e32 v214, v38
	v_mov_b32_e32 v215, v39
	s_nop 0
	v_mov_b32_dpp v36, v32 row_shr:8 row_mask:0xf bank_mask:0xc
	v_mov_b32_dpp v37, v33 row_shr:8 row_mask:0xf bank_mask:0xc
	v_mov_b32_dpp v38, v34 row_shr:8 row_mask:0xf bank_mask:0xc
	v_mov_b32_dpp v39, v35 row_shr:8 row_mask:0xf bank_mask:0xc
	v_mov_b32_dpp v32, v212 row_shl:8 row_mask:0xf bank_mask:0x3
	v_mov_b32_dpp v33, v213 row_shl:8 row_mask:0xf bank_mask:0x3
	v_mov_b32_dpp v34, v214 row_shl:8 row_mask:0xf bank_mask:0x3
	v_mov_b32_dpp v35, v215 row_shl:8 row_mask:0xf bank_mask:0x3
	v_pk_add_f32 v[60:61], v[60:61], v[140:141]
	v_pk_add_f32 v[62:63], v[62:63], v[142:143]
	v_pk_add_f32 v[56:57], v[56:57], v[152:153]
	v_pk_add_f32 v[58:59], v[58:59], v[154:155]
	v_pk_add_f32 v[52:53], v[52:53], v[156:157]
	v_pk_add_f32 v[54:55], v[54:55], v[158:159]
	v_pk_add_f32 v[44:45], v[44:45], v[160:161]
	v_pk_add_f32 v[46:47], v[46:47], v[162:163]
	v_pk_add_f32 v[48:49], v[48:49], v[164:165]
	v_pk_add_f32 v[50:51], v[50:51], v[166:167]
	v_pk_add_f32 v[40:41], v[40:41], v[168:169]
	v_pk_add_f32 v[42:43], v[42:43], v[170:171]
	v_pk_add_f32 v[36:37], v[36:37], v[172:173]
	v_pk_add_f32 v[38:39], v[38:39], v[174:175]
	v_pk_add_f32 v[32:33], v[32:33], v[176:177]
	v_pk_add_f32 v[34:35], v[34:35], v[178:179]
	global_store_dwordx4 v228, v[60:63], s[52:53]
	v_add_u32_e32 v144, v220, v233
	global_store_dwordx4 v144, v[56:59], s[52:53]
	global_store_dwordx4 v228, v[52:55], s[52:53] offset:512
	v_add_u32_e32 v144, v220, v233
	global_store_dwordx4 v144, v[44:47], s[52:53] offset:512
	global_store_dwordx4 v229, v[48:51], s[52:53]
	v_add_u32_e32 v144, v221, v233
	global_store_dwordx4 v144, v[40:43], s[52:53]
	global_store_dwordx4 v229, v[36:39], s[52:53] offset:512
	v_add_u32_e32 v144, v221, v233
	global_store_dwordx4 v144, v[32:35], s[52:53] offset:512
	s_barrier
; #define PG8_WAIT_V(n) asm volatile("s_waitcnt vmcnt(" #n ")" ::: "memory")
; #define PG8_BAR __builtin_amdgcn_s_barrier()
; template <class Epi>
; __device__ __forceinline__ void gemm_phase(LAS unsigned char* lds, const Gemm g, const StaticOrder& S, const Epi& E) {
;     ...
;         cur = nxt; cA = nA; cB = nB; ++ui;
;     }
;     PG8_WAIT_V(0);
;     if (wr == 0) PG8_BAR;
;     PG8_BAR;
;     __device__ __forceinline__ void operator()(AccRef acc, const Unit& u, int wr, int wc, int fr, int fq) const {
;     ...
;                         for (int n = 0; n < 2; ++n) bs[m][bj][n] = *(const f32x4*)(base + (size_t)(row0 + ai * 128 + (2 * mh + m) * 16) * D + col0 + bj * 128 + n * 16);
; #pragma unroll
;                 for (int m = 0; m < 2; ++m)
; #pragma unroll
;                     for (int bj = 0; bj < 2; ++bj)
; #pragma unroll
;                         for (int n = 0; n < 2; ++n) *(f32x4*)(out + (size_t)(row0 + ai * 128 + (2 * mh + m) * 16) * D + col0 + bj * 128 + n * 16) = bs[m][bj][n] + sv[bj][n] * (acc[ai][bj][2 * mh + m][n] + bv[bj][n]);
;                 asm volatile("" ::: "memory"); }
	s_waitcnt vmcnt(8)
	v_mov_b32_e32 v212, v28
	v_mov_b32_e32 v213, v29
	v_mov_b32_e32 v214, v30
	v_mov_b32_e32 v215, v31
	s_nop 0
	v_mov_b32_dpp v28, v24 row_shr:8 row_mask:0xf bank_mask:0xc
	v_mov_b32_dpp v29, v25 row_shr:8 row_mask:0xf bank_mask:0xc
	v_mov_b32_dpp v30, v26 row_shr:8 row_mask:0xf bank_mask:0xc
	v_mov_b32_dpp v31, v27 row_shr:8 row_mask:0xf bank_mask:0xc
	v_mov_b32_dpp v24, v212 row_shl:8 row_mask:0xf bank_mask:0x3
	v_mov_b32_dpp v25, v213 row_shl:8 row_mask:0xf bank_mask:0x3
	v_mov_b32_dpp v26, v214 row_shl:8 row_mask:0xf bank_mask:0x3
	v_mov_b32_dpp v27, v215 row_shl:8 row_mask:0xf bank_mask:0x3
	v_mov_b32_e32 v212, v20
	v_mov_b32_e32 v213, v21
	v_mov_b32_e32 v214, v22
	v_mov_b32_e32 v215, v23
	s_nop 0
	v_mov_b32_dpp v20, v12 row_shr:8 row_mask:0xf bank_mask:0xc
	v_mov_b32_dpp v21, v13 row_shr:8 row_mask:0xf bank_mask:0xc
	v_mov_b32_dpp v22, v14 row_shr:8 row_mask:0xf bank_mask:0xc
	v_mov_b32_dpp v23, v15 row_shr:8 row_mask:0xf bank_mask:0xc
	v_mov_b32_dpp v12, v212 row_shl:8 row_mask:0xf bank_mask:0x3
	v_mov_b32_dpp v13, v213 row_shl:8 row_mask:0xf bank_mask:0x3
	v_mov_b32_dpp v14, v214 row_shl:8 row_mask:0xf bank_mask:0x3
	v_mov_b32_dpp v15, v215 row_shl:8 row_mask:0xf bank_mask:0x3
	v_mov_b32_e32 v212, v16
	v_mov_b32_e32 v213, v17
	v_mov_b32_e32 v214, v18
	v_mov_b32_e32 v215, v19
	s_nop 0
	v_mov_b32_dpp v16, v8 row_shr:8 row_mask:0xf bank_mask:0xc
	v_mov_b32_dpp v17, v9 row_shr:8 row_mask:0xf bank_mask:0xc
	v_mov_b32_dpp v18, v10 row_shr:8 row_mask:0xf bank_mask:0xc
	v_mov_b32_dpp v19, v11 row_shr:8 row_mask:0xf bank_mask:0xc
	v_mov_b32_dpp v8, v212 row_shl:8 row_mask:0xf bank_mask:0x3
	v_mov_b32_dpp v9, v213 row_shl:8 row_mask:0xf bank_mask:0x3
	v_mov_b32_dpp v10, v214 row_shl:8 row_mask:0xf bank_mask:0x3
	v_mov_b32_dpp v11, v215 row_shl:8 row_mask:0xf bank_mask:0x3
	v_mov_b32_e32 v212, v4
	v_mov_b32_e32 v213, v5
	v_mov_b32_e32 v214, v6
	v_mov_b32_e32 v215, v7
	s_nop 0
	v_mov_b32_dpp v4, v0 row_shr:8 row_mask:0xf bank_mask:0xc
	v_mov_b32_dpp v5, v1 row_shr:8 row_mask:0xf bank_mask:0xc
	v_mov_b32_dpp v6, v2 row_shr:8 row_mask:0xf bank_mask:0xc
	v_mov_b32_dpp v7, v3 row_shr:8 row_mask:0xf bank_mask:0xc
	v_mov_b32_dpp v0, v212 row_shl:8 row_mask:0xf bank_mask:0x3
	v_mov_b32_dpp v1, v213 row_shl:8 row_mask:0xf bank_mask:0x3
	v_mov_b32_dpp v2, v214 row_shl:8 row_mask:0xf bank_mask:0x3
	v_mov_b32_dpp v3, v215 row_shl:8 row_mask:0xf bank_mask:0x3
	v_pk_add_f32 v[28:29], v[28:29], v[180:181]
	v_pk_add_f32 v[30:31], v[30:31], v[182:183]
	v_pk_add_f32 v[24:25], v[24:25], v[184:185]
	v_pk_add_f32 v[26:27], v[26:27], v[186:187]
	v_pk_add_f32 v[20:21], v[20:21], v[188:189]
	v_pk_add_f32 v[22:23], v[22:23], v[190:191]
	v_pk_add_f32 v[12:13], v[12:13], v[192:193]
	v_pk_add_f32 v[14:15], v[14:15], v[194:195]
	v_pk_add_f32 v[16:17], v[16:17], v[196:197]
	v_pk_add_f32 v[18:19], v[18:19], v[198:199]
	v_pk_add_f32 v[8:9], v[8:9], v[200:201]
	v_pk_add_f32 v[10:11], v[10:11], v[202:203]
	v_pk_add_f32 v[4:5], v[4:5], v[204:205]
	v_pk_add_f32 v[6:7], v[6:7], v[206:207]
	v_pk_add_f32 v[0:1], v[0:1], v[208:209]
	v_pk_add_f32 v[2:3], v[2:3], v[210:211]
	global_store_dwordx4 v230, v[28:31], s[52:53]
	v_add_u32_e32 v144, v222, v233
	global_store_dwordx4 v144, v[24:27], s[52:53]
	global_store_dwordx4 v230, v[20:23], s[52:53] offset:512
	v_add_u32_e32 v144, v222, v233
	global_store_dwordx4 v144, v[12:15], s[52:53] offset:512
	global_store_dwordx4 v231, v[16:19], s[52:53]
	v_add_u32_e32 v144, v223, v233
	global_store_dwordx4 v144, v[8:11], s[52:53]
	global_store_dwordx4 v231, v[4:7], s[52:53] offset:512
	v_add_u32_e32 v144, v223, v233
	global_store_dwordx4 v144, v[0:3], s[52:53] offset:512
	s_cbranch_vccz .LBB0_2031
	s_waitcnt vmcnt(0)
	s_cmpk_gt_u32 s26, 0xff
	s_cbranch_scc1 .LBB0_2046
	s_barrier
